# all GEMM phases (incl. the four small RWKV GEMMs and the GLU GEMM) on the hand-written LDS-DMA engine with LDS-transposed coalesced epilogues
# speedup vs baseline: 1.0434x; 1.0128x over previous
; template <class Epi>
; DI void gemm_phase(char* smem, const bf16_t* A0, int lda0, int ksplit, const bf16_t* A1, int lda1, const bf16_t* Bt, int K, int nN, const Epi& epi, int tid) {
;   const int G = gridDim.x;
;   if ((G & 7) == 0) {
;     const int x = blockIdx.x & 7, l = blockIdx.x >> 3, L = G >> 3, per = 8 * nN, tot = 2 * per;
;     for (int q = l; q < tot; q += L) { const int rgl = q / per, rem = q % per, ct = rem >> 3, rt = (x * 2 + rgl) * 8 + (rem & 7);
;       gemm_tile(smem, A0, lda0, ksplit, A1, lda1, Bt, K, rt * 256, ct * 128, epi, tid); }
; DI void phase_rw_small_gemms(const Ctx& c, char* smem) {
;   const Params& p = c.p; (void)p;
;   const int tid = TIDX;
;   const bf16_t* sm = (const bf16_t*)(p.ws + OFF_SM);
;   bf16_t* E0 = (bf16_t*)(p.ws + OFF_R1); bf16_t* E1 = E0 + (size_t)NTOK * 512; bf16_t* Ab = E1 + (size_t)NTOK * 512;
;   bf16_t* G = (bf16_t*)(p.ws + OFF_XN);
;   const bf16_t* W2 = (const bf16_t*)(p.ws + OFF_WW2); const bf16_t* A2 = (const bf16_t*)(p.ws + OFF_WA2); const bf16_t* G2 = (const bf16_t*)(p.ws + OFF_WG2);
;   gemm_phase(smem, sm, 256, 1 << 30, sm, 256, W2, 64, 4, EpiSmall{0, p.rw_w0, E0}, tid);
.LBB0_549:
	s_cmp_gt_i32 s94, 3
	s_cselect_b64 s[0:1], -1, 0
	s_cmp_lt_i32 s95, 4
	s_cselect_b64 s[2:3], -1, 0
	s_or_b64 s[0:1], s[0:1], s[2:3]
	s_and_b64 vcc, exec, s[0:1]
	s_cbranch_vccnz .LBB0_600
	s_and_b32 s14, s72, 0xffffffc0
	s_add_u32 s4, s92, 0x1ea00000
	s_load_dword s12, s[74:75], 0x180
	s_addc_u32 s5, s93, 0
	s_add_u32 s0, s92, 0x7800000
	s_addc_u32 s1, s93, 0
	s_add_u32 s6, s92, 0x34a0000
	s_addc_u32 s7, s93, 0
	s_waitcnt lgkmcnt(0)
	s_and_b32 s13, s12, 7
	s_cmp_lg_u32 s13, 0
	s_waitcnt vmcnt(7)
	v_mbcnt_hi_u32_b32 v136, -1, v194
	s_cselect_b64 s[2:3], -1, 0
	v_add_u32_e32 v137, s14, v136
	s_and_b64 vcc, exec, s[2:3]
	v_mbcnt_lo_u32_b32 v240, -1, 0
	v_mbcnt_hi_u32_b32 v240, -1, v240
	s_lshr_b32 s27, s72, 6
	s_lshl_b32 s100, s27, 10
	v_and_b32_e32 v241, 15, v240
	v_lshrrev_b32_e32 v242, 4, v240
	v_bfe_u32 v243, v240, 3, 1
	v_mul_u32_u24_e32 v243, 3, v243
	v_xor_b32_e32 v243, v242, v243
	v_lshlrev_b32_e32 v243, 4, v243
	v_lshl_add_u32 v243, v241, 6, v243
	s_lshr_b32 s26, s27, 1
	s_lshl_b32 s26, s26, 13
	v_add_u32_e32 v230, s26, v243
	s_and_b32 s26, s27, 1
	s_lshl_b32 s26, s26, 12
	s_add_u32 s26, s26, 16384
	v_add_u32_e32 v231, s26, v243
	s_lshr_b32 s26, s27, 1
	s_lshl_b32 s26, s26, 7
	v_add_u32_e32 v244, s26, v241
	s_and_b32 s26, s27, 1
	s_lshl_b32 s26, s26, 6
	v_lshl_add_u32 v245, v242, 2, s26
	v_lshlrev_b32_e32 v235, 2, v245
	s_mul_i32 s26, s27, 18432
	v_mul_u32_u24_e32 v246, 144, v241
	v_lshl_add_u32 v246, v242, 3, v246
	v_add_u32_e32 v236, s26, v246
	v_lshrrev_b32_e32 v246, 3, v240
	v_mul_u32_u24_e32 v246, 144, v246
	v_and_b32_e32 v247, 7, v240
	v_lshl_add_u32 v246, v247, 4, v246
	v_add_u32_e32 v237, s26, v246
	s_lshr_b32 s26, s27, 1
	s_lshl_b32 s26, s26, 7
	v_lshrrev_b32_e32 v246, 3, v240
	v_add_u32_e32 v246, s26, v246
	s_and_b32 s26, s27, 1
	s_lshl_b32 s26, s26, 6
	v_lshl_add_u32 v248, v247, 3, s26
	s_movk_i32 s26, 1024
	v_mul_lo_u32 v247, v246, s26
	v_lshl_add_u32 v238, v248, 1, v247
	v_lshrrev_b32_e32 v241, 2, v240
	s_lshl_b32 s26, s27, 4
	v_add_u32_e32 v241, s26, v241
	v_bfe_u32 v242, v240, 5, 1
	v_mul_u32_u24_e32 v242, 3, v242
	v_and_b32_e32 v243, 3, v240
	v_xor_b32_e32 v243, v243, v242
	v_lshlrev_b32_e32 v243, 4, v243
	s_mov_b32 s26, 512
	v_mad_u32_u24 v224, v241, s26, v243
	v_add_u32_e32 v225, 0x8000, v224
	v_add_u32_e32 v226, 0x10000, v224
	v_add_u32_e32 v227, 0x18000, v224
	s_mov_b32 s26, 128
	v_mad_u32_u24 v228, v241, s26, v243
	v_add_u32_e32 v229, 0x2000, v228
	s_load_dwordx2 s[6:7], s[74:75], 0x48
	s_lshr_b32 s15, s96, 3
	s_and_b32 s101, s96, 7
	s_lshl_b32 s101, s101, 1
	s_waitcnt lgkmcnt(0)
.Lg3a_tile:
	s_cmpk_ge_u32 s15, 64
	s_cbranch_scc1 .Lg3a_done
	s_cmpk_ge_u32 s15, 32
	s_cselect_b32 s27, 1, 0
	s_cselect_b32 s26, 32, 0
	s_sub_u32 s26, s15, s26
	s_add_u32 s27, s27, s101
	s_lshl_b32 s27, s27, 3
	s_and_b32 s29, s26, 7
	s_add_u32 s29, s29, s27
	s_lshl_b32 s29, s29, 8
	s_lshr_b32 s28, s26, 3
	s_lshl_b32 s28, s28, 7
	s_mul_i32 s27, s29, 512
	s_add_u32 s27, s27, 0x1ea00000
	s_add_u32 s0, s92, s27
	s_addc_u32 s1, s93, 0
	s_mul_i32 s27, s28, 128
	s_add_u32 s27, s27, 0x34a0000
	s_add_u32 s2, s92, s27
	s_addc_u32 s3, s93, 0
	s_waitcnt lgkmcnt(0)
	s_barrier
	s_mov_b32 s99, 0
	s_mov_b32 s30, 0
	s_add_u32 s26, s30, s100
	s_add_u32 m0, s26, 0
	s_nop 0
	global_load_lds_dwordx4 v224, s[0:1]
	s_add_u32 m0, s26, 4096
	s_nop 0
	global_load_lds_dwordx4 v225, s[0:1]
	s_add_u32 m0, s26, 8192
	s_nop 0
	global_load_lds_dwordx4 v226, s[0:1]
	s_add_u32 m0, s26, 12288
	s_nop 0
	global_load_lds_dwordx4 v227, s[0:1]
	s_add_u32 m0, s26, 16384
	s_nop 0
	global_load_lds_dwordx4 v228, s[2:3]
	s_add_u32 m0, s26, 20480
	s_nop 0
	global_load_lds_dwordx4 v229, s[2:3]
	s_add_u32 s0, s0, 64
	s_addc_u32 s1, s1, 0
	s_add_u32 s2, s2, 64
	s_addc_u32 s3, s3, 0
	s_add_u32 s99, s99, 1
	s_add_u32 s30, s30, 24576
	s_cmp_eq_u32 s30, 73728
	s_cselect_b32 s30, 0, s30
	s_add_u32 s26, s30, s100
	s_add_u32 m0, s26, 0
	s_nop 0
	global_load_lds_dwordx4 v224, s[0:1]
	s_add_u32 m0, s26, 4096
	s_nop 0
	global_load_lds_dwordx4 v225, s[0:1]
	s_add_u32 m0, s26, 8192
	s_nop 0
	global_load_lds_dwordx4 v226, s[0:1]
	s_add_u32 m0, s26, 12288
	s_nop 0
	global_load_lds_dwordx4 v227, s[0:1]
	s_add_u32 m0, s26, 16384
	s_nop 0
	global_load_lds_dwordx4 v228, s[2:3]
	s_add_u32 m0, s26, 20480
	s_nop 0
	global_load_lds_dwordx4 v229, s[2:3]
	s_add_u32 s0, s0, 64
	s_addc_u32 s1, s1, 0
	s_add_u32 s2, s2, 64
	s_addc_u32 s3, s3, 0
	s_add_u32 s99, s99, 1
	s_add_u32 s30, s30, 24576
	s_cmp_eq_u32 s30, 73728
	s_cselect_b32 s30, 0, s30
	v_mov_b32_e32 v0, 0
	v_mov_b32_e32 v1, 0
	v_mov_b32_e32 v2, 0
	v_mov_b32_e32 v3, 0
	v_mov_b32_e32 v4, 0
	v_mov_b32_e32 v5, 0
	v_mov_b32_e32 v6, 0
	v_mov_b32_e32 v7, 0
	v_mov_b32_e32 v8, 0
	v_mov_b32_e32 v9, 0
	v_mov_b32_e32 v10, 0
	v_mov_b32_e32 v11, 0
	v_mov_b32_e32 v12, 0
	v_mov_b32_e32 v13, 0
	v_mov_b32_e32 v14, 0
	v_mov_b32_e32 v15, 0
	v_mov_b32_e32 v16, 0
	v_mov_b32_e32 v17, 0
	v_mov_b32_e32 v18, 0
	v_mov_b32_e32 v19, 0
	v_mov_b32_e32 v20, 0
	v_mov_b32_e32 v21, 0
	v_mov_b32_e32 v22, 0
	v_mov_b32_e32 v23, 0
	v_mov_b32_e32 v24, 0
	v_mov_b32_e32 v25, 0
	v_mov_b32_e32 v26, 0
	v_mov_b32_e32 v27, 0
	v_mov_b32_e32 v28, 0
	v_mov_b32_e32 v29, 0
	v_mov_b32_e32 v30, 0
	v_mov_b32_e32 v31, 0
	v_mov_b32_e32 v32, 0
	v_mov_b32_e32 v33, 0
	v_mov_b32_e32 v34, 0
	v_mov_b32_e32 v35, 0
	v_mov_b32_e32 v36, 0
	v_mov_b32_e32 v37, 0
	v_mov_b32_e32 v38, 0
	v_mov_b32_e32 v39, 0
	v_mov_b32_e32 v40, 0
	v_mov_b32_e32 v41, 0
	v_mov_b32_e32 v42, 0
	v_mov_b32_e32 v43, 0
	v_mov_b32_e32 v44, 0
	v_mov_b32_e32 v45, 0
	v_mov_b32_e32 v46, 0
	v_mov_b32_e32 v47, 0
	v_mov_b32_e32 v48, 0
	v_mov_b32_e32 v49, 0
	v_mov_b32_e32 v50, 0
	v_mov_b32_e32 v51, 0
	v_mov_b32_e32 v52, 0
	v_mov_b32_e32 v53, 0
; #define LWRITE(S, buf) do { bf16_t* sA_ = sbase + (buf) * BUF; bf16_t* sB_ = sA_ + 256 * PITCH; \
;     _Pragma("unroll") for (int i_ = 0; i_ < 4; ++i_) *(u32x4*)(sA_ + (sr + i_ * 64) * PITCH + scv * 8) = ra[S][i_]; \
;     _Pragma("unroll") for (int i_ = 0; i_ < 2; ++i_) *(u32x4*)(sB_ + (sr + i_ * 64) * PITCH + scv * 8) = rb[S][i_]; } while (0)
; template <class Epi>
; DI void gemm_tile(char* smem, const bf16_t* __restrict__ A0, int lda0, int ksplit, const bf16_t* __restrict__ A1, int lda1,
;                   const bf16_t* __restrict__ Bt, int K, int row0, int col0, const Epi& epi, int tid) {
;     ...
;   __syncthreads();
;   {
;     const int last = nk - 1;
;     GLOAD(0, 0);
;     __builtin_amdgcn_sched_barrier(0);
;     GLOAD(1, 1);
;     __builtin_amdgcn_sched_barrier(0);
;     LWRITE(0, 0);
;     __builtin_amdgcn_sched_barrier(0);
;     GLOAD(0, (2 < last ? 2 : last));
;     __builtin_amdgcn_sched_barrier(0);
;     __syncthreads();
;     for (int kt = 0; kt < nk; kt += 2) {
;       LWRITE(1, 1);
;       __builtin_amdgcn_sched_barrier(0);
;       GLOAD(1, (kt + 3 < last ? kt + 3 : last));
;       __builtin_amdgcn_sched_barrier(0);
;       COMPUTE(0);
;       __syncthreads();
;       LWRITE(0, 0);
;       __builtin_amdgcn_sched_barrier(0);
;       GLOAD(0, (kt + 4 < last ? kt + 4 : last));
;       __builtin_amdgcn_sched_barrier(0);
;       COMPUTE(1);
;       __syncthreads();
	v_mov_b32_e32 v54, 0
	v_mov_b32_e32 v55, 0
	v_mov_b32_e32 v56, 0
	v_mov_b32_e32 v57, 0
	v_mov_b32_e32 v58, 0
	v_mov_b32_e32 v59, 0
	v_mov_b32_e32 v60, 0
	v_mov_b32_e32 v61, 0
	v_mov_b32_e32 v62, 0
	v_mov_b32_e32 v63, 0
	v_mov_b32_e32 v64, 0
	v_mov_b32_e32 v65, 0
	v_mov_b32_e32 v66, 0
	v_mov_b32_e32 v67, 0
	v_mov_b32_e32 v68, 0
	v_mov_b32_e32 v69, 0
	v_mov_b32_e32 v70, 0
	v_mov_b32_e32 v71, 0
	v_mov_b32_e32 v72, 0
	v_mov_b32_e32 v73, 0
	v_mov_b32_e32 v74, 0
	v_mov_b32_e32 v75, 0
	v_mov_b32_e32 v76, 0
	v_mov_b32_e32 v77, 0
	v_mov_b32_e32 v78, 0
	v_mov_b32_e32 v79, 0
	v_mov_b32_e32 v80, 0
	v_mov_b32_e32 v81, 0
	v_mov_b32_e32 v82, 0
	v_mov_b32_e32 v83, 0
	v_mov_b32_e32 v84, 0
	v_mov_b32_e32 v85, 0
	v_mov_b32_e32 v86, 0
	v_mov_b32_e32 v87, 0
	v_mov_b32_e32 v88, 0
	v_mov_b32_e32 v89, 0
	v_mov_b32_e32 v90, 0
	v_mov_b32_e32 v91, 0
	v_mov_b32_e32 v92, 0
	v_mov_b32_e32 v93, 0
	v_mov_b32_e32 v94, 0
	v_mov_b32_e32 v95, 0
	v_mov_b32_e32 v96, 0
	v_mov_b32_e32 v97, 0
	v_mov_b32_e32 v98, 0
	v_mov_b32_e32 v99, 0
	v_mov_b32_e32 v100, 0
	v_mov_b32_e32 v101, 0
	v_mov_b32_e32 v102, 0
	v_mov_b32_e32 v103, 0
	v_mov_b32_e32 v104, 0
	v_mov_b32_e32 v105, 0
	v_mov_b32_e32 v106, 0
	v_mov_b32_e32 v107, 0
	v_mov_b32_e32 v108, 0
	v_mov_b32_e32 v109, 0
	v_mov_b32_e32 v110, 0
	v_mov_b32_e32 v111, 0
	v_mov_b32_e32 v112, 0
	v_mov_b32_e32 v113, 0
	v_mov_b32_e32 v114, 0
	v_mov_b32_e32 v115, 0
	v_mov_b32_e32 v116, 0
	v_mov_b32_e32 v117, 0
	v_mov_b32_e32 v118, 0
	v_mov_b32_e32 v119, 0
	v_mov_b32_e32 v120, 0
	v_mov_b32_e32 v121, 0
	v_mov_b32_e32 v122, 0
	v_mov_b32_e32 v123, 0
	v_mov_b32_e32 v124, 0
	v_mov_b32_e32 v125, 0
	v_mov_b32_e32 v126, 0
	v_mov_b32_e32 v127, 0
	s_mov_b32 s98, 0
	s_mov_b32 s31, 24576
	s_waitcnt vmcnt(6)
	s_barrier
	ds_read_b128 v[128:131], v231 offset:0
	ds_read_b128 v[132:135], v231 offset:1024
	ds_read_b128 v[136:139], v231 offset:2048
	ds_read_b128 v[140:143], v231 offset:3072
	ds_read_b128 v[144:147], v230 offset:0
	ds_read_b128 v[148:151], v230 offset:1024
	ds_read_b128 v[152:155], v230 offset:2048
	ds_read_b128 v[156:159], v230 offset:3072
	ds_read_b128 v[160:163], v230 offset:4096
	ds_read_b128 v[164:167], v230 offset:5120
	ds_read_b128 v[168:171], v230 offset:6144
	ds_read_b128 v[172:175], v230 offset:7168
	s_waitcnt vmcnt(0)
	s_waitcnt lgkmcnt(0)
	s_barrier
	v_add_u32_e32 v232, s31, v230
	v_add_u32_e32 v233, s31, v231
	v_mfma_f32_16x16x32_bf16 v[0:3], v[128:131], v[144:147], v[0:3]
	v_mfma_f32_16x16x32_bf16 v[4:7], v[132:135], v[144:147], v[4:7]
	v_mfma_f32_16x16x32_bf16 v[8:11], v[136:139], v[144:147], v[8:11]
	v_mfma_f32_16x16x32_bf16 v[12:15], v[140:143], v[144:147], v[12:15]
	ds_read_b128 v[176:179], v233 offset:0
	ds_read_b128 v[180:183], v233 offset:1024
	v_mfma_f32_16x16x32_bf16 v[16:19], v[128:131], v[148:151], v[16:19]
	v_mfma_f32_16x16x32_bf16 v[20:23], v[132:135], v[148:151], v[20:23]
	v_mfma_f32_16x16x32_bf16 v[24:27], v[136:139], v[148:151], v[24:27]
	v_mfma_f32_16x16x32_bf16 v[28:31], v[140:143], v[148:151], v[28:31]
	ds_read_b128 v[184:187], v233 offset:2048
	ds_read_b128 v[188:191], v233 offset:3072
	v_mfma_f32_16x16x32_bf16 v[32:35], v[128:131], v[152:155], v[32:35]
	v_mfma_f32_16x16x32_bf16 v[36:39], v[132:135], v[152:155], v[36:39]
	v_mfma_f32_16x16x32_bf16 v[40:43], v[136:139], v[152:155], v[40:43]
	v_mfma_f32_16x16x32_bf16 v[44:47], v[140:143], v[152:155], v[44:47]
	ds_read_b128 v[192:195], v232 offset:0
	ds_read_b128 v[196:199], v232 offset:1024
	v_mfma_f32_16x16x32_bf16 v[48:51], v[128:131], v[156:159], v[48:51]
	v_mfma_f32_16x16x32_bf16 v[52:55], v[132:135], v[156:159], v[52:55]
	v_mfma_f32_16x16x32_bf16 v[56:59], v[136:139], v[156:159], v[56:59]
	v_mfma_f32_16x16x32_bf16 v[60:63], v[140:143], v[156:159], v[60:63]
	ds_read_b128 v[200:203], v232 offset:2048
	ds_read_b128 v[204:207], v232 offset:3072
	v_mfma_f32_16x16x32_bf16 v[64:67], v[128:131], v[160:163], v[64:67]
	v_mfma_f32_16x16x32_bf16 v[68:71], v[132:135], v[160:163], v[68:71]
	v_mfma_f32_16x16x32_bf16 v[72:75], v[136:139], v[160:163], v[72:75]
	v_mfma_f32_16x16x32_bf16 v[76:79], v[140:143], v[160:163], v[76:79]
	ds_read_b128 v[208:211], v232 offset:4096
	v_mfma_f32_16x16x32_bf16 v[80:83], v[128:131], v[164:167], v[80:83]
	v_mfma_f32_16x16x32_bf16 v[84:87], v[132:135], v[164:167], v[84:87]
	v_mfma_f32_16x16x32_bf16 v[88:91], v[136:139], v[164:167], v[88:91]
	v_mfma_f32_16x16x32_bf16 v[92:95], v[140:143], v[164:167], v[92:95]
	ds_read_b128 v[212:215], v232 offset:5120
	v_mfma_f32_16x16x32_bf16 v[96:99], v[128:131], v[168:171], v[96:99]
	v_mfma_f32_16x16x32_bf16 v[100:103], v[132:135], v[168:171], v[100:103]
	v_mfma_f32_16x16x32_bf16 v[104:107], v[136:139], v[168:171], v[104:107]
	v_mfma_f32_16x16x32_bf16 v[108:111], v[140:143], v[168:171], v[108:111]
	ds_read_b128 v[216:219], v232 offset:6144
	s_add_u32 s31, s31, 24576
	s_cmp_eq_u32 s31, 73728
	s_cselect_b32 s31, 0, s31
	v_mfma_f32_16x16x32_bf16 v[112:115], v[128:131], v[172:175], v[112:115]
	v_mfma_f32_16x16x32_bf16 v[116:119], v[132:135], v[172:175], v[116:119]
	v_mfma_f32_16x16x32_bf16 v[120:123], v[136:139], v[172:175], v[120:123]
	v_mfma_f32_16x16x32_bf16 v[124:127], v[140:143], v[172:175], v[124:127]
	ds_read_b128 v[220:223], v232 offset:7168
	s_waitcnt lgkmcnt(0)
	s_barrier
; DI unsigned pack2(float lo, float hi) { const f32x2c v = {lo, hi}; return __builtin_bit_cast(unsigned, __builtin_convertvector(v, bf16x2c)); }
; template <class Epi>
; DI void gemm_tile(char* smem, const bf16_t* __restrict__ A0, int lda0, int ksplit, const bf16_t* __restrict__ A1, int lda1,
;                   const bf16_t* __restrict__ Bt, int K, int row0, int col0, const Epi& epi, int tid) {
;     ...
; #pragma unroll
;   for (int m = 0; m < 8; ++m)
; #pragma unroll
;     for (int n = 0; n < 4; ++n) epi(row0 + wr * 128 + m * 16 + fr, col0 + wc * 64 + n * 16 + fq * 4, acc[m][n]);
; }
; DI void st_bf16x4(bf16_t* o, f32x4 v) { u32x2 q; q.x = pack2(v[0], v[1]); q.y = pack2(v[2], v[3]); *(u32x2*)o = q; }
;   DI void operator()(int row, int col, f32x4 v) const {
;     if (col < n0) st_bf16x4(o0 + (size_t)row * ld0 + col, v);
;     else { const int c = col - n0; if (c < n1) st_bf16x4(o1 + (size_t)row * ld1 + c, v); }
;   }
	v_mfma_f32_16x16x32_bf16 v[0:3], v[176:179], v[192:195], v[0:3]
	v_mfma_f32_16x16x32_bf16 v[4:7], v[180:183], v[192:195], v[4:7]
	v_mfma_f32_16x16x32_bf16 v[8:11], v[184:187], v[192:195], v[8:11]
	v_mfma_f32_16x16x32_bf16 v[12:15], v[188:191], v[192:195], v[12:15]
	v_mfma_f32_16x16x32_bf16 v[16:19], v[176:179], v[196:199], v[16:19]
	v_mfma_f32_16x16x32_bf16 v[20:23], v[180:183], v[196:199], v[20:23]
	v_mfma_f32_16x16x32_bf16 v[24:27], v[184:187], v[196:199], v[24:27]
	v_mfma_f32_16x16x32_bf16 v[28:31], v[188:191], v[196:199], v[28:31]
	v_mfma_f32_16x16x32_bf16 v[32:35], v[176:179], v[200:203], v[32:35]
	v_mfma_f32_16x16x32_bf16 v[36:39], v[180:183], v[200:203], v[36:39]
	v_mfma_f32_16x16x32_bf16 v[40:43], v[184:187], v[200:203], v[40:43]
	v_mfma_f32_16x16x32_bf16 v[44:47], v[188:191], v[200:203], v[44:47]
	v_mfma_f32_16x16x32_bf16 v[48:51], v[176:179], v[204:207], v[48:51]
	v_mfma_f32_16x16x32_bf16 v[52:55], v[180:183], v[204:207], v[52:55]
	v_mfma_f32_16x16x32_bf16 v[56:59], v[184:187], v[204:207], v[56:59]
	v_mfma_f32_16x16x32_bf16 v[60:63], v[188:191], v[204:207], v[60:63]
	v_mfma_f32_16x16x32_bf16 v[64:67], v[176:179], v[208:211], v[64:67]
	v_mfma_f32_16x16x32_bf16 v[68:71], v[180:183], v[208:211], v[68:71]
	v_mfma_f32_16x16x32_bf16 v[72:75], v[184:187], v[208:211], v[72:75]
	v_mfma_f32_16x16x32_bf16 v[76:79], v[188:191], v[208:211], v[76:79]
	v_mfma_f32_16x16x32_bf16 v[80:83], v[176:179], v[212:215], v[80:83]
	v_mfma_f32_16x16x32_bf16 v[84:87], v[180:183], v[212:215], v[84:87]
	v_mfma_f32_16x16x32_bf16 v[88:91], v[184:187], v[212:215], v[88:91]
	v_mfma_f32_16x16x32_bf16 v[92:95], v[188:191], v[212:215], v[92:95]
	v_mfma_f32_16x16x32_bf16 v[96:99], v[176:179], v[216:219], v[96:99]
	v_mfma_f32_16x16x32_bf16 v[100:103], v[180:183], v[216:219], v[100:103]
	v_mfma_f32_16x16x32_bf16 v[104:107], v[184:187], v[216:219], v[104:107]
	v_mfma_f32_16x16x32_bf16 v[108:111], v[188:191], v[216:219], v[108:111]
	v_mfma_f32_16x16x32_bf16 v[112:115], v[176:179], v[220:223], v[112:115]
	v_mfma_f32_16x16x32_bf16 v[116:119], v[180:183], v[220:223], v[116:119]
	v_mfma_f32_16x16x32_bf16 v[120:123], v[184:187], v[220:223], v[120:123]
	v_mfma_f32_16x16x32_bf16 v[124:127], v[188:191], v[220:223], v[124:127]
	s_branch .Lg3a_epi
.Lg3a_epi:
	s_nop 7
	s_nop 7
	s_mul_i32 s27, s29, 1024
	s_lshl_b32 s26, s28, 1
	s_add_u32 s27, s27, s26
	s_add_u32 s27, s27, 0x7800000
	s_add_u32 s4, s92, s27
	s_addc_u32 s5, s93, 0
	s_lshl_b32 s27, s28, 2
	s_add_u32 s27, s27, 0x0
	s_add_u32 s2, s6, s27
	s_addc_u32 s3, s7, 0
	global_load_dwordx4 v[192:195], v235, s[2:3] offset:0
	global_load_dwordx4 v[196:199], v235, s[2:3] offset:64
	global_load_dwordx4 v[200:203], v235, s[2:3] offset:128
	global_load_dwordx4 v[204:207], v235, s[2:3] offset:192
	s_waitcnt vmcnt(0)
	v_add_f32_e32 v0, v0, v192
	v_add_f32_e32 v1, v1, v193
	v_add_f32_e32 v2, v2, v194
	v_add_f32_e32 v3, v3, v195
	v_mul_f32_e32 v0, 0xbfb8aa3b, v0
	v_mul_f32_e32 v1, 0xbfb8aa3b, v1
	v_mul_f32_e32 v2, 0xbfb8aa3b, v2
	v_mul_f32_e32 v3, 0xbfb8aa3b, v3
	v_exp_f32_e32 v0, v0
	v_exp_f32_e32 v1, v1
	v_exp_f32_e32 v2, v2
	v_exp_f32_e32 v3, v3
	s_nop 0
	v_add_f32_e32 v0, 1.0, v0
	v_add_f32_e32 v1, 1.0, v1
	v_add_f32_e32 v2, 1.0, v2
	v_add_f32_e32 v3, 1.0, v3
	v_rcp_f32_e32 v0, v0
	v_rcp_f32_e32 v1, v1
	v_rcp_f32_e32 v2, v2
	v_rcp_f32_e32 v3, v3
	s_nop 0
	v_mul_f32_e32 v0, 0x3f1b4598, v0
	v_mul_f32_e32 v1, 0x3f1b4598, v1
	v_mul_f32_e32 v2, 0x3f1b4598, v2
	v_mul_f32_e32 v3, 0x3f1b4598, v3
	v_cvt_pk_bf16_f32 v128, v0, v1
	v_cvt_pk_bf16_f32 v129, v2, v3
	ds_write_b64 v236, v[128:129]
	v_add_f32_e32 v4, v4, v196
	v_add_f32_e32 v5, v5, v197
	v_add_f32_e32 v6, v6, v198
	v_add_f32_e32 v7, v7, v199
	v_mul_f32_e32 v4, 0xbfb8aa3b, v4
	v_mul_f32_e32 v5, 0xbfb8aa3b, v5
	v_mul_f32_e32 v6, 0xbfb8aa3b, v6
	v_mul_f32_e32 v7, 0xbfb8aa3b, v7
	v_exp_f32_e32 v4, v4
	v_exp_f32_e32 v5, v5
	v_exp_f32_e32 v6, v6
	v_exp_f32_e32 v7, v7
	s_nop 0
	v_add_f32_e32 v4, 1.0, v4
	v_add_f32_e32 v5, 1.0, v5
	v_add_f32_e32 v6, 1.0, v6
	v_add_f32_e32 v7, 1.0, v7
	v_rcp_f32_e32 v4, v4
	v_rcp_f32_e32 v5, v5
	v_rcp_f32_e32 v6, v6
	v_rcp_f32_e32 v7, v7
	s_nop 0
	v_mul_f32_e32 v4, 0x3f1b4598, v4
	v_mul_f32_e32 v5, 0x3f1b4598, v5
	v_mul_f32_e32 v6, 0x3f1b4598, v6
	v_mul_f32_e32 v7, 0x3f1b4598, v7
	v_cvt_pk_bf16_f32 v130, v4, v5
	v_cvt_pk_bf16_f32 v131, v6, v7
	ds_write_b64 v236, v[130:131] offset:32
	v_add_f32_e32 v8, v8, v200
	v_add_f32_e32 v9, v9, v201
	v_add_f32_e32 v10, v10, v202
	v_add_f32_e32 v11, v11, v203
	v_mul_f32_e32 v8, 0xbfb8aa3b, v8
	v_mul_f32_e32 v9, 0xbfb8aa3b, v9
	v_mul_f32_e32 v10, 0xbfb8aa3b, v10
	v_mul_f32_e32 v11, 0xbfb8aa3b, v11
	v_exp_f32_e32 v8, v8
	v_exp_f32_e32 v9, v9
	v_exp_f32_e32 v10, v10
	v_exp_f32_e32 v11, v11
	s_nop 0
	v_add_f32_e32 v8, 1.0, v8
	v_add_f32_e32 v9, 1.0, v9
	v_add_f32_e32 v10, 1.0, v10
	v_add_f32_e32 v11, 1.0, v11
	v_rcp_f32_e32 v8, v8
	v_rcp_f32_e32 v9, v9
	v_rcp_f32_e32 v10, v10
	v_rcp_f32_e32 v11, v11
	s_nop 0
	v_mul_f32_e32 v8, 0x3f1b4598, v8
	v_mul_f32_e32 v9, 0x3f1b4598, v9
	v_mul_f32_e32 v10, 0x3f1b4598, v10
	v_mul_f32_e32 v11, 0x3f1b4598, v11
	v_cvt_pk_bf16_f32 v132, v8, v9
	v_cvt_pk_bf16_f32 v133, v10, v11
	ds_write_b64 v236, v[132:133] offset:64
	v_add_f32_e32 v12, v12, v204
	v_add_f32_e32 v13, v13, v205
	v_add_f32_e32 v14, v14, v206
	v_add_f32_e32 v15, v15, v207
	v_mul_f32_e32 v12, 0xbfb8aa3b, v12
	v_mul_f32_e32 v13, 0xbfb8aa3b, v13
	v_mul_f32_e32 v14, 0xbfb8aa3b, v14
	v_mul_f32_e32 v15, 0xbfb8aa3b, v15
	v_exp_f32_e32 v12, v12
	v_exp_f32_e32 v13, v13
	v_exp_f32_e32 v14, v14
	v_exp_f32_e32 v15, v15
	s_nop 0
	v_add_f32_e32 v12, 1.0, v12
	v_add_f32_e32 v13, 1.0, v13
	v_add_f32_e32 v14, 1.0, v14
	v_add_f32_e32 v15, 1.0, v15
; DI unsigned pack2(float lo, float hi) { const f32x2c v = {lo, hi}; return __builtin_bit_cast(unsigned, __builtin_convertvector(v, bf16x2c)); }
; template <class Epi>
; DI void gemm_tile(char* smem, const bf16_t* __restrict__ A0, int lda0, int ksplit, const bf16_t* __restrict__ A1, int lda1,
;                   const bf16_t* __restrict__ Bt, int K, int row0, int col0, const Epi& epi, int tid) {
;     ...
; #pragma unroll
;   for (int m = 0; m < 8; ++m)
; #pragma unroll
;     for (int n = 0; n < 4; ++n) epi(row0 + wr * 128 + m * 16 + fr, col0 + wc * 64 + n * 16 + fq * 4, acc[m][n]);
; }
; DI void st_bf16x4(bf16_t* o, f32x4 v) { u32x2 q; q.x = pack2(v[0], v[1]); q.y = pack2(v[2], v[3]); *(u32x2*)o = q; }
;   DI void operator()(int row, int col, f32x4 v) const {
;     if (col < n0) st_bf16x4(o0 + (size_t)row * ld0 + col, v);
;     else { const int c = col - n0; if (c < n1) st_bf16x4(o1 + (size_t)row * ld1 + c, v); }
;   }
	v_rcp_f32_e32 v12, v12
	v_rcp_f32_e32 v13, v13
	v_rcp_f32_e32 v14, v14
	v_rcp_f32_e32 v15, v15
	s_nop 0
	v_mul_f32_e32 v12, 0x3f1b4598, v12
	v_mul_f32_e32 v13, 0x3f1b4598, v13
	v_mul_f32_e32 v14, 0x3f1b4598, v14
	v_mul_f32_e32 v15, 0x3f1b4598, v15
	v_cvt_pk_bf16_f32 v134, v12, v13
	v_cvt_pk_bf16_f32 v135, v14, v15
	ds_write_b64 v236, v[134:135] offset:96
	v_add_f32_e32 v16, v16, v192
	v_add_f32_e32 v17, v17, v193
	v_add_f32_e32 v18, v18, v194
	v_add_f32_e32 v19, v19, v195
	v_mul_f32_e32 v16, 0xbfb8aa3b, v16
	v_mul_f32_e32 v17, 0xbfb8aa3b, v17
	v_mul_f32_e32 v18, 0xbfb8aa3b, v18
	v_mul_f32_e32 v19, 0xbfb8aa3b, v19
	v_exp_f32_e32 v16, v16
	v_exp_f32_e32 v17, v17
	v_exp_f32_e32 v18, v18
	v_exp_f32_e32 v19, v19
	s_nop 0
	v_add_f32_e32 v16, 1.0, v16
	v_add_f32_e32 v17, 1.0, v17
	v_add_f32_e32 v18, 1.0, v18
	v_add_f32_e32 v19, 1.0, v19
	v_rcp_f32_e32 v16, v16
	v_rcp_f32_e32 v17, v17
	v_rcp_f32_e32 v18, v18
	v_rcp_f32_e32 v19, v19
	s_nop 0
	v_mul_f32_e32 v16, 0x3f1b4598, v16
	v_mul_f32_e32 v17, 0x3f1b4598, v17
	v_mul_f32_e32 v18, 0x3f1b4598, v18
	v_mul_f32_e32 v19, 0x3f1b4598, v19
	v_cvt_pk_bf16_f32 v136, v16, v17
	v_cvt_pk_bf16_f32 v137, v18, v19
	ds_write_b64 v236, v[136:137] offset:2304
	v_add_f32_e32 v20, v20, v196
	v_add_f32_e32 v21, v21, v197
	v_add_f32_e32 v22, v22, v198
	v_add_f32_e32 v23, v23, v199
	v_mul_f32_e32 v20, 0xbfb8aa3b, v20
	v_mul_f32_e32 v21, 0xbfb8aa3b, v21
	v_mul_f32_e32 v22, 0xbfb8aa3b, v22
	v_mul_f32_e32 v23, 0xbfb8aa3b, v23
	v_exp_f32_e32 v20, v20
	v_exp_f32_e32 v21, v21
	v_exp_f32_e32 v22, v22
	v_exp_f32_e32 v23, v23
	s_nop 0
	v_add_f32_e32 v20, 1.0, v20
	v_add_f32_e32 v21, 1.0, v21
	v_add_f32_e32 v22, 1.0, v22
	v_add_f32_e32 v23, 1.0, v23
	v_rcp_f32_e32 v20, v20
	v_rcp_f32_e32 v21, v21
	v_rcp_f32_e32 v22, v22
	v_rcp_f32_e32 v23, v23
	s_nop 0
	v_mul_f32_e32 v20, 0x3f1b4598, v20
	v_mul_f32_e32 v21, 0x3f1b4598, v21
	v_mul_f32_e32 v22, 0x3f1b4598, v22
	v_mul_f32_e32 v23, 0x3f1b4598, v23
	v_cvt_pk_bf16_f32 v138, v20, v21
	v_cvt_pk_bf16_f32 v139, v22, v23
	ds_write_b64 v236, v[138:139] offset:2336
	v_add_f32_e32 v24, v24, v200
	v_add_f32_e32 v25, v25, v201
	v_add_f32_e32 v26, v26, v202
	v_add_f32_e32 v27, v27, v203
	v_mul_f32_e32 v24, 0xbfb8aa3b, v24
	v_mul_f32_e32 v25, 0xbfb8aa3b, v25
	v_mul_f32_e32 v26, 0xbfb8aa3b, v26
	v_mul_f32_e32 v27, 0xbfb8aa3b, v27
	v_exp_f32_e32 v24, v24
	v_exp_f32_e32 v25, v25
	v_exp_f32_e32 v26, v26
	v_exp_f32_e32 v27, v27
	s_nop 0
	v_add_f32_e32 v24, 1.0, v24
	v_add_f32_e32 v25, 1.0, v25
	v_add_f32_e32 v26, 1.0, v26
	v_add_f32_e32 v27, 1.0, v27
	v_rcp_f32_e32 v24, v24
	v_rcp_f32_e32 v25, v25
	v_rcp_f32_e32 v26, v26
	v_rcp_f32_e32 v27, v27
	s_nop 0
	v_mul_f32_e32 v24, 0x3f1b4598, v24
	v_mul_f32_e32 v25, 0x3f1b4598, v25
	v_mul_f32_e32 v26, 0x3f1b4598, v26
	v_mul_f32_e32 v27, 0x3f1b4598, v27
	v_cvt_pk_bf16_f32 v140, v24, v25
	v_cvt_pk_bf16_f32 v141, v26, v27
	ds_write_b64 v236, v[140:141] offset:2368
	v_add_f32_e32 v28, v28, v204
	v_add_f32_e32 v29, v29, v205
	v_add_f32_e32 v30, v30, v206
	v_add_f32_e32 v31, v31, v207
	v_mul_f32_e32 v28, 0xbfb8aa3b, v28
	v_mul_f32_e32 v29, 0xbfb8aa3b, v29
	v_mul_f32_e32 v30, 0xbfb8aa3b, v30
	v_mul_f32_e32 v31, 0xbfb8aa3b, v31
	v_exp_f32_e32 v28, v28
	v_exp_f32_e32 v29, v29
	v_exp_f32_e32 v30, v30
	v_exp_f32_e32 v31, v31
	s_nop 0
	v_add_f32_e32 v28, 1.0, v28
	v_add_f32_e32 v29, 1.0, v29
	v_add_f32_e32 v30, 1.0, v30
	v_add_f32_e32 v31, 1.0, v31
	v_rcp_f32_e32 v28, v28
	v_rcp_f32_e32 v29, v29
	v_rcp_f32_e32 v30, v30
	v_rcp_f32_e32 v31, v31
	s_nop 0
	v_mul_f32_e32 v28, 0x3f1b4598, v28
	v_mul_f32_e32 v29, 0x3f1b4598, v29
	v_mul_f32_e32 v30, 0x3f1b4598, v30
	v_mul_f32_e32 v31, 0x3f1b4598, v31
	v_cvt_pk_bf16_f32 v142, v28, v29
	v_cvt_pk_bf16_f32 v143, v30, v31
	ds_write_b64 v236, v[142:143] offset:2400
	v_add_f32_e32 v32, v32, v192
	v_add_f32_e32 v33, v33, v193
	v_add_f32_e32 v34, v34, v194
	v_add_f32_e32 v35, v35, v195
	v_mul_f32_e32 v32, 0xbfb8aa3b, v32
	v_mul_f32_e32 v33, 0xbfb8aa3b, v33
	v_mul_f32_e32 v34, 0xbfb8aa3b, v34
	v_mul_f32_e32 v35, 0xbfb8aa3b, v35
	v_exp_f32_e32 v32, v32
	v_exp_f32_e32 v33, v33
	v_exp_f32_e32 v34, v34
	v_exp_f32_e32 v35, v35
	s_nop 0
	v_add_f32_e32 v32, 1.0, v32
	v_add_f32_e32 v33, 1.0, v33
	v_add_f32_e32 v34, 1.0, v34
	v_add_f32_e32 v35, 1.0, v35
	v_rcp_f32_e32 v32, v32
	v_rcp_f32_e32 v33, v33
	v_rcp_f32_e32 v34, v34
	v_rcp_f32_e32 v35, v35
	s_nop 0
	v_mul_f32_e32 v32, 0x3f1b4598, v32
	v_mul_f32_e32 v33, 0x3f1b4598, v33
	v_mul_f32_e32 v34, 0x3f1b4598, v34
	v_mul_f32_e32 v35, 0x3f1b4598, v35
	v_cvt_pk_bf16_f32 v144, v32, v33
	v_cvt_pk_bf16_f32 v145, v34, v35
	ds_write_b64 v236, v[144:145] offset:4608
	v_add_f32_e32 v36, v36, v196
	v_add_f32_e32 v37, v37, v197
	v_add_f32_e32 v38, v38, v198
	v_add_f32_e32 v39, v39, v199
	v_mul_f32_e32 v36, 0xbfb8aa3b, v36
	v_mul_f32_e32 v37, 0xbfb8aa3b, v37
	v_mul_f32_e32 v38, 0xbfb8aa3b, v38
	v_mul_f32_e32 v39, 0xbfb8aa3b, v39
	v_exp_f32_e32 v36, v36
	v_exp_f32_e32 v37, v37
	v_exp_f32_e32 v38, v38
	v_exp_f32_e32 v39, v39
	s_nop 0
	v_add_f32_e32 v36, 1.0, v36
	v_add_f32_e32 v37, 1.0, v37
	v_add_f32_e32 v38, 1.0, v38
	v_add_f32_e32 v39, 1.0, v39
	v_rcp_f32_e32 v36, v36
	v_rcp_f32_e32 v37, v37
	v_rcp_f32_e32 v38, v38
	v_rcp_f32_e32 v39, v39
	s_nop 0
	v_mul_f32_e32 v36, 0x3f1b4598, v36
	v_mul_f32_e32 v37, 0x3f1b4598, v37
	v_mul_f32_e32 v38, 0x3f1b4598, v38
	v_mul_f32_e32 v39, 0x3f1b4598, v39
	v_cvt_pk_bf16_f32 v146, v36, v37
	v_cvt_pk_bf16_f32 v147, v38, v39
	ds_write_b64 v236, v[146:147] offset:4640
	v_add_f32_e32 v40, v40, v200
	v_add_f32_e32 v41, v41, v201
	v_add_f32_e32 v42, v42, v202
	v_add_f32_e32 v43, v43, v203
	v_mul_f32_e32 v40, 0xbfb8aa3b, v40
	v_mul_f32_e32 v41, 0xbfb8aa3b, v41
	v_mul_f32_e32 v42, 0xbfb8aa3b, v42
; DI unsigned pack2(float lo, float hi) { const f32x2c v = {lo, hi}; return __builtin_bit_cast(unsigned, __builtin_convertvector(v, bf16x2c)); }
; template <class Epi>
; DI void gemm_tile(char* smem, const bf16_t* __restrict__ A0, int lda0, int ksplit, const bf16_t* __restrict__ A1, int lda1,
;                   const bf16_t* __restrict__ Bt, int K, int row0, int col0, const Epi& epi, int tid) {
;     ...
; #pragma unroll
;   for (int m = 0; m < 8; ++m)
; #pragma unroll
;     for (int n = 0; n < 4; ++n) epi(row0 + wr * 128 + m * 16 + fr, col0 + wc * 64 + n * 16 + fq * 4, acc[m][n]);
; }
; DI void st_bf16x4(bf16_t* o, f32x4 v) { u32x2 q; q.x = pack2(v[0], v[1]); q.y = pack2(v[2], v[3]); *(u32x2*)o = q; }
;   DI void operator()(int row, int col, f32x4 v) const {
;     if (col < n0) st_bf16x4(o0 + (size_t)row * ld0 + col, v);
;     else { const int c = col - n0; if (c < n1) st_bf16x4(o1 + (size_t)row * ld1 + c, v); }
;   }
	v_mul_f32_e32 v43, 0xbfb8aa3b, v43
	v_exp_f32_e32 v40, v40
	v_exp_f32_e32 v41, v41
	v_exp_f32_e32 v42, v42
	v_exp_f32_e32 v43, v43
	s_nop 0
	v_add_f32_e32 v40, 1.0, v40
	v_add_f32_e32 v41, 1.0, v41
	v_add_f32_e32 v42, 1.0, v42
	v_add_f32_e32 v43, 1.0, v43
	v_rcp_f32_e32 v40, v40
	v_rcp_f32_e32 v41, v41
	v_rcp_f32_e32 v42, v42
	v_rcp_f32_e32 v43, v43
	s_nop 0
	v_mul_f32_e32 v40, 0x3f1b4598, v40
	v_mul_f32_e32 v41, 0x3f1b4598, v41
	v_mul_f32_e32 v42, 0x3f1b4598, v42
	v_mul_f32_e32 v43, 0x3f1b4598, v43
	v_cvt_pk_bf16_f32 v148, v40, v41
	v_cvt_pk_bf16_f32 v149, v42, v43
	ds_write_b64 v236, v[148:149] offset:4672
	v_add_f32_e32 v44, v44, v204
	v_add_f32_e32 v45, v45, v205
	v_add_f32_e32 v46, v46, v206
	v_add_f32_e32 v47, v47, v207
	v_mul_f32_e32 v44, 0xbfb8aa3b, v44
	v_mul_f32_e32 v45, 0xbfb8aa3b, v45
	v_mul_f32_e32 v46, 0xbfb8aa3b, v46
	v_mul_f32_e32 v47, 0xbfb8aa3b, v47
	v_exp_f32_e32 v44, v44
	v_exp_f32_e32 v45, v45
	v_exp_f32_e32 v46, v46
	v_exp_f32_e32 v47, v47
	s_nop 0
	v_add_f32_e32 v44, 1.0, v44
	v_add_f32_e32 v45, 1.0, v45
	v_add_f32_e32 v46, 1.0, v46
	v_add_f32_e32 v47, 1.0, v47
	v_rcp_f32_e32 v44, v44
	v_rcp_f32_e32 v45, v45
	v_rcp_f32_e32 v46, v46
	v_rcp_f32_e32 v47, v47
	s_nop 0
	v_mul_f32_e32 v44, 0x3f1b4598, v44
	v_mul_f32_e32 v45, 0x3f1b4598, v45
	v_mul_f32_e32 v46, 0x3f1b4598, v46
	v_mul_f32_e32 v47, 0x3f1b4598, v47
	v_cvt_pk_bf16_f32 v150, v44, v45
	v_cvt_pk_bf16_f32 v151, v46, v47
	ds_write_b64 v236, v[150:151] offset:4704
	v_add_f32_e32 v48, v48, v192
	v_add_f32_e32 v49, v49, v193
	v_add_f32_e32 v50, v50, v194
	v_add_f32_e32 v51, v51, v195
	v_mul_f32_e32 v48, 0xbfb8aa3b, v48
	v_mul_f32_e32 v49, 0xbfb8aa3b, v49
	v_mul_f32_e32 v50, 0xbfb8aa3b, v50
	v_mul_f32_e32 v51, 0xbfb8aa3b, v51
	v_exp_f32_e32 v48, v48
	v_exp_f32_e32 v49, v49
	v_exp_f32_e32 v50, v50
	v_exp_f32_e32 v51, v51
	s_nop 0
	v_add_f32_e32 v48, 1.0, v48
	v_add_f32_e32 v49, 1.0, v49
	v_add_f32_e32 v50, 1.0, v50
	v_add_f32_e32 v51, 1.0, v51
	v_rcp_f32_e32 v48, v48
	v_rcp_f32_e32 v49, v49
	v_rcp_f32_e32 v50, v50
	v_rcp_f32_e32 v51, v51
	s_nop 0
	v_mul_f32_e32 v48, 0x3f1b4598, v48
	v_mul_f32_e32 v49, 0x3f1b4598, v49
	v_mul_f32_e32 v50, 0x3f1b4598, v50
	v_mul_f32_e32 v51, 0x3f1b4598, v51
	v_cvt_pk_bf16_f32 v152, v48, v49
	v_cvt_pk_bf16_f32 v153, v50, v51
	ds_write_b64 v236, v[152:153] offset:6912
	v_add_f32_e32 v52, v52, v196
	v_add_f32_e32 v53, v53, v197
	v_add_f32_e32 v54, v54, v198
	v_add_f32_e32 v55, v55, v199
	v_mul_f32_e32 v52, 0xbfb8aa3b, v52
	v_mul_f32_e32 v53, 0xbfb8aa3b, v53
	v_mul_f32_e32 v54, 0xbfb8aa3b, v54
	v_mul_f32_e32 v55, 0xbfb8aa3b, v55
	v_exp_f32_e32 v52, v52
	v_exp_f32_e32 v53, v53
	v_exp_f32_e32 v54, v54
	v_exp_f32_e32 v55, v55
	s_nop 0
	v_add_f32_e32 v52, 1.0, v52
	v_add_f32_e32 v53, 1.0, v53
	v_add_f32_e32 v54, 1.0, v54
	v_add_f32_e32 v55, 1.0, v55
	v_rcp_f32_e32 v52, v52
	v_rcp_f32_e32 v53, v53
	v_rcp_f32_e32 v54, v54
	v_rcp_f32_e32 v55, v55
	s_nop 0
	v_mul_f32_e32 v52, 0x3f1b4598, v52
	v_mul_f32_e32 v53, 0x3f1b4598, v53
	v_mul_f32_e32 v54, 0x3f1b4598, v54
	v_mul_f32_e32 v55, 0x3f1b4598, v55
	v_cvt_pk_bf16_f32 v154, v52, v53
	v_cvt_pk_bf16_f32 v155, v54, v55
	ds_write_b64 v236, v[154:155] offset:6944
	v_add_f32_e32 v56, v56, v200
	v_add_f32_e32 v57, v57, v201
	v_add_f32_e32 v58, v58, v202
	v_add_f32_e32 v59, v59, v203
	v_mul_f32_e32 v56, 0xbfb8aa3b, v56
	v_mul_f32_e32 v57, 0xbfb8aa3b, v57
	v_mul_f32_e32 v58, 0xbfb8aa3b, v58
	v_mul_f32_e32 v59, 0xbfb8aa3b, v59
	v_exp_f32_e32 v56, v56
	v_exp_f32_e32 v57, v57
	v_exp_f32_e32 v58, v58
	v_exp_f32_e32 v59, v59
	s_nop 0
	v_add_f32_e32 v56, 1.0, v56
	v_add_f32_e32 v57, 1.0, v57
	v_add_f32_e32 v58, 1.0, v58
	v_add_f32_e32 v59, 1.0, v59
	v_rcp_f32_e32 v56, v56
	v_rcp_f32_e32 v57, v57
	v_rcp_f32_e32 v58, v58
	v_rcp_f32_e32 v59, v59
	s_nop 0
	v_mul_f32_e32 v56, 0x3f1b4598, v56
	v_mul_f32_e32 v57, 0x3f1b4598, v57
	v_mul_f32_e32 v58, 0x3f1b4598, v58
	v_mul_f32_e32 v59, 0x3f1b4598, v59
	v_cvt_pk_bf16_f32 v156, v56, v57
	v_cvt_pk_bf16_f32 v157, v58, v59
	ds_write_b64 v236, v[156:157] offset:6976
	v_add_f32_e32 v60, v60, v204
	v_add_f32_e32 v61, v61, v205
	v_add_f32_e32 v62, v62, v206
	v_add_f32_e32 v63, v63, v207
	v_mul_f32_e32 v60, 0xbfb8aa3b, v60
	v_mul_f32_e32 v61, 0xbfb8aa3b, v61
	v_mul_f32_e32 v62, 0xbfb8aa3b, v62
	v_mul_f32_e32 v63, 0xbfb8aa3b, v63
	v_exp_f32_e32 v60, v60
	v_exp_f32_e32 v61, v61
	v_exp_f32_e32 v62, v62
	v_exp_f32_e32 v63, v63
	s_nop 0
	v_add_f32_e32 v60, 1.0, v60
	v_add_f32_e32 v61, 1.0, v61
	v_add_f32_e32 v62, 1.0, v62
	v_add_f32_e32 v63, 1.0, v63
	v_rcp_f32_e32 v60, v60
	v_rcp_f32_e32 v61, v61
	v_rcp_f32_e32 v62, v62
	v_rcp_f32_e32 v63, v63
	s_nop 0
	v_mul_f32_e32 v60, 0x3f1b4598, v60
	v_mul_f32_e32 v61, 0x3f1b4598, v61
	v_mul_f32_e32 v62, 0x3f1b4598, v62
	v_mul_f32_e32 v63, 0x3f1b4598, v63
	v_cvt_pk_bf16_f32 v158, v60, v61
	v_cvt_pk_bf16_f32 v159, v62, v63
	ds_write_b64 v236, v[158:159] offset:7008
	v_add_f32_e32 v64, v64, v192
	v_add_f32_e32 v65, v65, v193
	v_add_f32_e32 v66, v66, v194
	v_add_f32_e32 v67, v67, v195
	v_mul_f32_e32 v64, 0xbfb8aa3b, v64
	v_mul_f32_e32 v65, 0xbfb8aa3b, v65
	v_mul_f32_e32 v66, 0xbfb8aa3b, v66
	v_mul_f32_e32 v67, 0xbfb8aa3b, v67
	v_exp_f32_e32 v64, v64
	v_exp_f32_e32 v65, v65
	v_exp_f32_e32 v66, v66
	v_exp_f32_e32 v67, v67
	s_nop 0
	v_add_f32_e32 v64, 1.0, v64
	v_add_f32_e32 v65, 1.0, v65
	v_add_f32_e32 v66, 1.0, v66
	v_add_f32_e32 v67, 1.0, v67
	v_rcp_f32_e32 v64, v64
	v_rcp_f32_e32 v65, v65
	v_rcp_f32_e32 v66, v66
	v_rcp_f32_e32 v67, v67
	s_nop 0
	v_mul_f32_e32 v64, 0x3f1b4598, v64
	v_mul_f32_e32 v65, 0x3f1b4598, v65
	v_mul_f32_e32 v66, 0x3f1b4598, v66
	v_mul_f32_e32 v67, 0x3f1b4598, v67
	v_cvt_pk_bf16_f32 v128, v64, v65
	v_cvt_pk_bf16_f32 v129, v66, v67
; DI unsigned pack2(float lo, float hi) { const f32x2c v = {lo, hi}; return __builtin_bit_cast(unsigned, __builtin_convertvector(v, bf16x2c)); }
; template <class Epi>
; DI void gemm_tile(char* smem, const bf16_t* __restrict__ A0, int lda0, int ksplit, const bf16_t* __restrict__ A1, int lda1,
;                   const bf16_t* __restrict__ Bt, int K, int row0, int col0, const Epi& epi, int tid) {
;     ...
; #pragma unroll
;   for (int m = 0; m < 8; ++m)
; #pragma unroll
;     for (int n = 0; n < 4; ++n) epi(row0 + wr * 128 + m * 16 + fr, col0 + wc * 64 + n * 16 + fq * 4, acc[m][n]);
; }
; DI void st_bf16x4(bf16_t* o, f32x4 v) { u32x2 q; q.x = pack2(v[0], v[1]); q.y = pack2(v[2], v[3]); *(u32x2*)o = q; }
;   DI void operator()(int row, int col, f32x4 v) const {
;     if (col < n0) st_bf16x4(o0 + (size_t)row * ld0 + col, v);
;     else { const int c = col - n0; if (c < n1) st_bf16x4(o1 + (size_t)row * ld1 + c, v); }
;   }
	ds_write_b64 v236, v[128:129] offset:9216
	v_add_f32_e32 v68, v68, v196
	v_add_f32_e32 v69, v69, v197
	v_add_f32_e32 v70, v70, v198
	v_add_f32_e32 v71, v71, v199
	v_mul_f32_e32 v68, 0xbfb8aa3b, v68
	v_mul_f32_e32 v69, 0xbfb8aa3b, v69
	v_mul_f32_e32 v70, 0xbfb8aa3b, v70
	v_mul_f32_e32 v71, 0xbfb8aa3b, v71
	v_exp_f32_e32 v68, v68
	v_exp_f32_e32 v69, v69
	v_exp_f32_e32 v70, v70
	v_exp_f32_e32 v71, v71
	s_nop 0
	v_add_f32_e32 v68, 1.0, v68
	v_add_f32_e32 v69, 1.0, v69
	v_add_f32_e32 v70, 1.0, v70
	v_add_f32_e32 v71, 1.0, v71
	v_rcp_f32_e32 v68, v68
	v_rcp_f32_e32 v69, v69
	v_rcp_f32_e32 v70, v70
	v_rcp_f32_e32 v71, v71
	s_nop 0
	v_mul_f32_e32 v68, 0x3f1b4598, v68
	v_mul_f32_e32 v69, 0x3f1b4598, v69
	v_mul_f32_e32 v70, 0x3f1b4598, v70
	v_mul_f32_e32 v71, 0x3f1b4598, v71
	v_cvt_pk_bf16_f32 v130, v68, v69
	v_cvt_pk_bf16_f32 v131, v70, v71
	ds_write_b64 v236, v[130:131] offset:9248
	v_add_f32_e32 v72, v72, v200
	v_add_f32_e32 v73, v73, v201
	v_add_f32_e32 v74, v74, v202
	v_add_f32_e32 v75, v75, v203
	v_mul_f32_e32 v72, 0xbfb8aa3b, v72
	v_mul_f32_e32 v73, 0xbfb8aa3b, v73
	v_mul_f32_e32 v74, 0xbfb8aa3b, v74
	v_mul_f32_e32 v75, 0xbfb8aa3b, v75
	v_exp_f32_e32 v72, v72
	v_exp_f32_e32 v73, v73
	v_exp_f32_e32 v74, v74
	v_exp_f32_e32 v75, v75
	s_nop 0
	v_add_f32_e32 v72, 1.0, v72
	v_add_f32_e32 v73, 1.0, v73
	v_add_f32_e32 v74, 1.0, v74
	v_add_f32_e32 v75, 1.0, v75
	v_rcp_f32_e32 v72, v72
	v_rcp_f32_e32 v73, v73
	v_rcp_f32_e32 v74, v74
	v_rcp_f32_e32 v75, v75
	s_nop 0
	v_mul_f32_e32 v72, 0x3f1b4598, v72
	v_mul_f32_e32 v73, 0x3f1b4598, v73
	v_mul_f32_e32 v74, 0x3f1b4598, v74
	v_mul_f32_e32 v75, 0x3f1b4598, v75
	v_cvt_pk_bf16_f32 v132, v72, v73
	v_cvt_pk_bf16_f32 v133, v74, v75
	ds_write_b64 v236, v[132:133] offset:9280
	v_add_f32_e32 v76, v76, v204
	v_add_f32_e32 v77, v77, v205
	v_add_f32_e32 v78, v78, v206
	v_add_f32_e32 v79, v79, v207
	v_mul_f32_e32 v76, 0xbfb8aa3b, v76
	v_mul_f32_e32 v77, 0xbfb8aa3b, v77
	v_mul_f32_e32 v78, 0xbfb8aa3b, v78
	v_mul_f32_e32 v79, 0xbfb8aa3b, v79
	v_exp_f32_e32 v76, v76
	v_exp_f32_e32 v77, v77
	v_exp_f32_e32 v78, v78
	v_exp_f32_e32 v79, v79
	s_nop 0
	v_add_f32_e32 v76, 1.0, v76
	v_add_f32_e32 v77, 1.0, v77
	v_add_f32_e32 v78, 1.0, v78
	v_add_f32_e32 v79, 1.0, v79
	v_rcp_f32_e32 v76, v76
	v_rcp_f32_e32 v77, v77
	v_rcp_f32_e32 v78, v78
	v_rcp_f32_e32 v79, v79
	s_nop 0
	v_mul_f32_e32 v76, 0x3f1b4598, v76
	v_mul_f32_e32 v77, 0x3f1b4598, v77
	v_mul_f32_e32 v78, 0x3f1b4598, v78
	v_mul_f32_e32 v79, 0x3f1b4598, v79
	v_cvt_pk_bf16_f32 v134, v76, v77
	v_cvt_pk_bf16_f32 v135, v78, v79
	ds_write_b64 v236, v[134:135] offset:9312
	v_add_f32_e32 v80, v80, v192
	v_add_f32_e32 v81, v81, v193
	v_add_f32_e32 v82, v82, v194
	v_add_f32_e32 v83, v83, v195
	v_mul_f32_e32 v80, 0xbfb8aa3b, v80
	v_mul_f32_e32 v81, 0xbfb8aa3b, v81
	v_mul_f32_e32 v82, 0xbfb8aa3b, v82
	v_mul_f32_e32 v83, 0xbfb8aa3b, v83
	v_exp_f32_e32 v80, v80
	v_exp_f32_e32 v81, v81
	v_exp_f32_e32 v82, v82
	v_exp_f32_e32 v83, v83
	s_nop 0
	v_add_f32_e32 v80, 1.0, v80
	v_add_f32_e32 v81, 1.0, v81
	v_add_f32_e32 v82, 1.0, v82
	v_add_f32_e32 v83, 1.0, v83
	v_rcp_f32_e32 v80, v80
	v_rcp_f32_e32 v81, v81
	v_rcp_f32_e32 v82, v82
	v_rcp_f32_e32 v83, v83
	s_nop 0
	v_mul_f32_e32 v80, 0x3f1b4598, v80
	v_mul_f32_e32 v81, 0x3f1b4598, v81
	v_mul_f32_e32 v82, 0x3f1b4598, v82
	v_mul_f32_e32 v83, 0x3f1b4598, v83
	v_cvt_pk_bf16_f32 v136, v80, v81
	v_cvt_pk_bf16_f32 v137, v82, v83
	ds_write_b64 v236, v[136:137] offset:11520
	v_add_f32_e32 v84, v84, v196
	v_add_f32_e32 v85, v85, v197
	v_add_f32_e32 v86, v86, v198
	v_add_f32_e32 v87, v87, v199
	v_mul_f32_e32 v84, 0xbfb8aa3b, v84
	v_mul_f32_e32 v85, 0xbfb8aa3b, v85
	v_mul_f32_e32 v86, 0xbfb8aa3b, v86
	v_mul_f32_e32 v87, 0xbfb8aa3b, v87
	v_exp_f32_e32 v84, v84
	v_exp_f32_e32 v85, v85
	v_exp_f32_e32 v86, v86
	v_exp_f32_e32 v87, v87
	s_nop 0
	v_add_f32_e32 v84, 1.0, v84
	v_add_f32_e32 v85, 1.0, v85
	v_add_f32_e32 v86, 1.0, v86
	v_add_f32_e32 v87, 1.0, v87
	v_rcp_f32_e32 v84, v84
	v_rcp_f32_e32 v85, v85
	v_rcp_f32_e32 v86, v86
	v_rcp_f32_e32 v87, v87
	s_nop 0
	v_mul_f32_e32 v84, 0x3f1b4598, v84
	v_mul_f32_e32 v85, 0x3f1b4598, v85
	v_mul_f32_e32 v86, 0x3f1b4598, v86
	v_mul_f32_e32 v87, 0x3f1b4598, v87
	v_cvt_pk_bf16_f32 v138, v84, v85
	v_cvt_pk_bf16_f32 v139, v86, v87
	ds_write_b64 v236, v[138:139] offset:11552
	v_add_f32_e32 v88, v88, v200
	v_add_f32_e32 v89, v89, v201
	v_add_f32_e32 v90, v90, v202
	v_add_f32_e32 v91, v91, v203
	v_mul_f32_e32 v88, 0xbfb8aa3b, v88
	v_mul_f32_e32 v89, 0xbfb8aa3b, v89
	v_mul_f32_e32 v90, 0xbfb8aa3b, v90
	v_mul_f32_e32 v91, 0xbfb8aa3b, v91
	v_exp_f32_e32 v88, v88
	v_exp_f32_e32 v89, v89
	v_exp_f32_e32 v90, v90
	v_exp_f32_e32 v91, v91
	s_nop 0
	v_add_f32_e32 v88, 1.0, v88
	v_add_f32_e32 v89, 1.0, v89
	v_add_f32_e32 v90, 1.0, v90
	v_add_f32_e32 v91, 1.0, v91
	v_rcp_f32_e32 v88, v88
	v_rcp_f32_e32 v89, v89
	v_rcp_f32_e32 v90, v90
	v_rcp_f32_e32 v91, v91
	s_nop 0
	v_mul_f32_e32 v88, 0x3f1b4598, v88
	v_mul_f32_e32 v89, 0x3f1b4598, v89
	v_mul_f32_e32 v90, 0x3f1b4598, v90
	v_mul_f32_e32 v91, 0x3f1b4598, v91
	v_cvt_pk_bf16_f32 v140, v88, v89
	v_cvt_pk_bf16_f32 v141, v90, v91
	ds_write_b64 v236, v[140:141] offset:11584
	v_add_f32_e32 v92, v92, v204
	v_add_f32_e32 v93, v93, v205
	v_add_f32_e32 v94, v94, v206
	v_add_f32_e32 v95, v95, v207
	v_mul_f32_e32 v92, 0xbfb8aa3b, v92
	v_mul_f32_e32 v93, 0xbfb8aa3b, v93
	v_mul_f32_e32 v94, 0xbfb8aa3b, v94
	v_mul_f32_e32 v95, 0xbfb8aa3b, v95
	v_exp_f32_e32 v92, v92
	v_exp_f32_e32 v93, v93
	v_exp_f32_e32 v94, v94
	v_exp_f32_e32 v95, v95
	s_nop 0
	v_add_f32_e32 v92, 1.0, v92
	v_add_f32_e32 v93, 1.0, v93
	v_add_f32_e32 v94, 1.0, v94
	v_add_f32_e32 v95, 1.0, v95
	v_rcp_f32_e32 v92, v92
	v_rcp_f32_e32 v93, v93
; DI unsigned pack2(float lo, float hi) { const f32x2c v = {lo, hi}; return __builtin_bit_cast(unsigned, __builtin_convertvector(v, bf16x2c)); }
; template <class Epi>
; DI void gemm_tile(char* smem, const bf16_t* __restrict__ A0, int lda0, int ksplit, const bf16_t* __restrict__ A1, int lda1,
;                   const bf16_t* __restrict__ Bt, int K, int row0, int col0, const Epi& epi, int tid) {
;     ...
; #pragma unroll
;   for (int m = 0; m < 8; ++m)
; #pragma unroll
;     for (int n = 0; n < 4; ++n) epi(row0 + wr * 128 + m * 16 + fr, col0 + wc * 64 + n * 16 + fq * 4, acc[m][n]);
; }
; DI void st_bf16x4(bf16_t* o, f32x4 v) { u32x2 q; q.x = pack2(v[0], v[1]); q.y = pack2(v[2], v[3]); *(u32x2*)o = q; }
;   DI void operator()(int row, int col, f32x4 v) const {
;     if (col < n0) st_bf16x4(o0 + (size_t)row * ld0 + col, v);
;     else { const int c = col - n0; if (c < n1) st_bf16x4(o1 + (size_t)row * ld1 + c, v); }
;   }
	v_rcp_f32_e32 v94, v94
	v_rcp_f32_e32 v95, v95
	s_nop 0
	v_mul_f32_e32 v92, 0x3f1b4598, v92
	v_mul_f32_e32 v93, 0x3f1b4598, v93
	v_mul_f32_e32 v94, 0x3f1b4598, v94
	v_mul_f32_e32 v95, 0x3f1b4598, v95
	v_cvt_pk_bf16_f32 v142, v92, v93
	v_cvt_pk_bf16_f32 v143, v94, v95
	ds_write_b64 v236, v[142:143] offset:11616
	v_add_f32_e32 v96, v96, v192
	v_add_f32_e32 v97, v97, v193
	v_add_f32_e32 v98, v98, v194
	v_add_f32_e32 v99, v99, v195
	v_mul_f32_e32 v96, 0xbfb8aa3b, v96
	v_mul_f32_e32 v97, 0xbfb8aa3b, v97
	v_mul_f32_e32 v98, 0xbfb8aa3b, v98
	v_mul_f32_e32 v99, 0xbfb8aa3b, v99
	v_exp_f32_e32 v96, v96
	v_exp_f32_e32 v97, v97
	v_exp_f32_e32 v98, v98
	v_exp_f32_e32 v99, v99
	s_nop 0
	v_add_f32_e32 v96, 1.0, v96
	v_add_f32_e32 v97, 1.0, v97
	v_add_f32_e32 v98, 1.0, v98
	v_add_f32_e32 v99, 1.0, v99
	v_rcp_f32_e32 v96, v96
	v_rcp_f32_e32 v97, v97
	v_rcp_f32_e32 v98, v98
	v_rcp_f32_e32 v99, v99
	s_nop 0
	v_mul_f32_e32 v96, 0x3f1b4598, v96
	v_mul_f32_e32 v97, 0x3f1b4598, v97
	v_mul_f32_e32 v98, 0x3f1b4598, v98
	v_mul_f32_e32 v99, 0x3f1b4598, v99
	v_cvt_pk_bf16_f32 v144, v96, v97
	v_cvt_pk_bf16_f32 v145, v98, v99
	ds_write_b64 v236, v[144:145] offset:13824
	v_add_f32_e32 v100, v100, v196
	v_add_f32_e32 v101, v101, v197
	v_add_f32_e32 v102, v102, v198
	v_add_f32_e32 v103, v103, v199
	v_mul_f32_e32 v100, 0xbfb8aa3b, v100
	v_mul_f32_e32 v101, 0xbfb8aa3b, v101
	v_mul_f32_e32 v102, 0xbfb8aa3b, v102
	v_mul_f32_e32 v103, 0xbfb8aa3b, v103
	v_exp_f32_e32 v100, v100
	v_exp_f32_e32 v101, v101
	v_exp_f32_e32 v102, v102
	v_exp_f32_e32 v103, v103
	s_nop 0
	v_add_f32_e32 v100, 1.0, v100
	v_add_f32_e32 v101, 1.0, v101
	v_add_f32_e32 v102, 1.0, v102
	v_add_f32_e32 v103, 1.0, v103
	v_rcp_f32_e32 v100, v100
	v_rcp_f32_e32 v101, v101
	v_rcp_f32_e32 v102, v102
	v_rcp_f32_e32 v103, v103
	s_nop 0
	v_mul_f32_e32 v100, 0x3f1b4598, v100
	v_mul_f32_e32 v101, 0x3f1b4598, v101
	v_mul_f32_e32 v102, 0x3f1b4598, v102
	v_mul_f32_e32 v103, 0x3f1b4598, v103
	v_cvt_pk_bf16_f32 v146, v100, v101
	v_cvt_pk_bf16_f32 v147, v102, v103
	ds_write_b64 v236, v[146:147] offset:13856
	v_add_f32_e32 v104, v104, v200
	v_add_f32_e32 v105, v105, v201
	v_add_f32_e32 v106, v106, v202
	v_add_f32_e32 v107, v107, v203
	v_mul_f32_e32 v104, 0xbfb8aa3b, v104
	v_mul_f32_e32 v105, 0xbfb8aa3b, v105
	v_mul_f32_e32 v106, 0xbfb8aa3b, v106
	v_mul_f32_e32 v107, 0xbfb8aa3b, v107
	v_exp_f32_e32 v104, v104
	v_exp_f32_e32 v105, v105
	v_exp_f32_e32 v106, v106
	v_exp_f32_e32 v107, v107
	s_nop 0
	v_add_f32_e32 v104, 1.0, v104
	v_add_f32_e32 v105, 1.0, v105
	v_add_f32_e32 v106, 1.0, v106
	v_add_f32_e32 v107, 1.0, v107
	v_rcp_f32_e32 v104, v104
	v_rcp_f32_e32 v105, v105
	v_rcp_f32_e32 v106, v106
	v_rcp_f32_e32 v107, v107
	s_nop 0
	v_mul_f32_e32 v104, 0x3f1b4598, v104
	v_mul_f32_e32 v105, 0x3f1b4598, v105
	v_mul_f32_e32 v106, 0x3f1b4598, v106
	v_mul_f32_e32 v107, 0x3f1b4598, v107
	v_cvt_pk_bf16_f32 v148, v104, v105
	v_cvt_pk_bf16_f32 v149, v106, v107
	ds_write_b64 v236, v[148:149] offset:13888
	v_add_f32_e32 v108, v108, v204
	v_add_f32_e32 v109, v109, v205
	v_add_f32_e32 v110, v110, v206
	v_add_f32_e32 v111, v111, v207
	v_mul_f32_e32 v108, 0xbfb8aa3b, v108
	v_mul_f32_e32 v109, 0xbfb8aa3b, v109
	v_mul_f32_e32 v110, 0xbfb8aa3b, v110
	v_mul_f32_e32 v111, 0xbfb8aa3b, v111
	v_exp_f32_e32 v108, v108
	v_exp_f32_e32 v109, v109
	v_exp_f32_e32 v110, v110
	v_exp_f32_e32 v111, v111
	s_nop 0
	v_add_f32_e32 v108, 1.0, v108
	v_add_f32_e32 v109, 1.0, v109
	v_add_f32_e32 v110, 1.0, v110
	v_add_f32_e32 v111, 1.0, v111
	v_rcp_f32_e32 v108, v108
	v_rcp_f32_e32 v109, v109
	v_rcp_f32_e32 v110, v110
	v_rcp_f32_e32 v111, v111
	s_nop 0
	v_mul_f32_e32 v108, 0x3f1b4598, v108
	v_mul_f32_e32 v109, 0x3f1b4598, v109
	v_mul_f32_e32 v110, 0x3f1b4598, v110
	v_mul_f32_e32 v111, 0x3f1b4598, v111
	v_cvt_pk_bf16_f32 v150, v108, v109
	v_cvt_pk_bf16_f32 v151, v110, v111
	ds_write_b64 v236, v[150:151] offset:13920
	v_add_f32_e32 v112, v112, v192
	v_add_f32_e32 v113, v113, v193
	v_add_f32_e32 v114, v114, v194
	v_add_f32_e32 v115, v115, v195
	v_mul_f32_e32 v112, 0xbfb8aa3b, v112
	v_mul_f32_e32 v113, 0xbfb8aa3b, v113
	v_mul_f32_e32 v114, 0xbfb8aa3b, v114
	v_mul_f32_e32 v115, 0xbfb8aa3b, v115
	v_exp_f32_e32 v112, v112
	v_exp_f32_e32 v113, v113
	v_exp_f32_e32 v114, v114
	v_exp_f32_e32 v115, v115
	s_nop 0
	v_add_f32_e32 v112, 1.0, v112
	v_add_f32_e32 v113, 1.0, v113
	v_add_f32_e32 v114, 1.0, v114
	v_add_f32_e32 v115, 1.0, v115
	v_rcp_f32_e32 v112, v112
	v_rcp_f32_e32 v113, v113
	v_rcp_f32_e32 v114, v114
	v_rcp_f32_e32 v115, v115
	s_nop 0
	v_mul_f32_e32 v112, 0x3f1b4598, v112
	v_mul_f32_e32 v113, 0x3f1b4598, v113
	v_mul_f32_e32 v114, 0x3f1b4598, v114
	v_mul_f32_e32 v115, 0x3f1b4598, v115
	v_cvt_pk_bf16_f32 v152, v112, v113
	v_cvt_pk_bf16_f32 v153, v114, v115
	ds_write_b64 v236, v[152:153] offset:16128
	v_add_f32_e32 v116, v116, v196
	v_add_f32_e32 v117, v117, v197
	v_add_f32_e32 v118, v118, v198
	v_add_f32_e32 v119, v119, v199
	v_mul_f32_e32 v116, 0xbfb8aa3b, v116
	v_mul_f32_e32 v117, 0xbfb8aa3b, v117
	v_mul_f32_e32 v118, 0xbfb8aa3b, v118
	v_mul_f32_e32 v119, 0xbfb8aa3b, v119
	v_exp_f32_e32 v116, v116
	v_exp_f32_e32 v117, v117
	v_exp_f32_e32 v118, v118
	v_exp_f32_e32 v119, v119
	s_nop 0
	v_add_f32_e32 v116, 1.0, v116
	v_add_f32_e32 v117, 1.0, v117
	v_add_f32_e32 v118, 1.0, v118
	v_add_f32_e32 v119, 1.0, v119
	v_rcp_f32_e32 v116, v116
	v_rcp_f32_e32 v117, v117
	v_rcp_f32_e32 v118, v118
	v_rcp_f32_e32 v119, v119
	s_nop 0
	v_mul_f32_e32 v116, 0x3f1b4598, v116
	v_mul_f32_e32 v117, 0x3f1b4598, v117
	v_mul_f32_e32 v118, 0x3f1b4598, v118
	v_mul_f32_e32 v119, 0x3f1b4598, v119
	v_cvt_pk_bf16_f32 v154, v116, v117
	v_cvt_pk_bf16_f32 v155, v118, v119
	ds_write_b64 v236, v[154:155] offset:16160
; DI unsigned pack2(float lo, float hi) { const f32x2c v = {lo, hi}; return __builtin_bit_cast(unsigned, __builtin_convertvector(v, bf16x2c)); }
; template <class Epi>
; DI void gemm_tile(char* smem, const bf16_t* __restrict__ A0, int lda0, int ksplit, const bf16_t* __restrict__ A1, int lda1,
;                   const bf16_t* __restrict__ Bt, int K, int row0, int col0, const Epi& epi, int tid) {
;     ...
; #pragma unroll
;   for (int m = 0; m < 8; ++m)
; #pragma unroll
;     for (int n = 0; n < 4; ++n) epi(row0 + wr * 128 + m * 16 + fr, col0 + wc * 64 + n * 16 + fq * 4, acc[m][n]);
; }
; DI void st_bf16x4(bf16_t* o, f32x4 v) { u32x2 q; q.x = pack2(v[0], v[1]); q.y = pack2(v[2], v[3]); *(u32x2*)o = q; }
;   DI void operator()(int row, int col, f32x4 v) const {
;     if (col < n0) st_bf16x4(o0 + (size_t)row * ld0 + col, v);
;     else { const int c = col - n0; if (c < n1) st_bf16x4(o1 + (size_t)row * ld1 + c, v); }
;   }
; DI void phase_rw_small_gemms(const Ctx& c, char* smem) {
;     ...
;   gemm_phase(smem, sm, 256, 1 << 30, sm, 256, W2 + 512 * 64, 64, 4, EpiSmall{0, p.rw_w0 + 512, E1}, tid);
	v_add_f32_e32 v120, v120, v200
	v_add_f32_e32 v121, v121, v201
	v_add_f32_e32 v122, v122, v202
	v_add_f32_e32 v123, v123, v203
	v_mul_f32_e32 v120, 0xbfb8aa3b, v120
	v_mul_f32_e32 v121, 0xbfb8aa3b, v121
	v_mul_f32_e32 v122, 0xbfb8aa3b, v122
	v_mul_f32_e32 v123, 0xbfb8aa3b, v123
	v_exp_f32_e32 v120, v120
	v_exp_f32_e32 v121, v121
	v_exp_f32_e32 v122, v122
	v_exp_f32_e32 v123, v123
	s_nop 0
	v_add_f32_e32 v120, 1.0, v120
	v_add_f32_e32 v121, 1.0, v121
	v_add_f32_e32 v122, 1.0, v122
	v_add_f32_e32 v123, 1.0, v123
	v_rcp_f32_e32 v120, v120
	v_rcp_f32_e32 v121, v121
	v_rcp_f32_e32 v122, v122
	v_rcp_f32_e32 v123, v123
	s_nop 0
	v_mul_f32_e32 v120, 0x3f1b4598, v120
	v_mul_f32_e32 v121, 0x3f1b4598, v121
	v_mul_f32_e32 v122, 0x3f1b4598, v122
	v_mul_f32_e32 v123, 0x3f1b4598, v123
	v_cvt_pk_bf16_f32 v156, v120, v121
	v_cvt_pk_bf16_f32 v157, v122, v123
	ds_write_b64 v236, v[156:157] offset:16192
	v_add_f32_e32 v124, v124, v204
	v_add_f32_e32 v125, v125, v205
	v_add_f32_e32 v126, v126, v206
	v_add_f32_e32 v127, v127, v207
	v_mul_f32_e32 v124, 0xbfb8aa3b, v124
	v_mul_f32_e32 v125, 0xbfb8aa3b, v125
	v_mul_f32_e32 v126, 0xbfb8aa3b, v126
	v_mul_f32_e32 v127, 0xbfb8aa3b, v127
	v_exp_f32_e32 v124, v124
	v_exp_f32_e32 v125, v125
	v_exp_f32_e32 v126, v126
	v_exp_f32_e32 v127, v127
	s_nop 0
	v_add_f32_e32 v124, 1.0, v124
	v_add_f32_e32 v125, 1.0, v125
	v_add_f32_e32 v126, 1.0, v126
	v_add_f32_e32 v127, 1.0, v127
	v_rcp_f32_e32 v124, v124
	v_rcp_f32_e32 v125, v125
	v_rcp_f32_e32 v126, v126
	v_rcp_f32_e32 v127, v127
	s_nop 0
	v_mul_f32_e32 v124, 0x3f1b4598, v124
	v_mul_f32_e32 v125, 0x3f1b4598, v125
	v_mul_f32_e32 v126, 0x3f1b4598, v126
	v_mul_f32_e32 v127, 0x3f1b4598, v127
	v_cvt_pk_bf16_f32 v158, v124, v125
	v_cvt_pk_bf16_f32 v159, v126, v127
	ds_write_b64 v236, v[158:159] offset:16224
	s_waitcnt lgkmcnt(0)
	ds_read_b128 v[128:131], v237
	ds_read_b128 v[132:135], v237 offset:1152
	ds_read_b128 v[136:139], v237 offset:2304
	ds_read_b128 v[140:143], v237 offset:3456
	ds_read_b128 v[144:147], v237 offset:4608
	ds_read_b128 v[148:151], v237 offset:5760
	ds_read_b128 v[152:155], v237 offset:6912
	ds_read_b128 v[156:159], v237 offset:8064
	ds_read_b128 v[160:163], v237 offset:9216
	ds_read_b128 v[164:167], v237 offset:10368
	ds_read_b128 v[168:171], v237 offset:11520
	ds_read_b128 v[172:175], v237 offset:12672
	ds_read_b128 v[176:179], v237 offset:13824
	ds_read_b128 v[180:183], v237 offset:14976
	ds_read_b128 v[184:187], v237 offset:16128
	ds_read_b128 v[188:191], v237 offset:17280
	s_waitcnt lgkmcnt(15)
	global_store_dwordx4 v238, v[128:131], s[4:5]
	s_add_u32 s4, s4, 0x2000
	s_addc_u32 s5, s5, 0
	s_waitcnt lgkmcnt(14)
	global_store_dwordx4 v238, v[132:135], s[4:5]
	s_add_u32 s4, s4, 0x2000
	s_addc_u32 s5, s5, 0
	s_waitcnt lgkmcnt(13)
	global_store_dwordx4 v238, v[136:139], s[4:5]
	s_add_u32 s4, s4, 0x2000
	s_addc_u32 s5, s5, 0
	s_waitcnt lgkmcnt(12)
	global_store_dwordx4 v238, v[140:143], s[4:5]
	s_add_u32 s4, s4, 0x2000
	s_addc_u32 s5, s5, 0
	s_waitcnt lgkmcnt(11)
	global_store_dwordx4 v238, v[144:147], s[4:5]
	s_add_u32 s4, s4, 0x2000
	s_addc_u32 s5, s5, 0
	s_waitcnt lgkmcnt(10)
	global_store_dwordx4 v238, v[148:151], s[4:5]
	s_add_u32 s4, s4, 0x2000
	s_addc_u32 s5, s5, 0
	s_waitcnt lgkmcnt(9)
	global_store_dwordx4 v238, v[152:155], s[4:5]
	s_add_u32 s4, s4, 0x2000
	s_addc_u32 s5, s5, 0
	s_waitcnt lgkmcnt(8)
	global_store_dwordx4 v238, v[156:159], s[4:5]
	s_add_u32 s4, s4, 0x2000
	s_addc_u32 s5, s5, 0
	s_waitcnt lgkmcnt(7)
	global_store_dwordx4 v238, v[160:163], s[4:5]
	s_add_u32 s4, s4, 0x2000
	s_addc_u32 s5, s5, 0
	s_waitcnt lgkmcnt(6)
	global_store_dwordx4 v238, v[164:167], s[4:5]
	s_add_u32 s4, s4, 0x2000
	s_addc_u32 s5, s5, 0
	s_waitcnt lgkmcnt(5)
	global_store_dwordx4 v238, v[168:171], s[4:5]
	s_add_u32 s4, s4, 0x2000
	s_addc_u32 s5, s5, 0
	s_waitcnt lgkmcnt(4)
	global_store_dwordx4 v238, v[172:175], s[4:5]
	s_add_u32 s4, s4, 0x2000
	s_addc_u32 s5, s5, 0
	s_waitcnt lgkmcnt(3)
	global_store_dwordx4 v238, v[176:179], s[4:5]
	s_add_u32 s4, s4, 0x2000
	s_addc_u32 s5, s5, 0
	s_waitcnt lgkmcnt(2)
	global_store_dwordx4 v238, v[180:183], s[4:5]
	s_add_u32 s4, s4, 0x2000
	s_addc_u32 s5, s5, 0
	s_waitcnt lgkmcnt(1)
	global_store_dwordx4 v238, v[184:187], s[4:5]
	s_add_u32 s4, s4, 0x2000
	s_addc_u32 s5, s5, 0
	s_waitcnt lgkmcnt(0)
	global_store_dwordx4 v238, v[188:191], s[4:5]
	s_nop 1
	s_add_u32 s15, s15, 64
	s_branch .Lg3a_tile
.Lg3a_done:
	v_mbcnt_lo_u32_b32 v194, -1, 0
	v_mbcnt_hi_u32_b32 v136, -1, v194
	v_mbcnt_lo_u32_b32 v240, -1, 0
	v_mbcnt_hi_u32_b32 v240, -1, v240
	s_lshr_b32 s27, s72, 6
	s_lshl_b32 s100, s27, 10
	v_and_b32_e32 v241, 15, v240
	v_lshrrev_b32_e32 v242, 4, v240
	v_bfe_u32 v243, v240, 3, 1
	v_mul_u32_u24_e32 v243, 3, v243
	v_xor_b32_e32 v243, v242, v243
	v_lshlrev_b32_e32 v243, 4, v243
	v_lshl_add_u32 v243, v241, 6, v243
	s_lshr_b32 s26, s27, 1
	s_lshl_b32 s26, s26, 13
	v_add_u32_e32 v230, s26, v243
	s_and_b32 s26, s27, 1
	s_lshl_b32 s26, s26, 12
	s_add_u32 s26, s26, 16384
	v_add_u32_e32 v231, s26, v243
	s_lshr_b32 s26, s27, 1
	s_lshl_b32 s26, s26, 7
	v_add_u32_e32 v244, s26, v241
	s_and_b32 s26, s27, 1
	s_lshl_b32 s26, s26, 6
	v_lshl_add_u32 v245, v242, 2, s26
	v_lshlrev_b32_e32 v235, 2, v245
	s_mul_i32 s26, s27, 18432
	v_mul_u32_u24_e32 v246, 144, v241
	v_lshl_add_u32 v246, v242, 3, v246
	v_add_u32_e32 v236, s26, v246
	v_lshrrev_b32_e32 v246, 3, v240
	v_mul_u32_u24_e32 v246, 144, v246
	v_and_b32_e32 v247, 7, v240
	v_lshl_add_u32 v246, v247, 4, v246
	v_add_u32_e32 v237, s26, v246
	s_lshr_b32 s26, s27, 1
	s_lshl_b32 s26, s26, 7
	v_lshrrev_b32_e32 v246, 3, v240
	v_add_u32_e32 v246, s26, v246
	s_and_b32 s26, s27, 1
	s_lshl_b32 s26, s26, 6
	v_lshl_add_u32 v248, v247, 3, s26
	s_movk_i32 s26, 1024
	v_mul_lo_u32 v247, v246, s26
	v_lshl_add_u32 v238, v248, 1, v247
	v_lshrrev_b32_e32 v241, 2, v240
	s_lshl_b32 s26, s27, 4
	v_add_u32_e32 v241, s26, v241
	v_bfe_u32 v242, v240, 5, 1
	v_mul_u32_u24_e32 v242, 3, v242
	v_and_b32_e32 v243, 3, v240
	v_xor_b32_e32 v243, v243, v242
	v_lshlrev_b32_e32 v243, 4, v243
	s_mov_b32 s26, 512
	v_mad_u32_u24 v224, v241, s26, v243
	v_add_u32_e32 v225, 0x8000, v224
	v_add_u32_e32 v226, 0x10000, v224
	v_add_u32_e32 v227, 0x18000, v224
	s_mov_b32 s26, 128
	v_mad_u32_u24 v228, v241, s26, v243
	v_add_u32_e32 v229, 0x2000, v228
	s_load_dwordx2 s[6:7], s[74:75], 0x48
	s_lshr_b32 s15, s96, 3
	s_and_b32 s101, s96, 7
	s_lshl_b32 s101, s101, 1
	s_waitcnt lgkmcnt(0)
; #define LWRITE(S, buf) do { bf16_t* sA_ = sbase + (buf) * BUF; bf16_t* sB_ = sA_ + 256 * PITCH; \
;     _Pragma("unroll") for (int i_ = 0; i_ < 4; ++i_) *(u32x4*)(sA_ + (sr + i_ * 64) * PITCH + scv * 8) = ra[S][i_]; \
;     _Pragma("unroll") for (int i_ = 0; i_ < 2; ++i_) *(u32x4*)(sB_ + (sr + i_ * 64) * PITCH + scv * 8) = rb[S][i_]; } while (0)
; template <class Epi>
; DI void gemm_tile(char* smem, const bf16_t* __restrict__ A0, int lda0, int ksplit, const bf16_t* __restrict__ A1, int lda1,
;                   const bf16_t* __restrict__ Bt, int K, int row0, int col0, const Epi& epi, int tid) {
;     ...
;   __syncthreads();
;   {
;     const int last = nk - 1;
;     GLOAD(0, 0);
;     __builtin_amdgcn_sched_barrier(0);
;     GLOAD(1, 1);
;     __builtin_amdgcn_sched_barrier(0);
;     LWRITE(0, 0);
;     __builtin_amdgcn_sched_barrier(0);
;     GLOAD(0, (2 < last ? 2 : last));
;     __builtin_amdgcn_sched_barrier(0);
;     __syncthreads();
; DI void phase_rw_small_gemms(const Ctx& c, char* smem) {
;     ...
;   gemm_phase(smem, sm, 256, 1 << 30, sm, 256, W2 + 512 * 64, 64, 4, EpiSmall{0, p.rw_w0 + 512, E1}, tid);
.Lg3b_tile:
	s_cmpk_ge_u32 s15, 64
	s_cbranch_scc1 .Lg3b_done
	s_cmpk_ge_u32 s15, 32
	s_cselect_b32 s27, 1, 0
	s_cselect_b32 s26, 32, 0
	s_sub_u32 s26, s15, s26
	s_add_u32 s27, s27, s101
	s_lshl_b32 s27, s27, 3
	s_and_b32 s29, s26, 7
	s_add_u32 s29, s29, s27
	s_lshl_b32 s29, s29, 8
	s_lshr_b32 s28, s26, 3
	s_lshl_b32 s28, s28, 7
	s_mul_i32 s27, s29, 512
	s_add_u32 s27, s27, 0x1ea00000
	s_add_u32 s0, s92, s27
	s_addc_u32 s1, s93, 0
	s_mul_i32 s27, s28, 128
	s_add_u32 s27, s27, 0x34b0000
	s_add_u32 s2, s92, s27
	s_addc_u32 s3, s93, 0
	s_waitcnt lgkmcnt(0)
	s_barrier
	s_mov_b32 s99, 0
	s_mov_b32 s30, 0
	s_add_u32 s26, s30, s100
	s_add_u32 m0, s26, 0
	s_nop 0
	global_load_lds_dwordx4 v224, s[0:1]
	s_add_u32 m0, s26, 4096
	s_nop 0
	global_load_lds_dwordx4 v225, s[0:1]
	s_add_u32 m0, s26, 8192
	s_nop 0
	global_load_lds_dwordx4 v226, s[0:1]
	s_add_u32 m0, s26, 12288
	s_nop 0
	global_load_lds_dwordx4 v227, s[0:1]
	s_add_u32 m0, s26, 16384
	s_nop 0
	global_load_lds_dwordx4 v228, s[2:3]
	s_add_u32 m0, s26, 20480
	s_nop 0
	global_load_lds_dwordx4 v229, s[2:3]
	s_add_u32 s0, s0, 64
	s_addc_u32 s1, s1, 0
	s_add_u32 s2, s2, 64
	s_addc_u32 s3, s3, 0
	s_add_u32 s99, s99, 1
	s_add_u32 s30, s30, 24576
	s_cmp_eq_u32 s30, 73728
	s_cselect_b32 s30, 0, s30
	s_add_u32 s26, s30, s100
	s_add_u32 m0, s26, 0
	s_nop 0
	global_load_lds_dwordx4 v224, s[0:1]
	s_add_u32 m0, s26, 4096
	s_nop 0
	global_load_lds_dwordx4 v225, s[0:1]
	s_add_u32 m0, s26, 8192
	s_nop 0
	global_load_lds_dwordx4 v226, s[0:1]
	s_add_u32 m0, s26, 12288
	s_nop 0
	global_load_lds_dwordx4 v227, s[0:1]
	s_add_u32 m0, s26, 16384
	s_nop 0
	global_load_lds_dwordx4 v228, s[2:3]
	s_add_u32 m0, s26, 20480
	s_nop 0
	global_load_lds_dwordx4 v229, s[2:3]
	s_add_u32 s0, s0, 64
	s_addc_u32 s1, s1, 0
	s_add_u32 s2, s2, 64
	s_addc_u32 s3, s3, 0
	s_add_u32 s99, s99, 1
	s_add_u32 s30, s30, 24576
	s_cmp_eq_u32 s30, 73728
	s_cselect_b32 s30, 0, s30
	v_mov_b32_e32 v0, 0
	v_mov_b32_e32 v1, 0
	v_mov_b32_e32 v2, 0
	v_mov_b32_e32 v3, 0
	v_mov_b32_e32 v4, 0
	v_mov_b32_e32 v5, 0
	v_mov_b32_e32 v6, 0
	v_mov_b32_e32 v7, 0
	v_mov_b32_e32 v8, 0
	v_mov_b32_e32 v9, 0
	v_mov_b32_e32 v10, 0
	v_mov_b32_e32 v11, 0
	v_mov_b32_e32 v12, 0
	v_mov_b32_e32 v13, 0
	v_mov_b32_e32 v14, 0
	v_mov_b32_e32 v15, 0
	v_mov_b32_e32 v16, 0
	v_mov_b32_e32 v17, 0
	v_mov_b32_e32 v18, 0
	v_mov_b32_e32 v19, 0
	v_mov_b32_e32 v20, 0
	v_mov_b32_e32 v21, 0
	v_mov_b32_e32 v22, 0
	v_mov_b32_e32 v23, 0
	v_mov_b32_e32 v24, 0
	v_mov_b32_e32 v25, 0
	v_mov_b32_e32 v26, 0
	v_mov_b32_e32 v27, 0
	v_mov_b32_e32 v28, 0
	v_mov_b32_e32 v29, 0
	v_mov_b32_e32 v30, 0
	v_mov_b32_e32 v31, 0
	v_mov_b32_e32 v32, 0
	v_mov_b32_e32 v33, 0
	v_mov_b32_e32 v34, 0
	v_mov_b32_e32 v35, 0
	v_mov_b32_e32 v36, 0
	v_mov_b32_e32 v37, 0
	v_mov_b32_e32 v38, 0
	v_mov_b32_e32 v39, 0
	v_mov_b32_e32 v40, 0
	v_mov_b32_e32 v41, 0
	v_mov_b32_e32 v42, 0
	v_mov_b32_e32 v43, 0
	v_mov_b32_e32 v44, 0
	v_mov_b32_e32 v45, 0
	v_mov_b32_e32 v46, 0
	v_mov_b32_e32 v47, 0
	v_mov_b32_e32 v48, 0
	v_mov_b32_e32 v49, 0
	v_mov_b32_e32 v50, 0
	v_mov_b32_e32 v51, 0
	v_mov_b32_e32 v52, 0
	v_mov_b32_e32 v53, 0
	v_mov_b32_e32 v54, 0
	v_mov_b32_e32 v55, 0
	v_mov_b32_e32 v56, 0
	v_mov_b32_e32 v57, 0
	v_mov_b32_e32 v58, 0
	v_mov_b32_e32 v59, 0
	v_mov_b32_e32 v60, 0
	v_mov_b32_e32 v61, 0
	v_mov_b32_e32 v62, 0
	v_mov_b32_e32 v63, 0
	v_mov_b32_e32 v64, 0
	v_mov_b32_e32 v65, 0
	v_mov_b32_e32 v66, 0
	v_mov_b32_e32 v67, 0
	v_mov_b32_e32 v68, 0
	v_mov_b32_e32 v69, 0
	v_mov_b32_e32 v70, 0
	v_mov_b32_e32 v71, 0
	v_mov_b32_e32 v72, 0
	v_mov_b32_e32 v73, 0
	v_mov_b32_e32 v74, 0
	v_mov_b32_e32 v75, 0
	v_mov_b32_e32 v76, 0
	v_mov_b32_e32 v77, 0
	v_mov_b32_e32 v78, 0
	v_mov_b32_e32 v79, 0
	v_mov_b32_e32 v80, 0
	v_mov_b32_e32 v81, 0
	v_mov_b32_e32 v82, 0
	v_mov_b32_e32 v83, 0
	v_mov_b32_e32 v84, 0
	v_mov_b32_e32 v85, 0
	v_mov_b32_e32 v86, 0
	v_mov_b32_e32 v87, 0
	v_mov_b32_e32 v88, 0
	v_mov_b32_e32 v89, 0
	v_mov_b32_e32 v90, 0
	v_mov_b32_e32 v91, 0
	v_mov_b32_e32 v92, 0
	v_mov_b32_e32 v93, 0
	v_mov_b32_e32 v94, 0
	v_mov_b32_e32 v95, 0
	v_mov_b32_e32 v96, 0
	v_mov_b32_e32 v97, 0
	v_mov_b32_e32 v98, 0
	v_mov_b32_e32 v99, 0
	v_mov_b32_e32 v100, 0
	v_mov_b32_e32 v101, 0
	v_mov_b32_e32 v102, 0
	v_mov_b32_e32 v103, 0
	v_mov_b32_e32 v104, 0
	v_mov_b32_e32 v105, 0
	v_mov_b32_e32 v106, 0
	v_mov_b32_e32 v107, 0
	v_mov_b32_e32 v108, 0
	v_mov_b32_e32 v109, 0
	v_mov_b32_e32 v110, 0
	v_mov_b32_e32 v111, 0
	v_mov_b32_e32 v112, 0
	v_mov_b32_e32 v113, 0
	v_mov_b32_e32 v114, 0
	v_mov_b32_e32 v115, 0
	v_mov_b32_e32 v116, 0
	v_mov_b32_e32 v117, 0
	v_mov_b32_e32 v118, 0
	v_mov_b32_e32 v119, 0
	v_mov_b32_e32 v120, 0
	v_mov_b32_e32 v121, 0
	v_mov_b32_e32 v122, 0
	v_mov_b32_e32 v123, 0
	v_mov_b32_e32 v124, 0
	v_mov_b32_e32 v125, 0
	v_mov_b32_e32 v126, 0
	v_mov_b32_e32 v127, 0
	s_mov_b32 s98, 0
	s_mov_b32 s31, 24576
	s_waitcnt vmcnt(6)
	s_barrier
	ds_read_b128 v[128:131], v231 offset:0
	ds_read_b128 v[132:135], v231 offset:1024
	ds_read_b128 v[136:139], v231 offset:2048
	ds_read_b128 v[140:143], v231 offset:3072
	ds_read_b128 v[144:147], v230 offset:0
	ds_read_b128 v[148:151], v230 offset:1024
	ds_read_b128 v[152:155], v230 offset:2048
	ds_read_b128 v[156:159], v230 offset:3072
	ds_read_b128 v[160:163], v230 offset:4096
	ds_read_b128 v[164:167], v230 offset:5120
	ds_read_b128 v[168:171], v230 offset:6144
	ds_read_b128 v[172:175], v230 offset:7168
	s_waitcnt vmcnt(0)
	s_waitcnt lgkmcnt(0)
	s_barrier
; #define LWRITE(S, buf) do { bf16_t* sA_ = sbase + (buf) * BUF; bf16_t* sB_ = sA_ + 256 * PITCH; \
;     _Pragma("unroll") for (int i_ = 0; i_ < 4; ++i_) *(u32x4*)(sA_ + (sr + i_ * 64) * PITCH + scv * 8) = ra[S][i_]; \
;     _Pragma("unroll") for (int i_ = 0; i_ < 2; ++i_) *(u32x4*)(sB_ + (sr + i_ * 64) * PITCH + scv * 8) = rb[S][i_]; } while (0)
; template <class Epi>
; DI void gemm_tile(char* smem, const bf16_t* __restrict__ A0, int lda0, int ksplit, const bf16_t* __restrict__ A1, int lda1,
;                   const bf16_t* __restrict__ Bt, int K, int row0, int col0, const Epi& epi, int tid) {
;     ...
;   __syncthreads();
;   {
;     const int last = nk - 1;
;     GLOAD(0, 0);
;     __builtin_amdgcn_sched_barrier(0);
;     GLOAD(1, 1);
;     __builtin_amdgcn_sched_barrier(0);
;     LWRITE(0, 0);
;     __builtin_amdgcn_sched_barrier(0);
;     GLOAD(0, (2 < last ? 2 : last));
;     __builtin_amdgcn_sched_barrier(0);
;     __syncthreads();
;     for (int kt = 0; kt < nk; kt += 2) {
;       LWRITE(1, 1);
;       __builtin_amdgcn_sched_barrier(0);
;       GLOAD(1, (kt + 3 < last ? kt + 3 : last));
;       __builtin_amdgcn_sched_barrier(0);
;       COMPUTE(0);
;       __syncthreads();
;       LWRITE(0, 0);
;       __builtin_amdgcn_sched_barrier(0);
;       GLOAD(0, (kt + 4 < last ? kt + 4 : last));
;       __builtin_amdgcn_sched_barrier(0);
;       COMPUTE(1);
;       __syncthreads();
	v_add_u32_e32 v232, s31, v230
	v_add_u32_e32 v233, s31, v231
	v_mfma_f32_16x16x32_bf16 v[0:3], v[128:131], v[144:147], v[0:3]
	v_mfma_f32_16x16x32_bf16 v[4:7], v[132:135], v[144:147], v[4:7]
	v_mfma_f32_16x16x32_bf16 v[8:11], v[136:139], v[144:147], v[8:11]
	v_mfma_f32_16x16x32_bf16 v[12:15], v[140:143], v[144:147], v[12:15]
	ds_read_b128 v[176:179], v233 offset:0
	ds_read_b128 v[180:183], v233 offset:1024
	v_mfma_f32_16x16x32_bf16 v[16:19], v[128:131], v[148:151], v[16:19]
	v_mfma_f32_16x16x32_bf16 v[20:23], v[132:135], v[148:151], v[20:23]
	v_mfma_f32_16x16x32_bf16 v[24:27], v[136:139], v[148:151], v[24:27]
	v_mfma_f32_16x16x32_bf16 v[28:31], v[140:143], v[148:151], v[28:31]
	ds_read_b128 v[184:187], v233 offset:2048
	ds_read_b128 v[188:191], v233 offset:3072
	v_mfma_f32_16x16x32_bf16 v[32:35], v[128:131], v[152:155], v[32:35]
	v_mfma_f32_16x16x32_bf16 v[36:39], v[132:135], v[152:155], v[36:39]
	v_mfma_f32_16x16x32_bf16 v[40:43], v[136:139], v[152:155], v[40:43]
	v_mfma_f32_16x16x32_bf16 v[44:47], v[140:143], v[152:155], v[44:47]
	ds_read_b128 v[192:195], v232 offset:0
	ds_read_b128 v[196:199], v232 offset:1024
	v_mfma_f32_16x16x32_bf16 v[48:51], v[128:131], v[156:159], v[48:51]
	v_mfma_f32_16x16x32_bf16 v[52:55], v[132:135], v[156:159], v[52:55]
	v_mfma_f32_16x16x32_bf16 v[56:59], v[136:139], v[156:159], v[56:59]
	v_mfma_f32_16x16x32_bf16 v[60:63], v[140:143], v[156:159], v[60:63]
	ds_read_b128 v[200:203], v232 offset:2048
	ds_read_b128 v[204:207], v232 offset:3072
	v_mfma_f32_16x16x32_bf16 v[64:67], v[128:131], v[160:163], v[64:67]
	v_mfma_f32_16x16x32_bf16 v[68:71], v[132:135], v[160:163], v[68:71]
	v_mfma_f32_16x16x32_bf16 v[72:75], v[136:139], v[160:163], v[72:75]
	v_mfma_f32_16x16x32_bf16 v[76:79], v[140:143], v[160:163], v[76:79]
	ds_read_b128 v[208:211], v232 offset:4096
	v_mfma_f32_16x16x32_bf16 v[80:83], v[128:131], v[164:167], v[80:83]
	v_mfma_f32_16x16x32_bf16 v[84:87], v[132:135], v[164:167], v[84:87]
	v_mfma_f32_16x16x32_bf16 v[88:91], v[136:139], v[164:167], v[88:91]
	v_mfma_f32_16x16x32_bf16 v[92:95], v[140:143], v[164:167], v[92:95]
	ds_read_b128 v[212:215], v232 offset:5120
	v_mfma_f32_16x16x32_bf16 v[96:99], v[128:131], v[168:171], v[96:99]
	v_mfma_f32_16x16x32_bf16 v[100:103], v[132:135], v[168:171], v[100:103]
	v_mfma_f32_16x16x32_bf16 v[104:107], v[136:139], v[168:171], v[104:107]
	v_mfma_f32_16x16x32_bf16 v[108:111], v[140:143], v[168:171], v[108:111]
	ds_read_b128 v[216:219], v232 offset:6144
	s_add_u32 s31, s31, 24576
	s_cmp_eq_u32 s31, 73728
	s_cselect_b32 s31, 0, s31
	v_mfma_f32_16x16x32_bf16 v[112:115], v[128:131], v[172:175], v[112:115]
	v_mfma_f32_16x16x32_bf16 v[116:119], v[132:135], v[172:175], v[116:119]
	v_mfma_f32_16x16x32_bf16 v[120:123], v[136:139], v[172:175], v[120:123]
	v_mfma_f32_16x16x32_bf16 v[124:127], v[140:143], v[172:175], v[124:127]
	ds_read_b128 v[220:223], v232 offset:7168
	s_waitcnt lgkmcnt(0)
	s_barrier
	v_mfma_f32_16x16x32_bf16 v[0:3], v[176:179], v[192:195], v[0:3]
	v_mfma_f32_16x16x32_bf16 v[4:7], v[180:183], v[192:195], v[4:7]
	v_mfma_f32_16x16x32_bf16 v[8:11], v[184:187], v[192:195], v[8:11]
	v_mfma_f32_16x16x32_bf16 v[12:15], v[188:191], v[192:195], v[12:15]
	v_mfma_f32_16x16x32_bf16 v[16:19], v[176:179], v[196:199], v[16:19]
	v_mfma_f32_16x16x32_bf16 v[20:23], v[180:183], v[196:199], v[20:23]
	v_mfma_f32_16x16x32_bf16 v[24:27], v[184:187], v[196:199], v[24:27]
	v_mfma_f32_16x16x32_bf16 v[28:31], v[188:191], v[196:199], v[28:31]
	v_mfma_f32_16x16x32_bf16 v[32:35], v[176:179], v[200:203], v[32:35]
	v_mfma_f32_16x16x32_bf16 v[36:39], v[180:183], v[200:203], v[36:39]
	v_mfma_f32_16x16x32_bf16 v[40:43], v[184:187], v[200:203], v[40:43]
	v_mfma_f32_16x16x32_bf16 v[44:47], v[188:191], v[200:203], v[44:47]
	v_mfma_f32_16x16x32_bf16 v[48:51], v[176:179], v[204:207], v[48:51]
	v_mfma_f32_16x16x32_bf16 v[52:55], v[180:183], v[204:207], v[52:55]
	v_mfma_f32_16x16x32_bf16 v[56:59], v[184:187], v[204:207], v[56:59]
	v_mfma_f32_16x16x32_bf16 v[60:63], v[188:191], v[204:207], v[60:63]
	v_mfma_f32_16x16x32_bf16 v[64:67], v[176:179], v[208:211], v[64:67]
	v_mfma_f32_16x16x32_bf16 v[68:71], v[180:183], v[208:211], v[68:71]
	v_mfma_f32_16x16x32_bf16 v[72:75], v[184:187], v[208:211], v[72:75]
	v_mfma_f32_16x16x32_bf16 v[76:79], v[188:191], v[208:211], v[76:79]
	v_mfma_f32_16x16x32_bf16 v[80:83], v[176:179], v[212:215], v[80:83]
	v_mfma_f32_16x16x32_bf16 v[84:87], v[180:183], v[212:215], v[84:87]
	v_mfma_f32_16x16x32_bf16 v[88:91], v[184:187], v[212:215], v[88:91]
	v_mfma_f32_16x16x32_bf16 v[92:95], v[188:191], v[212:215], v[92:95]
	v_mfma_f32_16x16x32_bf16 v[96:99], v[176:179], v[216:219], v[96:99]
	v_mfma_f32_16x16x32_bf16 v[100:103], v[180:183], v[216:219], v[100:103]
	v_mfma_f32_16x16x32_bf16 v[104:107], v[184:187], v[216:219], v[104:107]
	v_mfma_f32_16x16x32_bf16 v[108:111], v[188:191], v[216:219], v[108:111]
	v_mfma_f32_16x16x32_bf16 v[112:115], v[176:179], v[220:223], v[112:115]
	v_mfma_f32_16x16x32_bf16 v[116:119], v[180:183], v[220:223], v[116:119]
	v_mfma_f32_16x16x32_bf16 v[120:123], v[184:187], v[220:223], v[120:123]
	v_mfma_f32_16x16x32_bf16 v[124:127], v[188:191], v[220:223], v[124:127]
	s_branch .Lg3b_epi
; DI unsigned pack2(float lo, float hi) { const f32x2c v = {lo, hi}; return __builtin_bit_cast(unsigned, __builtin_convertvector(v, bf16x2c)); }
; template <class Epi>
; DI void gemm_tile(char* smem, const bf16_t* __restrict__ A0, int lda0, int ksplit, const bf16_t* __restrict__ A1, int lda1,
;                   const bf16_t* __restrict__ Bt, int K, int row0, int col0, const Epi& epi, int tid) {
;     ...
; #pragma unroll
;   for (int m = 0; m < 8; ++m)
; #pragma unroll
;     for (int n = 0; n < 4; ++n) epi(row0 + wr * 128 + m * 16 + fr, col0 + wc * 64 + n * 16 + fq * 4, acc[m][n]);
; }
; DI void st_bf16x4(bf16_t* o, f32x4 v) { u32x2 q; q.x = pack2(v[0], v[1]); q.y = pack2(v[2], v[3]); *(u32x2*)o = q; }
;   DI void operator()(int row, int col, f32x4 v) const {
;     if (col < n0) st_bf16x4(o0 + (size_t)row * ld0 + col, v);
;     else { const int c = col - n0; if (c < n1) st_bf16x4(o1 + (size_t)row * ld1 + c, v); }
;   }
.Lg3b_epi:
	s_nop 7
	s_nop 7
	s_mul_i32 s27, s29, 1024
	s_lshl_b32 s26, s28, 1
	s_add_u32 s27, s27, s26
	s_add_u32 s27, s27, 0x9800000
	s_add_u32 s4, s92, s27
	s_addc_u32 s5, s93, 0
	s_lshl_b32 s27, s28, 2
	s_add_u32 s27, s27, 0x800
	s_add_u32 s2, s6, s27
	s_addc_u32 s3, s7, 0
	global_load_dwordx4 v[192:195], v235, s[2:3] offset:0
	global_load_dwordx4 v[196:199], v235, s[2:3] offset:64
	global_load_dwordx4 v[200:203], v235, s[2:3] offset:128
	global_load_dwordx4 v[204:207], v235, s[2:3] offset:192
	s_waitcnt vmcnt(0)
	v_add_f32_e32 v0, v0, v192
	v_add_f32_e32 v1, v1, v193
	v_add_f32_e32 v2, v2, v194
	v_add_f32_e32 v3, v3, v195
	v_mul_f32_e32 v0, 0xbfb8aa3b, v0
	v_mul_f32_e32 v1, 0xbfb8aa3b, v1
	v_mul_f32_e32 v2, 0xbfb8aa3b, v2
	v_mul_f32_e32 v3, 0xbfb8aa3b, v3
	v_exp_f32_e32 v0, v0
	v_exp_f32_e32 v1, v1
	v_exp_f32_e32 v2, v2
	v_exp_f32_e32 v3, v3
	s_nop 0
	v_add_f32_e32 v0, 1.0, v0
	v_add_f32_e32 v1, 1.0, v1
	v_add_f32_e32 v2, 1.0, v2
	v_add_f32_e32 v3, 1.0, v3
	v_rcp_f32_e32 v0, v0
	v_rcp_f32_e32 v1, v1
	v_rcp_f32_e32 v2, v2
	v_rcp_f32_e32 v3, v3
	s_nop 0
	v_mul_f32_e32 v0, 0x3f1b4598, v0
	v_mul_f32_e32 v1, 0x3f1b4598, v1
	v_mul_f32_e32 v2, 0x3f1b4598, v2
	v_mul_f32_e32 v3, 0x3f1b4598, v3
	v_cvt_pk_bf16_f32 v128, v0, v1
	v_cvt_pk_bf16_f32 v129, v2, v3
	ds_write_b64 v236, v[128:129]
	v_add_f32_e32 v4, v4, v196
	v_add_f32_e32 v5, v5, v197
	v_add_f32_e32 v6, v6, v198
	v_add_f32_e32 v7, v7, v199
	v_mul_f32_e32 v4, 0xbfb8aa3b, v4
	v_mul_f32_e32 v5, 0xbfb8aa3b, v5
	v_mul_f32_e32 v6, 0xbfb8aa3b, v6
	v_mul_f32_e32 v7, 0xbfb8aa3b, v7
	v_exp_f32_e32 v4, v4
	v_exp_f32_e32 v5, v5
	v_exp_f32_e32 v6, v6
	v_exp_f32_e32 v7, v7
	s_nop 0
	v_add_f32_e32 v4, 1.0, v4
	v_add_f32_e32 v5, 1.0, v5
	v_add_f32_e32 v6, 1.0, v6
	v_add_f32_e32 v7, 1.0, v7
	v_rcp_f32_e32 v4, v4
	v_rcp_f32_e32 v5, v5
	v_rcp_f32_e32 v6, v6
	v_rcp_f32_e32 v7, v7
	s_nop 0
	v_mul_f32_e32 v4, 0x3f1b4598, v4
	v_mul_f32_e32 v5, 0x3f1b4598, v5
	v_mul_f32_e32 v6, 0x3f1b4598, v6
	v_mul_f32_e32 v7, 0x3f1b4598, v7
	v_cvt_pk_bf16_f32 v130, v4, v5
	v_cvt_pk_bf16_f32 v131, v6, v7
	ds_write_b64 v236, v[130:131] offset:32
	v_add_f32_e32 v8, v8, v200
	v_add_f32_e32 v9, v9, v201
	v_add_f32_e32 v10, v10, v202
	v_add_f32_e32 v11, v11, v203
	v_mul_f32_e32 v8, 0xbfb8aa3b, v8
	v_mul_f32_e32 v9, 0xbfb8aa3b, v9
	v_mul_f32_e32 v10, 0xbfb8aa3b, v10
	v_mul_f32_e32 v11, 0xbfb8aa3b, v11
	v_exp_f32_e32 v8, v8
	v_exp_f32_e32 v9, v9
	v_exp_f32_e32 v10, v10
	v_exp_f32_e32 v11, v11
	s_nop 0
	v_add_f32_e32 v8, 1.0, v8
	v_add_f32_e32 v9, 1.0, v9
	v_add_f32_e32 v10, 1.0, v10
	v_add_f32_e32 v11, 1.0, v11
	v_rcp_f32_e32 v8, v8
	v_rcp_f32_e32 v9, v9
	v_rcp_f32_e32 v10, v10
	v_rcp_f32_e32 v11, v11
	s_nop 0
	v_mul_f32_e32 v8, 0x3f1b4598, v8
	v_mul_f32_e32 v9, 0x3f1b4598, v9
	v_mul_f32_e32 v10, 0x3f1b4598, v10
	v_mul_f32_e32 v11, 0x3f1b4598, v11
	v_cvt_pk_bf16_f32 v132, v8, v9
	v_cvt_pk_bf16_f32 v133, v10, v11
	ds_write_b64 v236, v[132:133] offset:64
	v_add_f32_e32 v12, v12, v204
	v_add_f32_e32 v13, v13, v205
	v_add_f32_e32 v14, v14, v206
	v_add_f32_e32 v15, v15, v207
	v_mul_f32_e32 v12, 0xbfb8aa3b, v12
	v_mul_f32_e32 v13, 0xbfb8aa3b, v13
	v_mul_f32_e32 v14, 0xbfb8aa3b, v14
	v_mul_f32_e32 v15, 0xbfb8aa3b, v15
	v_exp_f32_e32 v12, v12
	v_exp_f32_e32 v13, v13
	v_exp_f32_e32 v14, v14
	v_exp_f32_e32 v15, v15
	s_nop 0
	v_add_f32_e32 v12, 1.0, v12
	v_add_f32_e32 v13, 1.0, v13
	v_add_f32_e32 v14, 1.0, v14
	v_add_f32_e32 v15, 1.0, v15
	v_rcp_f32_e32 v12, v12
	v_rcp_f32_e32 v13, v13
	v_rcp_f32_e32 v14, v14
	v_rcp_f32_e32 v15, v15
	s_nop 0
	v_mul_f32_e32 v12, 0x3f1b4598, v12
	v_mul_f32_e32 v13, 0x3f1b4598, v13
	v_mul_f32_e32 v14, 0x3f1b4598, v14
	v_mul_f32_e32 v15, 0x3f1b4598, v15
	v_cvt_pk_bf16_f32 v134, v12, v13
	v_cvt_pk_bf16_f32 v135, v14, v15
	ds_write_b64 v236, v[134:135] offset:96
	v_add_f32_e32 v16, v16, v192
	v_add_f32_e32 v17, v17, v193
	v_add_f32_e32 v18, v18, v194
	v_add_f32_e32 v19, v19, v195
	v_mul_f32_e32 v16, 0xbfb8aa3b, v16
	v_mul_f32_e32 v17, 0xbfb8aa3b, v17
	v_mul_f32_e32 v18, 0xbfb8aa3b, v18
	v_mul_f32_e32 v19, 0xbfb8aa3b, v19
	v_exp_f32_e32 v16, v16
	v_exp_f32_e32 v17, v17
	v_exp_f32_e32 v18, v18
	v_exp_f32_e32 v19, v19
	s_nop 0
	v_add_f32_e32 v16, 1.0, v16
	v_add_f32_e32 v17, 1.0, v17
	v_add_f32_e32 v18, 1.0, v18
	v_add_f32_e32 v19, 1.0, v19
	v_rcp_f32_e32 v16, v16
	v_rcp_f32_e32 v17, v17
	v_rcp_f32_e32 v18, v18
	v_rcp_f32_e32 v19, v19
	s_nop 0
	v_mul_f32_e32 v16, 0x3f1b4598, v16
	v_mul_f32_e32 v17, 0x3f1b4598, v17
	v_mul_f32_e32 v18, 0x3f1b4598, v18
	v_mul_f32_e32 v19, 0x3f1b4598, v19
	v_cvt_pk_bf16_f32 v136, v16, v17
	v_cvt_pk_bf16_f32 v137, v18, v19
	ds_write_b64 v236, v[136:137] offset:2304
	v_add_f32_e32 v20, v20, v196
	v_add_f32_e32 v21, v21, v197
	v_add_f32_e32 v22, v22, v198
	v_add_f32_e32 v23, v23, v199
	v_mul_f32_e32 v20, 0xbfb8aa3b, v20
	v_mul_f32_e32 v21, 0xbfb8aa3b, v21
	v_mul_f32_e32 v22, 0xbfb8aa3b, v22
	v_mul_f32_e32 v23, 0xbfb8aa3b, v23
	v_exp_f32_e32 v20, v20
	v_exp_f32_e32 v21, v21
	v_exp_f32_e32 v22, v22
	v_exp_f32_e32 v23, v23
	s_nop 0
	v_add_f32_e32 v20, 1.0, v20
	v_add_f32_e32 v21, 1.0, v21
	v_add_f32_e32 v22, 1.0, v22
	v_add_f32_e32 v23, 1.0, v23
	v_rcp_f32_e32 v20, v20
	v_rcp_f32_e32 v21, v21
	v_rcp_f32_e32 v22, v22
	v_rcp_f32_e32 v23, v23
	s_nop 0
	v_mul_f32_e32 v20, 0x3f1b4598, v20
	v_mul_f32_e32 v21, 0x3f1b4598, v21
	v_mul_f32_e32 v22, 0x3f1b4598, v22
	v_mul_f32_e32 v23, 0x3f1b4598, v23
	v_cvt_pk_bf16_f32 v138, v20, v21
	v_cvt_pk_bf16_f32 v139, v22, v23
	ds_write_b64 v236, v[138:139] offset:2336
	v_add_f32_e32 v24, v24, v200
	v_add_f32_e32 v25, v25, v201
	v_add_f32_e32 v26, v26, v202
	v_add_f32_e32 v27, v27, v203
	v_mul_f32_e32 v24, 0xbfb8aa3b, v24
	v_mul_f32_e32 v25, 0xbfb8aa3b, v25
; template <class Epi>
; DI void gemm_tile(char* smem, const bf16_t* __restrict__ A0, int lda0, int ksplit, const bf16_t* __restrict__ A1, int lda1,
;                   const bf16_t* __restrict__ Bt, int K, int row0, int col0, const Epi& epi, int tid) {
;     ...
; #pragma unroll
;   for (int m = 0; m < 8; ++m)
; #pragma unroll
;     for (int n = 0; n < 4; ++n) epi(row0 + wr * 128 + m * 16 + fr, col0 + wc * 64 + n * 16 + fq * 4, acc[m][n]);
	v_mul_f32_e32 v26, 0xbfb8aa3b, v26
	v_mul_f32_e32 v27, 0xbfb8aa3b, v27
	v_exp_f32_e32 v24, v24
	v_exp_f32_e32 v25, v25
	v_exp_f32_e32 v26, v26
	v_exp_f32_e32 v27, v27
	s_nop 0
	v_add_f32_e32 v24, 1.0, v24
	v_add_f32_e32 v25, 1.0, v25
	v_add_f32_e32 v26, 1.0, v26
	v_add_f32_e32 v27, 1.0, v27
	v_rcp_f32_e32 v24, v24
	v_rcp_f32_e32 v25, v25
	v_rcp_f32_e32 v26, v26
	v_rcp_f32_e32 v27, v27
	s_nop 0
	v_mul_f32_e32 v24, 0x3f1b4598, v24
	v_mul_f32_e32 v25, 0x3f1b4598, v25
	v_mul_f32_e32 v26, 0x3f1b4598, v26
	v_mul_f32_e32 v27, 0x3f1b4598, v27
	v_cvt_pk_bf16_f32 v140, v24, v25
	v_cvt_pk_bf16_f32 v141, v26, v27
	ds_write_b64 v236, v[140:141] offset:2368
	v_add_f32_e32 v28, v28, v204
	v_add_f32_e32 v29, v29, v205
	v_add_f32_e32 v30, v30, v206
	v_add_f32_e32 v31, v31, v207
	v_mul_f32_e32 v28, 0xbfb8aa3b, v28
	v_mul_f32_e32 v29, 0xbfb8aa3b, v29
	v_mul_f32_e32 v30, 0xbfb8aa3b, v30
	v_mul_f32_e32 v31, 0xbfb8aa3b, v31
	v_exp_f32_e32 v28, v28
	v_exp_f32_e32 v29, v29
	v_exp_f32_e32 v30, v30
	v_exp_f32_e32 v31, v31
	s_nop 0
	v_add_f32_e32 v28, 1.0, v28
	v_add_f32_e32 v29, 1.0, v29
	v_add_f32_e32 v30, 1.0, v30
	v_add_f32_e32 v31, 1.0, v31
	v_rcp_f32_e32 v28, v28
	v_rcp_f32_e32 v29, v29
	v_rcp_f32_e32 v30, v30
	v_rcp_f32_e32 v31, v31
	s_nop 0
	v_mul_f32_e32 v28, 0x3f1b4598, v28
	v_mul_f32_e32 v29, 0x3f1b4598, v29
	v_mul_f32_e32 v30, 0x3f1b4598, v30
	v_mul_f32_e32 v31, 0x3f1b4598, v31
	v_cvt_pk_bf16_f32 v142, v28, v29
	v_cvt_pk_bf16_f32 v143, v30, v31
	ds_write_b64 v236, v[142:143] offset:2400
	v_add_f32_e32 v32, v32, v192
	v_add_f32_e32 v33, v33, v193
	v_add_f32_e32 v34, v34, v194
	v_add_f32_e32 v35, v35, v195
	v_mul_f32_e32 v32, 0xbfb8aa3b, v32
	v_mul_f32_e32 v33, 0xbfb8aa3b, v33
	v_mul_f32_e32 v34, 0xbfb8aa3b, v34
	v_mul_f32_e32 v35, 0xbfb8aa3b, v35
	v_exp_f32_e32 v32, v32
	v_exp_f32_e32 v33, v33
	v_exp_f32_e32 v34, v34
	v_exp_f32_e32 v35, v35
	s_nop 0
	v_add_f32_e32 v32, 1.0, v32
	v_add_f32_e32 v33, 1.0, v33
	v_add_f32_e32 v34, 1.0, v34
	v_add_f32_e32 v35, 1.0, v35
	v_rcp_f32_e32 v32, v32
	v_rcp_f32_e32 v33, v33
	v_rcp_f32_e32 v34, v34
	v_rcp_f32_e32 v35, v35
	s_nop 0
	v_mul_f32_e32 v32, 0x3f1b4598, v32
	v_mul_f32_e32 v33, 0x3f1b4598, v33
	v_mul_f32_e32 v34, 0x3f1b4598, v34
	v_mul_f32_e32 v35, 0x3f1b4598, v35
	v_cvt_pk_bf16_f32 v144, v32, v33
	v_cvt_pk_bf16_f32 v145, v34, v35
	ds_write_b64 v236, v[144:145] offset:4608
	v_add_f32_e32 v36, v36, v196
	v_add_f32_e32 v37, v37, v197
	v_add_f32_e32 v38, v38, v198
	v_add_f32_e32 v39, v39, v199
	v_mul_f32_e32 v36, 0xbfb8aa3b, v36
	v_mul_f32_e32 v37, 0xbfb8aa3b, v37
	v_mul_f32_e32 v38, 0xbfb8aa3b, v38
	v_mul_f32_e32 v39, 0xbfb8aa3b, v39
	v_exp_f32_e32 v36, v36
	v_exp_f32_e32 v37, v37
	v_exp_f32_e32 v38, v38
	v_exp_f32_e32 v39, v39
	s_nop 0
	v_add_f32_e32 v36, 1.0, v36
	v_add_f32_e32 v37, 1.0, v37
	v_add_f32_e32 v38, 1.0, v38
	v_add_f32_e32 v39, 1.0, v39
	v_rcp_f32_e32 v36, v36
	v_rcp_f32_e32 v37, v37
	v_rcp_f32_e32 v38, v38
	v_rcp_f32_e32 v39, v39
	s_nop 0
	v_mul_f32_e32 v36, 0x3f1b4598, v36
	v_mul_f32_e32 v37, 0x3f1b4598, v37
	v_mul_f32_e32 v38, 0x3f1b4598, v38
	v_mul_f32_e32 v39, 0x3f1b4598, v39
	v_cvt_pk_bf16_f32 v146, v36, v37
	v_cvt_pk_bf16_f32 v147, v38, v39
	ds_write_b64 v236, v[146:147] offset:4640
	v_add_f32_e32 v40, v40, v200
	v_add_f32_e32 v41, v41, v201
	v_add_f32_e32 v42, v42, v202
	v_add_f32_e32 v43, v43, v203
	v_mul_f32_e32 v40, 0xbfb8aa3b, v40
	v_mul_f32_e32 v41, 0xbfb8aa3b, v41
	v_mul_f32_e32 v42, 0xbfb8aa3b, v42
	v_mul_f32_e32 v43, 0xbfb8aa3b, v43
	v_exp_f32_e32 v40, v40
	v_exp_f32_e32 v41, v41
	v_exp_f32_e32 v42, v42
	v_exp_f32_e32 v43, v43
	s_nop 0
	v_add_f32_e32 v40, 1.0, v40
	v_add_f32_e32 v41, 1.0, v41
	v_add_f32_e32 v42, 1.0, v42
	v_add_f32_e32 v43, 1.0, v43
	v_rcp_f32_e32 v40, v40
	v_rcp_f32_e32 v41, v41
	v_rcp_f32_e32 v42, v42
	v_rcp_f32_e32 v43, v43
	s_nop 0
	v_mul_f32_e32 v40, 0x3f1b4598, v40
	v_mul_f32_e32 v41, 0x3f1b4598, v41
	v_mul_f32_e32 v42, 0x3f1b4598, v42
	v_mul_f32_e32 v43, 0x3f1b4598, v43
	v_cvt_pk_bf16_f32 v148, v40, v41
	v_cvt_pk_bf16_f32 v149, v42, v43
	ds_write_b64 v236, v[148:149] offset:4672
	v_add_f32_e32 v44, v44, v204
	v_add_f32_e32 v45, v45, v205
	v_add_f32_e32 v46, v46, v206
	v_add_f32_e32 v47, v47, v207
	v_mul_f32_e32 v44, 0xbfb8aa3b, v44
	v_mul_f32_e32 v45, 0xbfb8aa3b, v45
	v_mul_f32_e32 v46, 0xbfb8aa3b, v46
	v_mul_f32_e32 v47, 0xbfb8aa3b, v47
	v_exp_f32_e32 v44, v44
	v_exp_f32_e32 v45, v45
	v_exp_f32_e32 v46, v46
	v_exp_f32_e32 v47, v47
	s_nop 0
	v_add_f32_e32 v44, 1.0, v44
	v_add_f32_e32 v45, 1.0, v45
	v_add_f32_e32 v46, 1.0, v46
	v_add_f32_e32 v47, 1.0, v47
	v_rcp_f32_e32 v44, v44
	v_rcp_f32_e32 v45, v45
	v_rcp_f32_e32 v46, v46
	v_rcp_f32_e32 v47, v47
	s_nop 0
	v_mul_f32_e32 v44, 0x3f1b4598, v44
	v_mul_f32_e32 v45, 0x3f1b4598, v45
	v_mul_f32_e32 v46, 0x3f1b4598, v46
	v_mul_f32_e32 v47, 0x3f1b4598, v47
	v_cvt_pk_bf16_f32 v150, v44, v45
	v_cvt_pk_bf16_f32 v151, v46, v47
	ds_write_b64 v236, v[150:151] offset:4704
	v_add_f32_e32 v48, v48, v192
	v_add_f32_e32 v49, v49, v193
	v_add_f32_e32 v50, v50, v194
	v_add_f32_e32 v51, v51, v195
	v_mul_f32_e32 v48, 0xbfb8aa3b, v48
	v_mul_f32_e32 v49, 0xbfb8aa3b, v49
	v_mul_f32_e32 v50, 0xbfb8aa3b, v50
	v_mul_f32_e32 v51, 0xbfb8aa3b, v51
	v_exp_f32_e32 v48, v48
	v_exp_f32_e32 v49, v49
	v_exp_f32_e32 v50, v50
	v_exp_f32_e32 v51, v51
	s_nop 0
	v_add_f32_e32 v48, 1.0, v48
	v_add_f32_e32 v49, 1.0, v49
	v_add_f32_e32 v50, 1.0, v50
	v_add_f32_e32 v51, 1.0, v51
	v_rcp_f32_e32 v48, v48
	v_rcp_f32_e32 v49, v49
	v_rcp_f32_e32 v50, v50
	v_rcp_f32_e32 v51, v51
	s_nop 0
	v_mul_f32_e32 v48, 0x3f1b4598, v48
	v_mul_f32_e32 v49, 0x3f1b4598, v49
	v_mul_f32_e32 v50, 0x3f1b4598, v50
	v_mul_f32_e32 v51, 0x3f1b4598, v51
	v_cvt_pk_bf16_f32 v152, v48, v49
; template <class Epi>
; DI void gemm_tile(char* smem, const bf16_t* __restrict__ A0, int lda0, int ksplit, const bf16_t* __restrict__ A1, int lda1,
;                   const bf16_t* __restrict__ Bt, int K, int row0, int col0, const Epi& epi, int tid) {
;     ...
; #pragma unroll
;   for (int m = 0; m < 8; ++m)
; #pragma unroll
;     for (int n = 0; n < 4; ++n) epi(row0 + wr * 128 + m * 16 + fr, col0 + wc * 64 + n * 16 + fq * 4, acc[m][n]);
	v_cvt_pk_bf16_f32 v153, v50, v51
	ds_write_b64 v236, v[152:153] offset:6912
	v_add_f32_e32 v52, v52, v196
	v_add_f32_e32 v53, v53, v197
	v_add_f32_e32 v54, v54, v198
	v_add_f32_e32 v55, v55, v199
	v_mul_f32_e32 v52, 0xbfb8aa3b, v52
	v_mul_f32_e32 v53, 0xbfb8aa3b, v53
	v_mul_f32_e32 v54, 0xbfb8aa3b, v54
	v_mul_f32_e32 v55, 0xbfb8aa3b, v55
	v_exp_f32_e32 v52, v52
	v_exp_f32_e32 v53, v53
	v_exp_f32_e32 v54, v54
	v_exp_f32_e32 v55, v55
	s_nop 0
	v_add_f32_e32 v52, 1.0, v52
	v_add_f32_e32 v53, 1.0, v53
	v_add_f32_e32 v54, 1.0, v54
	v_add_f32_e32 v55, 1.0, v55
	v_rcp_f32_e32 v52, v52
	v_rcp_f32_e32 v53, v53
	v_rcp_f32_e32 v54, v54
	v_rcp_f32_e32 v55, v55
	s_nop 0
	v_mul_f32_e32 v52, 0x3f1b4598, v52
	v_mul_f32_e32 v53, 0x3f1b4598, v53
	v_mul_f32_e32 v54, 0x3f1b4598, v54
	v_mul_f32_e32 v55, 0x3f1b4598, v55
	v_cvt_pk_bf16_f32 v154, v52, v53
	v_cvt_pk_bf16_f32 v155, v54, v55
	ds_write_b64 v236, v[154:155] offset:6944
	v_add_f32_e32 v56, v56, v200
	v_add_f32_e32 v57, v57, v201
	v_add_f32_e32 v58, v58, v202
	v_add_f32_e32 v59, v59, v203
	v_mul_f32_e32 v56, 0xbfb8aa3b, v56
	v_mul_f32_e32 v57, 0xbfb8aa3b, v57
	v_mul_f32_e32 v58, 0xbfb8aa3b, v58
	v_mul_f32_e32 v59, 0xbfb8aa3b, v59
	v_exp_f32_e32 v56, v56
	v_exp_f32_e32 v57, v57
	v_exp_f32_e32 v58, v58
	v_exp_f32_e32 v59, v59
	s_nop 0
	v_add_f32_e32 v56, 1.0, v56
	v_add_f32_e32 v57, 1.0, v57
	v_add_f32_e32 v58, 1.0, v58
	v_add_f32_e32 v59, 1.0, v59
	v_rcp_f32_e32 v56, v56
	v_rcp_f32_e32 v57, v57
	v_rcp_f32_e32 v58, v58
	v_rcp_f32_e32 v59, v59
	s_nop 0
	v_mul_f32_e32 v56, 0x3f1b4598, v56
	v_mul_f32_e32 v57, 0x3f1b4598, v57
	v_mul_f32_e32 v58, 0x3f1b4598, v58
	v_mul_f32_e32 v59, 0x3f1b4598, v59
	v_cvt_pk_bf16_f32 v156, v56, v57
	v_cvt_pk_bf16_f32 v157, v58, v59
	ds_write_b64 v236, v[156:157] offset:6976
	v_add_f32_e32 v60, v60, v204
	v_add_f32_e32 v61, v61, v205
	v_add_f32_e32 v62, v62, v206
	v_add_f32_e32 v63, v63, v207
	v_mul_f32_e32 v60, 0xbfb8aa3b, v60
	v_mul_f32_e32 v61, 0xbfb8aa3b, v61
	v_mul_f32_e32 v62, 0xbfb8aa3b, v62
	v_mul_f32_e32 v63, 0xbfb8aa3b, v63
	v_exp_f32_e32 v60, v60
	v_exp_f32_e32 v61, v61
	v_exp_f32_e32 v62, v62
	v_exp_f32_e32 v63, v63
	s_nop 0
	v_add_f32_e32 v60, 1.0, v60
	v_add_f32_e32 v61, 1.0, v61
	v_add_f32_e32 v62, 1.0, v62
	v_add_f32_e32 v63, 1.0, v63
	v_rcp_f32_e32 v60, v60
	v_rcp_f32_e32 v61, v61
	v_rcp_f32_e32 v62, v62
	v_rcp_f32_e32 v63, v63
	s_nop 0
	v_mul_f32_e32 v60, 0x3f1b4598, v60
	v_mul_f32_e32 v61, 0x3f1b4598, v61
	v_mul_f32_e32 v62, 0x3f1b4598, v62
	v_mul_f32_e32 v63, 0x3f1b4598, v63
	v_cvt_pk_bf16_f32 v158, v60, v61
	v_cvt_pk_bf16_f32 v159, v62, v63
	ds_write_b64 v236, v[158:159] offset:7008
	v_add_f32_e32 v64, v64, v192
	v_add_f32_e32 v65, v65, v193
	v_add_f32_e32 v66, v66, v194
	v_add_f32_e32 v67, v67, v195
	v_mul_f32_e32 v64, 0xbfb8aa3b, v64
	v_mul_f32_e32 v65, 0xbfb8aa3b, v65
	v_mul_f32_e32 v66, 0xbfb8aa3b, v66
	v_mul_f32_e32 v67, 0xbfb8aa3b, v67
	v_exp_f32_e32 v64, v64
	v_exp_f32_e32 v65, v65
	v_exp_f32_e32 v66, v66
	v_exp_f32_e32 v67, v67
	s_nop 0
	v_add_f32_e32 v64, 1.0, v64
	v_add_f32_e32 v65, 1.0, v65
	v_add_f32_e32 v66, 1.0, v66
	v_add_f32_e32 v67, 1.0, v67
	v_rcp_f32_e32 v64, v64
	v_rcp_f32_e32 v65, v65
	v_rcp_f32_e32 v66, v66
	v_rcp_f32_e32 v67, v67
	s_nop 0
	v_mul_f32_e32 v64, 0x3f1b4598, v64
	v_mul_f32_e32 v65, 0x3f1b4598, v65
	v_mul_f32_e32 v66, 0x3f1b4598, v66
	v_mul_f32_e32 v67, 0x3f1b4598, v67
	v_cvt_pk_bf16_f32 v128, v64, v65
	v_cvt_pk_bf16_f32 v129, v66, v67
	ds_write_b64 v236, v[128:129] offset:9216
	v_add_f32_e32 v68, v68, v196
	v_add_f32_e32 v69, v69, v197
	v_add_f32_e32 v70, v70, v198
	v_add_f32_e32 v71, v71, v199
	v_mul_f32_e32 v68, 0xbfb8aa3b, v68
	v_mul_f32_e32 v69, 0xbfb8aa3b, v69
	v_mul_f32_e32 v70, 0xbfb8aa3b, v70
	v_mul_f32_e32 v71, 0xbfb8aa3b, v71
	v_exp_f32_e32 v68, v68
	v_exp_f32_e32 v69, v69
	v_exp_f32_e32 v70, v70
	v_exp_f32_e32 v71, v71
	s_nop 0
	v_add_f32_e32 v68, 1.0, v68
	v_add_f32_e32 v69, 1.0, v69
	v_add_f32_e32 v70, 1.0, v70
	v_add_f32_e32 v71, 1.0, v71
	v_rcp_f32_e32 v68, v68
	v_rcp_f32_e32 v69, v69
	v_rcp_f32_e32 v70, v70
	v_rcp_f32_e32 v71, v71
	s_nop 0
	v_mul_f32_e32 v68, 0x3f1b4598, v68
	v_mul_f32_e32 v69, 0x3f1b4598, v69
	v_mul_f32_e32 v70, 0x3f1b4598, v70
	v_mul_f32_e32 v71, 0x3f1b4598, v71
	v_cvt_pk_bf16_f32 v130, v68, v69
	v_cvt_pk_bf16_f32 v131, v70, v71
	ds_write_b64 v236, v[130:131] offset:9248
	v_add_f32_e32 v72, v72, v200
	v_add_f32_e32 v73, v73, v201
	v_add_f32_e32 v74, v74, v202
	v_add_f32_e32 v75, v75, v203
	v_mul_f32_e32 v72, 0xbfb8aa3b, v72
	v_mul_f32_e32 v73, 0xbfb8aa3b, v73
	v_mul_f32_e32 v74, 0xbfb8aa3b, v74
	v_mul_f32_e32 v75, 0xbfb8aa3b, v75
	v_exp_f32_e32 v72, v72
	v_exp_f32_e32 v73, v73
	v_exp_f32_e32 v74, v74
	v_exp_f32_e32 v75, v75
	s_nop 0
	v_add_f32_e32 v72, 1.0, v72
	v_add_f32_e32 v73, 1.0, v73
	v_add_f32_e32 v74, 1.0, v74
	v_add_f32_e32 v75, 1.0, v75
	v_rcp_f32_e32 v72, v72
	v_rcp_f32_e32 v73, v73
	v_rcp_f32_e32 v74, v74
	v_rcp_f32_e32 v75, v75
	s_nop 0
	v_mul_f32_e32 v72, 0x3f1b4598, v72
	v_mul_f32_e32 v73, 0x3f1b4598, v73
	v_mul_f32_e32 v74, 0x3f1b4598, v74
	v_mul_f32_e32 v75, 0x3f1b4598, v75
	v_cvt_pk_bf16_f32 v132, v72, v73
	v_cvt_pk_bf16_f32 v133, v74, v75
	ds_write_b64 v236, v[132:133] offset:9280
	v_add_f32_e32 v76, v76, v204
	v_add_f32_e32 v77, v77, v205
	v_add_f32_e32 v78, v78, v206
	v_add_f32_e32 v79, v79, v207
	v_mul_f32_e32 v76, 0xbfb8aa3b, v76
	v_mul_f32_e32 v77, 0xbfb8aa3b, v77
	v_mul_f32_e32 v78, 0xbfb8aa3b, v78
	v_mul_f32_e32 v79, 0xbfb8aa3b, v79
	v_exp_f32_e32 v76, v76
	v_exp_f32_e32 v77, v77
	v_exp_f32_e32 v78, v78
	v_exp_f32_e32 v79, v79
	s_nop 0
	v_add_f32_e32 v76, 1.0, v76
	v_add_f32_e32 v77, 1.0, v77
	v_add_f32_e32 v78, 1.0, v78
	v_add_f32_e32 v79, 1.0, v79
; template <class Epi>
; DI void gemm_tile(char* smem, const bf16_t* __restrict__ A0, int lda0, int ksplit, const bf16_t* __restrict__ A1, int lda1,
;                   const bf16_t* __restrict__ Bt, int K, int row0, int col0, const Epi& epi, int tid) {
;     ...
; #pragma unroll
;   for (int m = 0; m < 8; ++m)
; #pragma unroll
;     for (int n = 0; n < 4; ++n) epi(row0 + wr * 128 + m * 16 + fr, col0 + wc * 64 + n * 16 + fq * 4, acc[m][n]);
	v_rcp_f32_e32 v76, v76
	v_rcp_f32_e32 v77, v77
	v_rcp_f32_e32 v78, v78
	v_rcp_f32_e32 v79, v79
	s_nop 0
	v_mul_f32_e32 v76, 0x3f1b4598, v76
	v_mul_f32_e32 v77, 0x3f1b4598, v77
	v_mul_f32_e32 v78, 0x3f1b4598, v78
	v_mul_f32_e32 v79, 0x3f1b4598, v79
	v_cvt_pk_bf16_f32 v134, v76, v77
	v_cvt_pk_bf16_f32 v135, v78, v79
	ds_write_b64 v236, v[134:135] offset:9312
	v_add_f32_e32 v80, v80, v192
	v_add_f32_e32 v81, v81, v193
	v_add_f32_e32 v82, v82, v194
	v_add_f32_e32 v83, v83, v195
	v_mul_f32_e32 v80, 0xbfb8aa3b, v80
	v_mul_f32_e32 v81, 0xbfb8aa3b, v81
	v_mul_f32_e32 v82, 0xbfb8aa3b, v82
	v_mul_f32_e32 v83, 0xbfb8aa3b, v83
	v_exp_f32_e32 v80, v80
	v_exp_f32_e32 v81, v81
	v_exp_f32_e32 v82, v82
	v_exp_f32_e32 v83, v83
	s_nop 0
	v_add_f32_e32 v80, 1.0, v80
	v_add_f32_e32 v81, 1.0, v81
	v_add_f32_e32 v82, 1.0, v82
	v_add_f32_e32 v83, 1.0, v83
	v_rcp_f32_e32 v80, v80
	v_rcp_f32_e32 v81, v81
	v_rcp_f32_e32 v82, v82
	v_rcp_f32_e32 v83, v83
	s_nop 0
	v_mul_f32_e32 v80, 0x3f1b4598, v80
	v_mul_f32_e32 v81, 0x3f1b4598, v81
	v_mul_f32_e32 v82, 0x3f1b4598, v82
	v_mul_f32_e32 v83, 0x3f1b4598, v83
	v_cvt_pk_bf16_f32 v136, v80, v81
	v_cvt_pk_bf16_f32 v137, v82, v83
	ds_write_b64 v236, v[136:137] offset:11520
	v_add_f32_e32 v84, v84, v196
	v_add_f32_e32 v85, v85, v197
	v_add_f32_e32 v86, v86, v198
	v_add_f32_e32 v87, v87, v199
	v_mul_f32_e32 v84, 0xbfb8aa3b, v84
	v_mul_f32_e32 v85, 0xbfb8aa3b, v85
	v_mul_f32_e32 v86, 0xbfb8aa3b, v86
	v_mul_f32_e32 v87, 0xbfb8aa3b, v87
	v_exp_f32_e32 v84, v84
	v_exp_f32_e32 v85, v85
	v_exp_f32_e32 v86, v86
	v_exp_f32_e32 v87, v87
	s_nop 0
	v_add_f32_e32 v84, 1.0, v84
	v_add_f32_e32 v85, 1.0, v85
	v_add_f32_e32 v86, 1.0, v86
	v_add_f32_e32 v87, 1.0, v87
	v_rcp_f32_e32 v84, v84
	v_rcp_f32_e32 v85, v85
	v_rcp_f32_e32 v86, v86
	v_rcp_f32_e32 v87, v87
	s_nop 0
	v_mul_f32_e32 v84, 0x3f1b4598, v84
	v_mul_f32_e32 v85, 0x3f1b4598, v85
	v_mul_f32_e32 v86, 0x3f1b4598, v86
	v_mul_f32_e32 v87, 0x3f1b4598, v87
	v_cvt_pk_bf16_f32 v138, v84, v85
	v_cvt_pk_bf16_f32 v139, v86, v87
	ds_write_b64 v236, v[138:139] offset:11552
	v_add_f32_e32 v88, v88, v200
	v_add_f32_e32 v89, v89, v201
	v_add_f32_e32 v90, v90, v202
	v_add_f32_e32 v91, v91, v203
	v_mul_f32_e32 v88, 0xbfb8aa3b, v88
	v_mul_f32_e32 v89, 0xbfb8aa3b, v89
	v_mul_f32_e32 v90, 0xbfb8aa3b, v90
	v_mul_f32_e32 v91, 0xbfb8aa3b, v91
	v_exp_f32_e32 v88, v88
	v_exp_f32_e32 v89, v89
	v_exp_f32_e32 v90, v90
	v_exp_f32_e32 v91, v91
	s_nop 0
	v_add_f32_e32 v88, 1.0, v88
	v_add_f32_e32 v89, 1.0, v89
	v_add_f32_e32 v90, 1.0, v90
	v_add_f32_e32 v91, 1.0, v91
	v_rcp_f32_e32 v88, v88
	v_rcp_f32_e32 v89, v89
	v_rcp_f32_e32 v90, v90
	v_rcp_f32_e32 v91, v91
	s_nop 0
	v_mul_f32_e32 v88, 0x3f1b4598, v88
	v_mul_f32_e32 v89, 0x3f1b4598, v89
	v_mul_f32_e32 v90, 0x3f1b4598, v90
	v_mul_f32_e32 v91, 0x3f1b4598, v91
	v_cvt_pk_bf16_f32 v140, v88, v89
	v_cvt_pk_bf16_f32 v141, v90, v91
	ds_write_b64 v236, v[140:141] offset:11584
	v_add_f32_e32 v92, v92, v204
	v_add_f32_e32 v93, v93, v205
	v_add_f32_e32 v94, v94, v206
	v_add_f32_e32 v95, v95, v207
	v_mul_f32_e32 v92, 0xbfb8aa3b, v92
	v_mul_f32_e32 v93, 0xbfb8aa3b, v93
	v_mul_f32_e32 v94, 0xbfb8aa3b, v94
	v_mul_f32_e32 v95, 0xbfb8aa3b, v95
	v_exp_f32_e32 v92, v92
	v_exp_f32_e32 v93, v93
	v_exp_f32_e32 v94, v94
	v_exp_f32_e32 v95, v95
	s_nop 0
	v_add_f32_e32 v92, 1.0, v92
	v_add_f32_e32 v93, 1.0, v93
	v_add_f32_e32 v94, 1.0, v94
	v_add_f32_e32 v95, 1.0, v95
	v_rcp_f32_e32 v92, v92
	v_rcp_f32_e32 v93, v93
	v_rcp_f32_e32 v94, v94
	v_rcp_f32_e32 v95, v95
	s_nop 0
	v_mul_f32_e32 v92, 0x3f1b4598, v92
	v_mul_f32_e32 v93, 0x3f1b4598, v93
	v_mul_f32_e32 v94, 0x3f1b4598, v94
	v_mul_f32_e32 v95, 0x3f1b4598, v95
	v_cvt_pk_bf16_f32 v142, v92, v93
	v_cvt_pk_bf16_f32 v143, v94, v95
	ds_write_b64 v236, v[142:143] offset:11616
	v_add_f32_e32 v96, v96, v192
	v_add_f32_e32 v97, v97, v193
	v_add_f32_e32 v98, v98, v194
	v_add_f32_e32 v99, v99, v195
	v_mul_f32_e32 v96, 0xbfb8aa3b, v96
	v_mul_f32_e32 v97, 0xbfb8aa3b, v97
	v_mul_f32_e32 v98, 0xbfb8aa3b, v98
	v_mul_f32_e32 v99, 0xbfb8aa3b, v99
	v_exp_f32_e32 v96, v96
	v_exp_f32_e32 v97, v97
	v_exp_f32_e32 v98, v98
	v_exp_f32_e32 v99, v99
	s_nop 0
	v_add_f32_e32 v96, 1.0, v96
	v_add_f32_e32 v97, 1.0, v97
	v_add_f32_e32 v98, 1.0, v98
	v_add_f32_e32 v99, 1.0, v99
	v_rcp_f32_e32 v96, v96
	v_rcp_f32_e32 v97, v97
	v_rcp_f32_e32 v98, v98
	v_rcp_f32_e32 v99, v99
	s_nop 0
	v_mul_f32_e32 v96, 0x3f1b4598, v96
	v_mul_f32_e32 v97, 0x3f1b4598, v97
	v_mul_f32_e32 v98, 0x3f1b4598, v98
	v_mul_f32_e32 v99, 0x3f1b4598, v99
	v_cvt_pk_bf16_f32 v144, v96, v97
	v_cvt_pk_bf16_f32 v145, v98, v99
	ds_write_b64 v236, v[144:145] offset:13824
	v_add_f32_e32 v100, v100, v196
	v_add_f32_e32 v101, v101, v197
	v_add_f32_e32 v102, v102, v198
	v_add_f32_e32 v103, v103, v199
	v_mul_f32_e32 v100, 0xbfb8aa3b, v100
	v_mul_f32_e32 v101, 0xbfb8aa3b, v101
	v_mul_f32_e32 v102, 0xbfb8aa3b, v102
	v_mul_f32_e32 v103, 0xbfb8aa3b, v103
	v_exp_f32_e32 v100, v100
	v_exp_f32_e32 v101, v101
	v_exp_f32_e32 v102, v102
	v_exp_f32_e32 v103, v103
	s_nop 0
	v_add_f32_e32 v100, 1.0, v100
	v_add_f32_e32 v101, 1.0, v101
	v_add_f32_e32 v102, 1.0, v102
	v_add_f32_e32 v103, 1.0, v103
	v_rcp_f32_e32 v100, v100
	v_rcp_f32_e32 v101, v101
	v_rcp_f32_e32 v102, v102
	v_rcp_f32_e32 v103, v103
	s_nop 0
	v_mul_f32_e32 v100, 0x3f1b4598, v100
	v_mul_f32_e32 v101, 0x3f1b4598, v101
	v_mul_f32_e32 v102, 0x3f1b4598, v102
	v_mul_f32_e32 v103, 0x3f1b4598, v103
	v_cvt_pk_bf16_f32 v146, v100, v101
	v_cvt_pk_bf16_f32 v147, v102, v103
	ds_write_b64 v236, v[146:147] offset:13856
	v_add_f32_e32 v104, v104, v200
	v_add_f32_e32 v105, v105, v201
	v_add_f32_e32 v106, v106, v202
	v_add_f32_e32 v107, v107, v203
	v_mul_f32_e32 v104, 0xbfb8aa3b, v104
; template <class Epi>
; DI void gemm_tile(char* smem, const bf16_t* __restrict__ A0, int lda0, int ksplit, const bf16_t* __restrict__ A1, int lda1,
;                   const bf16_t* __restrict__ Bt, int K, int row0, int col0, const Epi& epi, int tid) {
;     ...
; #pragma unroll
;   for (int m = 0; m < 8; ++m)
; #pragma unroll
;     for (int n = 0; n < 4; ++n) epi(row0 + wr * 128 + m * 16 + fr, col0 + wc * 64 + n * 16 + fq * 4, acc[m][n]);
	v_mul_f32_e32 v105, 0xbfb8aa3b, v105
	v_mul_f32_e32 v106, 0xbfb8aa3b, v106
	v_mul_f32_e32 v107, 0xbfb8aa3b, v107
	v_exp_f32_e32 v104, v104
	v_exp_f32_e32 v105, v105
	v_exp_f32_e32 v106, v106
	v_exp_f32_e32 v107, v107
	s_nop 0
	v_add_f32_e32 v104, 1.0, v104
	v_add_f32_e32 v105, 1.0, v105
	v_add_f32_e32 v106, 1.0, v106
	v_add_f32_e32 v107, 1.0, v107
	v_rcp_f32_e32 v104, v104
	v_rcp_f32_e32 v105, v105
	v_rcp_f32_e32 v106, v106
	v_rcp_f32_e32 v107, v107
	s_nop 0
	v_mul_f32_e32 v104, 0x3f1b4598, v104
	v_mul_f32_e32 v105, 0x3f1b4598, v105
	v_mul_f32_e32 v106, 0x3f1b4598, v106
	v_mul_f32_e32 v107, 0x3f1b4598, v107
	v_cvt_pk_bf16_f32 v148, v104, v105
	v_cvt_pk_bf16_f32 v149, v106, v107
	ds_write_b64 v236, v[148:149] offset:13888
	v_add_f32_e32 v108, v108, v204
	v_add_f32_e32 v109, v109, v205
	v_add_f32_e32 v110, v110, v206
	v_add_f32_e32 v111, v111, v207
	v_mul_f32_e32 v108, 0xbfb8aa3b, v108
	v_mul_f32_e32 v109, 0xbfb8aa3b, v109
	v_mul_f32_e32 v110, 0xbfb8aa3b, v110
	v_mul_f32_e32 v111, 0xbfb8aa3b, v111
	v_exp_f32_e32 v108, v108
	v_exp_f32_e32 v109, v109
	v_exp_f32_e32 v110, v110
	v_exp_f32_e32 v111, v111
	s_nop 0
	v_add_f32_e32 v108, 1.0, v108
	v_add_f32_e32 v109, 1.0, v109
	v_add_f32_e32 v110, 1.0, v110
	v_add_f32_e32 v111, 1.0, v111
	v_rcp_f32_e32 v108, v108
	v_rcp_f32_e32 v109, v109
	v_rcp_f32_e32 v110, v110
	v_rcp_f32_e32 v111, v111
	s_nop 0
	v_mul_f32_e32 v108, 0x3f1b4598, v108
	v_mul_f32_e32 v109, 0x3f1b4598, v109
	v_mul_f32_e32 v110, 0x3f1b4598, v110
	v_mul_f32_e32 v111, 0x3f1b4598, v111
	v_cvt_pk_bf16_f32 v150, v108, v109
	v_cvt_pk_bf16_f32 v151, v110, v111
	ds_write_b64 v236, v[150:151] offset:13920
	v_add_f32_e32 v112, v112, v192
	v_add_f32_e32 v113, v113, v193
	v_add_f32_e32 v114, v114, v194
	v_add_f32_e32 v115, v115, v195
	v_mul_f32_e32 v112, 0xbfb8aa3b, v112
	v_mul_f32_e32 v113, 0xbfb8aa3b, v113
	v_mul_f32_e32 v114, 0xbfb8aa3b, v114
	v_mul_f32_e32 v115, 0xbfb8aa3b, v115
	v_exp_f32_e32 v112, v112
	v_exp_f32_e32 v113, v113
	v_exp_f32_e32 v114, v114
	v_exp_f32_e32 v115, v115
	s_nop 0
	v_add_f32_e32 v112, 1.0, v112
	v_add_f32_e32 v113, 1.0, v113
	v_add_f32_e32 v114, 1.0, v114
	v_add_f32_e32 v115, 1.0, v115
	v_rcp_f32_e32 v112, v112
	v_rcp_f32_e32 v113, v113
	v_rcp_f32_e32 v114, v114
	v_rcp_f32_e32 v115, v115
	s_nop 0
	v_mul_f32_e32 v112, 0x3f1b4598, v112
	v_mul_f32_e32 v113, 0x3f1b4598, v113
	v_mul_f32_e32 v114, 0x3f1b4598, v114
	v_mul_f32_e32 v115, 0x3f1b4598, v115
	v_cvt_pk_bf16_f32 v152, v112, v113
	v_cvt_pk_bf16_f32 v153, v114, v115
	ds_write_b64 v236, v[152:153] offset:16128
	v_add_f32_e32 v116, v116, v196
	v_add_f32_e32 v117, v117, v197
	v_add_f32_e32 v118, v118, v198
	v_add_f32_e32 v119, v119, v199
	v_mul_f32_e32 v116, 0xbfb8aa3b, v116
	v_mul_f32_e32 v117, 0xbfb8aa3b, v117
	v_mul_f32_e32 v118, 0xbfb8aa3b, v118
	v_mul_f32_e32 v119, 0xbfb8aa3b, v119
	v_exp_f32_e32 v116, v116
	v_exp_f32_e32 v117, v117
	v_exp_f32_e32 v118, v118
	v_exp_f32_e32 v119, v119
	s_nop 0
	v_add_f32_e32 v116, 1.0, v116
	v_add_f32_e32 v117, 1.0, v117
	v_add_f32_e32 v118, 1.0, v118
	v_add_f32_e32 v119, 1.0, v119
	v_rcp_f32_e32 v116, v116
	v_rcp_f32_e32 v117, v117
	v_rcp_f32_e32 v118, v118
	v_rcp_f32_e32 v119, v119
	s_nop 0
	v_mul_f32_e32 v116, 0x3f1b4598, v116
	v_mul_f32_e32 v117, 0x3f1b4598, v117
	v_mul_f32_e32 v118, 0x3f1b4598, v118
	v_mul_f32_e32 v119, 0x3f1b4598, v119
	v_cvt_pk_bf16_f32 v154, v116, v117
	v_cvt_pk_bf16_f32 v155, v118, v119
	ds_write_b64 v236, v[154:155] offset:16160
	v_add_f32_e32 v120, v120, v200
	v_add_f32_e32 v121, v121, v201
	v_add_f32_e32 v122, v122, v202
	v_add_f32_e32 v123, v123, v203
	v_mul_f32_e32 v120, 0xbfb8aa3b, v120
	v_mul_f32_e32 v121, 0xbfb8aa3b, v121
	v_mul_f32_e32 v122, 0xbfb8aa3b, v122
	v_mul_f32_e32 v123, 0xbfb8aa3b, v123
	v_exp_f32_e32 v120, v120
	v_exp_f32_e32 v121, v121
	v_exp_f32_e32 v122, v122
	v_exp_f32_e32 v123, v123
	s_nop 0
	v_add_f32_e32 v120, 1.0, v120
	v_add_f32_e32 v121, 1.0, v121
	v_add_f32_e32 v122, 1.0, v122
	v_add_f32_e32 v123, 1.0, v123
	v_rcp_f32_e32 v120, v120
	v_rcp_f32_e32 v121, v121
	v_rcp_f32_e32 v122, v122
	v_rcp_f32_e32 v123, v123
	s_nop 0
	v_mul_f32_e32 v120, 0x3f1b4598, v120
	v_mul_f32_e32 v121, 0x3f1b4598, v121
	v_mul_f32_e32 v122, 0x3f1b4598, v122
	v_mul_f32_e32 v123, 0x3f1b4598, v123
	v_cvt_pk_bf16_f32 v156, v120, v121
	v_cvt_pk_bf16_f32 v157, v122, v123
	ds_write_b64 v236, v[156:157] offset:16192
	v_add_f32_e32 v124, v124, v204
	v_add_f32_e32 v125, v125, v205
	v_add_f32_e32 v126, v126, v206
	v_add_f32_e32 v127, v127, v207
	v_mul_f32_e32 v124, 0xbfb8aa3b, v124
	v_mul_f32_e32 v125, 0xbfb8aa3b, v125
	v_mul_f32_e32 v126, 0xbfb8aa3b, v126
	v_mul_f32_e32 v127, 0xbfb8aa3b, v127
	v_exp_f32_e32 v124, v124
	v_exp_f32_e32 v125, v125
	v_exp_f32_e32 v126, v126
	v_exp_f32_e32 v127, v127
	s_nop 0
	v_add_f32_e32 v124, 1.0, v124
	v_add_f32_e32 v125, 1.0, v125
	v_add_f32_e32 v126, 1.0, v126
	v_add_f32_e32 v127, 1.0, v127
	v_rcp_f32_e32 v124, v124
	v_rcp_f32_e32 v125, v125
	v_rcp_f32_e32 v126, v126
	v_rcp_f32_e32 v127, v127
	s_nop 0
	v_mul_f32_e32 v124, 0x3f1b4598, v124
	v_mul_f32_e32 v125, 0x3f1b4598, v125
	v_mul_f32_e32 v126, 0x3f1b4598, v126
	v_mul_f32_e32 v127, 0x3f1b4598, v127
	v_cvt_pk_bf16_f32 v158, v124, v125
	v_cvt_pk_bf16_f32 v159, v126, v127
	ds_write_b64 v236, v[158:159] offset:16224
	s_waitcnt lgkmcnt(0)
	ds_read_b128 v[128:131], v237
	ds_read_b128 v[132:135], v237 offset:1152
	ds_read_b128 v[136:139], v237 offset:2304
	ds_read_b128 v[140:143], v237 offset:3456
	ds_read_b128 v[144:147], v237 offset:4608
	ds_read_b128 v[148:151], v237 offset:5760
	ds_read_b128 v[152:155], v237 offset:6912
	ds_read_b128 v[156:159], v237 offset:8064
	ds_read_b128 v[160:163], v237 offset:9216
	ds_read_b128 v[164:167], v237 offset:10368
	ds_read_b128 v[168:171], v237 offset:11520
	ds_read_b128 v[172:175], v237 offset:12672
	ds_read_b128 v[176:179], v237 offset:13824
	ds_read_b128 v[180:183], v237 offset:14976
	ds_read_b128 v[184:187], v237 offset:16128
	ds_read_b128 v[188:191], v237 offset:17280
	s_waitcnt lgkmcnt(15)
; template <class Epi>
; DI void gemm_tile(char* smem, const bf16_t* __restrict__ A0, int lda0, int ksplit, const bf16_t* __restrict__ A1, int lda1,
;                   const bf16_t* __restrict__ Bt, int K, int row0, int col0, const Epi& epi, int tid) {
;     ...
;   const int sr = tid >> 2, scv = tid & 3;
; template <class Epi>
; DI void gemm_phase(char* smem, const bf16_t* A0, int lda0, int ksplit, const bf16_t* A1, int lda1, const bf16_t* Bt, int K, int nN, const Epi& epi, int tid) {
;   const int G = gridDim.x;
;   if ((G & 7) == 0) {
;     const int x = blockIdx.x & 7, l = blockIdx.x >> 3, L = G >> 3, per = 8 * nN, tot = 2 * per;
;     for (int q = l; q < tot; q += L) { const int rgl = q / per, rem = q % per, ct = rem >> 3, rt = (x * 2 + rgl) * 8 + (rem & 7);
;       gemm_tile(smem, A0, lda0, ksplit, A1, lda1, Bt, K, rt * 256, ct * 128, epi, tid); }
	global_store_dwordx4 v238, v[128:131], s[4:5]
	s_add_u32 s4, s4, 0x2000
	s_addc_u32 s5, s5, 0
	s_waitcnt lgkmcnt(14)
	global_store_dwordx4 v238, v[132:135], s[4:5]
	s_add_u32 s4, s4, 0x2000
	s_addc_u32 s5, s5, 0
	s_waitcnt lgkmcnt(13)
	global_store_dwordx4 v238, v[136:139], s[4:5]
	s_add_u32 s4, s4, 0x2000
	s_addc_u32 s5, s5, 0
	s_waitcnt lgkmcnt(12)
	global_store_dwordx4 v238, v[140:143], s[4:5]
	s_add_u32 s4, s4, 0x2000
	s_addc_u32 s5, s5, 0
	s_waitcnt lgkmcnt(11)
	global_store_dwordx4 v238, v[144:147], s[4:5]
	s_add_u32 s4, s4, 0x2000
	s_addc_u32 s5, s5, 0
	s_waitcnt lgkmcnt(10)
	global_store_dwordx4 v238, v[148:151], s[4:5]
	s_add_u32 s4, s4, 0x2000
	s_addc_u32 s5, s5, 0
	s_waitcnt lgkmcnt(9)
	global_store_dwordx4 v238, v[152:155], s[4:5]
	s_add_u32 s4, s4, 0x2000
	s_addc_u32 s5, s5, 0
	s_waitcnt lgkmcnt(8)
	global_store_dwordx4 v238, v[156:159], s[4:5]
	s_add_u32 s4, s4, 0x2000
	s_addc_u32 s5, s5, 0
	s_waitcnt lgkmcnt(7)
	global_store_dwordx4 v238, v[160:163], s[4:5]
	s_add_u32 s4, s4, 0x2000
	s_addc_u32 s5, s5, 0
	s_waitcnt lgkmcnt(6)
	global_store_dwordx4 v238, v[164:167], s[4:5]
	s_add_u32 s4, s4, 0x2000
	s_addc_u32 s5, s5, 0
	s_waitcnt lgkmcnt(5)
	global_store_dwordx4 v238, v[168:171], s[4:5]
	s_add_u32 s4, s4, 0x2000
	s_addc_u32 s5, s5, 0
	s_waitcnt lgkmcnt(4)
	global_store_dwordx4 v238, v[172:175], s[4:5]
	s_add_u32 s4, s4, 0x2000
	s_addc_u32 s5, s5, 0
	s_waitcnt lgkmcnt(3)
	global_store_dwordx4 v238, v[176:179], s[4:5]
	s_add_u32 s4, s4, 0x2000
	s_addc_u32 s5, s5, 0
	s_waitcnt lgkmcnt(2)
	global_store_dwordx4 v238, v[180:183], s[4:5]
	s_add_u32 s4, s4, 0x2000
	s_addc_u32 s5, s5, 0
	s_waitcnt lgkmcnt(1)
	global_store_dwordx4 v238, v[184:187], s[4:5]
	s_add_u32 s4, s4, 0x2000
	s_addc_u32 s5, s5, 0
	s_waitcnt lgkmcnt(0)
	global_store_dwordx4 v238, v[188:191], s[4:5]
	s_nop 1
	s_add_u32 s15, s15, 64
	s_branch .Lg3b_tile
.Lg3b_done:
	v_mbcnt_lo_u32_b32 v194, -1, 0
	v_mbcnt_hi_u32_b32 v136, -1, v194
	v_mbcnt_lo_u32_b32 v240, -1, 0
	v_mbcnt_hi_u32_b32 v240, -1, v240
	s_lshr_b32 s27, s72, 6
	s_lshl_b32 s100, s27, 10
	v_and_b32_e32 v241, 15, v240
	v_lshrrev_b32_e32 v242, 4, v240
	v_bfe_u32 v243, v240, 3, 1
	v_mul_u32_u24_e32 v243, 3, v243
	v_xor_b32_e32 v243, v242, v243
	v_lshlrev_b32_e32 v243, 4, v243
	v_lshl_add_u32 v243, v241, 6, v243
	s_lshr_b32 s26, s27, 1
	s_lshl_b32 s26, s26, 13
	v_add_u32_e32 v230, s26, v243
	s_and_b32 s26, s27, 1
	s_lshl_b32 s26, s26, 12
	s_add_u32 s26, s26, 16384
	v_add_u32_e32 v231, s26, v243
	s_lshr_b32 s26, s27, 1
	s_lshl_b32 s26, s26, 7
	v_add_u32_e32 v244, s26, v241
	s_and_b32 s26, s27, 1
	s_lshl_b32 s26, s26, 6
	v_lshl_add_u32 v245, v242, 2, s26
	v_lshlrev_b32_e32 v235, 2, v245
	s_mul_i32 s26, s27, 18432
	v_mul_u32_u24_e32 v246, 144, v241
	v_lshl_add_u32 v246, v242, 3, v246
	v_add_u32_e32 v236, s26, v246
	v_lshrrev_b32_e32 v246, 3, v240
	v_mul_u32_u24_e32 v246, 144, v246
	v_and_b32_e32 v247, 7, v240
	v_lshl_add_u32 v246, v247, 4, v246
	v_add_u32_e32 v237, s26, v246
	s_lshr_b32 s26, s27, 1
	s_lshl_b32 s26, s26, 7
	v_lshrrev_b32_e32 v246, 3, v240
	v_add_u32_e32 v246, s26, v246
	s_and_b32 s26, s27, 1
	s_lshl_b32 s26, s26, 6
	v_lshl_add_u32 v248, v247, 3, s26
	s_movk_i32 s26, 1024
	v_mul_lo_u32 v247, v246, s26
	v_lshl_add_u32 v238, v248, 1, v247
	v_lshrrev_b32_e32 v241, 2, v240
	s_lshl_b32 s26, s27, 4
	v_add_u32_e32 v241, s26, v241
	v_bfe_u32 v242, v240, 5, 1
	v_mul_u32_u24_e32 v242, 3, v242
	v_and_b32_e32 v243, 3, v240
	v_xor_b32_e32 v243, v243, v242
	v_lshlrev_b32_e32 v243, 4, v243
	s_mov_b32 s26, 512
	v_mad_u32_u24 v224, v241, s26, v243
	v_add_u32_e32 v225, 0x8000, v224
	v_add_u32_e32 v226, 0x10000, v224
	v_add_u32_e32 v227, 0x18000, v224
	s_mov_b32 s26, 128
	v_mad_u32_u24 v228, v241, s26, v243
	v_add_u32_e32 v229, 0x2000, v228
	s_load_dwordx2 s[6:7], s[74:75], 0x58
	s_lshr_b32 s15, s96, 3
	s_and_b32 s101, s96, 7
	s_lshl_b32 s101, s101, 1
	s_waitcnt lgkmcnt(0)
.Lg3c_tile:
	s_cmpk_ge_u32 s15, 64
	s_cbranch_scc1 .Lg3c_done
	s_cmpk_ge_u32 s15, 32
	s_cselect_b32 s27, 1, 0
	s_cselect_b32 s26, 32, 0
	s_sub_u32 s26, s15, s26
	s_add_u32 s27, s27, s101
	s_lshl_b32 s27, s27, 3
	s_and_b32 s29, s26, 7
	s_add_u32 s29, s29, s27
	s_lshl_b32 s29, s29, 8
	s_lshr_b32 s28, s26, 3
	s_lshl_b32 s28, s28, 7
	s_mul_i32 s27, s29, 512
	s_add_u32 s27, s27, 0x1ea00080
	s_add_u32 s0, s92, s27
	s_addc_u32 s1, s93, 0
	s_mul_i32 s27, s28, 128
	s_add_u32 s27, s27, 0x34c0000
	s_add_u32 s2, s92, s27
	s_addc_u32 s3, s93, 0
	s_waitcnt lgkmcnt(0)
	s_barrier
; #define LWRITE(S, buf) do { bf16_t* sA_ = sbase + (buf) * BUF; bf16_t* sB_ = sA_ + 256 * PITCH; \
;     _Pragma("unroll") for (int i_ = 0; i_ < 4; ++i_) *(u32x4*)(sA_ + (sr + i_ * 64) * PITCH + scv * 8) = ra[S][i_]; \
;     _Pragma("unroll") for (int i_ = 0; i_ < 2; ++i_) *(u32x4*)(sB_ + (sr + i_ * 64) * PITCH + scv * 8) = rb[S][i_]; } while (0)
; template <class Epi>
; DI void gemm_tile(char* smem, const bf16_t* __restrict__ A0, int lda0, int ksplit, const bf16_t* __restrict__ A1, int lda1,
;                   const bf16_t* __restrict__ Bt, int K, int row0, int col0, const Epi& epi, int tid) {
;   constexpr int BK = 32, PITCH = 40, BUF = (256 + 128) * PITCH;
;   bf16_t* sbase = (bf16_t*)smem;
;   const int lane = tid & 63, wid = tid >> 6, wr = wid >> 1, wc = wid & 1, fr = lane & 15, fq = lane >> 4;
;   f32x4 acc[8][4];
; #pragma unroll
;   for (int m = 0; m < 8; ++m)
; #pragma unroll
;     for (int n = 0; n < 4; ++n) acc[m][n] = (f32x4){0.f, 0.f, 0.f, 0.f};
;   u32x4 ra[2][4], rb[2][2];
;   const int nk = K / BK;
;   const int sr = tid >> 2, scv = tid & 3;
;     ...
;   __syncthreads();
;   {
;     const int last = nk - 1;
;     GLOAD(0, 0);
;     __builtin_amdgcn_sched_barrier(0);
;     GLOAD(1, 1);
;     __builtin_amdgcn_sched_barrier(0);
;     LWRITE(0, 0);
;     __builtin_amdgcn_sched_barrier(0);
;     GLOAD(0, (2 < last ? 2 : last));
;     __builtin_amdgcn_sched_barrier(0);
;     __syncthreads();
	s_mov_b32 s99, 0
	s_mov_b32 s30, 0
	s_add_u32 s26, s30, s100
	s_add_u32 m0, s26, 0
	s_nop 0
	global_load_lds_dwordx4 v224, s[0:1]
	s_add_u32 m0, s26, 4096
	s_nop 0
	global_load_lds_dwordx4 v225, s[0:1]
	s_add_u32 m0, s26, 8192
	s_nop 0
	global_load_lds_dwordx4 v226, s[0:1]
	s_add_u32 m0, s26, 12288
	s_nop 0
	global_load_lds_dwordx4 v227, s[0:1]
	s_add_u32 m0, s26, 16384
	s_nop 0
	global_load_lds_dwordx4 v228, s[2:3]
	s_add_u32 m0, s26, 20480
	s_nop 0
	global_load_lds_dwordx4 v229, s[2:3]
	s_add_u32 s0, s0, 64
	s_addc_u32 s1, s1, 0
	s_add_u32 s2, s2, 64
	s_addc_u32 s3, s3, 0
	s_add_u32 s99, s99, 1
	s_add_u32 s30, s30, 24576
	s_cmp_eq_u32 s30, 73728
	s_cselect_b32 s30, 0, s30
	s_add_u32 s26, s30, s100
	s_add_u32 m0, s26, 0
	s_nop 0
	global_load_lds_dwordx4 v224, s[0:1]
	s_add_u32 m0, s26, 4096
	s_nop 0
	global_load_lds_dwordx4 v225, s[0:1]
	s_add_u32 m0, s26, 8192
	s_nop 0
	global_load_lds_dwordx4 v226, s[0:1]
	s_add_u32 m0, s26, 12288
	s_nop 0
	global_load_lds_dwordx4 v227, s[0:1]
	s_add_u32 m0, s26, 16384
	s_nop 0
	global_load_lds_dwordx4 v228, s[2:3]
	s_add_u32 m0, s26, 20480
	s_nop 0
	global_load_lds_dwordx4 v229, s[2:3]
	s_add_u32 s0, s0, 64
	s_addc_u32 s1, s1, 0
	s_add_u32 s2, s2, 64
	s_addc_u32 s3, s3, 0
	s_add_u32 s99, s99, 1
	s_add_u32 s30, s30, 24576
	s_cmp_eq_u32 s30, 73728
	s_cselect_b32 s30, 0, s30
	v_mov_b32_e32 v0, 0
	v_mov_b32_e32 v1, 0
	v_mov_b32_e32 v2, 0
	v_mov_b32_e32 v3, 0
	v_mov_b32_e32 v4, 0
	v_mov_b32_e32 v5, 0
	v_mov_b32_e32 v6, 0
	v_mov_b32_e32 v7, 0
	v_mov_b32_e32 v8, 0
	v_mov_b32_e32 v9, 0
	v_mov_b32_e32 v10, 0
	v_mov_b32_e32 v11, 0
	v_mov_b32_e32 v12, 0
	v_mov_b32_e32 v13, 0
	v_mov_b32_e32 v14, 0
	v_mov_b32_e32 v15, 0
	v_mov_b32_e32 v16, 0
	v_mov_b32_e32 v17, 0
	v_mov_b32_e32 v18, 0
	v_mov_b32_e32 v19, 0
	v_mov_b32_e32 v20, 0
	v_mov_b32_e32 v21, 0
	v_mov_b32_e32 v22, 0
	v_mov_b32_e32 v23, 0
	v_mov_b32_e32 v24, 0
	v_mov_b32_e32 v25, 0
	v_mov_b32_e32 v26, 0
	v_mov_b32_e32 v27, 0
	v_mov_b32_e32 v28, 0
	v_mov_b32_e32 v29, 0
	v_mov_b32_e32 v30, 0
	v_mov_b32_e32 v31, 0
	v_mov_b32_e32 v32, 0
	v_mov_b32_e32 v33, 0
	v_mov_b32_e32 v34, 0
	v_mov_b32_e32 v35, 0
	v_mov_b32_e32 v36, 0
	v_mov_b32_e32 v37, 0
	v_mov_b32_e32 v38, 0
	v_mov_b32_e32 v39, 0
	v_mov_b32_e32 v40, 0
	v_mov_b32_e32 v41, 0
	v_mov_b32_e32 v42, 0
	v_mov_b32_e32 v43, 0
	v_mov_b32_e32 v44, 0
	v_mov_b32_e32 v45, 0
	v_mov_b32_e32 v46, 0
	v_mov_b32_e32 v47, 0
	v_mov_b32_e32 v48, 0
	v_mov_b32_e32 v49, 0
	v_mov_b32_e32 v50, 0
	v_mov_b32_e32 v51, 0
	v_mov_b32_e32 v52, 0
	v_mov_b32_e32 v53, 0
	v_mov_b32_e32 v54, 0
	v_mov_b32_e32 v55, 0
	v_mov_b32_e32 v56, 0
	v_mov_b32_e32 v57, 0
	v_mov_b32_e32 v58, 0
	v_mov_b32_e32 v59, 0
	v_mov_b32_e32 v60, 0
	v_mov_b32_e32 v61, 0
	v_mov_b32_e32 v62, 0
	v_mov_b32_e32 v63, 0
	v_mov_b32_e32 v64, 0
	v_mov_b32_e32 v65, 0
	v_mov_b32_e32 v66, 0
	v_mov_b32_e32 v67, 0
	v_mov_b32_e32 v68, 0
	v_mov_b32_e32 v69, 0
	v_mov_b32_e32 v70, 0
	v_mov_b32_e32 v71, 0
	v_mov_b32_e32 v72, 0
	v_mov_b32_e32 v73, 0
	v_mov_b32_e32 v74, 0
	v_mov_b32_e32 v75, 0
	v_mov_b32_e32 v76, 0
	v_mov_b32_e32 v77, 0
	v_mov_b32_e32 v78, 0
	v_mov_b32_e32 v79, 0
	v_mov_b32_e32 v80, 0
	v_mov_b32_e32 v81, 0
	v_mov_b32_e32 v82, 0
	v_mov_b32_e32 v83, 0
	v_mov_b32_e32 v84, 0
	v_mov_b32_e32 v85, 0
	v_mov_b32_e32 v86, 0
	v_mov_b32_e32 v87, 0
	v_mov_b32_e32 v88, 0
	v_mov_b32_e32 v89, 0
	v_mov_b32_e32 v90, 0
	v_mov_b32_e32 v91, 0
	v_mov_b32_e32 v92, 0
	v_mov_b32_e32 v93, 0
	v_mov_b32_e32 v94, 0
	v_mov_b32_e32 v95, 0
	v_mov_b32_e32 v96, 0
	v_mov_b32_e32 v97, 0
	v_mov_b32_e32 v98, 0
	v_mov_b32_e32 v99, 0
	v_mov_b32_e32 v100, 0
	v_mov_b32_e32 v101, 0
	v_mov_b32_e32 v102, 0
	v_mov_b32_e32 v103, 0
	v_mov_b32_e32 v104, 0
	v_mov_b32_e32 v105, 0
	v_mov_b32_e32 v106, 0
	v_mov_b32_e32 v107, 0
	v_mov_b32_e32 v108, 0
	v_mov_b32_e32 v109, 0
	v_mov_b32_e32 v110, 0
	v_mov_b32_e32 v111, 0
	v_mov_b32_e32 v112, 0
	v_mov_b32_e32 v113, 0
	v_mov_b32_e32 v114, 0
	v_mov_b32_e32 v115, 0
	v_mov_b32_e32 v116, 0
	v_mov_b32_e32 v117, 0
	v_mov_b32_e32 v118, 0
	v_mov_b32_e32 v119, 0
	v_mov_b32_e32 v120, 0
	v_mov_b32_e32 v121, 0
	v_mov_b32_e32 v122, 0
	v_mov_b32_e32 v123, 0
	v_mov_b32_e32 v124, 0
	v_mov_b32_e32 v125, 0
	v_mov_b32_e32 v126, 0
	v_mov_b32_e32 v127, 0
	s_mov_b32 s98, 0
	s_mov_b32 s31, 24576
	s_waitcnt vmcnt(6)
	s_barrier
	ds_read_b128 v[128:131], v231 offset:0
	ds_read_b128 v[132:135], v231 offset:1024
	ds_read_b128 v[136:139], v231 offset:2048
	ds_read_b128 v[140:143], v231 offset:3072
	ds_read_b128 v[144:147], v230 offset:0
	ds_read_b128 v[148:151], v230 offset:1024
	ds_read_b128 v[152:155], v230 offset:2048
	ds_read_b128 v[156:159], v230 offset:3072
	ds_read_b128 v[160:163], v230 offset:4096
	ds_read_b128 v[164:167], v230 offset:5120
	ds_read_b128 v[168:171], v230 offset:6144
	ds_read_b128 v[172:175], v230 offset:7168
	s_waitcnt vmcnt(0)
	s_waitcnt lgkmcnt(0)
	s_barrier
; #define LWRITE(S, buf) do { bf16_t* sA_ = sbase + (buf) * BUF; bf16_t* sB_ = sA_ + 256 * PITCH; \
;     _Pragma("unroll") for (int i_ = 0; i_ < 4; ++i_) *(u32x4*)(sA_ + (sr + i_ * 64) * PITCH + scv * 8) = ra[S][i_]; \
;     _Pragma("unroll") for (int i_ = 0; i_ < 2; ++i_) *(u32x4*)(sB_ + (sr + i_ * 64) * PITCH + scv * 8) = rb[S][i_]; } while (0)
; template <class Epi>
; DI void gemm_tile(char* smem, const bf16_t* __restrict__ A0, int lda0, int ksplit, const bf16_t* __restrict__ A1, int lda1,
;                   const bf16_t* __restrict__ Bt, int K, int row0, int col0, const Epi& epi, int tid) {
;     ...
;     for (int kt = 0; kt < nk; kt += 2) {
;       LWRITE(1, 1);
;       __builtin_amdgcn_sched_barrier(0);
;       GLOAD(1, (kt + 3 < last ? kt + 3 : last));
;       __builtin_amdgcn_sched_barrier(0);
;       COMPUTE(0);
;       __syncthreads();
;       LWRITE(0, 0);
;       __builtin_amdgcn_sched_barrier(0);
;       GLOAD(0, (kt + 4 < last ? kt + 4 : last));
;       __builtin_amdgcn_sched_barrier(0);
;       COMPUTE(1);
;       __syncthreads();
;     }
	v_add_u32_e32 v232, s31, v230
	v_add_u32_e32 v233, s31, v231
	v_mfma_f32_16x16x32_bf16 v[0:3], v[128:131], v[144:147], v[0:3]
	v_mfma_f32_16x16x32_bf16 v[4:7], v[132:135], v[144:147], v[4:7]
	v_mfma_f32_16x16x32_bf16 v[8:11], v[136:139], v[144:147], v[8:11]
	v_mfma_f32_16x16x32_bf16 v[12:15], v[140:143], v[144:147], v[12:15]
	ds_read_b128 v[176:179], v233 offset:0
	ds_read_b128 v[180:183], v233 offset:1024
	v_mfma_f32_16x16x32_bf16 v[16:19], v[128:131], v[148:151], v[16:19]
	v_mfma_f32_16x16x32_bf16 v[20:23], v[132:135], v[148:151], v[20:23]
	v_mfma_f32_16x16x32_bf16 v[24:27], v[136:139], v[148:151], v[24:27]
	v_mfma_f32_16x16x32_bf16 v[28:31], v[140:143], v[148:151], v[28:31]
	ds_read_b128 v[184:187], v233 offset:2048
	ds_read_b128 v[188:191], v233 offset:3072
	v_mfma_f32_16x16x32_bf16 v[32:35], v[128:131], v[152:155], v[32:35]
	v_mfma_f32_16x16x32_bf16 v[36:39], v[132:135], v[152:155], v[36:39]
	v_mfma_f32_16x16x32_bf16 v[40:43], v[136:139], v[152:155], v[40:43]
	v_mfma_f32_16x16x32_bf16 v[44:47], v[140:143], v[152:155], v[44:47]
	ds_read_b128 v[192:195], v232 offset:0
	ds_read_b128 v[196:199], v232 offset:1024
	v_mfma_f32_16x16x32_bf16 v[48:51], v[128:131], v[156:159], v[48:51]
	v_mfma_f32_16x16x32_bf16 v[52:55], v[132:135], v[156:159], v[52:55]
	v_mfma_f32_16x16x32_bf16 v[56:59], v[136:139], v[156:159], v[56:59]
	v_mfma_f32_16x16x32_bf16 v[60:63], v[140:143], v[156:159], v[60:63]
	ds_read_b128 v[200:203], v232 offset:2048
	ds_read_b128 v[204:207], v232 offset:3072
	v_mfma_f32_16x16x32_bf16 v[64:67], v[128:131], v[160:163], v[64:67]
	v_mfma_f32_16x16x32_bf16 v[68:71], v[132:135], v[160:163], v[68:71]
	v_mfma_f32_16x16x32_bf16 v[72:75], v[136:139], v[160:163], v[72:75]
	v_mfma_f32_16x16x32_bf16 v[76:79], v[140:143], v[160:163], v[76:79]
	ds_read_b128 v[208:211], v232 offset:4096
	v_mfma_f32_16x16x32_bf16 v[80:83], v[128:131], v[164:167], v[80:83]
	v_mfma_f32_16x16x32_bf16 v[84:87], v[132:135], v[164:167], v[84:87]
	v_mfma_f32_16x16x32_bf16 v[88:91], v[136:139], v[164:167], v[88:91]
	v_mfma_f32_16x16x32_bf16 v[92:95], v[140:143], v[164:167], v[92:95]
	ds_read_b128 v[212:215], v232 offset:5120
	v_mfma_f32_16x16x32_bf16 v[96:99], v[128:131], v[168:171], v[96:99]
	v_mfma_f32_16x16x32_bf16 v[100:103], v[132:135], v[168:171], v[100:103]
	v_mfma_f32_16x16x32_bf16 v[104:107], v[136:139], v[168:171], v[104:107]
	v_mfma_f32_16x16x32_bf16 v[108:111], v[140:143], v[168:171], v[108:111]
	ds_read_b128 v[216:219], v232 offset:6144
	s_add_u32 s31, s31, 24576
	s_cmp_eq_u32 s31, 73728
	s_cselect_b32 s31, 0, s31
	v_mfma_f32_16x16x32_bf16 v[112:115], v[128:131], v[172:175], v[112:115]
	v_mfma_f32_16x16x32_bf16 v[116:119], v[132:135], v[172:175], v[116:119]
	v_mfma_f32_16x16x32_bf16 v[120:123], v[136:139], v[172:175], v[120:123]
	v_mfma_f32_16x16x32_bf16 v[124:127], v[140:143], v[172:175], v[124:127]
	ds_read_b128 v[220:223], v232 offset:7168
	s_waitcnt lgkmcnt(0)
	s_barrier
	v_mfma_f32_16x16x32_bf16 v[0:3], v[176:179], v[192:195], v[0:3]
	v_mfma_f32_16x16x32_bf16 v[4:7], v[180:183], v[192:195], v[4:7]
	v_mfma_f32_16x16x32_bf16 v[8:11], v[184:187], v[192:195], v[8:11]
	v_mfma_f32_16x16x32_bf16 v[12:15], v[188:191], v[192:195], v[12:15]
	v_mfma_f32_16x16x32_bf16 v[16:19], v[176:179], v[196:199], v[16:19]
	v_mfma_f32_16x16x32_bf16 v[20:23], v[180:183], v[196:199], v[20:23]
	v_mfma_f32_16x16x32_bf16 v[24:27], v[184:187], v[196:199], v[24:27]
	v_mfma_f32_16x16x32_bf16 v[28:31], v[188:191], v[196:199], v[28:31]
	v_mfma_f32_16x16x32_bf16 v[32:35], v[176:179], v[200:203], v[32:35]
	v_mfma_f32_16x16x32_bf16 v[36:39], v[180:183], v[200:203], v[36:39]
	v_mfma_f32_16x16x32_bf16 v[40:43], v[184:187], v[200:203], v[40:43]
	v_mfma_f32_16x16x32_bf16 v[44:47], v[188:191], v[200:203], v[44:47]
	v_mfma_f32_16x16x32_bf16 v[48:51], v[176:179], v[204:207], v[48:51]
	v_mfma_f32_16x16x32_bf16 v[52:55], v[180:183], v[204:207], v[52:55]
	v_mfma_f32_16x16x32_bf16 v[56:59], v[184:187], v[204:207], v[56:59]
	v_mfma_f32_16x16x32_bf16 v[60:63], v[188:191], v[204:207], v[60:63]
	v_mfma_f32_16x16x32_bf16 v[64:67], v[176:179], v[208:211], v[64:67]
	v_mfma_f32_16x16x32_bf16 v[68:71], v[180:183], v[208:211], v[68:71]
	v_mfma_f32_16x16x32_bf16 v[72:75], v[184:187], v[208:211], v[72:75]
	v_mfma_f32_16x16x32_bf16 v[76:79], v[188:191], v[208:211], v[76:79]
	v_mfma_f32_16x16x32_bf16 v[80:83], v[176:179], v[212:215], v[80:83]
	v_mfma_f32_16x16x32_bf16 v[84:87], v[180:183], v[212:215], v[84:87]
	v_mfma_f32_16x16x32_bf16 v[88:91], v[184:187], v[212:215], v[88:91]
	v_mfma_f32_16x16x32_bf16 v[92:95], v[188:191], v[212:215], v[92:95]
	v_mfma_f32_16x16x32_bf16 v[96:99], v[176:179], v[216:219], v[96:99]
	v_mfma_f32_16x16x32_bf16 v[100:103], v[180:183], v[216:219], v[100:103]
	v_mfma_f32_16x16x32_bf16 v[104:107], v[184:187], v[216:219], v[104:107]
	v_mfma_f32_16x16x32_bf16 v[108:111], v[188:191], v[216:219], v[108:111]
	v_mfma_f32_16x16x32_bf16 v[112:115], v[176:179], v[220:223], v[112:115]
	v_mfma_f32_16x16x32_bf16 v[116:119], v[180:183], v[220:223], v[116:119]
	v_mfma_f32_16x16x32_bf16 v[120:123], v[184:187], v[220:223], v[120:123]
	v_mfma_f32_16x16x32_bf16 v[124:127], v[188:191], v[220:223], v[124:127]
	s_branch .Lg3c_epi
; template <class Epi>
; DI void gemm_tile(char* smem, const bf16_t* __restrict__ A0, int lda0, int ksplit, const bf16_t* __restrict__ A1, int lda1,
;                   const bf16_t* __restrict__ Bt, int K, int row0, int col0, const Epi& epi, int tid) {
;     ...
; #pragma unroll
;   for (int m = 0; m < 8; ++m)
; #pragma unroll
;     for (int n = 0; n < 4; ++n) epi(row0 + wr * 128 + m * 16 + fr, col0 + wc * 64 + n * 16 + fq * 4, acc[m][n]);
.Lg3c_epi:
	s_nop 7
	s_nop 7
	s_mul_i32 s27, s29, 1024
	s_lshl_b32 s26, s28, 1
	s_add_u32 s27, s27, s26
	s_add_u32 s27, s27, 0xb800000
	s_add_u32 s4, s92, s27
	s_addc_u32 s5, s93, 0
	s_lshl_b32 s27, s28, 2
	s_add_u32 s27, s27, 0x0
	s_add_u32 s2, s6, s27
	s_addc_u32 s3, s7, 0
	global_load_dwordx4 v[192:195], v235, s[2:3] offset:0
	global_load_dwordx4 v[196:199], v235, s[2:3] offset:64
	global_load_dwordx4 v[200:203], v235, s[2:3] offset:128
	global_load_dwordx4 v[204:207], v235, s[2:3] offset:192
	s_waitcnt vmcnt(0)
	v_add_f32_e32 v0, v0, v192
	v_add_f32_e32 v1, v1, v193
	v_add_f32_e32 v2, v2, v194
	v_add_f32_e32 v3, v3, v195
	v_mul_f32_e32 v0, 0xbfb8aa3b, v0
	v_mul_f32_e32 v1, 0xbfb8aa3b, v1
	v_mul_f32_e32 v2, 0xbfb8aa3b, v2
	v_mul_f32_e32 v3, 0xbfb8aa3b, v3
	v_exp_f32_e32 v0, v0
	v_exp_f32_e32 v1, v1
	v_exp_f32_e32 v2, v2
	v_exp_f32_e32 v3, v3
	s_nop 0
	v_add_f32_e32 v0, 1.0, v0
	v_add_f32_e32 v1, 1.0, v1
	v_add_f32_e32 v2, 1.0, v2
	v_add_f32_e32 v3, 1.0, v3
	v_rcp_f32_e32 v0, v0
	v_rcp_f32_e32 v1, v1
	v_rcp_f32_e32 v2, v2
	v_rcp_f32_e32 v3, v3
	s_nop 0
	v_cvt_pk_bf16_f32 v128, v0, v1
	v_cvt_pk_bf16_f32 v129, v2, v3
	ds_write_b64 v236, v[128:129]
	v_add_f32_e32 v4, v4, v196
	v_add_f32_e32 v5, v5, v197
	v_add_f32_e32 v6, v6, v198
	v_add_f32_e32 v7, v7, v199
	v_mul_f32_e32 v4, 0xbfb8aa3b, v4
	v_mul_f32_e32 v5, 0xbfb8aa3b, v5
	v_mul_f32_e32 v6, 0xbfb8aa3b, v6
	v_mul_f32_e32 v7, 0xbfb8aa3b, v7
	v_exp_f32_e32 v4, v4
	v_exp_f32_e32 v5, v5
	v_exp_f32_e32 v6, v6
	v_exp_f32_e32 v7, v7
	s_nop 0
	v_add_f32_e32 v4, 1.0, v4
	v_add_f32_e32 v5, 1.0, v5
	v_add_f32_e32 v6, 1.0, v6
	v_add_f32_e32 v7, 1.0, v7
	v_rcp_f32_e32 v4, v4
	v_rcp_f32_e32 v5, v5
	v_rcp_f32_e32 v6, v6
	v_rcp_f32_e32 v7, v7
	s_nop 0
	v_cvt_pk_bf16_f32 v130, v4, v5
	v_cvt_pk_bf16_f32 v131, v6, v7
	ds_write_b64 v236, v[130:131] offset:32
	v_add_f32_e32 v8, v8, v200
	v_add_f32_e32 v9, v9, v201
	v_add_f32_e32 v10, v10, v202
	v_add_f32_e32 v11, v11, v203
	v_mul_f32_e32 v8, 0xbfb8aa3b, v8
	v_mul_f32_e32 v9, 0xbfb8aa3b, v9
	v_mul_f32_e32 v10, 0xbfb8aa3b, v10
	v_mul_f32_e32 v11, 0xbfb8aa3b, v11
	v_exp_f32_e32 v8, v8
	v_exp_f32_e32 v9, v9
	v_exp_f32_e32 v10, v10
	v_exp_f32_e32 v11, v11
	s_nop 0
	v_add_f32_e32 v8, 1.0, v8
	v_add_f32_e32 v9, 1.0, v9
	v_add_f32_e32 v10, 1.0, v10
	v_add_f32_e32 v11, 1.0, v11
	v_rcp_f32_e32 v8, v8
	v_rcp_f32_e32 v9, v9
	v_rcp_f32_e32 v10, v10
	v_rcp_f32_e32 v11, v11
	s_nop 0
	v_cvt_pk_bf16_f32 v132, v8, v9
	v_cvt_pk_bf16_f32 v133, v10, v11
	ds_write_b64 v236, v[132:133] offset:64
	v_add_f32_e32 v12, v12, v204
	v_add_f32_e32 v13, v13, v205
	v_add_f32_e32 v14, v14, v206
	v_add_f32_e32 v15, v15, v207
	v_mul_f32_e32 v12, 0xbfb8aa3b, v12
	v_mul_f32_e32 v13, 0xbfb8aa3b, v13
	v_mul_f32_e32 v14, 0xbfb8aa3b, v14
	v_mul_f32_e32 v15, 0xbfb8aa3b, v15
	v_exp_f32_e32 v12, v12
	v_exp_f32_e32 v13, v13
	v_exp_f32_e32 v14, v14
	v_exp_f32_e32 v15, v15
	s_nop 0
	v_add_f32_e32 v12, 1.0, v12
	v_add_f32_e32 v13, 1.0, v13
	v_add_f32_e32 v14, 1.0, v14
	v_add_f32_e32 v15, 1.0, v15
	v_rcp_f32_e32 v12, v12
	v_rcp_f32_e32 v13, v13
	v_rcp_f32_e32 v14, v14
	v_rcp_f32_e32 v15, v15
	s_nop 0
	v_cvt_pk_bf16_f32 v134, v12, v13
	v_cvt_pk_bf16_f32 v135, v14, v15
	ds_write_b64 v236, v[134:135] offset:96
	v_add_f32_e32 v16, v16, v192
	v_add_f32_e32 v17, v17, v193
	v_add_f32_e32 v18, v18, v194
	v_add_f32_e32 v19, v19, v195
	v_mul_f32_e32 v16, 0xbfb8aa3b, v16
	v_mul_f32_e32 v17, 0xbfb8aa3b, v17
	v_mul_f32_e32 v18, 0xbfb8aa3b, v18
	v_mul_f32_e32 v19, 0xbfb8aa3b, v19
	v_exp_f32_e32 v16, v16
	v_exp_f32_e32 v17, v17
	v_exp_f32_e32 v18, v18
	v_exp_f32_e32 v19, v19
	s_nop 0
	v_add_f32_e32 v16, 1.0, v16
	v_add_f32_e32 v17, 1.0, v17
	v_add_f32_e32 v18, 1.0, v18
	v_add_f32_e32 v19, 1.0, v19
	v_rcp_f32_e32 v16, v16
	v_rcp_f32_e32 v17, v17
	v_rcp_f32_e32 v18, v18
	v_rcp_f32_e32 v19, v19
	s_nop 0
	v_cvt_pk_bf16_f32 v136, v16, v17
	v_cvt_pk_bf16_f32 v137, v18, v19
	ds_write_b64 v236, v[136:137] offset:2304
	v_add_f32_e32 v20, v20, v196
	v_add_f32_e32 v21, v21, v197
	v_add_f32_e32 v22, v22, v198
	v_add_f32_e32 v23, v23, v199
	v_mul_f32_e32 v20, 0xbfb8aa3b, v20
	v_mul_f32_e32 v21, 0xbfb8aa3b, v21
	v_mul_f32_e32 v22, 0xbfb8aa3b, v22
	v_mul_f32_e32 v23, 0xbfb8aa3b, v23
	v_exp_f32_e32 v20, v20
	v_exp_f32_e32 v21, v21
	v_exp_f32_e32 v22, v22
	v_exp_f32_e32 v23, v23
	s_nop 0
	v_add_f32_e32 v20, 1.0, v20
	v_add_f32_e32 v21, 1.0, v21
	v_add_f32_e32 v22, 1.0, v22
	v_add_f32_e32 v23, 1.0, v23
	v_rcp_f32_e32 v20, v20
	v_rcp_f32_e32 v21, v21
	v_rcp_f32_e32 v22, v22
	v_rcp_f32_e32 v23, v23
	s_nop 0
	v_cvt_pk_bf16_f32 v138, v20, v21
	v_cvt_pk_bf16_f32 v139, v22, v23
	ds_write_b64 v236, v[138:139] offset:2336
	v_add_f32_e32 v24, v24, v200
	v_add_f32_e32 v25, v25, v201
	v_add_f32_e32 v26, v26, v202
	v_add_f32_e32 v27, v27, v203
	v_mul_f32_e32 v24, 0xbfb8aa3b, v24
	v_mul_f32_e32 v25, 0xbfb8aa3b, v25
	v_mul_f32_e32 v26, 0xbfb8aa3b, v26
	v_mul_f32_e32 v27, 0xbfb8aa3b, v27
	v_exp_f32_e32 v24, v24
	v_exp_f32_e32 v25, v25
	v_exp_f32_e32 v26, v26
	v_exp_f32_e32 v27, v27
	s_nop 0
	v_add_f32_e32 v24, 1.0, v24
	v_add_f32_e32 v25, 1.0, v25
	v_add_f32_e32 v26, 1.0, v26
	v_add_f32_e32 v27, 1.0, v27
	v_rcp_f32_e32 v24, v24
	v_rcp_f32_e32 v25, v25
	v_rcp_f32_e32 v26, v26
	v_rcp_f32_e32 v27, v27
	s_nop 0
	v_cvt_pk_bf16_f32 v140, v24, v25
	v_cvt_pk_bf16_f32 v141, v26, v27
	ds_write_b64 v236, v[140:141] offset:2368
	v_add_f32_e32 v28, v28, v204
	v_add_f32_e32 v29, v29, v205
	v_add_f32_e32 v30, v30, v206
	v_add_f32_e32 v31, v31, v207
	v_mul_f32_e32 v28, 0xbfb8aa3b, v28
	v_mul_f32_e32 v29, 0xbfb8aa3b, v29
	v_mul_f32_e32 v30, 0xbfb8aa3b, v30
	v_mul_f32_e32 v31, 0xbfb8aa3b, v31
	v_exp_f32_e32 v28, v28
	v_exp_f32_e32 v29, v29
	v_exp_f32_e32 v30, v30
; template <class Epi>
; DI void gemm_tile(char* smem, const bf16_t* __restrict__ A0, int lda0, int ksplit, const bf16_t* __restrict__ A1, int lda1,
;                   const bf16_t* __restrict__ Bt, int K, int row0, int col0, const Epi& epi, int tid) {
;     ...
; #pragma unroll
;   for (int m = 0; m < 8; ++m)
; #pragma unroll
;     for (int n = 0; n < 4; ++n) epi(row0 + wr * 128 + m * 16 + fr, col0 + wc * 64 + n * 16 + fq * 4, acc[m][n]);
	v_exp_f32_e32 v31, v31
	s_nop 0
	v_add_f32_e32 v28, 1.0, v28
	v_add_f32_e32 v29, 1.0, v29
	v_add_f32_e32 v30, 1.0, v30
	v_add_f32_e32 v31, 1.0, v31
	v_rcp_f32_e32 v28, v28
	v_rcp_f32_e32 v29, v29
	v_rcp_f32_e32 v30, v30
	v_rcp_f32_e32 v31, v31
	s_nop 0
	v_cvt_pk_bf16_f32 v142, v28, v29
	v_cvt_pk_bf16_f32 v143, v30, v31
	ds_write_b64 v236, v[142:143] offset:2400
	v_add_f32_e32 v32, v32, v192
	v_add_f32_e32 v33, v33, v193
	v_add_f32_e32 v34, v34, v194
	v_add_f32_e32 v35, v35, v195
	v_mul_f32_e32 v32, 0xbfb8aa3b, v32
	v_mul_f32_e32 v33, 0xbfb8aa3b, v33
	v_mul_f32_e32 v34, 0xbfb8aa3b, v34
	v_mul_f32_e32 v35, 0xbfb8aa3b, v35
	v_exp_f32_e32 v32, v32
	v_exp_f32_e32 v33, v33
	v_exp_f32_e32 v34, v34
	v_exp_f32_e32 v35, v35
	s_nop 0
	v_add_f32_e32 v32, 1.0, v32
	v_add_f32_e32 v33, 1.0, v33
	v_add_f32_e32 v34, 1.0, v34
	v_add_f32_e32 v35, 1.0, v35
	v_rcp_f32_e32 v32, v32
	v_rcp_f32_e32 v33, v33
	v_rcp_f32_e32 v34, v34
	v_rcp_f32_e32 v35, v35
	s_nop 0
	v_cvt_pk_bf16_f32 v144, v32, v33
	v_cvt_pk_bf16_f32 v145, v34, v35
	ds_write_b64 v236, v[144:145] offset:4608
	v_add_f32_e32 v36, v36, v196
	v_add_f32_e32 v37, v37, v197
	v_add_f32_e32 v38, v38, v198
	v_add_f32_e32 v39, v39, v199
	v_mul_f32_e32 v36, 0xbfb8aa3b, v36
	v_mul_f32_e32 v37, 0xbfb8aa3b, v37
	v_mul_f32_e32 v38, 0xbfb8aa3b, v38
	v_mul_f32_e32 v39, 0xbfb8aa3b, v39
	v_exp_f32_e32 v36, v36
	v_exp_f32_e32 v37, v37
	v_exp_f32_e32 v38, v38
	v_exp_f32_e32 v39, v39
	s_nop 0
	v_add_f32_e32 v36, 1.0, v36
	v_add_f32_e32 v37, 1.0, v37
	v_add_f32_e32 v38, 1.0, v38
	v_add_f32_e32 v39, 1.0, v39
	v_rcp_f32_e32 v36, v36
	v_rcp_f32_e32 v37, v37
	v_rcp_f32_e32 v38, v38
	v_rcp_f32_e32 v39, v39
	s_nop 0
	v_cvt_pk_bf16_f32 v146, v36, v37
	v_cvt_pk_bf16_f32 v147, v38, v39
	ds_write_b64 v236, v[146:147] offset:4640
	v_add_f32_e32 v40, v40, v200
	v_add_f32_e32 v41, v41, v201
	v_add_f32_e32 v42, v42, v202
	v_add_f32_e32 v43, v43, v203
	v_mul_f32_e32 v40, 0xbfb8aa3b, v40
	v_mul_f32_e32 v41, 0xbfb8aa3b, v41
	v_mul_f32_e32 v42, 0xbfb8aa3b, v42
	v_mul_f32_e32 v43, 0xbfb8aa3b, v43
	v_exp_f32_e32 v40, v40
	v_exp_f32_e32 v41, v41
	v_exp_f32_e32 v42, v42
	v_exp_f32_e32 v43, v43
	s_nop 0
	v_add_f32_e32 v40, 1.0, v40
	v_add_f32_e32 v41, 1.0, v41
	v_add_f32_e32 v42, 1.0, v42
	v_add_f32_e32 v43, 1.0, v43
	v_rcp_f32_e32 v40, v40
	v_rcp_f32_e32 v41, v41
	v_rcp_f32_e32 v42, v42
	v_rcp_f32_e32 v43, v43
	s_nop 0
	v_cvt_pk_bf16_f32 v148, v40, v41
	v_cvt_pk_bf16_f32 v149, v42, v43
	ds_write_b64 v236, v[148:149] offset:4672
	v_add_f32_e32 v44, v44, v204
	v_add_f32_e32 v45, v45, v205
	v_add_f32_e32 v46, v46, v206
	v_add_f32_e32 v47, v47, v207
	v_mul_f32_e32 v44, 0xbfb8aa3b, v44
	v_mul_f32_e32 v45, 0xbfb8aa3b, v45
	v_mul_f32_e32 v46, 0xbfb8aa3b, v46
	v_mul_f32_e32 v47, 0xbfb8aa3b, v47
	v_exp_f32_e32 v44, v44
	v_exp_f32_e32 v45, v45
	v_exp_f32_e32 v46, v46
	v_exp_f32_e32 v47, v47
	s_nop 0
	v_add_f32_e32 v44, 1.0, v44
	v_add_f32_e32 v45, 1.0, v45
	v_add_f32_e32 v46, 1.0, v46
	v_add_f32_e32 v47, 1.0, v47
	v_rcp_f32_e32 v44, v44
	v_rcp_f32_e32 v45, v45
	v_rcp_f32_e32 v46, v46
	v_rcp_f32_e32 v47, v47
	s_nop 0
	v_cvt_pk_bf16_f32 v150, v44, v45
	v_cvt_pk_bf16_f32 v151, v46, v47
	ds_write_b64 v236, v[150:151] offset:4704
	v_add_f32_e32 v48, v48, v192
	v_add_f32_e32 v49, v49, v193
	v_add_f32_e32 v50, v50, v194
	v_add_f32_e32 v51, v51, v195
	v_mul_f32_e32 v48, 0xbfb8aa3b, v48
	v_mul_f32_e32 v49, 0xbfb8aa3b, v49
	v_mul_f32_e32 v50, 0xbfb8aa3b, v50
	v_mul_f32_e32 v51, 0xbfb8aa3b, v51
	v_exp_f32_e32 v48, v48
	v_exp_f32_e32 v49, v49
	v_exp_f32_e32 v50, v50
	v_exp_f32_e32 v51, v51
	s_nop 0
	v_add_f32_e32 v48, 1.0, v48
	v_add_f32_e32 v49, 1.0, v49
	v_add_f32_e32 v50, 1.0, v50
	v_add_f32_e32 v51, 1.0, v51
	v_rcp_f32_e32 v48, v48
	v_rcp_f32_e32 v49, v49
	v_rcp_f32_e32 v50, v50
	v_rcp_f32_e32 v51, v51
	s_nop 0
	v_cvt_pk_bf16_f32 v152, v48, v49
	v_cvt_pk_bf16_f32 v153, v50, v51
	ds_write_b64 v236, v[152:153] offset:6912
	v_add_f32_e32 v52, v52, v196
	v_add_f32_e32 v53, v53, v197
	v_add_f32_e32 v54, v54, v198
	v_add_f32_e32 v55, v55, v199
	v_mul_f32_e32 v52, 0xbfb8aa3b, v52
	v_mul_f32_e32 v53, 0xbfb8aa3b, v53
	v_mul_f32_e32 v54, 0xbfb8aa3b, v54
	v_mul_f32_e32 v55, 0xbfb8aa3b, v55
	v_exp_f32_e32 v52, v52
	v_exp_f32_e32 v53, v53
	v_exp_f32_e32 v54, v54
	v_exp_f32_e32 v55, v55
	s_nop 0
	v_add_f32_e32 v52, 1.0, v52
	v_add_f32_e32 v53, 1.0, v53
	v_add_f32_e32 v54, 1.0, v54
	v_add_f32_e32 v55, 1.0, v55
	v_rcp_f32_e32 v52, v52
	v_rcp_f32_e32 v53, v53
	v_rcp_f32_e32 v54, v54
	v_rcp_f32_e32 v55, v55
	s_nop 0
	v_cvt_pk_bf16_f32 v154, v52, v53
	v_cvt_pk_bf16_f32 v155, v54, v55
	ds_write_b64 v236, v[154:155] offset:6944
	v_add_f32_e32 v56, v56, v200
	v_add_f32_e32 v57, v57, v201
	v_add_f32_e32 v58, v58, v202
	v_add_f32_e32 v59, v59, v203
	v_mul_f32_e32 v56, 0xbfb8aa3b, v56
	v_mul_f32_e32 v57, 0xbfb8aa3b, v57
	v_mul_f32_e32 v58, 0xbfb8aa3b, v58
	v_mul_f32_e32 v59, 0xbfb8aa3b, v59
	v_exp_f32_e32 v56, v56
	v_exp_f32_e32 v57, v57
	v_exp_f32_e32 v58, v58
	v_exp_f32_e32 v59, v59
	s_nop 0
	v_add_f32_e32 v56, 1.0, v56
	v_add_f32_e32 v57, 1.0, v57
	v_add_f32_e32 v58, 1.0, v58
	v_add_f32_e32 v59, 1.0, v59
	v_rcp_f32_e32 v56, v56
	v_rcp_f32_e32 v57, v57
	v_rcp_f32_e32 v58, v58
	v_rcp_f32_e32 v59, v59
	s_nop 0
	v_cvt_pk_bf16_f32 v156, v56, v57
	v_cvt_pk_bf16_f32 v157, v58, v59
	ds_write_b64 v236, v[156:157] offset:6976
	v_add_f32_e32 v60, v60, v204
	v_add_f32_e32 v61, v61, v205
	v_add_f32_e32 v62, v62, v206
	v_add_f32_e32 v63, v63, v207
	v_mul_f32_e32 v60, 0xbfb8aa3b, v60
	v_mul_f32_e32 v61, 0xbfb8aa3b, v61
	v_mul_f32_e32 v62, 0xbfb8aa3b, v62
	v_mul_f32_e32 v63, 0xbfb8aa3b, v63
	v_exp_f32_e32 v60, v60
	v_exp_f32_e32 v61, v61
	v_exp_f32_e32 v62, v62
	v_exp_f32_e32 v63, v63
	s_nop 0
; template <class Epi>
; DI void gemm_tile(char* smem, const bf16_t* __restrict__ A0, int lda0, int ksplit, const bf16_t* __restrict__ A1, int lda1,
;                   const bf16_t* __restrict__ Bt, int K, int row0, int col0, const Epi& epi, int tid) {
;     ...
; #pragma unroll
;   for (int m = 0; m < 8; ++m)
; #pragma unroll
;     for (int n = 0; n < 4; ++n) epi(row0 + wr * 128 + m * 16 + fr, col0 + wc * 64 + n * 16 + fq * 4, acc[m][n]);
	v_add_f32_e32 v60, 1.0, v60
	v_add_f32_e32 v61, 1.0, v61
	v_add_f32_e32 v62, 1.0, v62
	v_add_f32_e32 v63, 1.0, v63
	v_rcp_f32_e32 v60, v60
	v_rcp_f32_e32 v61, v61
	v_rcp_f32_e32 v62, v62
	v_rcp_f32_e32 v63, v63
	s_nop 0
	v_cvt_pk_bf16_f32 v158, v60, v61
	v_cvt_pk_bf16_f32 v159, v62, v63
	ds_write_b64 v236, v[158:159] offset:7008
	v_add_f32_e32 v64, v64, v192
	v_add_f32_e32 v65, v65, v193
	v_add_f32_e32 v66, v66, v194
	v_add_f32_e32 v67, v67, v195
	v_mul_f32_e32 v64, 0xbfb8aa3b, v64
	v_mul_f32_e32 v65, 0xbfb8aa3b, v65
	v_mul_f32_e32 v66, 0xbfb8aa3b, v66
	v_mul_f32_e32 v67, 0xbfb8aa3b, v67
	v_exp_f32_e32 v64, v64
	v_exp_f32_e32 v65, v65
	v_exp_f32_e32 v66, v66
	v_exp_f32_e32 v67, v67
	s_nop 0
	v_add_f32_e32 v64, 1.0, v64
	v_add_f32_e32 v65, 1.0, v65
	v_add_f32_e32 v66, 1.0, v66
	v_add_f32_e32 v67, 1.0, v67
	v_rcp_f32_e32 v64, v64
	v_rcp_f32_e32 v65, v65
	v_rcp_f32_e32 v66, v66
	v_rcp_f32_e32 v67, v67
	s_nop 0
	v_cvt_pk_bf16_f32 v128, v64, v65
	v_cvt_pk_bf16_f32 v129, v66, v67
	ds_write_b64 v236, v[128:129] offset:9216
	v_add_f32_e32 v68, v68, v196
	v_add_f32_e32 v69, v69, v197
	v_add_f32_e32 v70, v70, v198
	v_add_f32_e32 v71, v71, v199
	v_mul_f32_e32 v68, 0xbfb8aa3b, v68
	v_mul_f32_e32 v69, 0xbfb8aa3b, v69
	v_mul_f32_e32 v70, 0xbfb8aa3b, v70
	v_mul_f32_e32 v71, 0xbfb8aa3b, v71
	v_exp_f32_e32 v68, v68
	v_exp_f32_e32 v69, v69
	v_exp_f32_e32 v70, v70
	v_exp_f32_e32 v71, v71
	s_nop 0
	v_add_f32_e32 v68, 1.0, v68
	v_add_f32_e32 v69, 1.0, v69
	v_add_f32_e32 v70, 1.0, v70
	v_add_f32_e32 v71, 1.0, v71
	v_rcp_f32_e32 v68, v68
	v_rcp_f32_e32 v69, v69
	v_rcp_f32_e32 v70, v70
	v_rcp_f32_e32 v71, v71
	s_nop 0
	v_cvt_pk_bf16_f32 v130, v68, v69
	v_cvt_pk_bf16_f32 v131, v70, v71
	ds_write_b64 v236, v[130:131] offset:9248
	v_add_f32_e32 v72, v72, v200
	v_add_f32_e32 v73, v73, v201
	v_add_f32_e32 v74, v74, v202
	v_add_f32_e32 v75, v75, v203
	v_mul_f32_e32 v72, 0xbfb8aa3b, v72
	v_mul_f32_e32 v73, 0xbfb8aa3b, v73
	v_mul_f32_e32 v74, 0xbfb8aa3b, v74
	v_mul_f32_e32 v75, 0xbfb8aa3b, v75
	v_exp_f32_e32 v72, v72
	v_exp_f32_e32 v73, v73
	v_exp_f32_e32 v74, v74
	v_exp_f32_e32 v75, v75
	s_nop 0
	v_add_f32_e32 v72, 1.0, v72
	v_add_f32_e32 v73, 1.0, v73
	v_add_f32_e32 v74, 1.0, v74
	v_add_f32_e32 v75, 1.0, v75
	v_rcp_f32_e32 v72, v72
	v_rcp_f32_e32 v73, v73
	v_rcp_f32_e32 v74, v74
	v_rcp_f32_e32 v75, v75
	s_nop 0
	v_cvt_pk_bf16_f32 v132, v72, v73
	v_cvt_pk_bf16_f32 v133, v74, v75
	ds_write_b64 v236, v[132:133] offset:9280
	v_add_f32_e32 v76, v76, v204
	v_add_f32_e32 v77, v77, v205
	v_add_f32_e32 v78, v78, v206
	v_add_f32_e32 v79, v79, v207
	v_mul_f32_e32 v76, 0xbfb8aa3b, v76
	v_mul_f32_e32 v77, 0xbfb8aa3b, v77
	v_mul_f32_e32 v78, 0xbfb8aa3b, v78
	v_mul_f32_e32 v79, 0xbfb8aa3b, v79
	v_exp_f32_e32 v76, v76
	v_exp_f32_e32 v77, v77
	v_exp_f32_e32 v78, v78
	v_exp_f32_e32 v79, v79
	s_nop 0
	v_add_f32_e32 v76, 1.0, v76
	v_add_f32_e32 v77, 1.0, v77
	v_add_f32_e32 v78, 1.0, v78
	v_add_f32_e32 v79, 1.0, v79
	v_rcp_f32_e32 v76, v76
	v_rcp_f32_e32 v77, v77
	v_rcp_f32_e32 v78, v78
	v_rcp_f32_e32 v79, v79
	s_nop 0
	v_cvt_pk_bf16_f32 v134, v76, v77
	v_cvt_pk_bf16_f32 v135, v78, v79
	ds_write_b64 v236, v[134:135] offset:9312
	v_add_f32_e32 v80, v80, v192
	v_add_f32_e32 v81, v81, v193
	v_add_f32_e32 v82, v82, v194
	v_add_f32_e32 v83, v83, v195
	v_mul_f32_e32 v80, 0xbfb8aa3b, v80
	v_mul_f32_e32 v81, 0xbfb8aa3b, v81
	v_mul_f32_e32 v82, 0xbfb8aa3b, v82
	v_mul_f32_e32 v83, 0xbfb8aa3b, v83
	v_exp_f32_e32 v80, v80
	v_exp_f32_e32 v81, v81
	v_exp_f32_e32 v82, v82
	v_exp_f32_e32 v83, v83
	s_nop 0
	v_add_f32_e32 v80, 1.0, v80
	v_add_f32_e32 v81, 1.0, v81
	v_add_f32_e32 v82, 1.0, v82
	v_add_f32_e32 v83, 1.0, v83
	v_rcp_f32_e32 v80, v80
	v_rcp_f32_e32 v81, v81
	v_rcp_f32_e32 v82, v82
	v_rcp_f32_e32 v83, v83
	s_nop 0
	v_cvt_pk_bf16_f32 v136, v80, v81
	v_cvt_pk_bf16_f32 v137, v82, v83
	ds_write_b64 v236, v[136:137] offset:11520
	v_add_f32_e32 v84, v84, v196
	v_add_f32_e32 v85, v85, v197
	v_add_f32_e32 v86, v86, v198
	v_add_f32_e32 v87, v87, v199
	v_mul_f32_e32 v84, 0xbfb8aa3b, v84
	v_mul_f32_e32 v85, 0xbfb8aa3b, v85
	v_mul_f32_e32 v86, 0xbfb8aa3b, v86
	v_mul_f32_e32 v87, 0xbfb8aa3b, v87
	v_exp_f32_e32 v84, v84
	v_exp_f32_e32 v85, v85
	v_exp_f32_e32 v86, v86
	v_exp_f32_e32 v87, v87
	s_nop 0
	v_add_f32_e32 v84, 1.0, v84
	v_add_f32_e32 v85, 1.0, v85
	v_add_f32_e32 v86, 1.0, v86
	v_add_f32_e32 v87, 1.0, v87
	v_rcp_f32_e32 v84, v84
	v_rcp_f32_e32 v85, v85
	v_rcp_f32_e32 v86, v86
	v_rcp_f32_e32 v87, v87
	s_nop 0
	v_cvt_pk_bf16_f32 v138, v84, v85
	v_cvt_pk_bf16_f32 v139, v86, v87
	ds_write_b64 v236, v[138:139] offset:11552
	v_add_f32_e32 v88, v88, v200
	v_add_f32_e32 v89, v89, v201
	v_add_f32_e32 v90, v90, v202
	v_add_f32_e32 v91, v91, v203
	v_mul_f32_e32 v88, 0xbfb8aa3b, v88
	v_mul_f32_e32 v89, 0xbfb8aa3b, v89
	v_mul_f32_e32 v90, 0xbfb8aa3b, v90
	v_mul_f32_e32 v91, 0xbfb8aa3b, v91
	v_exp_f32_e32 v88, v88
	v_exp_f32_e32 v89, v89
	v_exp_f32_e32 v90, v90
	v_exp_f32_e32 v91, v91
	s_nop 0
	v_add_f32_e32 v88, 1.0, v88
	v_add_f32_e32 v89, 1.0, v89
	v_add_f32_e32 v90, 1.0, v90
	v_add_f32_e32 v91, 1.0, v91
	v_rcp_f32_e32 v88, v88
	v_rcp_f32_e32 v89, v89
	v_rcp_f32_e32 v90, v90
	v_rcp_f32_e32 v91, v91
	s_nop 0
	v_cvt_pk_bf16_f32 v140, v88, v89
	v_cvt_pk_bf16_f32 v141, v90, v91
	ds_write_b64 v236, v[140:141] offset:11584
	v_add_f32_e32 v92, v92, v204
	v_add_f32_e32 v93, v93, v205
	v_add_f32_e32 v94, v94, v206
	v_add_f32_e32 v95, v95, v207
	v_mul_f32_e32 v92, 0xbfb8aa3b, v92
	v_mul_f32_e32 v93, 0xbfb8aa3b, v93
	v_mul_f32_e32 v94, 0xbfb8aa3b, v94
	v_mul_f32_e32 v95, 0xbfb8aa3b, v95
	v_exp_f32_e32 v92, v92
	v_exp_f32_e32 v93, v93
	v_exp_f32_e32 v94, v94
	v_exp_f32_e32 v95, v95
	s_nop 0
	v_add_f32_e32 v92, 1.0, v92
; template <class Epi>
; DI void gemm_tile(char* smem, const bf16_t* __restrict__ A0, int lda0, int ksplit, const bf16_t* __restrict__ A1, int lda1,
;                   const bf16_t* __restrict__ Bt, int K, int row0, int col0, const Epi& epi, int tid) {
;     ...
; #pragma unroll
;   for (int m = 0; m < 8; ++m)
; #pragma unroll
;     for (int n = 0; n < 4; ++n) epi(row0 + wr * 128 + m * 16 + fr, col0 + wc * 64 + n * 16 + fq * 4, acc[m][n]);
	v_add_f32_e32 v93, 1.0, v93
	v_add_f32_e32 v94, 1.0, v94
	v_add_f32_e32 v95, 1.0, v95
	v_rcp_f32_e32 v92, v92
	v_rcp_f32_e32 v93, v93
	v_rcp_f32_e32 v94, v94
	v_rcp_f32_e32 v95, v95
	s_nop 0
	v_cvt_pk_bf16_f32 v142, v92, v93
	v_cvt_pk_bf16_f32 v143, v94, v95
	ds_write_b64 v236, v[142:143] offset:11616
	v_add_f32_e32 v96, v96, v192
	v_add_f32_e32 v97, v97, v193
	v_add_f32_e32 v98, v98, v194
	v_add_f32_e32 v99, v99, v195
	v_mul_f32_e32 v96, 0xbfb8aa3b, v96
	v_mul_f32_e32 v97, 0xbfb8aa3b, v97
	v_mul_f32_e32 v98, 0xbfb8aa3b, v98
	v_mul_f32_e32 v99, 0xbfb8aa3b, v99
	v_exp_f32_e32 v96, v96
	v_exp_f32_e32 v97, v97
	v_exp_f32_e32 v98, v98
	v_exp_f32_e32 v99, v99
	s_nop 0
	v_add_f32_e32 v96, 1.0, v96
	v_add_f32_e32 v97, 1.0, v97
	v_add_f32_e32 v98, 1.0, v98
	v_add_f32_e32 v99, 1.0, v99
	v_rcp_f32_e32 v96, v96
	v_rcp_f32_e32 v97, v97
	v_rcp_f32_e32 v98, v98
	v_rcp_f32_e32 v99, v99
	s_nop 0
	v_cvt_pk_bf16_f32 v144, v96, v97
	v_cvt_pk_bf16_f32 v145, v98, v99
	ds_write_b64 v236, v[144:145] offset:13824
	v_add_f32_e32 v100, v100, v196
	v_add_f32_e32 v101, v101, v197
	v_add_f32_e32 v102, v102, v198
	v_add_f32_e32 v103, v103, v199
	v_mul_f32_e32 v100, 0xbfb8aa3b, v100
	v_mul_f32_e32 v101, 0xbfb8aa3b, v101
	v_mul_f32_e32 v102, 0xbfb8aa3b, v102
	v_mul_f32_e32 v103, 0xbfb8aa3b, v103
	v_exp_f32_e32 v100, v100
	v_exp_f32_e32 v101, v101
	v_exp_f32_e32 v102, v102
	v_exp_f32_e32 v103, v103
	s_nop 0
	v_add_f32_e32 v100, 1.0, v100
	v_add_f32_e32 v101, 1.0, v101
	v_add_f32_e32 v102, 1.0, v102
	v_add_f32_e32 v103, 1.0, v103
	v_rcp_f32_e32 v100, v100
	v_rcp_f32_e32 v101, v101
	v_rcp_f32_e32 v102, v102
	v_rcp_f32_e32 v103, v103
	s_nop 0
	v_cvt_pk_bf16_f32 v146, v100, v101
	v_cvt_pk_bf16_f32 v147, v102, v103
	ds_write_b64 v236, v[146:147] offset:13856
	v_add_f32_e32 v104, v104, v200
	v_add_f32_e32 v105, v105, v201
	v_add_f32_e32 v106, v106, v202
	v_add_f32_e32 v107, v107, v203
	v_mul_f32_e32 v104, 0xbfb8aa3b, v104
	v_mul_f32_e32 v105, 0xbfb8aa3b, v105
	v_mul_f32_e32 v106, 0xbfb8aa3b, v106
	v_mul_f32_e32 v107, 0xbfb8aa3b, v107
	v_exp_f32_e32 v104, v104
	v_exp_f32_e32 v105, v105
	v_exp_f32_e32 v106, v106
	v_exp_f32_e32 v107, v107
	s_nop 0
	v_add_f32_e32 v104, 1.0, v104
	v_add_f32_e32 v105, 1.0, v105
	v_add_f32_e32 v106, 1.0, v106
	v_add_f32_e32 v107, 1.0, v107
	v_rcp_f32_e32 v104, v104
	v_rcp_f32_e32 v105, v105
	v_rcp_f32_e32 v106, v106
	v_rcp_f32_e32 v107, v107
	s_nop 0
	v_cvt_pk_bf16_f32 v148, v104, v105
	v_cvt_pk_bf16_f32 v149, v106, v107
	ds_write_b64 v236, v[148:149] offset:13888
	v_add_f32_e32 v108, v108, v204
	v_add_f32_e32 v109, v109, v205
	v_add_f32_e32 v110, v110, v206
	v_add_f32_e32 v111, v111, v207
	v_mul_f32_e32 v108, 0xbfb8aa3b, v108
	v_mul_f32_e32 v109, 0xbfb8aa3b, v109
	v_mul_f32_e32 v110, 0xbfb8aa3b, v110
	v_mul_f32_e32 v111, 0xbfb8aa3b, v111
	v_exp_f32_e32 v108, v108
	v_exp_f32_e32 v109, v109
	v_exp_f32_e32 v110, v110
	v_exp_f32_e32 v111, v111
	s_nop 0
	v_add_f32_e32 v108, 1.0, v108
	v_add_f32_e32 v109, 1.0, v109
	v_add_f32_e32 v110, 1.0, v110
	v_add_f32_e32 v111, 1.0, v111
	v_rcp_f32_e32 v108, v108
	v_rcp_f32_e32 v109, v109
	v_rcp_f32_e32 v110, v110
	v_rcp_f32_e32 v111, v111
	s_nop 0
	v_cvt_pk_bf16_f32 v150, v108, v109
	v_cvt_pk_bf16_f32 v151, v110, v111
	ds_write_b64 v236, v[150:151] offset:13920
	v_add_f32_e32 v112, v112, v192
	v_add_f32_e32 v113, v113, v193
	v_add_f32_e32 v114, v114, v194
	v_add_f32_e32 v115, v115, v195
	v_mul_f32_e32 v112, 0xbfb8aa3b, v112
	v_mul_f32_e32 v113, 0xbfb8aa3b, v113
	v_mul_f32_e32 v114, 0xbfb8aa3b, v114
	v_mul_f32_e32 v115, 0xbfb8aa3b, v115
	v_exp_f32_e32 v112, v112
	v_exp_f32_e32 v113, v113
	v_exp_f32_e32 v114, v114
	v_exp_f32_e32 v115, v115
	s_nop 0
	v_add_f32_e32 v112, 1.0, v112
	v_add_f32_e32 v113, 1.0, v113
	v_add_f32_e32 v114, 1.0, v114
	v_add_f32_e32 v115, 1.0, v115
	v_rcp_f32_e32 v112, v112
	v_rcp_f32_e32 v113, v113
	v_rcp_f32_e32 v114, v114
	v_rcp_f32_e32 v115, v115
	s_nop 0
	v_cvt_pk_bf16_f32 v152, v112, v113
	v_cvt_pk_bf16_f32 v153, v114, v115
	ds_write_b64 v236, v[152:153] offset:16128
	v_add_f32_e32 v116, v116, v196
	v_add_f32_e32 v117, v117, v197
	v_add_f32_e32 v118, v118, v198
	v_add_f32_e32 v119, v119, v199
	v_mul_f32_e32 v116, 0xbfb8aa3b, v116
	v_mul_f32_e32 v117, 0xbfb8aa3b, v117
	v_mul_f32_e32 v118, 0xbfb8aa3b, v118
	v_mul_f32_e32 v119, 0xbfb8aa3b, v119
	v_exp_f32_e32 v116, v116
	v_exp_f32_e32 v117, v117
	v_exp_f32_e32 v118, v118
	v_exp_f32_e32 v119, v119
	s_nop 0
	v_add_f32_e32 v116, 1.0, v116
	v_add_f32_e32 v117, 1.0, v117
	v_add_f32_e32 v118, 1.0, v118
	v_add_f32_e32 v119, 1.0, v119
	v_rcp_f32_e32 v116, v116
	v_rcp_f32_e32 v117, v117
	v_rcp_f32_e32 v118, v118
	v_rcp_f32_e32 v119, v119
	s_nop 0
	v_cvt_pk_bf16_f32 v154, v116, v117
	v_cvt_pk_bf16_f32 v155, v118, v119
	ds_write_b64 v236, v[154:155] offset:16160
	v_add_f32_e32 v120, v120, v200
	v_add_f32_e32 v121, v121, v201
	v_add_f32_e32 v122, v122, v202
	v_add_f32_e32 v123, v123, v203
	v_mul_f32_e32 v120, 0xbfb8aa3b, v120
	v_mul_f32_e32 v121, 0xbfb8aa3b, v121
	v_mul_f32_e32 v122, 0xbfb8aa3b, v122
	v_mul_f32_e32 v123, 0xbfb8aa3b, v123
	v_exp_f32_e32 v120, v120
	v_exp_f32_e32 v121, v121
	v_exp_f32_e32 v122, v122
	v_exp_f32_e32 v123, v123
	s_nop 0
	v_add_f32_e32 v120, 1.0, v120
	v_add_f32_e32 v121, 1.0, v121
	v_add_f32_e32 v122, 1.0, v122
	v_add_f32_e32 v123, 1.0, v123
	v_rcp_f32_e32 v120, v120
	v_rcp_f32_e32 v121, v121
	v_rcp_f32_e32 v122, v122
	v_rcp_f32_e32 v123, v123
	s_nop 0
	v_cvt_pk_bf16_f32 v156, v120, v121
	v_cvt_pk_bf16_f32 v157, v122, v123
	ds_write_b64 v236, v[156:157] offset:16192
	v_add_f32_e32 v124, v124, v204
	v_add_f32_e32 v125, v125, v205
	v_add_f32_e32 v126, v126, v206
	v_add_f32_e32 v127, v127, v207
	v_mul_f32_e32 v124, 0xbfb8aa3b, v124
	v_mul_f32_e32 v125, 0xbfb8aa3b, v125
	v_mul_f32_e32 v126, 0xbfb8aa3b, v126
	v_mul_f32_e32 v127, 0xbfb8aa3b, v127
	v_exp_f32_e32 v124, v124
	v_exp_f32_e32 v125, v125
	v_exp_f32_e32 v126, v126
	v_exp_f32_e32 v127, v127
	s_nop 0
	v_add_f32_e32 v124, 1.0, v124
	v_add_f32_e32 v125, 1.0, v125
	v_add_f32_e32 v126, 1.0, v126
	v_add_f32_e32 v127, 1.0, v127
	v_rcp_f32_e32 v124, v124
	v_rcp_f32_e32 v125, v125
	v_rcp_f32_e32 v126, v126
	v_rcp_f32_e32 v127, v127
	s_nop 0
	v_cvt_pk_bf16_f32 v158, v124, v125
	v_cvt_pk_bf16_f32 v159, v126, v127
	ds_write_b64 v236, v[158:159] offset:16224
	s_waitcnt lgkmcnt(0)
; template <class Epi>
; DI void gemm_phase(char* smem, const bf16_t* A0, int lda0, int ksplit, const bf16_t* A1, int lda1, const bf16_t* Bt, int K, int nN, const Epi& epi, int tid) {
;   const int G = gridDim.x;
;   if ((G & 7) == 0) {
;     const int x = blockIdx.x & 7, l = blockIdx.x >> 3, L = G >> 3, per = 8 * nN, tot = 2 * per;
;     for (int q = l; q < tot; q += L) { const int rgl = q / per, rem = q % per, ct = rem >> 3, rt = (x * 2 + rgl) * 8 + (rem & 7);
;       gemm_tile(smem, A0, lda0, ksplit, A1, lda1, Bt, K, rt * 256, ct * 128, epi, tid); }
; DI void phase_rw_small_gemms(const Ctx& c, char* smem) {
;     ...
;   gemm_phase(smem, sm + 64, 256, 1 << 30, sm, 256, A2, 64, 4, EpiSmall{1, p.rw_a0, Ab}, tid);
;   gemm_phase(smem, sm + 128, 256, 1 << 30, sm, 256, G2, 128, 4, EpiSmall{2, p.rw_a0, G}, tid);
	ds_read_b128 v[128:131], v237
	ds_read_b128 v[132:135], v237 offset:1152
	ds_read_b128 v[136:139], v237 offset:2304
	ds_read_b128 v[140:143], v237 offset:3456
	ds_read_b128 v[144:147], v237 offset:4608
	ds_read_b128 v[148:151], v237 offset:5760
	ds_read_b128 v[152:155], v237 offset:6912
	ds_read_b128 v[156:159], v237 offset:8064
	ds_read_b128 v[160:163], v237 offset:9216
	ds_read_b128 v[164:167], v237 offset:10368
	ds_read_b128 v[168:171], v237 offset:11520
	ds_read_b128 v[172:175], v237 offset:12672
	ds_read_b128 v[176:179], v237 offset:13824
	ds_read_b128 v[180:183], v237 offset:14976
	ds_read_b128 v[184:187], v237 offset:16128
	ds_read_b128 v[188:191], v237 offset:17280
	s_waitcnt lgkmcnt(15)
	global_store_dwordx4 v238, v[128:131], s[4:5]
	s_add_u32 s4, s4, 0x2000
	s_addc_u32 s5, s5, 0
	s_waitcnt lgkmcnt(14)
	global_store_dwordx4 v238, v[132:135], s[4:5]
	s_add_u32 s4, s4, 0x2000
	s_addc_u32 s5, s5, 0
	s_waitcnt lgkmcnt(13)
	global_store_dwordx4 v238, v[136:139], s[4:5]
	s_add_u32 s4, s4, 0x2000
	s_addc_u32 s5, s5, 0
	s_waitcnt lgkmcnt(12)
	global_store_dwordx4 v238, v[140:143], s[4:5]
	s_add_u32 s4, s4, 0x2000
	s_addc_u32 s5, s5, 0
	s_waitcnt lgkmcnt(11)
	global_store_dwordx4 v238, v[144:147], s[4:5]
	s_add_u32 s4, s4, 0x2000
	s_addc_u32 s5, s5, 0
	s_waitcnt lgkmcnt(10)
	global_store_dwordx4 v238, v[148:151], s[4:5]
	s_add_u32 s4, s4, 0x2000
	s_addc_u32 s5, s5, 0
	s_waitcnt lgkmcnt(9)
	global_store_dwordx4 v238, v[152:155], s[4:5]
	s_add_u32 s4, s4, 0x2000
	s_addc_u32 s5, s5, 0
	s_waitcnt lgkmcnt(8)
	global_store_dwordx4 v238, v[156:159], s[4:5]
	s_add_u32 s4, s4, 0x2000
	s_addc_u32 s5, s5, 0
	s_waitcnt lgkmcnt(7)
	global_store_dwordx4 v238, v[160:163], s[4:5]
	s_add_u32 s4, s4, 0x2000
	s_addc_u32 s5, s5, 0
	s_waitcnt lgkmcnt(6)
	global_store_dwordx4 v238, v[164:167], s[4:5]
	s_add_u32 s4, s4, 0x2000
	s_addc_u32 s5, s5, 0
	s_waitcnt lgkmcnt(5)
	global_store_dwordx4 v238, v[168:171], s[4:5]
	s_add_u32 s4, s4, 0x2000
	s_addc_u32 s5, s5, 0
	s_waitcnt lgkmcnt(4)
	global_store_dwordx4 v238, v[172:175], s[4:5]
	s_add_u32 s4, s4, 0x2000
	s_addc_u32 s5, s5, 0
	s_waitcnt lgkmcnt(3)
	global_store_dwordx4 v238, v[176:179], s[4:5]
	s_add_u32 s4, s4, 0x2000
	s_addc_u32 s5, s5, 0
	s_waitcnt lgkmcnt(2)
	global_store_dwordx4 v238, v[180:183], s[4:5]
	s_add_u32 s4, s4, 0x2000
	s_addc_u32 s5, s5, 0
	s_waitcnt lgkmcnt(1)
	global_store_dwordx4 v238, v[184:187], s[4:5]
	s_add_u32 s4, s4, 0x2000
	s_addc_u32 s5, s5, 0
	s_waitcnt lgkmcnt(0)
	global_store_dwordx4 v238, v[188:191], s[4:5]
	s_nop 1
	s_add_u32 s15, s15, 64
	s_branch .Lg3c_tile
.Lg3c_done:
	v_mbcnt_lo_u32_b32 v194, -1, 0
	v_mbcnt_hi_u32_b32 v136, -1, v194
	v_mbcnt_lo_u32_b32 v240, -1, 0
	v_mbcnt_hi_u32_b32 v240, -1, v240
	s_lshr_b32 s27, s72, 6
	s_lshl_b32 s100, s27, 10
	v_and_b32_e32 v241, 15, v240
	v_lshrrev_b32_e32 v242, 4, v240
	v_bfe_u32 v243, v240, 3, 1
	v_mul_u32_u24_e32 v243, 3, v243
	v_xor_b32_e32 v243, v242, v243
	v_lshlrev_b32_e32 v243, 4, v243
	v_lshl_add_u32 v243, v241, 6, v243
	s_lshr_b32 s26, s27, 1
	s_lshl_b32 s26, s26, 13
	v_add_u32_e32 v230, s26, v243
	s_and_b32 s26, s27, 1
	s_lshl_b32 s26, s26, 12
	s_add_u32 s26, s26, 16384
	v_add_u32_e32 v231, s26, v243
	s_lshr_b32 s26, s27, 1
	s_lshl_b32 s26, s26, 7
	v_add_u32_e32 v244, s26, v241
	s_and_b32 s26, s27, 1
	s_lshl_b32 s26, s26, 6
	v_lshl_add_u32 v245, v242, 2, s26
	v_lshlrev_b32_e32 v235, 2, v245
	s_mul_i32 s26, s27, 18432
	v_mul_u32_u24_e32 v246, 144, v241
	v_lshl_add_u32 v246, v242, 3, v246
	v_add_u32_e32 v236, s26, v246
	v_lshrrev_b32_e32 v246, 3, v240
	v_mul_u32_u24_e32 v246, 144, v246
	v_and_b32_e32 v247, 7, v240
	v_lshl_add_u32 v246, v247, 4, v246
	v_add_u32_e32 v237, s26, v246
	s_lshr_b32 s26, s27, 1
	s_lshl_b32 s26, s26, 7
	v_lshrrev_b32_e32 v246, 3, v240
	v_add_u32_e32 v246, s26, v246
	s_and_b32 s26, s27, 1
	s_lshl_b32 s26, s26, 6
	v_lshl_add_u32 v248, v247, 3, s26
	s_movk_i32 s26, 1024
	v_mul_lo_u32 v247, v246, s26
	v_lshl_add_u32 v238, v248, 1, v247
	v_lshrrev_b32_e32 v241, 2, v240
	s_lshl_b32 s26, s27, 4
	v_add_u32_e32 v241, s26, v241
	v_bfe_u32 v242, v240, 5, 1
	v_mul_u32_u24_e32 v242, 3, v242
	v_and_b32_e32 v243, 3, v240
	v_xor_b32_e32 v243, v243, v242
	v_lshlrev_b32_e32 v243, 4, v243
	s_mov_b32 s26, 512
	v_mad_u32_u24 v224, v241, s26, v243
	v_add_u32_e32 v225, 0x8000, v224
	v_add_u32_e32 v226, 0x10000, v224
	v_add_u32_e32 v227, 0x18000, v224
	s_mov_b32 s26, 256
	v_mad_u32_u24 v228, v241, s26, v243
	v_add_u32_e32 v229, 0x4000, v228
	s_lshr_b32 s15, s96, 3
	s_and_b32 s101, s96, 7
	s_lshl_b32 s101, s101, 1
	s_waitcnt lgkmcnt(0)
; #define LWRITE(S, buf) do { bf16_t* sA_ = sbase + (buf) * BUF; bf16_t* sB_ = sA_ + 256 * PITCH; \
;     _Pragma("unroll") for (int i_ = 0; i_ < 4; ++i_) *(u32x4*)(sA_ + (sr + i_ * 64) * PITCH + scv * 8) = ra[S][i_]; \
;     _Pragma("unroll") for (int i_ = 0; i_ < 2; ++i_) *(u32x4*)(sB_ + (sr + i_ * 64) * PITCH + scv * 8) = rb[S][i_]; } while (0)
; template <class Epi>
; DI void gemm_tile(char* smem, const bf16_t* __restrict__ A0, int lda0, int ksplit, const bf16_t* __restrict__ A1, int lda1,
;                   const bf16_t* __restrict__ Bt, int K, int row0, int col0, const Epi& epi, int tid) {
;   constexpr int BK = 32, PITCH = 40, BUF = (256 + 128) * PITCH;
;   bf16_t* sbase = (bf16_t*)smem;
;   const int lane = tid & 63, wid = tid >> 6, wr = wid >> 1, wc = wid & 1, fr = lane & 15, fq = lane >> 4;
;   f32x4 acc[8][4];
; #pragma unroll
;   for (int m = 0; m < 8; ++m)
; #pragma unroll
;     for (int n = 0; n < 4; ++n) acc[m][n] = (f32x4){0.f, 0.f, 0.f, 0.f};
;   u32x4 ra[2][4], rb[2][2];
;   const int nk = K / BK;
;   const int sr = tid >> 2, scv = tid & 3;
;     ...
;   __syncthreads();
;   {
;     const int last = nk - 1;
;     GLOAD(0, 0);
;     __builtin_amdgcn_sched_barrier(0);
;     GLOAD(1, 1);
;     __builtin_amdgcn_sched_barrier(0);
;     LWRITE(0, 0);
;     __builtin_amdgcn_sched_barrier(0);
;     GLOAD(0, (2 < last ? 2 : last));
;     __builtin_amdgcn_sched_barrier(0);
;     __syncthreads();
; template <class Epi>
; DI void gemm_phase(char* smem, const bf16_t* A0, int lda0, int ksplit, const bf16_t* A1, int lda1, const bf16_t* Bt, int K, int nN, const Epi& epi, int tid) {
;     ...
;     const int x = blockIdx.x & 7, l = blockIdx.x >> 3, L = G >> 3, per = 8 * nN, tot = 2 * per;
;     for (int q = l; q < tot; q += L) { const int rgl = q / per, rem = q % per, ct = rem >> 3, rt = (x * 2 + rgl) * 8 + (rem & 7);
;       gemm_tile(smem, A0, lda0, ksplit, A1, lda1, Bt, K, rt * 256, ct * 128, epi, tid); }
.Lg3d_tile:
	s_cmpk_ge_u32 s15, 64
	s_cbranch_scc1 .Lg3d_done
	s_cmpk_ge_u32 s15, 32
	s_cselect_b32 s27, 1, 0
	s_cselect_b32 s26, 32, 0
	s_sub_u32 s26, s15, s26
	s_add_u32 s27, s27, s101
	s_lshl_b32 s27, s27, 3
	s_and_b32 s29, s26, 7
	s_add_u32 s29, s29, s27
	s_lshl_b32 s29, s29, 8
	s_lshr_b32 s28, s26, 3
	s_lshl_b32 s28, s28, 7
	s_mul_i32 s27, s29, 512
	s_add_u32 s27, s27, 0x1ea00100
	s_add_u32 s0, s92, s27
	s_addc_u32 s1, s93, 0
	s_mul_i32 s27, s28, 256
	s_add_u32 s27, s27, 0x3480000
	s_add_u32 s2, s92, s27
	s_addc_u32 s3, s93, 0
	s_waitcnt lgkmcnt(0)
	s_barrier
	s_mov_b32 s99, 0
	s_mov_b32 s30, 0
	s_add_u32 s26, s30, s100
	s_add_u32 m0, s26, 0
	s_nop 0
	global_load_lds_dwordx4 v224, s[0:1]
	s_add_u32 m0, s26, 4096
	s_nop 0
	global_load_lds_dwordx4 v225, s[0:1]
	s_add_u32 m0, s26, 8192
	s_nop 0
	global_load_lds_dwordx4 v226, s[0:1]
	s_add_u32 m0, s26, 12288
	s_nop 0
	global_load_lds_dwordx4 v227, s[0:1]
	s_add_u32 m0, s26, 16384
	s_nop 0
	global_load_lds_dwordx4 v228, s[2:3]
	s_add_u32 m0, s26, 20480
	s_nop 0
	global_load_lds_dwordx4 v229, s[2:3]
	s_add_u32 s0, s0, 64
	s_addc_u32 s1, s1, 0
	s_add_u32 s2, s2, 64
	s_addc_u32 s3, s3, 0
	s_add_u32 s99, s99, 1
	s_add_u32 s30, s30, 24576
	s_cmp_eq_u32 s30, 73728
	s_cselect_b32 s30, 0, s30
	s_add_u32 s26, s30, s100
	s_add_u32 m0, s26, 0
	s_nop 0
	global_load_lds_dwordx4 v224, s[0:1]
	s_add_u32 m0, s26, 4096
	s_nop 0
	global_load_lds_dwordx4 v225, s[0:1]
	s_add_u32 m0, s26, 8192
	s_nop 0
	global_load_lds_dwordx4 v226, s[0:1]
	s_add_u32 m0, s26, 12288
	s_nop 0
	global_load_lds_dwordx4 v227, s[0:1]
	s_add_u32 m0, s26, 16384
	s_nop 0
	global_load_lds_dwordx4 v228, s[2:3]
	s_add_u32 m0, s26, 20480
	s_nop 0
	global_load_lds_dwordx4 v229, s[2:3]
	s_add_u32 s0, s0, 64
	s_addc_u32 s1, s1, 0
	s_add_u32 s2, s2, 64
	s_addc_u32 s3, s3, 0
	s_add_u32 s99, s99, 1
	s_add_u32 s30, s30, 24576
	s_cmp_eq_u32 s30, 73728
	s_cselect_b32 s30, 0, s30
	s_add_u32 s26, s30, s100
	s_add_u32 m0, s26, 0
	s_nop 0
	global_load_lds_dwordx4 v224, s[0:1]
	s_add_u32 m0, s26, 4096
	s_nop 0
	global_load_lds_dwordx4 v225, s[0:1]
	s_add_u32 m0, s26, 8192
	s_nop 0
	global_load_lds_dwordx4 v226, s[0:1]
	s_add_u32 m0, s26, 12288
	s_nop 0
	global_load_lds_dwordx4 v227, s[0:1]
	s_add_u32 m0, s26, 16384
	s_nop 0
	global_load_lds_dwordx4 v228, s[2:3]
	s_add_u32 m0, s26, 20480
	s_nop 0
	global_load_lds_dwordx4 v229, s[2:3]
	s_add_u32 s0, s0, 64
	s_addc_u32 s1, s1, 0
	s_add_u32 s2, s2, 64
	s_addc_u32 s3, s3, 0
	s_add_u32 s99, s99, 1
	s_add_u32 s30, s30, 24576
	s_cmp_eq_u32 s30, 73728
	s_cselect_b32 s30, 0, s30
	v_mov_b32_e32 v0, 0
	v_mov_b32_e32 v1, 0
	v_mov_b32_e32 v2, 0
	v_mov_b32_e32 v3, 0
	v_mov_b32_e32 v4, 0
	v_mov_b32_e32 v5, 0
	v_mov_b32_e32 v6, 0
	v_mov_b32_e32 v7, 0
	v_mov_b32_e32 v8, 0
	v_mov_b32_e32 v9, 0
	v_mov_b32_e32 v10, 0
	v_mov_b32_e32 v11, 0
	v_mov_b32_e32 v12, 0
	v_mov_b32_e32 v13, 0
	v_mov_b32_e32 v14, 0
	v_mov_b32_e32 v15, 0
	v_mov_b32_e32 v16, 0
	v_mov_b32_e32 v17, 0
	v_mov_b32_e32 v18, 0
	v_mov_b32_e32 v19, 0
	v_mov_b32_e32 v20, 0
	v_mov_b32_e32 v21, 0
	v_mov_b32_e32 v22, 0
	v_mov_b32_e32 v23, 0
	v_mov_b32_e32 v24, 0
	v_mov_b32_e32 v25, 0
	v_mov_b32_e32 v26, 0
	v_mov_b32_e32 v27, 0
	v_mov_b32_e32 v28, 0
	v_mov_b32_e32 v29, 0
	v_mov_b32_e32 v30, 0
	v_mov_b32_e32 v31, 0
	v_mov_b32_e32 v32, 0
	v_mov_b32_e32 v33, 0
	v_mov_b32_e32 v34, 0
	v_mov_b32_e32 v35, 0
	v_mov_b32_e32 v36, 0
	v_mov_b32_e32 v37, 0
	v_mov_b32_e32 v38, 0
	v_mov_b32_e32 v39, 0
	v_mov_b32_e32 v40, 0
	v_mov_b32_e32 v41, 0
	v_mov_b32_e32 v42, 0
	v_mov_b32_e32 v43, 0
	v_mov_b32_e32 v44, 0
	v_mov_b32_e32 v45, 0
	v_mov_b32_e32 v46, 0
	v_mov_b32_e32 v47, 0
	v_mov_b32_e32 v48, 0
	v_mov_b32_e32 v49, 0
	v_mov_b32_e32 v50, 0
	v_mov_b32_e32 v51, 0
	v_mov_b32_e32 v52, 0
	v_mov_b32_e32 v53, 0
	v_mov_b32_e32 v54, 0
	v_mov_b32_e32 v55, 0
	v_mov_b32_e32 v56, 0
	v_mov_b32_e32 v57, 0
	v_mov_b32_e32 v58, 0
	v_mov_b32_e32 v59, 0
	v_mov_b32_e32 v60, 0
	v_mov_b32_e32 v61, 0
	v_mov_b32_e32 v62, 0
	v_mov_b32_e32 v63, 0
	v_mov_b32_e32 v64, 0
	v_mov_b32_e32 v65, 0
	v_mov_b32_e32 v66, 0
	v_mov_b32_e32 v67, 0
	v_mov_b32_e32 v68, 0
	v_mov_b32_e32 v69, 0
	v_mov_b32_e32 v70, 0
	v_mov_b32_e32 v71, 0
	v_mov_b32_e32 v72, 0
	v_mov_b32_e32 v73, 0
	v_mov_b32_e32 v74, 0
	v_mov_b32_e32 v75, 0
	v_mov_b32_e32 v76, 0
	v_mov_b32_e32 v77, 0
	v_mov_b32_e32 v78, 0
	v_mov_b32_e32 v79, 0
	v_mov_b32_e32 v80, 0
	v_mov_b32_e32 v81, 0
	v_mov_b32_e32 v82, 0
	v_mov_b32_e32 v83, 0
	v_mov_b32_e32 v84, 0
	v_mov_b32_e32 v85, 0
	v_mov_b32_e32 v86, 0
	v_mov_b32_e32 v87, 0
	v_mov_b32_e32 v88, 0
	v_mov_b32_e32 v89, 0
	v_mov_b32_e32 v90, 0
	v_mov_b32_e32 v91, 0
	v_mov_b32_e32 v92, 0
	v_mov_b32_e32 v93, 0
	v_mov_b32_e32 v94, 0
	v_mov_b32_e32 v95, 0
	v_mov_b32_e32 v96, 0
	v_mov_b32_e32 v97, 0
	v_mov_b32_e32 v98, 0
	v_mov_b32_e32 v99, 0
	v_mov_b32_e32 v100, 0
	v_mov_b32_e32 v101, 0
	v_mov_b32_e32 v102, 0
	v_mov_b32_e32 v103, 0
	v_mov_b32_e32 v104, 0
	v_mov_b32_e32 v105, 0
	v_mov_b32_e32 v106, 0
	v_mov_b32_e32 v107, 0
	v_mov_b32_e32 v108, 0
	v_mov_b32_e32 v109, 0
	v_mov_b32_e32 v110, 0
	v_mov_b32_e32 v111, 0
	v_mov_b32_e32 v112, 0
	v_mov_b32_e32 v113, 0
	v_mov_b32_e32 v114, 0
	v_mov_b32_e32 v115, 0
	v_mov_b32_e32 v116, 0
	v_mov_b32_e32 v117, 0
	v_mov_b32_e32 v118, 0
	v_mov_b32_e32 v119, 0
	v_mov_b32_e32 v120, 0
	v_mov_b32_e32 v121, 0
	v_mov_b32_e32 v122, 0
	v_mov_b32_e32 v123, 0
	v_mov_b32_e32 v124, 0
	v_mov_b32_e32 v125, 0
	v_mov_b32_e32 v126, 0
	v_mov_b32_e32 v127, 0
	s_mov_b32 s98, 0
	s_mov_b32 s31, 24576
	s_waitcnt vmcnt(12)
	s_barrier
; #define LWRITE(S, buf) do { bf16_t* sA_ = sbase + (buf) * BUF; bf16_t* sB_ = sA_ + 256 * PITCH; \
;     _Pragma("unroll") for (int i_ = 0; i_ < 4; ++i_) *(u32x4*)(sA_ + (sr + i_ * 64) * PITCH + scv * 8) = ra[S][i_]; \
;     _Pragma("unroll") for (int i_ = 0; i_ < 2; ++i_) *(u32x4*)(sB_ + (sr + i_ * 64) * PITCH + scv * 8) = rb[S][i_]; } while (0)
; template <class Epi>
; DI void gemm_tile(char* smem, const bf16_t* __restrict__ A0, int lda0, int ksplit, const bf16_t* __restrict__ A1, int lda1,
;                   const bf16_t* __restrict__ Bt, int K, int row0, int col0, const Epi& epi, int tid) {
;     ...
;     for (int kt = 0; kt < nk; kt += 2) {
;       LWRITE(1, 1);
;       __builtin_amdgcn_sched_barrier(0);
;       GLOAD(1, (kt + 3 < last ? kt + 3 : last));
;       __builtin_amdgcn_sched_barrier(0);
;       COMPUTE(0);
;       __syncthreads();
;       LWRITE(0, 0);
;       __builtin_amdgcn_sched_barrier(0);
;       GLOAD(0, (kt + 4 < last ? kt + 4 : last));
;       __builtin_amdgcn_sched_barrier(0);
;       COMPUTE(1);
;       __syncthreads();
;     }
	ds_read_b128 v[128:131], v231 offset:0
	ds_read_b128 v[132:135], v231 offset:1024
	ds_read_b128 v[136:139], v231 offset:2048
	ds_read_b128 v[140:143], v231 offset:3072
	ds_read_b128 v[144:147], v230 offset:0
	ds_read_b128 v[148:151], v230 offset:1024
	ds_read_b128 v[152:155], v230 offset:2048
	ds_read_b128 v[156:159], v230 offset:3072
	ds_read_b128 v[160:163], v230 offset:4096
	ds_read_b128 v[164:167], v230 offset:5120
	ds_read_b128 v[168:171], v230 offset:6144
	ds_read_b128 v[172:175], v230 offset:7168
	s_waitcnt vmcnt(6)
	s_waitcnt lgkmcnt(0)
	s_barrier
	v_add_u32_e32 v232, s31, v230
	v_add_u32_e32 v233, s31, v231
	s_add_u32 s26, s30, s100
	v_mfma_f32_16x16x32_bf16 v[0:3], v[128:131], v[144:147], v[0:3]
	v_mfma_f32_16x16x32_bf16 v[4:7], v[132:135], v[144:147], v[4:7]
	v_mfma_f32_16x16x32_bf16 v[8:11], v[136:139], v[144:147], v[8:11]
	v_mfma_f32_16x16x32_bf16 v[12:15], v[140:143], v[144:147], v[12:15]
	ds_read_b128 v[176:179], v233 offset:0
	ds_read_b128 v[180:183], v233 offset:1024
	s_add_u32 m0, s26, 0
	s_nop 0
	global_load_lds_dwordx4 v224, s[0:1]
	v_mfma_f32_16x16x32_bf16 v[16:19], v[128:131], v[148:151], v[16:19]
	v_mfma_f32_16x16x32_bf16 v[20:23], v[132:135], v[148:151], v[20:23]
	v_mfma_f32_16x16x32_bf16 v[24:27], v[136:139], v[148:151], v[24:27]
	v_mfma_f32_16x16x32_bf16 v[28:31], v[140:143], v[148:151], v[28:31]
	ds_read_b128 v[184:187], v233 offset:2048
	ds_read_b128 v[188:191], v233 offset:3072
	s_add_u32 m0, s26, 4096
	s_nop 0
	global_load_lds_dwordx4 v225, s[0:1]
	v_mfma_f32_16x16x32_bf16 v[32:35], v[128:131], v[152:155], v[32:35]
	v_mfma_f32_16x16x32_bf16 v[36:39], v[132:135], v[152:155], v[36:39]
	v_mfma_f32_16x16x32_bf16 v[40:43], v[136:139], v[152:155], v[40:43]
	v_mfma_f32_16x16x32_bf16 v[44:47], v[140:143], v[152:155], v[44:47]
	ds_read_b128 v[192:195], v232 offset:0
	ds_read_b128 v[196:199], v232 offset:1024
	s_add_u32 m0, s26, 8192
	s_nop 0
	global_load_lds_dwordx4 v226, s[0:1]
	v_mfma_f32_16x16x32_bf16 v[48:51], v[128:131], v[156:159], v[48:51]
	v_mfma_f32_16x16x32_bf16 v[52:55], v[132:135], v[156:159], v[52:55]
	v_mfma_f32_16x16x32_bf16 v[56:59], v[136:139], v[156:159], v[56:59]
	v_mfma_f32_16x16x32_bf16 v[60:63], v[140:143], v[156:159], v[60:63]
	ds_read_b128 v[200:203], v232 offset:2048
	ds_read_b128 v[204:207], v232 offset:3072
	s_add_u32 m0, s26, 12288
	s_nop 0
	global_load_lds_dwordx4 v227, s[0:1]
	v_mfma_f32_16x16x32_bf16 v[64:67], v[128:131], v[160:163], v[64:67]
	v_mfma_f32_16x16x32_bf16 v[68:71], v[132:135], v[160:163], v[68:71]
	v_mfma_f32_16x16x32_bf16 v[72:75], v[136:139], v[160:163], v[72:75]
	v_mfma_f32_16x16x32_bf16 v[76:79], v[140:143], v[160:163], v[76:79]
	ds_read_b128 v[208:211], v232 offset:4096
	s_add_u32 m0, s26, 16384
	s_nop 0
	global_load_lds_dwordx4 v228, s[2:3]
	v_mfma_f32_16x16x32_bf16 v[80:83], v[128:131], v[164:167], v[80:83]
	v_mfma_f32_16x16x32_bf16 v[84:87], v[132:135], v[164:167], v[84:87]
	v_mfma_f32_16x16x32_bf16 v[88:91], v[136:139], v[164:167], v[88:91]
	v_mfma_f32_16x16x32_bf16 v[92:95], v[140:143], v[164:167], v[92:95]
	ds_read_b128 v[212:215], v232 offset:5120
	s_add_u32 m0, s26, 20480
	s_nop 0
	global_load_lds_dwordx4 v229, s[2:3]
	v_mfma_f32_16x16x32_bf16 v[96:99], v[128:131], v[168:171], v[96:99]
	v_mfma_f32_16x16x32_bf16 v[100:103], v[132:135], v[168:171], v[100:103]
	v_mfma_f32_16x16x32_bf16 v[104:107], v[136:139], v[168:171], v[104:107]
	v_mfma_f32_16x16x32_bf16 v[108:111], v[140:143], v[168:171], v[108:111]
	ds_read_b128 v[216:219], v232 offset:6144
	s_add_u32 s0, s0, 64
	s_addc_u32 s1, s1, 0
	s_add_u32 s2, s2, 64
	s_addc_u32 s3, s3, 0
	s_add_u32 s99, s99, 1
	s_add_u32 s30, s30, 24576
	s_cmp_eq_u32 s30, 73728
	s_cselect_b32 s30, 0, s30
	s_add_u32 s31, s31, 24576
	s_cmp_eq_u32 s31, 73728
	s_cselect_b32 s31, 0, s31
	v_mfma_f32_16x16x32_bf16 v[112:115], v[128:131], v[172:175], v[112:115]
	v_mfma_f32_16x16x32_bf16 v[116:119], v[132:135], v[172:175], v[116:119]
	v_mfma_f32_16x16x32_bf16 v[120:123], v[136:139], v[172:175], v[120:123]
	v_mfma_f32_16x16x32_bf16 v[124:127], v[140:143], v[172:175], v[124:127]
	ds_read_b128 v[220:223], v232 offset:7168
	s_waitcnt vmcnt(6)
	s_waitcnt lgkmcnt(0)
	s_barrier
	v_add_u32_e32 v232, s31, v230
	v_add_u32_e32 v233, s31, v231
	v_mfma_f32_16x16x32_bf16 v[0:3], v[176:179], v[192:195], v[0:3]
	v_mfma_f32_16x16x32_bf16 v[4:7], v[180:183], v[192:195], v[4:7]
	v_mfma_f32_16x16x32_bf16 v[8:11], v[184:187], v[192:195], v[8:11]
	v_mfma_f32_16x16x32_bf16 v[12:15], v[188:191], v[192:195], v[12:15]
	ds_read_b128 v[128:131], v233 offset:0
	ds_read_b128 v[132:135], v233 offset:1024
	v_mfma_f32_16x16x32_bf16 v[16:19], v[176:179], v[196:199], v[16:19]
	v_mfma_f32_16x16x32_bf16 v[20:23], v[180:183], v[196:199], v[20:23]
	v_mfma_f32_16x16x32_bf16 v[24:27], v[184:187], v[196:199], v[24:27]
	v_mfma_f32_16x16x32_bf16 v[28:31], v[188:191], v[196:199], v[28:31]
	ds_read_b128 v[136:139], v233 offset:2048
	ds_read_b128 v[140:143], v233 offset:3072
	v_mfma_f32_16x16x32_bf16 v[32:35], v[176:179], v[200:203], v[32:35]
	v_mfma_f32_16x16x32_bf16 v[36:39], v[180:183], v[200:203], v[36:39]
	v_mfma_f32_16x16x32_bf16 v[40:43], v[184:187], v[200:203], v[40:43]
	v_mfma_f32_16x16x32_bf16 v[44:47], v[188:191], v[200:203], v[44:47]
	ds_read_b128 v[144:147], v232 offset:0
	ds_read_b128 v[148:151], v232 offset:1024
	v_mfma_f32_16x16x32_bf16 v[48:51], v[176:179], v[204:207], v[48:51]
	v_mfma_f32_16x16x32_bf16 v[52:55], v[180:183], v[204:207], v[52:55]
	v_mfma_f32_16x16x32_bf16 v[56:59], v[184:187], v[204:207], v[56:59]
	v_mfma_f32_16x16x32_bf16 v[60:63], v[188:191], v[204:207], v[60:63]
	ds_read_b128 v[152:155], v232 offset:2048
	ds_read_b128 v[156:159], v232 offset:3072
	v_mfma_f32_16x16x32_bf16 v[64:67], v[176:179], v[208:211], v[64:67]
	v_mfma_f32_16x16x32_bf16 v[68:71], v[180:183], v[208:211], v[68:71]
	v_mfma_f32_16x16x32_bf16 v[72:75], v[184:187], v[208:211], v[72:75]
	v_mfma_f32_16x16x32_bf16 v[76:79], v[188:191], v[208:211], v[76:79]
	ds_read_b128 v[160:163], v232 offset:4096
	v_mfma_f32_16x16x32_bf16 v[80:83], v[176:179], v[212:215], v[80:83]
	v_mfma_f32_16x16x32_bf16 v[84:87], v[180:183], v[212:215], v[84:87]
	v_mfma_f32_16x16x32_bf16 v[88:91], v[184:187], v[212:215], v[88:91]
	v_mfma_f32_16x16x32_bf16 v[92:95], v[188:191], v[212:215], v[92:95]
	ds_read_b128 v[164:167], v232 offset:5120
	v_mfma_f32_16x16x32_bf16 v[96:99], v[176:179], v[216:219], v[96:99]
	v_mfma_f32_16x16x32_bf16 v[100:103], v[180:183], v[216:219], v[100:103]
	v_mfma_f32_16x16x32_bf16 v[104:107], v[184:187], v[216:219], v[104:107]
	v_mfma_f32_16x16x32_bf16 v[108:111], v[188:191], v[216:219], v[108:111]
	ds_read_b128 v[168:171], v232 offset:6144
	s_add_u32 s31, s31, 24576
	s_cmp_eq_u32 s31, 73728
	s_cselect_b32 s31, 0, s31
	v_mfma_f32_16x16x32_bf16 v[112:115], v[176:179], v[220:223], v[112:115]
	v_mfma_f32_16x16x32_bf16 v[116:119], v[180:183], v[220:223], v[116:119]
	v_mfma_f32_16x16x32_bf16 v[120:123], v[184:187], v[220:223], v[120:123]
	v_mfma_f32_16x16x32_bf16 v[124:127], v[188:191], v[220:223], v[124:127]
	ds_read_b128 v[172:175], v232 offset:7168
	s_waitcnt vmcnt(0)
; #define LWRITE(S, buf) do { bf16_t* sA_ = sbase + (buf) * BUF; bf16_t* sB_ = sA_ + 256 * PITCH; \
;     _Pragma("unroll") for (int i_ = 0; i_ < 4; ++i_) *(u32x4*)(sA_ + (sr + i_ * 64) * PITCH + scv * 8) = ra[S][i_]; \
;     _Pragma("unroll") for (int i_ = 0; i_ < 2; ++i_) *(u32x4*)(sB_ + (sr + i_ * 64) * PITCH + scv * 8) = rb[S][i_]; } while (0)
; template <class Epi>
; DI void gemm_tile(char* smem, const bf16_t* __restrict__ A0, int lda0, int ksplit, const bf16_t* __restrict__ A1, int lda1,
;                   const bf16_t* __restrict__ Bt, int K, int row0, int col0, const Epi& epi, int tid) {
;     ...
;     for (int kt = 0; kt < nk; kt += 2) {
;       LWRITE(1, 1);
;       __builtin_amdgcn_sched_barrier(0);
;       GLOAD(1, (kt + 3 < last ? kt + 3 : last));
;       __builtin_amdgcn_sched_barrier(0);
;       COMPUTE(0);
;       __syncthreads();
;       LWRITE(0, 0);
;       __builtin_amdgcn_sched_barrier(0);
;       GLOAD(0, (kt + 4 < last ? kt + 4 : last));
;       __builtin_amdgcn_sched_barrier(0);
;       COMPUTE(1);
;       __syncthreads();
;     }
	s_waitcnt lgkmcnt(0)
	s_barrier
	v_add_u32_e32 v232, s31, v230
	v_add_u32_e32 v233, s31, v231
	v_mfma_f32_16x16x32_bf16 v[0:3], v[128:131], v[144:147], v[0:3]
	v_mfma_f32_16x16x32_bf16 v[4:7], v[132:135], v[144:147], v[4:7]
	v_mfma_f32_16x16x32_bf16 v[8:11], v[136:139], v[144:147], v[8:11]
	v_mfma_f32_16x16x32_bf16 v[12:15], v[140:143], v[144:147], v[12:15]
	ds_read_b128 v[176:179], v233 offset:0
	ds_read_b128 v[180:183], v233 offset:1024
	v_mfma_f32_16x16x32_bf16 v[16:19], v[128:131], v[148:151], v[16:19]
	v_mfma_f32_16x16x32_bf16 v[20:23], v[132:135], v[148:151], v[20:23]
	v_mfma_f32_16x16x32_bf16 v[24:27], v[136:139], v[148:151], v[24:27]
	v_mfma_f32_16x16x32_bf16 v[28:31], v[140:143], v[148:151], v[28:31]
	ds_read_b128 v[184:187], v233 offset:2048
	ds_read_b128 v[188:191], v233 offset:3072
	v_mfma_f32_16x16x32_bf16 v[32:35], v[128:131], v[152:155], v[32:35]
	v_mfma_f32_16x16x32_bf16 v[36:39], v[132:135], v[152:155], v[36:39]
	v_mfma_f32_16x16x32_bf16 v[40:43], v[136:139], v[152:155], v[40:43]
	v_mfma_f32_16x16x32_bf16 v[44:47], v[140:143], v[152:155], v[44:47]
	ds_read_b128 v[192:195], v232 offset:0
	ds_read_b128 v[196:199], v232 offset:1024
	v_mfma_f32_16x16x32_bf16 v[48:51], v[128:131], v[156:159], v[48:51]
	v_mfma_f32_16x16x32_bf16 v[52:55], v[132:135], v[156:159], v[52:55]
	v_mfma_f32_16x16x32_bf16 v[56:59], v[136:139], v[156:159], v[56:59]
	v_mfma_f32_16x16x32_bf16 v[60:63], v[140:143], v[156:159], v[60:63]
	ds_read_b128 v[200:203], v232 offset:2048
	ds_read_b128 v[204:207], v232 offset:3072
	v_mfma_f32_16x16x32_bf16 v[64:67], v[128:131], v[160:163], v[64:67]
	v_mfma_f32_16x16x32_bf16 v[68:71], v[132:135], v[160:163], v[68:71]
	v_mfma_f32_16x16x32_bf16 v[72:75], v[136:139], v[160:163], v[72:75]
	v_mfma_f32_16x16x32_bf16 v[76:79], v[140:143], v[160:163], v[76:79]
	ds_read_b128 v[208:211], v232 offset:4096
	v_mfma_f32_16x16x32_bf16 v[80:83], v[128:131], v[164:167], v[80:83]
	v_mfma_f32_16x16x32_bf16 v[84:87], v[132:135], v[164:167], v[84:87]
	v_mfma_f32_16x16x32_bf16 v[88:91], v[136:139], v[164:167], v[88:91]
	v_mfma_f32_16x16x32_bf16 v[92:95], v[140:143], v[164:167], v[92:95]
	ds_read_b128 v[212:215], v232 offset:5120
	v_mfma_f32_16x16x32_bf16 v[96:99], v[128:131], v[168:171], v[96:99]
	v_mfma_f32_16x16x32_bf16 v[100:103], v[132:135], v[168:171], v[100:103]
	v_mfma_f32_16x16x32_bf16 v[104:107], v[136:139], v[168:171], v[104:107]
	v_mfma_f32_16x16x32_bf16 v[108:111], v[140:143], v[168:171], v[108:111]
	ds_read_b128 v[216:219], v232 offset:6144
	s_add_u32 s31, s31, 24576
	s_cmp_eq_u32 s31, 73728
	s_cselect_b32 s31, 0, s31
	v_mfma_f32_16x16x32_bf16 v[112:115], v[128:131], v[172:175], v[112:115]
	v_mfma_f32_16x16x32_bf16 v[116:119], v[132:135], v[172:175], v[116:119]
	v_mfma_f32_16x16x32_bf16 v[120:123], v[136:139], v[172:175], v[120:123]
	v_mfma_f32_16x16x32_bf16 v[124:127], v[140:143], v[172:175], v[124:127]
	ds_read_b128 v[220:223], v232 offset:7168
	s_waitcnt lgkmcnt(0)
	s_barrier
	v_mfma_f32_16x16x32_bf16 v[0:3], v[176:179], v[192:195], v[0:3]
	v_mfma_f32_16x16x32_bf16 v[4:7], v[180:183], v[192:195], v[4:7]
	v_mfma_f32_16x16x32_bf16 v[8:11], v[184:187], v[192:195], v[8:11]
	v_mfma_f32_16x16x32_bf16 v[12:15], v[188:191], v[192:195], v[12:15]
	v_mfma_f32_16x16x32_bf16 v[16:19], v[176:179], v[196:199], v[16:19]
	v_mfma_f32_16x16x32_bf16 v[20:23], v[180:183], v[196:199], v[20:23]
	v_mfma_f32_16x16x32_bf16 v[24:27], v[184:187], v[196:199], v[24:27]
	v_mfma_f32_16x16x32_bf16 v[28:31], v[188:191], v[196:199], v[28:31]
	v_mfma_f32_16x16x32_bf16 v[32:35], v[176:179], v[200:203], v[32:35]
	v_mfma_f32_16x16x32_bf16 v[36:39], v[180:183], v[200:203], v[36:39]
	v_mfma_f32_16x16x32_bf16 v[40:43], v[184:187], v[200:203], v[40:43]
	v_mfma_f32_16x16x32_bf16 v[44:47], v[188:191], v[200:203], v[44:47]
	v_mfma_f32_16x16x32_bf16 v[48:51], v[176:179], v[204:207], v[48:51]
	v_mfma_f32_16x16x32_bf16 v[52:55], v[180:183], v[204:207], v[52:55]
	v_mfma_f32_16x16x32_bf16 v[56:59], v[184:187], v[204:207], v[56:59]
	v_mfma_f32_16x16x32_bf16 v[60:63], v[188:191], v[204:207], v[60:63]
	v_mfma_f32_16x16x32_bf16 v[64:67], v[176:179], v[208:211], v[64:67]
	v_mfma_f32_16x16x32_bf16 v[68:71], v[180:183], v[208:211], v[68:71]
	v_mfma_f32_16x16x32_bf16 v[72:75], v[184:187], v[208:211], v[72:75]
	v_mfma_f32_16x16x32_bf16 v[76:79], v[188:191], v[208:211], v[76:79]
	v_mfma_f32_16x16x32_bf16 v[80:83], v[176:179], v[212:215], v[80:83]
	v_mfma_f32_16x16x32_bf16 v[84:87], v[180:183], v[212:215], v[84:87]
	v_mfma_f32_16x16x32_bf16 v[88:91], v[184:187], v[212:215], v[88:91]
	v_mfma_f32_16x16x32_bf16 v[92:95], v[188:191], v[212:215], v[92:95]
	v_mfma_f32_16x16x32_bf16 v[96:99], v[176:179], v[216:219], v[96:99]
	v_mfma_f32_16x16x32_bf16 v[100:103], v[180:183], v[216:219], v[100:103]
	v_mfma_f32_16x16x32_bf16 v[104:107], v[184:187], v[216:219], v[104:107]
	v_mfma_f32_16x16x32_bf16 v[108:111], v[188:191], v[216:219], v[108:111]
	v_mfma_f32_16x16x32_bf16 v[112:115], v[176:179], v[220:223], v[112:115]
	v_mfma_f32_16x16x32_bf16 v[116:119], v[180:183], v[220:223], v[116:119]
	v_mfma_f32_16x16x32_bf16 v[120:123], v[184:187], v[220:223], v[120:123]
	v_mfma_f32_16x16x32_bf16 v[124:127], v[188:191], v[220:223], v[124:127]
	s_branch .Lg3d_epi
; template <class Epi>
; DI void gemm_tile(char* smem, const bf16_t* __restrict__ A0, int lda0, int ksplit, const bf16_t* __restrict__ A1, int lda1,
;                   const bf16_t* __restrict__ Bt, int K, int row0, int col0, const Epi& epi, int tid) {
;     ...
; #pragma unroll
;   for (int m = 0; m < 8; ++m)
; #pragma unroll
;     for (int n = 0; n < 4; ++n) epi(row0 + wr * 128 + m * 16 + fr, col0 + wc * 64 + n * 16 + fq * 4, acc[m][n]);
.Lg3d_epi:
	s_nop 7
	s_nop 7
	s_mul_i32 s27, s29, 1024
	s_lshl_b32 s26, s28, 1
	s_add_u32 s27, s27, s26
	s_add_u32 s27, s27, 0x3800000
	s_add_u32 s4, s92, s27
	s_addc_u32 s5, s93, 0
	v_cvt_pk_bf16_f32 v128, v0, v1
	v_cvt_pk_bf16_f32 v129, v2, v3
	ds_write_b64 v236, v[128:129]
	v_cvt_pk_bf16_f32 v130, v4, v5
	v_cvt_pk_bf16_f32 v131, v6, v7
	ds_write_b64 v236, v[130:131] offset:32
	v_cvt_pk_bf16_f32 v132, v8, v9
	v_cvt_pk_bf16_f32 v133, v10, v11
	ds_write_b64 v236, v[132:133] offset:64
	v_cvt_pk_bf16_f32 v134, v12, v13
	v_cvt_pk_bf16_f32 v135, v14, v15
	ds_write_b64 v236, v[134:135] offset:96
	v_cvt_pk_bf16_f32 v136, v16, v17
	v_cvt_pk_bf16_f32 v137, v18, v19
	ds_write_b64 v236, v[136:137] offset:2304
	v_cvt_pk_bf16_f32 v138, v20, v21
	v_cvt_pk_bf16_f32 v139, v22, v23
	ds_write_b64 v236, v[138:139] offset:2336
	v_cvt_pk_bf16_f32 v140, v24, v25
	v_cvt_pk_bf16_f32 v141, v26, v27
	ds_write_b64 v236, v[140:141] offset:2368
	v_cvt_pk_bf16_f32 v142, v28, v29
	v_cvt_pk_bf16_f32 v143, v30, v31
	ds_write_b64 v236, v[142:143] offset:2400
	v_cvt_pk_bf16_f32 v144, v32, v33
	v_cvt_pk_bf16_f32 v145, v34, v35
	ds_write_b64 v236, v[144:145] offset:4608
	v_cvt_pk_bf16_f32 v146, v36, v37
	v_cvt_pk_bf16_f32 v147, v38, v39
	ds_write_b64 v236, v[146:147] offset:4640
	v_cvt_pk_bf16_f32 v148, v40, v41
	v_cvt_pk_bf16_f32 v149, v42, v43
	ds_write_b64 v236, v[148:149] offset:4672
	v_cvt_pk_bf16_f32 v150, v44, v45
	v_cvt_pk_bf16_f32 v151, v46, v47
	ds_write_b64 v236, v[150:151] offset:4704
	v_cvt_pk_bf16_f32 v152, v48, v49
	v_cvt_pk_bf16_f32 v153, v50, v51
	ds_write_b64 v236, v[152:153] offset:6912
	v_cvt_pk_bf16_f32 v154, v52, v53
	v_cvt_pk_bf16_f32 v155, v54, v55
	ds_write_b64 v236, v[154:155] offset:6944
	v_cvt_pk_bf16_f32 v156, v56, v57
	v_cvt_pk_bf16_f32 v157, v58, v59
	ds_write_b64 v236, v[156:157] offset:6976
	v_cvt_pk_bf16_f32 v158, v60, v61
	v_cvt_pk_bf16_f32 v159, v62, v63
	ds_write_b64 v236, v[158:159] offset:7008
	v_cvt_pk_bf16_f32 v128, v64, v65
	v_cvt_pk_bf16_f32 v129, v66, v67
	ds_write_b64 v236, v[128:129] offset:9216
	v_cvt_pk_bf16_f32 v130, v68, v69
	v_cvt_pk_bf16_f32 v131, v70, v71
	ds_write_b64 v236, v[130:131] offset:9248
	v_cvt_pk_bf16_f32 v132, v72, v73
	v_cvt_pk_bf16_f32 v133, v74, v75
	ds_write_b64 v236, v[132:133] offset:9280
	v_cvt_pk_bf16_f32 v134, v76, v77
	v_cvt_pk_bf16_f32 v135, v78, v79
	ds_write_b64 v236, v[134:135] offset:9312
	v_cvt_pk_bf16_f32 v136, v80, v81
	v_cvt_pk_bf16_f32 v137, v82, v83
	ds_write_b64 v236, v[136:137] offset:11520
	v_cvt_pk_bf16_f32 v138, v84, v85
	v_cvt_pk_bf16_f32 v139, v86, v87
	ds_write_b64 v236, v[138:139] offset:11552
	v_cvt_pk_bf16_f32 v140, v88, v89
	v_cvt_pk_bf16_f32 v141, v90, v91
	ds_write_b64 v236, v[140:141] offset:11584
	v_cvt_pk_bf16_f32 v142, v92, v93
	v_cvt_pk_bf16_f32 v143, v94, v95
	ds_write_b64 v236, v[142:143] offset:11616
	v_cvt_pk_bf16_f32 v144, v96, v97
	v_cvt_pk_bf16_f32 v145, v98, v99
	ds_write_b64 v236, v[144:145] offset:13824
	v_cvt_pk_bf16_f32 v146, v100, v101
	v_cvt_pk_bf16_f32 v147, v102, v103
	ds_write_b64 v236, v[146:147] offset:13856
	v_cvt_pk_bf16_f32 v148, v104, v105
	v_cvt_pk_bf16_f32 v149, v106, v107
	ds_write_b64 v236, v[148:149] offset:13888
	v_cvt_pk_bf16_f32 v150, v108, v109
	v_cvt_pk_bf16_f32 v151, v110, v111
	ds_write_b64 v236, v[150:151] offset:13920
	v_cvt_pk_bf16_f32 v152, v112, v113
	v_cvt_pk_bf16_f32 v153, v114, v115
	ds_write_b64 v236, v[152:153] offset:16128
	v_cvt_pk_bf16_f32 v154, v116, v117
	v_cvt_pk_bf16_f32 v155, v118, v119
	ds_write_b64 v236, v[154:155] offset:16160
	v_cvt_pk_bf16_f32 v156, v120, v121
	v_cvt_pk_bf16_f32 v157, v122, v123
	ds_write_b64 v236, v[156:157] offset:16192
	v_cvt_pk_bf16_f32 v158, v124, v125
	v_cvt_pk_bf16_f32 v159, v126, v127
	ds_write_b64 v236, v[158:159] offset:16224
	s_waitcnt lgkmcnt(0)
	ds_read_b128 v[128:131], v237
	ds_read_b128 v[132:135], v237 offset:1152
	ds_read_b128 v[136:139], v237 offset:2304
	ds_read_b128 v[140:143], v237 offset:3456
	ds_read_b128 v[144:147], v237 offset:4608
	ds_read_b128 v[148:151], v237 offset:5760
	ds_read_b128 v[152:155], v237 offset:6912
	ds_read_b128 v[156:159], v237 offset:8064
	ds_read_b128 v[160:163], v237 offset:9216
	ds_read_b128 v[164:167], v237 offset:10368
	ds_read_b128 v[168:171], v237 offset:11520
	ds_read_b128 v[172:175], v237 offset:12672
	ds_read_b128 v[176:179], v237 offset:13824
	ds_read_b128 v[180:183], v237 offset:14976
	ds_read_b128 v[184:187], v237 offset:16128
	ds_read_b128 v[188:191], v237 offset:17280
	s_waitcnt lgkmcnt(15)
	global_store_dwordx4 v238, v[128:131], s[4:5]
	s_add_u32 s4, s4, 0x2000
	s_addc_u32 s5, s5, 0
	s_waitcnt lgkmcnt(14)
	global_store_dwordx4 v238, v[132:135], s[4:5]
	s_add_u32 s4, s4, 0x2000
	s_addc_u32 s5, s5, 0
	s_waitcnt lgkmcnt(13)
	global_store_dwordx4 v238, v[136:139], s[4:5]
	s_add_u32 s4, s4, 0x2000
	s_addc_u32 s5, s5, 0
	s_waitcnt lgkmcnt(12)
	global_store_dwordx4 v238, v[140:143], s[4:5]
	s_add_u32 s4, s4, 0x2000
	s_addc_u32 s5, s5, 0
	s_waitcnt lgkmcnt(11)
	global_store_dwordx4 v238, v[144:147], s[4:5]
	s_add_u32 s4, s4, 0x2000
	s_addc_u32 s5, s5, 0
	s_waitcnt lgkmcnt(10)
	global_store_dwordx4 v238, v[148:151], s[4:5]
	s_add_u32 s4, s4, 0x2000
	s_addc_u32 s5, s5, 0
	s_waitcnt lgkmcnt(9)
	global_store_dwordx4 v238, v[152:155], s[4:5]
	s_add_u32 s4, s4, 0x2000
	s_addc_u32 s5, s5, 0
	s_waitcnt lgkmcnt(8)
	global_store_dwordx4 v238, v[156:159], s[4:5]
	s_add_u32 s4, s4, 0x2000
	s_addc_u32 s5, s5, 0
	s_waitcnt lgkmcnt(7)
	global_store_dwordx4 v238, v[160:163], s[4:5]
	s_add_u32 s4, s4, 0x2000
	s_addc_u32 s5, s5, 0
	s_waitcnt lgkmcnt(6)
	global_store_dwordx4 v238, v[164:167], s[4:5]
	s_add_u32 s4, s4, 0x2000
	s_addc_u32 s5, s5, 0
	s_waitcnt lgkmcnt(5)
	global_store_dwordx4 v238, v[168:171], s[4:5]
	s_add_u32 s4, s4, 0x2000
	s_addc_u32 s5, s5, 0
	s_waitcnt lgkmcnt(4)
	global_store_dwordx4 v238, v[172:175], s[4:5]
	s_add_u32 s4, s4, 0x2000
	s_addc_u32 s5, s5, 0
	s_waitcnt lgkmcnt(3)
	global_store_dwordx4 v238, v[176:179], s[4:5]
	s_add_u32 s4, s4, 0x2000
	s_addc_u32 s5, s5, 0
	s_waitcnt lgkmcnt(2)
	global_store_dwordx4 v238, v[180:183], s[4:5]
	s_add_u32 s4, s4, 0x2000
	s_addc_u32 s5, s5, 0
	s_waitcnt lgkmcnt(1)
	global_store_dwordx4 v238, v[184:187], s[4:5]
	s_add_u32 s4, s4, 0x2000
	s_addc_u32 s5, s5, 0
	s_waitcnt lgkmcnt(0)
	global_store_dwordx4 v238, v[188:191], s[4:5]
	s_nop 1
	s_add_u32 s15, s15, 64
	s_branch .Lg3d_tile
.Lg3d_done:
	v_mbcnt_lo_u32_b32 v194, -1, 0
	v_mbcnt_hi_u32_b32 v136, -1, v194

; #define PH(k) case k: if (ONLY_PHASE >= 0 && ONLY_PHASE != k) break;
; template <class Epi>
; DI void gemm_phase(char* smem, const bf16_t* A0, int lda0, int ksplit, const bf16_t* A1, int lda1, const bf16_t* Bt, int K, int nN, const Epi& epi, int tid) {
;   const int G = gridDim.x;
;   if ((G & 7) == 0) {
;     const int x = blockIdx.x & 7, l = blockIdx.x >> 3, L = G >> 3, per = 8 * nN, tot = 2 * per;
; template <int ph> DI void run_phase(const Ctx& c, char* smem) {
;     ...
;     PH(6) gemm_phase(smem, (const bf16_t*)(ws + OFF_R1), 512, 512, (const bf16_t*)(ws + OFF_R2), 2592, (const bf16_t*)(ws + OFF_WABOUT), 1536, 8, EpiResid{p.x, p.out}, TIDX); break;
.LBB0_855:
	s_cmp_gt_i32 s94, 6
	s_cselect_b64 s[0:1], -1, 0
	s_cmp_lt_i32 s95, 7
	s_cselect_b64 s[2:3], -1, 0
	s_or_b64 s[0:1], s[0:1], s[2:3]
	s_and_b64 vcc, exec, s[0:1]
	s_cbranch_vccnz .LBB0_883
	s_add_u32 s0, s92, 0x7800000
	s_load_dword s12, s[74:75], 0x180
	s_addc_u32 s1, s93, 0
	s_add_u32 s6, s92, 0xe800000
	s_addc_u32 s7, s93, 0
	s_add_u32 s2, s92, 0x8c0000
	s_addc_u32 s3, s93, 0
	s_and_b32 s8, s72, 0xffffffc0
	v_mbcnt_hi_u32_b32 v195, -1, v194
	s_waitcnt lgkmcnt(0)
	s_and_b32 s10, s12, 7
	s_cmp_lg_u32 s10, 0
	s_waitcnt vmcnt(16)
	v_add_u32_e32 v196, s8, v195
	v_mbcnt_lo_u32_b32 v240, -1, 0
	v_mbcnt_hi_u32_b32 v240, -1, v240
	s_lshr_b32 s20, s72, 6
	s_lshl_b32 s13, s20, 10
	v_and_b32_e32 v241, 15, v240
	v_lshrrev_b32_e32 v242, 4, v240
	v_bfe_u32 v243, v240, 3, 1
	v_mul_u32_u24_e32 v243, 3, v243
	v_xor_b32_e32 v243, v242, v243
	v_lshlrev_b32_e32 v243, 4, v243
	v_lshl_add_u32 v243, v241, 6, v243
	s_lshr_b32 s19, s20, 1
	s_lshl_b32 s19, s19, 13
	v_add_u32_e32 v230, s19, v243
	s_and_b32 s19, s20, 1
	s_lshl_b32 s19, s19, 12
	s_add_u32 s19, s19, 16384
	v_add_u32_e32 v231, s19, v243
	s_lshr_b32 s19, s20, 1
	s_lshl_b32 s19, s19, 7
	v_add_u32_e32 v244, s19, v241
	s_and_b32 s19, s20, 1
	s_lshl_b32 s19, s19, 6
	v_lshl_add_u32 v245, v242, 2, s19
	s_movk_i32 s19, 0x1000
	v_mul_lo_u32 v246, v244, s19
	v_lshl_add_u32 v234, v245, 2, v246
	v_lshrrev_b32_e32 v241, 2, v240
	s_lshl_b32 s19, s20, 4
	v_add_u32_e32 v241, s19, v241
	v_bfe_u32 v242, v240, 5, 1
	v_mul_u32_u24_e32 v242, 3, v242
	v_and_b32_e32 v243, 3, v240
	v_xor_b32_e32 v243, v243, v242
	v_lshlrev_b32_e32 v243, 4, v243
	s_mov_b32 s19, 1024
	v_mad_u32_u24 v224, v241, s19, v243
	v_add_u32_e32 v225, 0x10000, v224
	v_add_u32_e32 v226, 0x20000, v224
	v_add_u32_e32 v227, 0x30000, v224
	s_mov_b32 s19, 5184
	v_mad_u32_u24 v236, v241, s19, v243
	v_add_u32_e32 v237, 0x51000, v236
	v_add_u32_e32 v238, 0xa2000, v236
	v_add_u32_e32 v239, 0xf3000, v236
	v_mov_b32_e32 v248, v224
	v_mov_b32_e32 v249, v225
	v_mov_b32_e32 v250, v226
	v_mov_b32_e32 v251, v227
	s_mov_b32 s19, 3072
	v_mad_u32_u24 v228, v241, s19, v243
	v_add_u32_e32 v229, 0x30000, v228
	s_load_dwordx2 s[6:7], s[74:75], 0x168
	s_load_dwordx2 s[14:15], s[74:75], 0x0
	v_mbcnt_lo_u32_b32 v240, -1, 0
	v_mbcnt_hi_u32_b32 v240, -1, v240
	s_lshr_b32 s20, s72, 6
	s_mul_i32 s19, s20, 17408
	v_and_b32_e32 v241, 15, v240
	v_lshrrev_b32_e32 v242, 4, v240
	v_mul_u32_u24_e32 v243, 0x110, v241
	v_lshl_add_u32 v243, v242, 4, v243
	v_add_u32_e32 v245, s19, v243
	v_mul_u32_u24_e32 v243, 0x110, v242
	v_lshl_add_u32 v243, v241, 4, v243
	v_add_u32_e32 v246, s19, v243
	s_lshr_b32 s19, s20, 1
	s_lshl_b32 s19, s19, 7
	v_add_u32_e32 v243, s19, v242
	v_lshlrev_b32_e32 v243, 12, v243
	s_and_b32 s19, s20, 1
	s_lshl_b32 s19, s19, 8
	v_lshl_add_u32 v244, v241, 4, s19
	v_add_u32_e32 v247, v243, v244
	s_lshr_b32 s9, s96, 3
	s_and_b32 s11, s96, 7
	s_lshl_b32 s11, s11, 1
	s_waitcnt lgkmcnt(0)
; #define LWRITE(S, buf) do { bf16_t* sA_ = sbase + (buf) * BUF; bf16_t* sB_ = sA_ + 256 * PITCH; \
;     _Pragma("unroll") for (int i_ = 0; i_ < 4; ++i_) *(u32x4*)(sA_ + (sr + i_ * 64) * PITCH + scv * 8) = ra[S][i_]; \
;     _Pragma("unroll") for (int i_ = 0; i_ < 2; ++i_) *(u32x4*)(sB_ + (sr + i_ * 64) * PITCH + scv * 8) = rb[S][i_]; } while (0)
; template <class Epi>
; DI void gemm_tile(char* smem, const bf16_t* __restrict__ A0, int lda0, int ksplit, const bf16_t* __restrict__ A1, int lda1,
;                   const bf16_t* __restrict__ Bt, int K, int row0, int col0, const Epi& epi, int tid) {
;     ...
;   __syncthreads();
;   {
;     const int last = nk - 1;
;     GLOAD(0, 0);
;     __builtin_amdgcn_sched_barrier(0);
;     GLOAD(1, 1);
;     __builtin_amdgcn_sched_barrier(0);
;     LWRITE(0, 0);
;     __builtin_amdgcn_sched_barrier(0);
;     GLOAD(0, (2 < last ? 2 : last));
;     __builtin_amdgcn_sched_barrier(0);
;     __syncthreads();
; template <class Epi>
; DI void gemm_phase(char* smem, const bf16_t* A0, int lda0, int ksplit, const bf16_t* A1, int lda1, const bf16_t* Bt, int K, int nN, const Epi& epi, int tid) {
;     ...
;     const int x = blockIdx.x & 7, l = blockIdx.x >> 3, L = G >> 3, per = 8 * nN, tot = 2 * per;
;     for (int q = l; q < tot; q += L) { const int rgl = q / per, rem = q % per, ct = rem >> 3, rt = (x * 2 + rgl) * 8 + (rem & 7);
;       gemm_tile(smem, A0, lda0, ksplit, A1, lda1, Bt, K, rt * 256, ct * 128, epi, tid); }
.Lg6_tile:
	s_cmpk_ge_u32 s9, 128
	s_cbranch_scc1 .Lg6_done
	s_cmpk_ge_u32 s9, 64
	s_cselect_b32 s20, 1, 0
	s_cselect_b32 s19, 64, 0
	s_sub_u32 s19, s9, s19
	s_and_b32 s98, s19, 7
	s_lshl_b32 s98, s98, 3
	s_bfe_u32 s21, s19, 0x30003
	s_or_b32 s98, s98, s21
	s_andn2_b32 s19, s19, 63
	s_or_b32 s19, s19, s98
	s_add_u32 s20, s20, s11
	s_lshl_b32 s20, s20, 3
	s_and_b32 s98, s19, 7
	s_add_u32 s98, s98, s20
	s_lshl_b32 s98, s98, 8
	s_lshr_b32 s21, s19, 3
	s_lshl_b32 s21, s21, 7
	s_mul_i32 s20, s98, 1024
	s_add_u32 s20, s20, 0x7800000
	s_add_u32 s0, s92, s20
	s_addc_u32 s1, s93, 0
	s_mul_i32 s20, s21, 3072
	s_add_u32 s20, s20, 0x8c0000
	s_add_u32 s2, s92, s20
	s_addc_u32 s3, s93, 0
	v_mov_b32_e32 v224, v248
	v_mov_b32_e32 v225, v249
	v_mov_b32_e32 v226, v250
	v_mov_b32_e32 v227, v251
	s_waitcnt lgkmcnt(0)
	s_barrier
	s_mov_b32 s22, 0
	s_mov_b32 s99, 0
	s_add_u32 s19, s99, s13
	s_add_u32 m0, s19, 0
	s_nop 0
	global_load_lds_dwordx4 v224, s[0:1]
	s_add_u32 m0, s19, 4096
	s_nop 0
	global_load_lds_dwordx4 v225, s[0:1]
	s_add_u32 m0, s19, 8192
	s_nop 0
	global_load_lds_dwordx4 v226, s[0:1]
	s_add_u32 m0, s19, 12288
	s_nop 0
	global_load_lds_dwordx4 v227, s[0:1]
	s_add_u32 m0, s19, 16384
	s_nop 0
	global_load_lds_dwordx4 v228, s[2:3]
	s_add_u32 m0, s19, 20480
	s_nop 0
	global_load_lds_dwordx4 v229, s[2:3]
	s_add_u32 s0, s0, 64
	s_addc_u32 s1, s1, 0
	s_add_u32 s2, s2, 64
	s_addc_u32 s3, s3, 0
	s_add_u32 s22, s22, 1
	s_add_u32 s99, s99, 24576
	s_cmp_eq_u32 s99, 73728
	s_cselect_b32 s99, 0, s99
	s_add_u32 s19, s99, s13
	s_add_u32 m0, s19, 0
	s_nop 0
	global_load_lds_dwordx4 v224, s[0:1]
	s_add_u32 m0, s19, 4096
	s_nop 0
	global_load_lds_dwordx4 v225, s[0:1]
	s_add_u32 m0, s19, 8192
	s_nop 0
	global_load_lds_dwordx4 v226, s[0:1]
	s_add_u32 m0, s19, 12288
	s_nop 0
	global_load_lds_dwordx4 v227, s[0:1]
	s_add_u32 m0, s19, 16384
	s_nop 0
	global_load_lds_dwordx4 v228, s[2:3]
	s_add_u32 m0, s19, 20480
	s_nop 0
	global_load_lds_dwordx4 v229, s[2:3]
	s_add_u32 s0, s0, 64
	s_addc_u32 s1, s1, 0
	s_add_u32 s2, s2, 64
	s_addc_u32 s3, s3, 0
	s_add_u32 s22, s22, 1
	s_add_u32 s99, s99, 24576
	s_cmp_eq_u32 s99, 73728
	s_cselect_b32 s99, 0, s99
	s_add_u32 s19, s99, s13
	s_add_u32 m0, s19, 0
	s_nop 0
	global_load_lds_dwordx4 v224, s[0:1]
	s_add_u32 m0, s19, 4096
	s_nop 0
	global_load_lds_dwordx4 v225, s[0:1]
	s_add_u32 m0, s19, 8192
	s_nop 0
	global_load_lds_dwordx4 v226, s[0:1]
	s_add_u32 m0, s19, 12288
	s_nop 0
	global_load_lds_dwordx4 v227, s[0:1]
	s_add_u32 m0, s19, 16384
	s_nop 0
	global_load_lds_dwordx4 v228, s[2:3]
	s_add_u32 m0, s19, 20480
	s_nop 0
	global_load_lds_dwordx4 v229, s[2:3]
	s_add_u32 s0, s0, 64
	s_addc_u32 s1, s1, 0
	s_add_u32 s2, s2, 64
	s_addc_u32 s3, s3, 0
	s_add_u32 s22, s22, 1
	s_add_u32 s99, s99, 24576
	s_cmp_eq_u32 s99, 73728
	s_cselect_b32 s99, 0, s99
	v_mov_b32_e32 v0, 0
	v_mov_b32_e32 v1, 0
	v_mov_b32_e32 v2, 0
	v_mov_b32_e32 v3, 0
	v_mov_b32_e32 v4, 0
	v_mov_b32_e32 v5, 0
	v_mov_b32_e32 v6, 0
	v_mov_b32_e32 v7, 0
	v_mov_b32_e32 v8, 0
	v_mov_b32_e32 v9, 0
	v_mov_b32_e32 v10, 0
	v_mov_b32_e32 v11, 0
	v_mov_b32_e32 v12, 0
	v_mov_b32_e32 v13, 0
	v_mov_b32_e32 v14, 0
	v_mov_b32_e32 v15, 0
	v_mov_b32_e32 v16, 0
	v_mov_b32_e32 v17, 0
	v_mov_b32_e32 v18, 0
	v_mov_b32_e32 v19, 0
	v_mov_b32_e32 v20, 0
	v_mov_b32_e32 v21, 0
	v_mov_b32_e32 v22, 0
	v_mov_b32_e32 v23, 0
	v_mov_b32_e32 v24, 0
	v_mov_b32_e32 v25, 0
	v_mov_b32_e32 v26, 0
	v_mov_b32_e32 v27, 0
	v_mov_b32_e32 v28, 0
	v_mov_b32_e32 v29, 0
	v_mov_b32_e32 v30, 0
	v_mov_b32_e32 v31, 0
	v_mov_b32_e32 v32, 0
	v_mov_b32_e32 v33, 0
	v_mov_b32_e32 v34, 0
	v_mov_b32_e32 v35, 0
	v_mov_b32_e32 v36, 0
	v_mov_b32_e32 v37, 0
	v_mov_b32_e32 v38, 0
	v_mov_b32_e32 v39, 0
	v_mov_b32_e32 v40, 0
	v_mov_b32_e32 v41, 0
	v_mov_b32_e32 v42, 0
	v_mov_b32_e32 v43, 0
	v_mov_b32_e32 v44, 0
	v_mov_b32_e32 v45, 0
	v_mov_b32_e32 v46, 0
	v_mov_b32_e32 v47, 0
	v_mov_b32_e32 v48, 0
	v_mov_b32_e32 v49, 0
	v_mov_b32_e32 v50, 0
	v_mov_b32_e32 v51, 0
	v_mov_b32_e32 v52, 0
	v_mov_b32_e32 v53, 0
	v_mov_b32_e32 v54, 0
	v_mov_b32_e32 v55, 0
	v_mov_b32_e32 v56, 0
	v_mov_b32_e32 v57, 0
	v_mov_b32_e32 v58, 0
	v_mov_b32_e32 v59, 0
	v_mov_b32_e32 v60, 0
	v_mov_b32_e32 v61, 0
	v_mov_b32_e32 v62, 0
	v_mov_b32_e32 v63, 0
	v_mov_b32_e32 v64, 0
	v_mov_b32_e32 v65, 0
	v_mov_b32_e32 v66, 0
	v_mov_b32_e32 v67, 0
	v_mov_b32_e32 v68, 0
	v_mov_b32_e32 v69, 0
	v_mov_b32_e32 v70, 0
	v_mov_b32_e32 v71, 0
	v_mov_b32_e32 v72, 0
	v_mov_b32_e32 v73, 0
	v_mov_b32_e32 v74, 0
	v_mov_b32_e32 v75, 0
	v_mov_b32_e32 v76, 0
	v_mov_b32_e32 v77, 0
	v_mov_b32_e32 v78, 0
	v_mov_b32_e32 v79, 0
	v_mov_b32_e32 v80, 0
	v_mov_b32_e32 v81, 0
	v_mov_b32_e32 v82, 0
	v_mov_b32_e32 v83, 0
	v_mov_b32_e32 v84, 0
	v_mov_b32_e32 v85, 0
	v_mov_b32_e32 v86, 0
	v_mov_b32_e32 v87, 0
	v_mov_b32_e32 v88, 0
	v_mov_b32_e32 v89, 0
	v_mov_b32_e32 v90, 0
	v_mov_b32_e32 v91, 0
	v_mov_b32_e32 v92, 0
	v_mov_b32_e32 v93, 0
	v_mov_b32_e32 v94, 0
	v_mov_b32_e32 v95, 0
	v_mov_b32_e32 v96, 0
	v_mov_b32_e32 v97, 0
	v_mov_b32_e32 v98, 0
	v_mov_b32_e32 v99, 0
	v_mov_b32_e32 v100, 0
	v_mov_b32_e32 v101, 0
	v_mov_b32_e32 v102, 0
	v_mov_b32_e32 v103, 0
	v_mov_b32_e32 v104, 0
	v_mov_b32_e32 v105, 0
	v_mov_b32_e32 v106, 0
	v_mov_b32_e32 v107, 0
	v_mov_b32_e32 v108, 0
	v_mov_b32_e32 v109, 0
	v_mov_b32_e32 v110, 0
	v_mov_b32_e32 v111, 0
	v_mov_b32_e32 v112, 0
	v_mov_b32_e32 v113, 0
	v_mov_b32_e32 v114, 0
	v_mov_b32_e32 v115, 0
	v_mov_b32_e32 v116, 0
	v_mov_b32_e32 v117, 0
	v_mov_b32_e32 v118, 0
	v_mov_b32_e32 v119, 0
	v_mov_b32_e32 v120, 0
	v_mov_b32_e32 v121, 0
	v_mov_b32_e32 v122, 0
	v_mov_b32_e32 v123, 0
	v_mov_b32_e32 v124, 0
	v_mov_b32_e32 v125, 0
	v_mov_b32_e32 v126, 0
	v_mov_b32_e32 v127, 0
	s_mov_b32 s101, 0
	s_mov_b32 s100, 24576
	s_waitcnt vmcnt(12)
	s_barrier
	ds_read_b128 v[128:131], v231 offset:0
	ds_read_b128 v[132:135], v231 offset:1024
	ds_read_b128 v[136:139], v231 offset:2048
	ds_read_b128 v[140:143], v231 offset:3072
	ds_read_b128 v[144:147], v230 offset:0
	ds_read_b128 v[148:151], v230 offset:1024
	ds_read_b128 v[152:155], v230 offset:2048
	ds_read_b128 v[156:159], v230 offset:3072
	ds_read_b128 v[160:163], v230 offset:4096
	ds_read_b128 v[164:167], v230 offset:5120
	ds_read_b128 v[168:171], v230 offset:6144
	ds_read_b128 v[172:175], v230 offset:7168

; template <class Epi>
; DI void gemm_tile(char* smem, const bf16_t* __restrict__ A0, int lda0, int ksplit, const bf16_t* __restrict__ A1, int lda1,
;                   const bf16_t* __restrict__ Bt, int K, int row0, int col0, const Epi& epi, int tid) {
;     ...
; #pragma unroll
;   for (int m = 0; m < 8; ++m)
; #pragma unroll
;     for (int n = 0; n < 4; ++n) epi(row0 + wr * 128 + m * 16 + fr, col0 + wc * 64 + n * 16 + fq * 4, acc[m][n]);
.Lg6_epi:
	s_nop 7
	s_nop 7
	s_lshl_b32 s20, s98, 12
	s_lshl_b32 s19, s21, 2
	s_add_u32 s20, s20, s19
	s_add_u32 s4, s6, s20
	s_addc_u32 s5, s7, 0
	s_lshl_b32 s20, s98, 12
	s_lshl_b32 s19, s21, 2
	s_add_u32 s20, s20, s19
	s_add_u32 s0, s14, s20
	s_addc_u32 s1, s15, 0
	ds_write_b128 v245, v[0:3]
	ds_write_b128 v245, v[4:7] offset:64
	ds_write_b128 v245, v[8:11] offset:128
	ds_write_b128 v245, v[12:15] offset:192
	ds_write_b128 v245, v[16:19] offset:4352
	ds_write_b128 v245, v[20:23] offset:4416
	ds_write_b128 v245, v[24:27] offset:4480
	ds_write_b128 v245, v[28:31] offset:4544
	ds_write_b128 v245, v[32:35] offset:8704
	ds_write_b128 v245, v[36:39] offset:8768
	ds_write_b128 v245, v[40:43] offset:8832
	ds_write_b128 v245, v[44:47] offset:8896
	ds_write_b128 v245, v[48:51] offset:13056
	ds_write_b128 v245, v[52:55] offset:13120
	ds_write_b128 v245, v[56:59] offset:13184
	ds_write_b128 v245, v[60:63] offset:13248
	global_load_dwordx4 v[128:131], v247, s[0:1]
	s_add_u32 s0, s0, 0x4000
	s_addc_u32 s1, s1, 0
	global_load_dwordx4 v[132:135], v247, s[0:1]
	s_add_u32 s0, s0, 0x4000
	s_addc_u32 s1, s1, 0
	global_load_dwordx4 v[136:139], v247, s[0:1]
	s_add_u32 s0, s0, 0x4000
	s_addc_u32 s1, s1, 0
	global_load_dwordx4 v[140:143], v247, s[0:1]
	s_add_u32 s0, s0, 0x4000
	s_addc_u32 s1, s1, 0
	global_load_dwordx4 v[144:147], v247, s[0:1]
	s_add_u32 s0, s0, 0x4000
	s_addc_u32 s1, s1, 0
	global_load_dwordx4 v[148:151], v247, s[0:1]
	s_add_u32 s0, s0, 0x4000
	s_addc_u32 s1, s1, 0
	global_load_dwordx4 v[152:155], v247, s[0:1]
	s_add_u32 s0, s0, 0x4000
	s_addc_u32 s1, s1, 0
	global_load_dwordx4 v[156:159], v247, s[0:1]
	s_add_u32 s0, s0, 0x4000
	s_addc_u32 s1, s1, 0
	s_waitcnt lgkmcnt(0)
	ds_read_b128 v[160:163], v246
	ds_read_b128 v[164:167], v246 offset:1088
	ds_read_b128 v[168:171], v246 offset:2176
	ds_read_b128 v[172:175], v246 offset:3264
	ds_read_b128 v[176:179], v246 offset:4352
	ds_read_b128 v[180:183], v246 offset:5440
	ds_read_b128 v[184:187], v246 offset:6528
	ds_read_b128 v[188:191], v246 offset:7616
	s_waitcnt vmcnt(7) lgkmcnt(7)
	v_pk_add_f32 v[128:129], v[128:129], v[160:161]
	v_pk_add_f32 v[130:131], v[130:131], v[162:163]
	global_store_dwordx4 v247, v[128:131], s[4:5]
	s_add_u32 s4, s4, 0x4000
	s_addc_u32 s5, s5, 0
	s_waitcnt vmcnt(7) lgkmcnt(6)
	v_pk_add_f32 v[132:133], v[132:133], v[164:165]
	v_pk_add_f32 v[134:135], v[134:135], v[166:167]
	global_store_dwordx4 v247, v[132:135], s[4:5]
	s_add_u32 s4, s4, 0x4000
	s_addc_u32 s5, s5, 0
	s_waitcnt vmcnt(7) lgkmcnt(5)
	v_pk_add_f32 v[136:137], v[136:137], v[168:169]
	v_pk_add_f32 v[138:139], v[138:139], v[170:171]
	global_store_dwordx4 v247, v[136:139], s[4:5]
	s_add_u32 s4, s4, 0x4000
	s_addc_u32 s5, s5, 0
	s_waitcnt vmcnt(7) lgkmcnt(4)
	v_pk_add_f32 v[140:141], v[140:141], v[172:173]
	v_pk_add_f32 v[142:143], v[142:143], v[174:175]
	global_store_dwordx4 v247, v[140:143], s[4:5]
	s_add_u32 s4, s4, 0x4000
	s_addc_u32 s5, s5, 0
	s_waitcnt vmcnt(7) lgkmcnt(3)
	v_pk_add_f32 v[144:145], v[144:145], v[176:177]
	v_pk_add_f32 v[146:147], v[146:147], v[178:179]
	global_store_dwordx4 v247, v[144:147], s[4:5]
	s_add_u32 s4, s4, 0x4000
	s_addc_u32 s5, s5, 0
	s_waitcnt vmcnt(7) lgkmcnt(2)
	v_pk_add_f32 v[148:149], v[148:149], v[180:181]
	v_pk_add_f32 v[150:151], v[150:151], v[182:183]
	global_store_dwordx4 v247, v[148:151], s[4:5]
	s_add_u32 s4, s4, 0x4000
	s_addc_u32 s5, s5, 0
	s_waitcnt vmcnt(7) lgkmcnt(1)
	v_pk_add_f32 v[152:153], v[152:153], v[184:185]
	v_pk_add_f32 v[154:155], v[154:155], v[186:187]
	global_store_dwordx4 v247, v[152:155], s[4:5]
	s_add_u32 s4, s4, 0x4000
	s_addc_u32 s5, s5, 0
	s_waitcnt vmcnt(7) lgkmcnt(0)
	v_pk_add_f32 v[156:157], v[156:157], v[188:189]
	v_pk_add_f32 v[158:159], v[158:159], v[190:191]
	global_store_dwordx4 v247, v[156:159], s[4:5]
	s_add_u32 s4, s4, 0x4000
	s_addc_u32 s5, s5, 0
	s_nop 1
	global_load_dwordx4 v[128:131], v247, s[0:1]
	s_add_u32 s0, s0, 0x4000
	s_addc_u32 s1, s1, 0
	global_load_dwordx4 v[132:135], v247, s[0:1]
	s_add_u32 s0, s0, 0x4000
	s_addc_u32 s1, s1, 0
	global_load_dwordx4 v[136:139], v247, s[0:1]
	s_add_u32 s0, s0, 0x4000
	s_addc_u32 s1, s1, 0
	global_load_dwordx4 v[140:143], v247, s[0:1]
	s_add_u32 s0, s0, 0x4000
	s_addc_u32 s1, s1, 0
	global_load_dwordx4 v[144:147], v247, s[0:1]
	s_add_u32 s0, s0, 0x4000
	s_addc_u32 s1, s1, 0
	global_load_dwordx4 v[148:151], v247, s[0:1]
	s_add_u32 s0, s0, 0x4000
	s_addc_u32 s1, s1, 0
	global_load_dwordx4 v[152:155], v247, s[0:1]
	s_add_u32 s0, s0, 0x4000
	s_addc_u32 s1, s1, 0
	global_load_dwordx4 v[156:159], v247, s[0:1]
	s_add_u32 s0, s0, 0x4000
	s_addc_u32 s1, s1, 0
	ds_read_b128 v[160:163], v246 offset:8704
	ds_read_b128 v[164:167], v246 offset:9792
	ds_read_b128 v[168:171], v246 offset:10880
	ds_read_b128 v[172:175], v246 offset:11968
	ds_read_b128 v[176:179], v246 offset:13056
	ds_read_b128 v[180:183], v246 offset:14144
	ds_read_b128 v[184:187], v246 offset:15232
	ds_read_b128 v[188:191], v246 offset:16320
	s_waitcnt vmcnt(7) lgkmcnt(7)
	v_pk_add_f32 v[128:129], v[128:129], v[160:161]
	v_pk_add_f32 v[130:131], v[130:131], v[162:163]
	global_store_dwordx4 v247, v[128:131], s[4:5]
	s_add_u32 s4, s4, 0x4000
	s_addc_u32 s5, s5, 0
	s_waitcnt vmcnt(7) lgkmcnt(6)
	v_pk_add_f32 v[132:133], v[132:133], v[164:165]
	v_pk_add_f32 v[134:135], v[134:135], v[166:167]
	global_store_dwordx4 v247, v[132:135], s[4:5]
	s_add_u32 s4, s4, 0x4000
	s_addc_u32 s5, s5, 0
	s_waitcnt vmcnt(7) lgkmcnt(5)
	v_pk_add_f32 v[136:137], v[136:137], v[168:169]
	v_pk_add_f32 v[138:139], v[138:139], v[170:171]
	global_store_dwordx4 v247, v[136:139], s[4:5]
	s_add_u32 s4, s4, 0x4000
	s_addc_u32 s5, s5, 0
	s_waitcnt vmcnt(7) lgkmcnt(4)
; template <class Epi>
; DI void gemm_tile(char* smem, const bf16_t* __restrict__ A0, int lda0, int ksplit, const bf16_t* __restrict__ A1, int lda1,
;                   const bf16_t* __restrict__ Bt, int K, int row0, int col0, const Epi& epi, int tid) {
;     ...
; #pragma unroll
;   for (int m = 0; m < 8; ++m)
; #pragma unroll
;     for (int n = 0; n < 4; ++n) epi(row0 + wr * 128 + m * 16 + fr, col0 + wc * 64 + n * 16 + fq * 4, acc[m][n]);
	v_pk_add_f32 v[140:141], v[140:141], v[172:173]
	v_pk_add_f32 v[142:143], v[142:143], v[174:175]
	global_store_dwordx4 v247, v[140:143], s[4:5]
	s_add_u32 s4, s4, 0x4000
	s_addc_u32 s5, s5, 0
	s_waitcnt vmcnt(7) lgkmcnt(3)
	v_pk_add_f32 v[144:145], v[144:145], v[176:177]
	v_pk_add_f32 v[146:147], v[146:147], v[178:179]
	global_store_dwordx4 v247, v[144:147], s[4:5]
	s_add_u32 s4, s4, 0x4000
	s_addc_u32 s5, s5, 0
	s_waitcnt vmcnt(7) lgkmcnt(2)
	v_pk_add_f32 v[148:149], v[148:149], v[180:181]
	v_pk_add_f32 v[150:151], v[150:151], v[182:183]
	global_store_dwordx4 v247, v[148:151], s[4:5]
	s_add_u32 s4, s4, 0x4000
	s_addc_u32 s5, s5, 0
	s_waitcnt vmcnt(7) lgkmcnt(1)
	v_pk_add_f32 v[152:153], v[152:153], v[184:185]
	v_pk_add_f32 v[154:155], v[154:155], v[186:187]
	global_store_dwordx4 v247, v[152:155], s[4:5]
	s_add_u32 s4, s4, 0x4000
	s_addc_u32 s5, s5, 0
	s_waitcnt vmcnt(7) lgkmcnt(0)
	v_pk_add_f32 v[156:157], v[156:157], v[188:189]
	v_pk_add_f32 v[158:159], v[158:159], v[190:191]
	global_store_dwordx4 v247, v[156:159], s[4:5]
	s_add_u32 s4, s4, 0x4000
	s_addc_u32 s5, s5, 0
	s_nop 1
	s_waitcnt lgkmcnt(0)
	ds_write_b128 v245, v[64:67]
	ds_write_b128 v245, v[68:71] offset:64
	ds_write_b128 v245, v[72:75] offset:128
	ds_write_b128 v245, v[76:79] offset:192
	ds_write_b128 v245, v[80:83] offset:4352
	ds_write_b128 v245, v[84:87] offset:4416
	ds_write_b128 v245, v[88:91] offset:4480
	ds_write_b128 v245, v[92:95] offset:4544
	ds_write_b128 v245, v[96:99] offset:8704
	ds_write_b128 v245, v[100:103] offset:8768
	ds_write_b128 v245, v[104:107] offset:8832
	ds_write_b128 v245, v[108:111] offset:8896
	ds_write_b128 v245, v[112:115] offset:13056
	ds_write_b128 v245, v[116:119] offset:13120
	ds_write_b128 v245, v[120:123] offset:13184
	ds_write_b128 v245, v[124:127] offset:13248
	global_load_dwordx4 v[128:131], v247, s[0:1]
	s_add_u32 s0, s0, 0x4000
	s_addc_u32 s1, s1, 0
	global_load_dwordx4 v[132:135], v247, s[0:1]
	s_add_u32 s0, s0, 0x4000
	s_addc_u32 s1, s1, 0
	global_load_dwordx4 v[136:139], v247, s[0:1]
	s_add_u32 s0, s0, 0x4000
	s_addc_u32 s1, s1, 0
	global_load_dwordx4 v[140:143], v247, s[0:1]
	s_add_u32 s0, s0, 0x4000
	s_addc_u32 s1, s1, 0
	global_load_dwordx4 v[144:147], v247, s[0:1]
	s_add_u32 s0, s0, 0x4000
	s_addc_u32 s1, s1, 0
	global_load_dwordx4 v[148:151], v247, s[0:1]
	s_add_u32 s0, s0, 0x4000
	s_addc_u32 s1, s1, 0
	global_load_dwordx4 v[152:155], v247, s[0:1]
	s_add_u32 s0, s0, 0x4000
	s_addc_u32 s1, s1, 0
	global_load_dwordx4 v[156:159], v247, s[0:1]
	s_add_u32 s0, s0, 0x4000
	s_addc_u32 s1, s1, 0
	s_waitcnt lgkmcnt(0)
	ds_read_b128 v[160:163], v246
	ds_read_b128 v[164:167], v246 offset:1088
	ds_read_b128 v[168:171], v246 offset:2176
	ds_read_b128 v[172:175], v246 offset:3264
	ds_read_b128 v[176:179], v246 offset:4352
	ds_read_b128 v[180:183], v246 offset:5440
	ds_read_b128 v[184:187], v246 offset:6528
	ds_read_b128 v[188:191], v246 offset:7616
	s_waitcnt vmcnt(7) lgkmcnt(7)
	v_pk_add_f32 v[128:129], v[128:129], v[160:161]
	v_pk_add_f32 v[130:131], v[130:131], v[162:163]
	global_store_dwordx4 v247, v[128:131], s[4:5]
	s_add_u32 s4, s4, 0x4000
	s_addc_u32 s5, s5, 0
	s_waitcnt vmcnt(7) lgkmcnt(6)
	v_pk_add_f32 v[132:133], v[132:133], v[164:165]
	v_pk_add_f32 v[134:135], v[134:135], v[166:167]
	global_store_dwordx4 v247, v[132:135], s[4:5]
	s_add_u32 s4, s4, 0x4000
	s_addc_u32 s5, s5, 0
	s_waitcnt vmcnt(7) lgkmcnt(5)
	v_pk_add_f32 v[136:137], v[136:137], v[168:169]
	v_pk_add_f32 v[138:139], v[138:139], v[170:171]
	global_store_dwordx4 v247, v[136:139], s[4:5]
	s_add_u32 s4, s4, 0x4000
	s_addc_u32 s5, s5, 0
	s_waitcnt vmcnt(7) lgkmcnt(4)
	v_pk_add_f32 v[140:141], v[140:141], v[172:173]
	v_pk_add_f32 v[142:143], v[142:143], v[174:175]
	global_store_dwordx4 v247, v[140:143], s[4:5]
	s_add_u32 s4, s4, 0x4000
	s_addc_u32 s5, s5, 0
	s_waitcnt vmcnt(7) lgkmcnt(3)
; template <class Epi>
; DI void gemm_tile(char* smem, const bf16_t* __restrict__ A0, int lda0, int ksplit, const bf16_t* __restrict__ A1, int lda1,
;                   const bf16_t* __restrict__ Bt, int K, int row0, int col0, const Epi& epi, int tid) {
;     ...
; #pragma unroll
;   for (int m = 0; m < 8; ++m)
; #pragma unroll
;     for (int n = 0; n < 4; ++n) epi(row0 + wr * 128 + m * 16 + fr, col0 + wc * 64 + n * 16 + fq * 4, acc[m][n]);
	v_pk_add_f32 v[144:145], v[144:145], v[176:177]
	v_pk_add_f32 v[146:147], v[146:147], v[178:179]
	global_store_dwordx4 v247, v[144:147], s[4:5]
	s_add_u32 s4, s4, 0x4000
	s_addc_u32 s5, s5, 0
	s_waitcnt vmcnt(7) lgkmcnt(2)
	v_pk_add_f32 v[148:149], v[148:149], v[180:181]
	v_pk_add_f32 v[150:151], v[150:151], v[182:183]
	global_store_dwordx4 v247, v[148:151], s[4:5]
	s_add_u32 s4, s4, 0x4000
	s_addc_u32 s5, s5, 0
	s_waitcnt vmcnt(7) lgkmcnt(1)
	v_pk_add_f32 v[152:153], v[152:153], v[184:185]
	v_pk_add_f32 v[154:155], v[154:155], v[186:187]
	global_store_dwordx4 v247, v[152:155], s[4:5]
	s_add_u32 s4, s4, 0x4000
	s_addc_u32 s5, s5, 0
	s_waitcnt vmcnt(7) lgkmcnt(0)
	v_pk_add_f32 v[156:157], v[156:157], v[188:189]
	v_pk_add_f32 v[158:159], v[158:159], v[190:191]
	global_store_dwordx4 v247, v[156:159], s[4:5]
	s_add_u32 s4, s4, 0x4000
	s_addc_u32 s5, s5, 0
	s_nop 1
	global_load_dwordx4 v[128:131], v247, s[0:1]
	s_add_u32 s0, s0, 0x4000
	s_addc_u32 s1, s1, 0
	global_load_dwordx4 v[132:135], v247, s[0:1]
	s_add_u32 s0, s0, 0x4000
	s_addc_u32 s1, s1, 0
	global_load_dwordx4 v[136:139], v247, s[0:1]
	s_add_u32 s0, s0, 0x4000
	s_addc_u32 s1, s1, 0
	global_load_dwordx4 v[140:143], v247, s[0:1]
	s_add_u32 s0, s0, 0x4000
	s_addc_u32 s1, s1, 0
	global_load_dwordx4 v[144:147], v247, s[0:1]
	s_add_u32 s0, s0, 0x4000
	s_addc_u32 s1, s1, 0
	global_load_dwordx4 v[148:151], v247, s[0:1]
	s_add_u32 s0, s0, 0x4000
	s_addc_u32 s1, s1, 0
	global_load_dwordx4 v[152:155], v247, s[0:1]
	s_add_u32 s0, s0, 0x4000
	s_addc_u32 s1, s1, 0
	global_load_dwordx4 v[156:159], v247, s[0:1]
	s_add_u32 s0, s0, 0x4000
	s_addc_u32 s1, s1, 0
	ds_read_b128 v[160:163], v246 offset:8704
	ds_read_b128 v[164:167], v246 offset:9792
	ds_read_b128 v[168:171], v246 offset:10880
	ds_read_b128 v[172:175], v246 offset:11968
	ds_read_b128 v[176:179], v246 offset:13056
	ds_read_b128 v[180:183], v246 offset:14144
	ds_read_b128 v[184:187], v246 offset:15232
	ds_read_b128 v[188:191], v246 offset:16320
	s_waitcnt vmcnt(7) lgkmcnt(7)
	v_pk_add_f32 v[128:129], v[128:129], v[160:161]
	v_pk_add_f32 v[130:131], v[130:131], v[162:163]
	global_store_dwordx4 v247, v[128:131], s[4:5]
	s_add_u32 s4, s4, 0x4000
	s_addc_u32 s5, s5, 0
	s_waitcnt vmcnt(7) lgkmcnt(6)
	v_pk_add_f32 v[132:133], v[132:133], v[164:165]
	v_pk_add_f32 v[134:135], v[134:135], v[166:167]
	global_store_dwordx4 v247, v[132:135], s[4:5]
	s_add_u32 s4, s4, 0x4000
	s_addc_u32 s5, s5, 0
	s_waitcnt vmcnt(7) lgkmcnt(5)
	v_pk_add_f32 v[136:137], v[136:137], v[168:169]
	v_pk_add_f32 v[138:139], v[138:139], v[170:171]
	global_store_dwordx4 v247, v[136:139], s[4:5]
	s_add_u32 s4, s4, 0x4000
	s_addc_u32 s5, s5, 0
	s_waitcnt vmcnt(7) lgkmcnt(4)
	v_pk_add_f32 v[140:141], v[140:141], v[172:173]
	v_pk_add_f32 v[142:143], v[142:143], v[174:175]
	global_store_dwordx4 v247, v[140:143], s[4:5]
	s_add_u32 s4, s4, 0x4000
	s_addc_u32 s5, s5, 0
	s_waitcnt vmcnt(7) lgkmcnt(3)
	v_pk_add_f32 v[144:145], v[144:145], v[176:177]
	v_pk_add_f32 v[146:147], v[146:147], v[178:179]
	global_store_dwordx4 v247, v[144:147], s[4:5]
	s_add_u32 s4, s4, 0x4000
	s_addc_u32 s5, s5, 0
	s_waitcnt vmcnt(7) lgkmcnt(2)
	v_pk_add_f32 v[148:149], v[148:149], v[180:181]
	v_pk_add_f32 v[150:151], v[150:151], v[182:183]
	global_store_dwordx4 v247, v[148:151], s[4:5]
	s_add_u32 s4, s4, 0x4000
	s_addc_u32 s5, s5, 0
	s_waitcnt vmcnt(7) lgkmcnt(1)
	v_pk_add_f32 v[152:153], v[152:153], v[184:185]
	v_pk_add_f32 v[154:155], v[154:155], v[186:187]
	global_store_dwordx4 v247, v[152:155], s[4:5]
	s_add_u32 s4, s4, 0x4000
	s_addc_u32 s5, s5, 0
	s_waitcnt vmcnt(7) lgkmcnt(0)
	v_pk_add_f32 v[156:157], v[156:157], v[188:189]
	v_pk_add_f32 v[158:159], v[158:159], v[190:191]
	global_store_dwordx4 v247, v[156:159], s[4:5]
	s_add_u32 s4, s4, 0x4000
	s_addc_u32 s5, s5, 0
	s_nop 1
	s_add_u32 s9, s9, 64
	s_branch .Lg6_tile

; #define PH(k) case k: if (ONLY_PHASE >= 0 && ONLY_PHASE != k) break;
; template <class Epi>
; DI void gemm_phase(char* smem, const bf16_t* A0, int lda0, int ksplit, const bf16_t* A1, int lda1, const bf16_t* Bt, int K, int nN, const Epi& epi, int tid) {
;   const int G = gridDim.x;
;   if ((G & 7) == 0) {
;     const int x = blockIdx.x & 7, l = blockIdx.x >> 3, L = G >> 3, per = 8 * nN, tot = 2 * per;
;     for (int q = l; q < tot; q += L) { const int rgl = q / per, rem = q % per, ct = rem >> 3, rt = (x * 2 + rgl) * 8 + (rem & 7);
;       gemm_tile(smem, A0, lda0, ksplit, A1, lda1, Bt, K, rt * 256, ct * 128, epi, tid); }
; template <int ph> DI void run_phase(const Ctx& c, char* smem) {
;     ...
;     PH(9) gemm_phase(smem, (const bf16_t*)(ws + OFF_R1), 4096, 1 << 30, XN, 1024, (const bf16_t*)(ws + OFF_W2), 4096, 8, EpiResid{p.out, p.out}, TIDX); break;
.LBB0_929:
	s_cmp_gt_i32 s94, 9
	s_cselect_b64 s[0:1], -1, 0
	s_cmp_lt_i32 s95, 10
	s_cselect_b64 s[2:3], -1, 0
	s_or_b64 s[0:1], s[0:1], s[2:3]
	s_and_b64 vcc, exec, s[0:1]
	s_cbranch_vccnz .LBB0_957
	s_load_dword s12, s[74:75], 0x180
	s_add_u32 s0, s92, 0x7800000
	s_addc_u32 s1, s93, 0
	s_add_u32 s2, s92, 0x1bc0000
	s_addc_u32 s3, s93, 0
	s_waitcnt lgkmcnt(0)
	s_and_b32 s14, s72, 0xffffffc0
	v_mbcnt_hi_u32_b32 v195, -1, v194
	s_and_b32 s13, s12, 7
	s_cmp_lg_u32 s13, 0
	s_waitcnt vmcnt(16)
	v_add_u32_e32 v196, s14, v195
	v_mbcnt_lo_u32_b32 v240, -1, 0
	v_mbcnt_hi_u32_b32 v240, -1, v240
	s_lshr_b32 s10, s72, 6
	s_lshl_b32 s101, s10, 10
	v_and_b32_e32 v241, 15, v240
	v_lshrrev_b32_e32 v242, 4, v240
	v_bfe_u32 v243, v240, 3, 1
	v_mul_u32_u24_e32 v243, 3, v243
	v_xor_b32_e32 v243, v242, v243
	v_lshlrev_b32_e32 v243, 4, v243
	v_lshl_add_u32 v243, v241, 6, v243
	s_lshr_b32 s9, s10, 1
	s_lshl_b32 s9, s9, 13
	v_add_u32_e32 v230, s9, v243
	s_and_b32 s9, s10, 1
	s_lshl_b32 s9, s9, 12
	s_add_u32 s9, s9, 16384
	v_add_u32_e32 v231, s9, v243
	s_lshr_b32 s9, s10, 1
	s_lshl_b32 s9, s9, 7
	v_add_u32_e32 v244, s9, v241
	s_and_b32 s9, s10, 1
	s_lshl_b32 s9, s9, 6
	v_lshl_add_u32 v245, v242, 2, s9
	s_movk_i32 s9, 0x1000
	v_mul_lo_u32 v246, v244, s9
	v_lshl_add_u32 v234, v245, 2, v246
	v_lshrrev_b32_e32 v241, 2, v240
	s_lshl_b32 s9, s10, 4
	v_add_u32_e32 v241, s9, v241
	v_bfe_u32 v242, v240, 5, 1
	v_mul_u32_u24_e32 v242, 3, v242
	v_and_b32_e32 v243, 3, v240
	v_xor_b32_e32 v243, v243, v242
	v_lshlrev_b32_e32 v243, 4, v243
	s_mov_b32 s9, 8192
	v_mad_u32_u24 v224, v241, s9, v243
	v_add_u32_e32 v225, 0x80000, v224
	v_add_u32_e32 v226, 0x100000, v224
	v_add_u32_e32 v227, 0x180000, v224
	s_mov_b32 s9, 8192
	v_mad_u32_u24 v228, v241, s9, v243
	v_add_u32_e32 v229, 0x80000, v228
	s_load_dwordx2 s[6:7], s[74:75], 0x168
	v_mbcnt_lo_u32_b32 v240, -1, 0
	v_mbcnt_hi_u32_b32 v240, -1, v240
	s_lshr_b32 s10, s72, 6
	s_mul_i32 s9, s10, 17408
	v_and_b32_e32 v241, 15, v240
	v_lshrrev_b32_e32 v242, 4, v240
	v_mul_u32_u24_e32 v243, 0x110, v241
	v_lshl_add_u32 v243, v242, 4, v243
	v_add_u32_e32 v245, s9, v243
	v_mul_u32_u24_e32 v243, 0x110, v242
	v_lshl_add_u32 v243, v241, 4, v243
	v_add_u32_e32 v246, s9, v243
	s_lshr_b32 s9, s10, 1
	s_lshl_b32 s9, s9, 7
	v_add_u32_e32 v243, s9, v242
	v_lshlrev_b32_e32 v243, 12, v243
	s_and_b32 s9, s10, 1
	s_lshl_b32 s9, s9, 8
	v_lshl_add_u32 v244, v241, 4, s9
	v_add_u32_e32 v247, v243, v244
	s_lshr_b32 s15, s96, 3
	s_and_b32 s18, s96, 7
	s_lshl_b32 s18, s18, 1
	s_waitcnt lgkmcnt(0)
; #define LWRITE(S, buf) do { bf16_t* sA_ = sbase + (buf) * BUF; bf16_t* sB_ = sA_ + 256 * PITCH; \
;     _Pragma("unroll") for (int i_ = 0; i_ < 4; ++i_) *(u32x4*)(sA_ + (sr + i_ * 64) * PITCH + scv * 8) = ra[S][i_]; \
;     _Pragma("unroll") for (int i_ = 0; i_ < 2; ++i_) *(u32x4*)(sB_ + (sr + i_ * 64) * PITCH + scv * 8) = rb[S][i_]; } while (0)
; template <class Epi>
; DI void gemm_tile(char* smem, const bf16_t* __restrict__ A0, int lda0, int ksplit, const bf16_t* __restrict__ A1, int lda1,
;                   const bf16_t* __restrict__ Bt, int K, int row0, int col0, const Epi& epi, int tid) {
;     ...
;   __syncthreads();
;   {
;     const int last = nk - 1;
;     GLOAD(0, 0);
;     __builtin_amdgcn_sched_barrier(0);
;     GLOAD(1, 1);
;     __builtin_amdgcn_sched_barrier(0);
;     LWRITE(0, 0);
;     __builtin_amdgcn_sched_barrier(0);
;     GLOAD(0, (2 < last ? 2 : last));
;     __builtin_amdgcn_sched_barrier(0);
;     __syncthreads();
; template <class Epi>
; DI void gemm_phase(char* smem, const bf16_t* A0, int lda0, int ksplit, const bf16_t* A1, int lda1, const bf16_t* Bt, int K, int nN, const Epi& epi, int tid) {
;     ...
;     const int x = blockIdx.x & 7, l = blockIdx.x >> 3, L = G >> 3, per = 8 * nN, tot = 2 * per;
;     for (int q = l; q < tot; q += L) { const int rgl = q / per, rem = q % per, ct = rem >> 3, rt = (x * 2 + rgl) * 8 + (rem & 7);
;       gemm_tile(smem, A0, lda0, ksplit, A1, lda1, Bt, K, rt * 256, ct * 128, epi, tid); }
.Lg9_tile:
	s_cmpk_ge_u32 s15, 128
	s_cbranch_scc1 .Lg9_done
	s_cmpk_ge_u32 s15, 64
	s_cselect_b32 s10, 1, 0
	s_cselect_b32 s9, 64, 0
	s_sub_u32 s9, s15, s9
	s_and_b32 s16, s9, 7
	s_lshl_b32 s16, s16, 3
	s_bfe_u32 s11, s9, 0x30003
	s_or_b32 s16, s16, s11
	s_andn2_b32 s9, s9, 63
	s_or_b32 s9, s9, s16
	s_add_u32 s10, s10, s18
	s_lshl_b32 s10, s10, 3
	s_and_b32 s16, s9, 7
	s_add_u32 s16, s16, s10
	s_lshl_b32 s16, s16, 8
	s_lshr_b32 s11, s9, 3
	s_lshl_b32 s11, s11, 7
	s_mul_i32 s10, s16, 8192
	s_add_u32 s10, s10, 0x7800000
	s_add_u32 s0, s92, s10
	s_addc_u32 s1, s93, 0
	s_mul_i32 s10, s11, 8192
	s_add_u32 s10, s10, 0x1bc0000
	s_add_u32 s2, s92, s10
	s_addc_u32 s3, s93, 0
	s_waitcnt lgkmcnt(0)
	s_barrier
	s_mov_b32 s100, 0
	s_mov_b32 s17, 0
	s_add_u32 s9, s17, s101
	s_add_u32 m0, s9, 0
	s_nop 0
	global_load_lds_dwordx4 v224, s[0:1]
	s_add_u32 m0, s9, 4096
	s_nop 0
	global_load_lds_dwordx4 v225, s[0:1]
	s_add_u32 m0, s9, 8192
	s_nop 0
	global_load_lds_dwordx4 v226, s[0:1]
	s_add_u32 m0, s9, 12288
	s_nop 0
	global_load_lds_dwordx4 v227, s[0:1]
	s_add_u32 m0, s9, 16384
	s_nop 0
	global_load_lds_dwordx4 v228, s[2:3]
	s_add_u32 m0, s9, 20480
	s_nop 0
	global_load_lds_dwordx4 v229, s[2:3]
	s_add_u32 s0, s0, 64
	s_addc_u32 s1, s1, 0
	s_add_u32 s2, s2, 64
	s_addc_u32 s3, s3, 0
	s_add_u32 s100, s100, 1
	s_add_u32 s17, s17, 24576
	s_cmp_eq_u32 s17, 73728
	s_cselect_b32 s17, 0, s17
	s_add_u32 s9, s17, s101
	s_add_u32 m0, s9, 0
	s_nop 0
	global_load_lds_dwordx4 v224, s[0:1]
	s_add_u32 m0, s9, 4096
	s_nop 0
	global_load_lds_dwordx4 v225, s[0:1]
	s_add_u32 m0, s9, 8192
	s_nop 0
	global_load_lds_dwordx4 v226, s[0:1]
	s_add_u32 m0, s9, 12288
	s_nop 0
	global_load_lds_dwordx4 v227, s[0:1]
	s_add_u32 m0, s9, 16384
	s_nop 0
	global_load_lds_dwordx4 v228, s[2:3]
	s_add_u32 m0, s9, 20480
	s_nop 0
	global_load_lds_dwordx4 v229, s[2:3]
	s_add_u32 s0, s0, 64
	s_addc_u32 s1, s1, 0
	s_add_u32 s2, s2, 64
	s_addc_u32 s3, s3, 0
	s_add_u32 s100, s100, 1
	s_add_u32 s17, s17, 24576
	s_cmp_eq_u32 s17, 73728
	s_cselect_b32 s17, 0, s17
	s_add_u32 s9, s17, s101
	s_add_u32 m0, s9, 0
	s_nop 0
	global_load_lds_dwordx4 v224, s[0:1]
	s_add_u32 m0, s9, 4096
	s_nop 0
	global_load_lds_dwordx4 v225, s[0:1]
	s_add_u32 m0, s9, 8192
	s_nop 0
	global_load_lds_dwordx4 v226, s[0:1]
	s_add_u32 m0, s9, 12288
	s_nop 0
	global_load_lds_dwordx4 v227, s[0:1]
	s_add_u32 m0, s9, 16384
	s_nop 0
	global_load_lds_dwordx4 v228, s[2:3]
	s_add_u32 m0, s9, 20480
	s_nop 0
	global_load_lds_dwordx4 v229, s[2:3]
	s_add_u32 s0, s0, 64
	s_addc_u32 s1, s1, 0
	s_add_u32 s2, s2, 64
	s_addc_u32 s3, s3, 0
	s_add_u32 s100, s100, 1
	s_add_u32 s17, s17, 24576
	s_cmp_eq_u32 s17, 73728
	s_cselect_b32 s17, 0, s17
	v_mov_b32_e32 v0, 0
	v_mov_b32_e32 v1, 0
	v_mov_b32_e32 v2, 0
	v_mov_b32_e32 v3, 0
	v_mov_b32_e32 v4, 0
	v_mov_b32_e32 v5, 0
	v_mov_b32_e32 v6, 0
	v_mov_b32_e32 v7, 0
	v_mov_b32_e32 v8, 0
	v_mov_b32_e32 v9, 0
	v_mov_b32_e32 v10, 0
	v_mov_b32_e32 v11, 0
	v_mov_b32_e32 v12, 0
	v_mov_b32_e32 v13, 0
	v_mov_b32_e32 v14, 0
	v_mov_b32_e32 v15, 0
	v_mov_b32_e32 v16, 0
	v_mov_b32_e32 v17, 0
	v_mov_b32_e32 v18, 0
	v_mov_b32_e32 v19, 0
	v_mov_b32_e32 v20, 0
	v_mov_b32_e32 v21, 0
	v_mov_b32_e32 v22, 0
	v_mov_b32_e32 v23, 0
	v_mov_b32_e32 v24, 0
	v_mov_b32_e32 v25, 0
	v_mov_b32_e32 v26, 0
	v_mov_b32_e32 v27, 0
	v_mov_b32_e32 v28, 0
	v_mov_b32_e32 v29, 0
	v_mov_b32_e32 v30, 0
	v_mov_b32_e32 v31, 0
	v_mov_b32_e32 v32, 0
	v_mov_b32_e32 v33, 0
	v_mov_b32_e32 v34, 0
	v_mov_b32_e32 v35, 0
	v_mov_b32_e32 v36, 0
	v_mov_b32_e32 v37, 0
	v_mov_b32_e32 v38, 0
	v_mov_b32_e32 v39, 0
	v_mov_b32_e32 v40, 0
	v_mov_b32_e32 v41, 0
	v_mov_b32_e32 v42, 0
	v_mov_b32_e32 v43, 0
	v_mov_b32_e32 v44, 0
	v_mov_b32_e32 v45, 0
	v_mov_b32_e32 v46, 0
	v_mov_b32_e32 v47, 0
	v_mov_b32_e32 v48, 0
	v_mov_b32_e32 v49, 0
	v_mov_b32_e32 v50, 0
	v_mov_b32_e32 v51, 0
	v_mov_b32_e32 v52, 0
	v_mov_b32_e32 v53, 0
	v_mov_b32_e32 v54, 0
	v_mov_b32_e32 v55, 0
	v_mov_b32_e32 v56, 0
	v_mov_b32_e32 v57, 0
	v_mov_b32_e32 v58, 0
	v_mov_b32_e32 v59, 0
	v_mov_b32_e32 v60, 0
	v_mov_b32_e32 v61, 0
	v_mov_b32_e32 v62, 0
	v_mov_b32_e32 v63, 0
	v_mov_b32_e32 v64, 0
	v_mov_b32_e32 v65, 0
	v_mov_b32_e32 v66, 0
	v_mov_b32_e32 v67, 0
	v_mov_b32_e32 v68, 0
	v_mov_b32_e32 v69, 0
	v_mov_b32_e32 v70, 0
	v_mov_b32_e32 v71, 0
	v_mov_b32_e32 v72, 0
	v_mov_b32_e32 v73, 0
	v_mov_b32_e32 v74, 0
	v_mov_b32_e32 v75, 0
	v_mov_b32_e32 v76, 0
	v_mov_b32_e32 v77, 0
	v_mov_b32_e32 v78, 0
	v_mov_b32_e32 v79, 0
	v_mov_b32_e32 v80, 0
	v_mov_b32_e32 v81, 0
	v_mov_b32_e32 v82, 0
	v_mov_b32_e32 v83, 0
	v_mov_b32_e32 v84, 0
	v_mov_b32_e32 v85, 0
	v_mov_b32_e32 v86, 0
	v_mov_b32_e32 v87, 0
	v_mov_b32_e32 v88, 0
	v_mov_b32_e32 v89, 0
	v_mov_b32_e32 v90, 0
	v_mov_b32_e32 v91, 0
	v_mov_b32_e32 v92, 0
	v_mov_b32_e32 v93, 0
	v_mov_b32_e32 v94, 0
	v_mov_b32_e32 v95, 0
	v_mov_b32_e32 v96, 0
	v_mov_b32_e32 v97, 0
	v_mov_b32_e32 v98, 0
	v_mov_b32_e32 v99, 0
	v_mov_b32_e32 v100, 0
	v_mov_b32_e32 v101, 0
	v_mov_b32_e32 v102, 0
	v_mov_b32_e32 v103, 0
	v_mov_b32_e32 v104, 0
	v_mov_b32_e32 v105, 0
	v_mov_b32_e32 v106, 0
	v_mov_b32_e32 v107, 0
	v_mov_b32_e32 v108, 0
	v_mov_b32_e32 v109, 0
	v_mov_b32_e32 v110, 0
	v_mov_b32_e32 v111, 0
	v_mov_b32_e32 v112, 0
	v_mov_b32_e32 v113, 0
	v_mov_b32_e32 v114, 0
	v_mov_b32_e32 v115, 0
	v_mov_b32_e32 v116, 0
	v_mov_b32_e32 v117, 0
	v_mov_b32_e32 v118, 0
	v_mov_b32_e32 v119, 0
	v_mov_b32_e32 v120, 0
	v_mov_b32_e32 v121, 0
	v_mov_b32_e32 v122, 0
	v_mov_b32_e32 v123, 0
	v_mov_b32_e32 v124, 0
	v_mov_b32_e32 v125, 0
	v_mov_b32_e32 v126, 0
	v_mov_b32_e32 v127, 0
	s_mov_b32 s99, 0
	s_mov_b32 s98, 24576
	s_waitcnt vmcnt(12)
	s_barrier
	ds_read_b128 v[128:131], v231 offset:0
	ds_read_b128 v[132:135], v231 offset:1024
	ds_read_b128 v[136:139], v231 offset:2048
	ds_read_b128 v[140:143], v231 offset:3072
	ds_read_b128 v[144:147], v230 offset:0
	ds_read_b128 v[148:151], v230 offset:1024
	ds_read_b128 v[152:155], v230 offset:2048
	ds_read_b128 v[156:159], v230 offset:3072
	ds_read_b128 v[160:163], v230 offset:4096
	ds_read_b128 v[164:167], v230 offset:5120
	ds_read_b128 v[168:171], v230 offset:6144
	ds_read_b128 v[172:175], v230 offset:7168

; template <class Epi>
; DI void gemm_tile(char* smem, const bf16_t* __restrict__ A0, int lda0, int ksplit, const bf16_t* __restrict__ A1, int lda1,
;                   const bf16_t* __restrict__ Bt, int K, int row0, int col0, const Epi& epi, int tid) {
;     ...
; #pragma unroll
;   for (int m = 0; m < 8; ++m)
; #pragma unroll
;     for (int n = 0; n < 4; ++n) epi(row0 + wr * 128 + m * 16 + fr, col0 + wc * 64 + n * 16 + fq * 4, acc[m][n]);
.Lg9_epi:
	s_nop 7
	s_nop 7
	s_lshl_b32 s10, s16, 12
	s_lshl_b32 s9, s11, 2
	s_add_u32 s10, s10, s9
	s_add_u32 s4, s6, s10
	s_addc_u32 s5, s7, 0
	s_lshl_b32 s10, s16, 12
	s_lshl_b32 s9, s11, 2
	s_add_u32 s10, s10, s9
	s_add_u32 s0, s6, s10
	s_addc_u32 s1, s7, 0
	ds_write_b128 v245, v[0:3]
	ds_write_b128 v245, v[4:7] offset:64
	ds_write_b128 v245, v[8:11] offset:128
	ds_write_b128 v245, v[12:15] offset:192
	ds_write_b128 v245, v[16:19] offset:4352
	ds_write_b128 v245, v[20:23] offset:4416
	ds_write_b128 v245, v[24:27] offset:4480
	ds_write_b128 v245, v[28:31] offset:4544
	ds_write_b128 v245, v[32:35] offset:8704
	ds_write_b128 v245, v[36:39] offset:8768
	ds_write_b128 v245, v[40:43] offset:8832
	ds_write_b128 v245, v[44:47] offset:8896
	ds_write_b128 v245, v[48:51] offset:13056
	ds_write_b128 v245, v[52:55] offset:13120
	ds_write_b128 v245, v[56:59] offset:13184
	ds_write_b128 v245, v[60:63] offset:13248
	global_load_dwordx4 v[128:131], v247, s[0:1]
	s_add_u32 s0, s0, 0x4000
	s_addc_u32 s1, s1, 0
	global_load_dwordx4 v[132:135], v247, s[0:1]
	s_add_u32 s0, s0, 0x4000
	s_addc_u32 s1, s1, 0
	global_load_dwordx4 v[136:139], v247, s[0:1]
	s_add_u32 s0, s0, 0x4000
	s_addc_u32 s1, s1, 0
	global_load_dwordx4 v[140:143], v247, s[0:1]
	s_add_u32 s0, s0, 0x4000
	s_addc_u32 s1, s1, 0
	global_load_dwordx4 v[144:147], v247, s[0:1]
	s_add_u32 s0, s0, 0x4000
	s_addc_u32 s1, s1, 0
	global_load_dwordx4 v[148:151], v247, s[0:1]
	s_add_u32 s0, s0, 0x4000
	s_addc_u32 s1, s1, 0
	global_load_dwordx4 v[152:155], v247, s[0:1]
	s_add_u32 s0, s0, 0x4000
	s_addc_u32 s1, s1, 0
	global_load_dwordx4 v[156:159], v247, s[0:1]
	s_add_u32 s0, s0, 0x4000
	s_addc_u32 s1, s1, 0
	s_waitcnt lgkmcnt(0)
	ds_read_b128 v[160:163], v246
	ds_read_b128 v[164:167], v246 offset:1088
	ds_read_b128 v[168:171], v246 offset:2176
	ds_read_b128 v[172:175], v246 offset:3264
	ds_read_b128 v[176:179], v246 offset:4352
	ds_read_b128 v[180:183], v246 offset:5440
	ds_read_b128 v[184:187], v246 offset:6528
	ds_read_b128 v[188:191], v246 offset:7616
	s_waitcnt vmcnt(7) lgkmcnt(7)
	v_pk_add_f32 v[128:129], v[128:129], v[160:161]
	v_pk_add_f32 v[130:131], v[130:131], v[162:163]
	global_store_dwordx4 v247, v[128:131], s[4:5]
	s_add_u32 s4, s4, 0x4000
	s_addc_u32 s5, s5, 0
	s_waitcnt vmcnt(7) lgkmcnt(6)
	v_pk_add_f32 v[132:133], v[132:133], v[164:165]
	v_pk_add_f32 v[134:135], v[134:135], v[166:167]
	global_store_dwordx4 v247, v[132:135], s[4:5]
	s_add_u32 s4, s4, 0x4000
	s_addc_u32 s5, s5, 0
	s_waitcnt vmcnt(7) lgkmcnt(5)
	v_pk_add_f32 v[136:137], v[136:137], v[168:169]
	v_pk_add_f32 v[138:139], v[138:139], v[170:171]
	global_store_dwordx4 v247, v[136:139], s[4:5]
	s_add_u32 s4, s4, 0x4000
	s_addc_u32 s5, s5, 0
	s_waitcnt vmcnt(7) lgkmcnt(4)
	v_pk_add_f32 v[140:141], v[140:141], v[172:173]
	v_pk_add_f32 v[142:143], v[142:143], v[174:175]
	global_store_dwordx4 v247, v[140:143], s[4:5]
	s_add_u32 s4, s4, 0x4000
	s_addc_u32 s5, s5, 0
	s_waitcnt vmcnt(7) lgkmcnt(3)
	v_pk_add_f32 v[144:145], v[144:145], v[176:177]
	v_pk_add_f32 v[146:147], v[146:147], v[178:179]
	global_store_dwordx4 v247, v[144:147], s[4:5]
	s_add_u32 s4, s4, 0x4000
	s_addc_u32 s5, s5, 0
	s_waitcnt vmcnt(7) lgkmcnt(2)
	v_pk_add_f32 v[148:149], v[148:149], v[180:181]
	v_pk_add_f32 v[150:151], v[150:151], v[182:183]
	global_store_dwordx4 v247, v[148:151], s[4:5]
	s_add_u32 s4, s4, 0x4000
	s_addc_u32 s5, s5, 0
	s_waitcnt vmcnt(7) lgkmcnt(1)
	v_pk_add_f32 v[152:153], v[152:153], v[184:185]
	v_pk_add_f32 v[154:155], v[154:155], v[186:187]
	global_store_dwordx4 v247, v[152:155], s[4:5]
	s_add_u32 s4, s4, 0x4000
	s_addc_u32 s5, s5, 0
	s_waitcnt vmcnt(7) lgkmcnt(0)
	v_pk_add_f32 v[156:157], v[156:157], v[188:189]
	v_pk_add_f32 v[158:159], v[158:159], v[190:191]
	global_store_dwordx4 v247, v[156:159], s[4:5]
	s_add_u32 s4, s4, 0x4000
	s_addc_u32 s5, s5, 0
	s_nop 1
	global_load_dwordx4 v[128:131], v247, s[0:1]
	s_add_u32 s0, s0, 0x4000
	s_addc_u32 s1, s1, 0
	global_load_dwordx4 v[132:135], v247, s[0:1]
	s_add_u32 s0, s0, 0x4000
	s_addc_u32 s1, s1, 0
	global_load_dwordx4 v[136:139], v247, s[0:1]
	s_add_u32 s0, s0, 0x4000
	s_addc_u32 s1, s1, 0
	global_load_dwordx4 v[140:143], v247, s[0:1]
	s_add_u32 s0, s0, 0x4000
	s_addc_u32 s1, s1, 0
	global_load_dwordx4 v[144:147], v247, s[0:1]
	s_add_u32 s0, s0, 0x4000
	s_addc_u32 s1, s1, 0
	global_load_dwordx4 v[148:151], v247, s[0:1]
	s_add_u32 s0, s0, 0x4000
	s_addc_u32 s1, s1, 0
	global_load_dwordx4 v[152:155], v247, s[0:1]
	s_add_u32 s0, s0, 0x4000
	s_addc_u32 s1, s1, 0
	global_load_dwordx4 v[156:159], v247, s[0:1]
	s_add_u32 s0, s0, 0x4000
	s_addc_u32 s1, s1, 0
	ds_read_b128 v[160:163], v246 offset:8704
	ds_read_b128 v[164:167], v246 offset:9792
	ds_read_b128 v[168:171], v246 offset:10880
	ds_read_b128 v[172:175], v246 offset:11968
	ds_read_b128 v[176:179], v246 offset:13056
	ds_read_b128 v[180:183], v246 offset:14144
	ds_read_b128 v[184:187], v246 offset:15232
	ds_read_b128 v[188:191], v246 offset:16320
	s_waitcnt vmcnt(7) lgkmcnt(7)
	v_pk_add_f32 v[128:129], v[128:129], v[160:161]
	v_pk_add_f32 v[130:131], v[130:131], v[162:163]
	global_store_dwordx4 v247, v[128:131], s[4:5]
	s_add_u32 s4, s4, 0x4000
	s_addc_u32 s5, s5, 0
	s_waitcnt vmcnt(7) lgkmcnt(6)
	v_pk_add_f32 v[132:133], v[132:133], v[164:165]
	v_pk_add_f32 v[134:135], v[134:135], v[166:167]
	global_store_dwordx4 v247, v[132:135], s[4:5]
	s_add_u32 s4, s4, 0x4000
	s_addc_u32 s5, s5, 0
	s_waitcnt vmcnt(7) lgkmcnt(5)
	v_pk_add_f32 v[136:137], v[136:137], v[168:169]
	v_pk_add_f32 v[138:139], v[138:139], v[170:171]
	global_store_dwordx4 v247, v[136:139], s[4:5]
	s_add_u32 s4, s4, 0x4000
	s_addc_u32 s5, s5, 0
	s_waitcnt vmcnt(7) lgkmcnt(4)
; template <class Epi>
; DI void gemm_tile(char* smem, const bf16_t* __restrict__ A0, int lda0, int ksplit, const bf16_t* __restrict__ A1, int lda1,
;                   const bf16_t* __restrict__ Bt, int K, int row0, int col0, const Epi& epi, int tid) {
;     ...
; #pragma unroll
;   for (int m = 0; m < 8; ++m)
; #pragma unroll
;     for (int n = 0; n < 4; ++n) epi(row0 + wr * 128 + m * 16 + fr, col0 + wc * 64 + n * 16 + fq * 4, acc[m][n]);
	v_pk_add_f32 v[140:141], v[140:141], v[172:173]
	v_pk_add_f32 v[142:143], v[142:143], v[174:175]
	global_store_dwordx4 v247, v[140:143], s[4:5]
	s_add_u32 s4, s4, 0x4000
	s_addc_u32 s5, s5, 0
	s_waitcnt vmcnt(7) lgkmcnt(3)
	v_pk_add_f32 v[144:145], v[144:145], v[176:177]
	v_pk_add_f32 v[146:147], v[146:147], v[178:179]
	global_store_dwordx4 v247, v[144:147], s[4:5]
	s_add_u32 s4, s4, 0x4000
	s_addc_u32 s5, s5, 0
	s_waitcnt vmcnt(7) lgkmcnt(2)
	v_pk_add_f32 v[148:149], v[148:149], v[180:181]
	v_pk_add_f32 v[150:151], v[150:151], v[182:183]
	global_store_dwordx4 v247, v[148:151], s[4:5]
	s_add_u32 s4, s4, 0x4000
	s_addc_u32 s5, s5, 0
	s_waitcnt vmcnt(7) lgkmcnt(1)
	v_pk_add_f32 v[152:153], v[152:153], v[184:185]
	v_pk_add_f32 v[154:155], v[154:155], v[186:187]
	global_store_dwordx4 v247, v[152:155], s[4:5]
	s_add_u32 s4, s4, 0x4000
	s_addc_u32 s5, s5, 0
	s_waitcnt vmcnt(7) lgkmcnt(0)
	v_pk_add_f32 v[156:157], v[156:157], v[188:189]
	v_pk_add_f32 v[158:159], v[158:159], v[190:191]
	global_store_dwordx4 v247, v[156:159], s[4:5]
	s_add_u32 s4, s4, 0x4000
	s_addc_u32 s5, s5, 0
	s_nop 1
	s_waitcnt lgkmcnt(0)
	ds_write_b128 v245, v[64:67]
	ds_write_b128 v245, v[68:71] offset:64
	ds_write_b128 v245, v[72:75] offset:128
	ds_write_b128 v245, v[76:79] offset:192
	ds_write_b128 v245, v[80:83] offset:4352
	ds_write_b128 v245, v[84:87] offset:4416
	ds_write_b128 v245, v[88:91] offset:4480
	ds_write_b128 v245, v[92:95] offset:4544
	ds_write_b128 v245, v[96:99] offset:8704
	ds_write_b128 v245, v[100:103] offset:8768
	ds_write_b128 v245, v[104:107] offset:8832
	ds_write_b128 v245, v[108:111] offset:8896
	ds_write_b128 v245, v[112:115] offset:13056
	ds_write_b128 v245, v[116:119] offset:13120
	ds_write_b128 v245, v[120:123] offset:13184
	ds_write_b128 v245, v[124:127] offset:13248
	global_load_dwordx4 v[128:131], v247, s[0:1]
	s_add_u32 s0, s0, 0x4000
	s_addc_u32 s1, s1, 0
	global_load_dwordx4 v[132:135], v247, s[0:1]
	s_add_u32 s0, s0, 0x4000
	s_addc_u32 s1, s1, 0
	global_load_dwordx4 v[136:139], v247, s[0:1]
	s_add_u32 s0, s0, 0x4000
	s_addc_u32 s1, s1, 0
	global_load_dwordx4 v[140:143], v247, s[0:1]
	s_add_u32 s0, s0, 0x4000
	s_addc_u32 s1, s1, 0
	global_load_dwordx4 v[144:147], v247, s[0:1]
	s_add_u32 s0, s0, 0x4000
	s_addc_u32 s1, s1, 0
	global_load_dwordx4 v[148:151], v247, s[0:1]
	s_add_u32 s0, s0, 0x4000
	s_addc_u32 s1, s1, 0
	global_load_dwordx4 v[152:155], v247, s[0:1]
	s_add_u32 s0, s0, 0x4000
	s_addc_u32 s1, s1, 0
	global_load_dwordx4 v[156:159], v247, s[0:1]
	s_add_u32 s0, s0, 0x4000
	s_addc_u32 s1, s1, 0
	s_waitcnt lgkmcnt(0)
	ds_read_b128 v[160:163], v246
	ds_read_b128 v[164:167], v246 offset:1088
	ds_read_b128 v[168:171], v246 offset:2176
	ds_read_b128 v[172:175], v246 offset:3264
	ds_read_b128 v[176:179], v246 offset:4352
	ds_read_b128 v[180:183], v246 offset:5440
	ds_read_b128 v[184:187], v246 offset:6528
	ds_read_b128 v[188:191], v246 offset:7616
	s_waitcnt vmcnt(7) lgkmcnt(7)
	v_pk_add_f32 v[128:129], v[128:129], v[160:161]
	v_pk_add_f32 v[130:131], v[130:131], v[162:163]
	global_store_dwordx4 v247, v[128:131], s[4:5]
	s_add_u32 s4, s4, 0x4000
	s_addc_u32 s5, s5, 0
	s_waitcnt vmcnt(7) lgkmcnt(6)
	v_pk_add_f32 v[132:133], v[132:133], v[164:165]
	v_pk_add_f32 v[134:135], v[134:135], v[166:167]
	global_store_dwordx4 v247, v[132:135], s[4:5]
	s_add_u32 s4, s4, 0x4000
	s_addc_u32 s5, s5, 0
	s_waitcnt vmcnt(7) lgkmcnt(5)
	v_pk_add_f32 v[136:137], v[136:137], v[168:169]
	v_pk_add_f32 v[138:139], v[138:139], v[170:171]
	global_store_dwordx4 v247, v[136:139], s[4:5]
	s_add_u32 s4, s4, 0x4000
	s_addc_u32 s5, s5, 0
	s_waitcnt vmcnt(7) lgkmcnt(4)
	v_pk_add_f32 v[140:141], v[140:141], v[172:173]
	v_pk_add_f32 v[142:143], v[142:143], v[174:175]
	global_store_dwordx4 v247, v[140:143], s[4:5]
	s_add_u32 s4, s4, 0x4000
	s_addc_u32 s5, s5, 0
	s_waitcnt vmcnt(7) lgkmcnt(3)
; template <class Epi>
; DI void gemm_tile(char* smem, const bf16_t* __restrict__ A0, int lda0, int ksplit, const bf16_t* __restrict__ A1, int lda1,
;                   const bf16_t* __restrict__ Bt, int K, int row0, int col0, const Epi& epi, int tid) {
;     ...
; #pragma unroll
;   for (int m = 0; m < 8; ++m)
; #pragma unroll
;     for (int n = 0; n < 4; ++n) epi(row0 + wr * 128 + m * 16 + fr, col0 + wc * 64 + n * 16 + fq * 4, acc[m][n]);
	v_pk_add_f32 v[144:145], v[144:145], v[176:177]
	v_pk_add_f32 v[146:147], v[146:147], v[178:179]
	global_store_dwordx4 v247, v[144:147], s[4:5]
	s_add_u32 s4, s4, 0x4000
	s_addc_u32 s5, s5, 0
	s_waitcnt vmcnt(7) lgkmcnt(2)
	v_pk_add_f32 v[148:149], v[148:149], v[180:181]
	v_pk_add_f32 v[150:151], v[150:151], v[182:183]
	global_store_dwordx4 v247, v[148:151], s[4:5]
	s_add_u32 s4, s4, 0x4000
	s_addc_u32 s5, s5, 0
	s_waitcnt vmcnt(7) lgkmcnt(1)
	v_pk_add_f32 v[152:153], v[152:153], v[184:185]
	v_pk_add_f32 v[154:155], v[154:155], v[186:187]
	global_store_dwordx4 v247, v[152:155], s[4:5]
	s_add_u32 s4, s4, 0x4000
	s_addc_u32 s5, s5, 0
	s_waitcnt vmcnt(7) lgkmcnt(0)
	v_pk_add_f32 v[156:157], v[156:157], v[188:189]
	v_pk_add_f32 v[158:159], v[158:159], v[190:191]
	global_store_dwordx4 v247, v[156:159], s[4:5]
	s_add_u32 s4, s4, 0x4000
	s_addc_u32 s5, s5, 0
	s_nop 1
	global_load_dwordx4 v[128:131], v247, s[0:1]
	s_add_u32 s0, s0, 0x4000
	s_addc_u32 s1, s1, 0
	global_load_dwordx4 v[132:135], v247, s[0:1]
	s_add_u32 s0, s0, 0x4000
	s_addc_u32 s1, s1, 0
	global_load_dwordx4 v[136:139], v247, s[0:1]
	s_add_u32 s0, s0, 0x4000
	s_addc_u32 s1, s1, 0
	global_load_dwordx4 v[140:143], v247, s[0:1]
	s_add_u32 s0, s0, 0x4000
	s_addc_u32 s1, s1, 0
	global_load_dwordx4 v[144:147], v247, s[0:1]
	s_add_u32 s0, s0, 0x4000
	s_addc_u32 s1, s1, 0
	global_load_dwordx4 v[148:151], v247, s[0:1]
	s_add_u32 s0, s0, 0x4000
	s_addc_u32 s1, s1, 0
	global_load_dwordx4 v[152:155], v247, s[0:1]
	s_add_u32 s0, s0, 0x4000
	s_addc_u32 s1, s1, 0
	global_load_dwordx4 v[156:159], v247, s[0:1]
	s_add_u32 s0, s0, 0x4000
	s_addc_u32 s1, s1, 0
	ds_read_b128 v[160:163], v246 offset:8704
	ds_read_b128 v[164:167], v246 offset:9792
	ds_read_b128 v[168:171], v246 offset:10880
	ds_read_b128 v[172:175], v246 offset:11968
	ds_read_b128 v[176:179], v246 offset:13056
	ds_read_b128 v[180:183], v246 offset:14144
	ds_read_b128 v[184:187], v246 offset:15232
	ds_read_b128 v[188:191], v246 offset:16320
	s_waitcnt vmcnt(7) lgkmcnt(7)
	v_pk_add_f32 v[128:129], v[128:129], v[160:161]
	v_pk_add_f32 v[130:131], v[130:131], v[162:163]
	global_store_dwordx4 v247, v[128:131], s[4:5]
	s_add_u32 s4, s4, 0x4000
	s_addc_u32 s5, s5, 0
	s_waitcnt vmcnt(7) lgkmcnt(6)
	v_pk_add_f32 v[132:133], v[132:133], v[164:165]
	v_pk_add_f32 v[134:135], v[134:135], v[166:167]
	global_store_dwordx4 v247, v[132:135], s[4:5]
	s_add_u32 s4, s4, 0x4000
	s_addc_u32 s5, s5, 0
	s_waitcnt vmcnt(7) lgkmcnt(5)
	v_pk_add_f32 v[136:137], v[136:137], v[168:169]
	v_pk_add_f32 v[138:139], v[138:139], v[170:171]
	global_store_dwordx4 v247, v[136:139], s[4:5]
	s_add_u32 s4, s4, 0x4000
	s_addc_u32 s5, s5, 0
	s_waitcnt vmcnt(7) lgkmcnt(4)
	v_pk_add_f32 v[140:141], v[140:141], v[172:173]
	v_pk_add_f32 v[142:143], v[142:143], v[174:175]
	global_store_dwordx4 v247, v[140:143], s[4:5]
	s_add_u32 s4, s4, 0x4000
	s_addc_u32 s5, s5, 0
	s_waitcnt vmcnt(7) lgkmcnt(3)
	v_pk_add_f32 v[144:145], v[144:145], v[176:177]
	v_pk_add_f32 v[146:147], v[146:147], v[178:179]
	global_store_dwordx4 v247, v[144:147], s[4:5]
	s_add_u32 s4, s4, 0x4000
	s_addc_u32 s5, s5, 0
	s_waitcnt vmcnt(7) lgkmcnt(2)
	v_pk_add_f32 v[148:149], v[148:149], v[180:181]
	v_pk_add_f32 v[150:151], v[150:151], v[182:183]
	global_store_dwordx4 v247, v[148:151], s[4:5]
	s_add_u32 s4, s4, 0x4000
	s_addc_u32 s5, s5, 0
	s_waitcnt vmcnt(7) lgkmcnt(1)
	v_pk_add_f32 v[152:153], v[152:153], v[184:185]
	v_pk_add_f32 v[154:155], v[154:155], v[186:187]
	global_store_dwordx4 v247, v[152:155], s[4:5]
	s_add_u32 s4, s4, 0x4000
	s_addc_u32 s5, s5, 0
	s_waitcnt vmcnt(7) lgkmcnt(0)
	v_pk_add_f32 v[156:157], v[156:157], v[188:189]
	v_pk_add_f32 v[158:159], v[158:159], v[190:191]
	global_store_dwordx4 v247, v[156:159], s[4:5]
	s_add_u32 s4, s4, 0x4000
	s_addc_u32 s5, s5, 0
	s_nop 1
	s_add_u32 s15, s15, 64
	s_branch .Lg9_tile

; #define PH(k) case k: if (ONLY_PHASE >= 0 && ONLY_PHASE != k) break;
; template <class Epi>
; DI void gemm_phase(char* smem, const bf16_t* A0, int lda0, int ksplit, const bf16_t* A1, int lda1, const bf16_t* Bt, int K, int nN, const Epi& epi, int tid) {
;   const int G = gridDim.x;
;   if ((G & 7) == 0) {
;     const int x = blockIdx.x & 7, l = blockIdx.x >> 3, L = G >> 3, per = 8 * nN, tot = 2 * per;
;     for (int q = l; q < tot; q += L) { const int rgl = q / per, rem = q % per, ct = rem >> 3, rt = (x * 2 + rgl) * 8 + (rem & 7);
;       gemm_tile(smem, A0, lda0, ksplit, A1, lda1, Bt, K, rt * 256, ct * 128, epi, tid); }
; template <int ph> DI void run_phase(const Ctx& c, char* smem) {
;     ...
;     PH(14) gemm_phase(smem, (const bf16_t*)(ws + OFF_YG), 512, 1 << 30, XN, 1024, (const bf16_t*)(ws + OFF_WGLU), 512, 4,
;                         EpiGlu{(const bf16_t*)(ws + OFF_YG), p.s5_glu_b, (bf16_t*)(ws + OFF_S5Y)}, TIDX); break;
.LBB0_1816:
	s_cmp_gt_i32 s94, 14
	s_cselect_b64 s[0:1], -1, 0
	s_cmp_lt_i32 s95, 15
	s_cselect_b64 s[2:3], -1, 0
	s_or_b64 s[0:1], s[0:1], s[2:3]
	v_readlane_b32 s36, v252, 8
	s_and_b64 vcc, exec, s[0:1]
	v_readlane_b32 s40, v252, 12
	v_readlane_b32 s41, v252, 13
	v_readlane_b32 s42, v252, 14
	v_readlane_b32 s43, v252, 15
	v_readlane_b32 s37, v252, 9
	v_readlane_b32 s38, v252, 10
	v_readlane_b32 s39, v252, 11
	v_readlane_b32 s44, v252, 16
	v_readlane_b32 s45, v252, 17
	v_readlane_b32 s46, v252, 18
	v_readlane_b32 s47, v252, 19
	v_readlane_b32 s48, v252, 20
	v_readlane_b32 s49, v252, 21
	v_readlane_b32 s50, v252, 22
	v_readlane_b32 s51, v252, 23
	s_cbranch_vccnz .LBB0_1844
	s_add_u32 s2, s92, 0x1da00000
	s_waitcnt lgkmcnt(0)
	s_load_dword s14, s[74:75], 0x180
	s_addc_u32 s3, s93, 0
	s_add_u32 s0, s92, 0x3400000
	s_addc_u32 s1, s93, 0
	s_add_u32 s4, s92, 0x11a00000
	s_addc_u32 s5, s93, 0
	s_and_b32 s16, s72, 0xffffffc0
	v_mbcnt_hi_u32_b32 v195, -1, v194
	s_waitcnt lgkmcnt(0)
	s_and_b32 s15, s14, 7
	s_cmp_lg_u32 s15, 0
	s_waitcnt vmcnt(16)
	v_add_u32_e32 v196, s16, v195
	v_mbcnt_lo_u32_b32 v240, -1, 0
	v_mbcnt_hi_u32_b32 v240, -1, v240
	s_lshr_b32 s12, s72, 6
	s_lshl_b32 s101, s12, 10
	v_and_b32_e32 v241, 15, v240
	v_lshrrev_b32_e32 v242, 4, v240
	v_bfe_u32 v243, v240, 3, 1
	v_mul_u32_u24_e32 v243, 3, v243
	v_xor_b32_e32 v243, v242, v243
	v_lshlrev_b32_e32 v243, 4, v243
	v_lshl_add_u32 v243, v241, 6, v243
	s_lshr_b32 s11, s12, 1
	s_lshl_b32 s11, s11, 13
	v_add_u32_e32 v230, s11, v243
	s_and_b32 s11, s12, 1
	s_lshl_b32 s11, s11, 12
	s_add_u32 s11, s11, 16384
	v_add_u32_e32 v231, s11, v243
	s_lshr_b32 s11, s12, 1
	s_lshl_b32 s11, s11, 7
	v_add_u32_e32 v244, s11, v241
	s_and_b32 s11, s12, 1
	s_lshl_b32 s11, s11, 6
	v_lshl_add_u32 v245, v242, 2, s11
	s_movk_i32 s11, 0x1000
	v_mul_lo_u32 v246, v244, s11
	v_lshl_add_u32 v234, v245, 2, v246
	v_lshrrev_b32_e32 v241, 2, v240
	s_lshl_b32 s11, s12, 4
	v_add_u32_e32 v241, s11, v241
	v_bfe_u32 v242, v240, 5, 1
	v_mul_u32_u24_e32 v242, 3, v242
	v_and_b32_e32 v243, 3, v240
	v_xor_b32_e32 v243, v243, v242
	v_lshlrev_b32_e32 v243, 4, v243
	s_mov_b32 s11, 1024
	v_mad_u32_u24 v224, v241, s11, v243
	v_add_u32_e32 v225, 0x10000, v224
	v_add_u32_e32 v226, 0x20000, v224
	v_add_u32_e32 v227, 0x30000, v224
	s_mov_b32 s11, 1024
	v_mad_u32_u24 v228, v241, s11, v243
	v_add_u32_e32 v229, 0x10000, v228
	s_load_dwordx2 s[6:7], s[74:75], 0x118
	v_mbcnt_lo_u32_b32 v240, -1, 0
	v_mbcnt_hi_u32_b32 v240, -1, v240
	s_lshr_b32 s12, s72, 6
	s_mul_i32 s11, s12, 17408
	v_and_b32_e32 v241, 15, v240
	v_lshrrev_b32_e32 v242, 4, v240
	v_mul_u32_u24_e32 v243, 0x110, v241
	v_lshl_add_u32 v243, v242, 4, v243
	v_add_u32_e32 v245, s11, v243
	v_mul_u32_u24_e32 v243, 0x110, v242
	v_lshl_add_u32 v243, v241, 4, v243
	v_add_u32_e32 v246, s11, v243
	s_lshr_b32 s11, s12, 1
	s_lshl_b32 s11, s11, 7
	v_add_u32_e32 v243, s11, v242
	v_lshlrev_b32_e32 v243, 12, v243
	s_and_b32 s11, s12, 1
	s_lshl_b32 s11, s11, 8
	v_lshl_add_u32 v244, v241, 4, s11
	v_add_u32_e32 v247, v243, v244
	v_lshrrev_b32_e32 v243, 2, v243
	v_lshrrev_b32_e32 v235, 1, v244
	v_add_u32_e32 v235, v243, v235
	v_mov_b32_e32 v234, v244
	s_lshr_b32 s17, s96, 3
	s_and_b32 s20, s96, 7
	s_lshl_b32 s20, s20, 1
	s_waitcnt lgkmcnt(0)
.Lg14_tile:
	s_cmpk_ge_u32 s17, 64
	s_cbranch_scc1 .Lg14_done
	s_cmpk_ge_u32 s17, 32
	s_cselect_b32 s12, 1, 0
	s_cselect_b32 s11, 32, 0
	s_sub_u32 s11, s17, s11
	s_add_u32 s12, s12, s20
	s_lshl_b32 s12, s12, 3
	s_and_b32 s18, s11, 7
	s_add_u32 s18, s18, s12
	s_lshl_b32 s18, s18, 8
	s_lshr_b32 s13, s11, 3
	s_lshl_b32 s13, s13, 7
	s_mul_i32 s12, s18, 1024
	s_add_u32 s12, s12, 0x1da00000
	s_add_u32 s0, s92, s12
	s_addc_u32 s1, s93, 0
	s_mul_i32 s12, s13, 1024
	s_add_u32 s12, s12, 0x3400000
	s_add_u32 s2, s92, s12
	s_addc_u32 s3, s93, 0
	s_waitcnt lgkmcnt(0)
	s_barrier
	s_mov_b32 s100, 0
	s_mov_b32 s19, 0
	s_add_u32 s11, s19, s101
	s_add_u32 m0, s11, 0
	s_nop 0
	global_load_lds_dwordx4 v224, s[0:1]
	s_add_u32 m0, s11, 4096
	s_nop 0
	global_load_lds_dwordx4 v225, s[0:1]
	s_add_u32 m0, s11, 8192
	s_nop 0
	global_load_lds_dwordx4 v226, s[0:1]
	s_add_u32 m0, s11, 12288
	s_nop 0
	global_load_lds_dwordx4 v227, s[0:1]
	s_add_u32 m0, s11, 16384
	s_nop 0
	global_load_lds_dwordx4 v228, s[2:3]
	s_add_u32 m0, s11, 20480
	s_nop 0
	global_load_lds_dwordx4 v229, s[2:3]
	s_add_u32 s0, s0, 64
	s_addc_u32 s1, s1, 0
	s_add_u32 s2, s2, 64
	s_addc_u32 s3, s3, 0
	s_add_u32 s100, s100, 1
	s_add_u32 s19, s19, 24576
	s_cmp_eq_u32 s19, 73728
	s_cselect_b32 s19, 0, s19
	s_add_u32 s11, s19, s101
	s_add_u32 m0, s11, 0
	s_nop 0
	global_load_lds_dwordx4 v224, s[0:1]
	s_add_u32 m0, s11, 4096
	s_nop 0
	global_load_lds_dwordx4 v225, s[0:1]
	s_add_u32 m0, s11, 8192
	s_nop 0
	global_load_lds_dwordx4 v226, s[0:1]
	s_add_u32 m0, s11, 12288
	s_nop 0
	global_load_lds_dwordx4 v227, s[0:1]
	s_add_u32 m0, s11, 16384
	s_nop 0
	global_load_lds_dwordx4 v228, s[2:3]
	s_add_u32 m0, s11, 20480
	s_nop 0
	global_load_lds_dwordx4 v229, s[2:3]
	s_add_u32 s0, s0, 64
	s_addc_u32 s1, s1, 0
	s_add_u32 s2, s2, 64
	s_addc_u32 s3, s3, 0
	s_add_u32 s100, s100, 1
	s_add_u32 s19, s19, 24576
	s_cmp_eq_u32 s19, 73728
	s_cselect_b32 s19, 0, s19
	s_add_u32 s11, s19, s101
	s_add_u32 m0, s11, 0
	s_nop 0
	global_load_lds_dwordx4 v224, s[0:1]
	s_add_u32 m0, s11, 4096
	s_nop 0
	global_load_lds_dwordx4 v225, s[0:1]
	s_add_u32 m0, s11, 8192
	s_nop 0
	global_load_lds_dwordx4 v226, s[0:1]
	s_add_u32 m0, s11, 12288
	s_nop 0
	global_load_lds_dwordx4 v227, s[0:1]
	s_add_u32 m0, s11, 16384
	s_nop 0
	global_load_lds_dwordx4 v228, s[2:3]
	s_add_u32 m0, s11, 20480
	s_nop 0
	global_load_lds_dwordx4 v229, s[2:3]
	s_add_u32 s0, s0, 64
	s_addc_u32 s1, s1, 0
; #define LWRITE(S, buf) do { bf16_t* sA_ = sbase + (buf) * BUF; bf16_t* sB_ = sA_ + 256 * PITCH; \
;     _Pragma("unroll") for (int i_ = 0; i_ < 4; ++i_) *(u32x4*)(sA_ + (sr + i_ * 64) * PITCH + scv * 8) = ra[S][i_]; \
;     _Pragma("unroll") for (int i_ = 0; i_ < 2; ++i_) *(u32x4*)(sB_ + (sr + i_ * 64) * PITCH + scv * 8) = rb[S][i_]; } while (0)
; template <class Epi>
; DI void gemm_tile(char* smem, const bf16_t* __restrict__ A0, int lda0, int ksplit, const bf16_t* __restrict__ A1, int lda1,
;                   const bf16_t* __restrict__ Bt, int K, int row0, int col0, const Epi& epi, int tid) {
;     ...
; #pragma unroll
;   for (int m = 0; m < 8; ++m)
; #pragma unroll
;     for (int n = 0; n < 4; ++n) acc[m][n] = (f32x4){0.f, 0.f, 0.f, 0.f};
;   u32x4 ra[2][4], rb[2][2];
;   const int nk = K / BK;
;   const int sr = tid >> 2, scv = tid & 3;
;     ...
;   __syncthreads();
;   {
;     const int last = nk - 1;
;     GLOAD(0, 0);
;     __builtin_amdgcn_sched_barrier(0);
;     GLOAD(1, 1);
;     __builtin_amdgcn_sched_barrier(0);
;     LWRITE(0, 0);
;     __builtin_amdgcn_sched_barrier(0);
;     GLOAD(0, (2 < last ? 2 : last));
;     __builtin_amdgcn_sched_barrier(0);
;     __syncthreads();
;     for (int kt = 0; kt < nk; kt += 2) {
;       LWRITE(1, 1);
;       __builtin_amdgcn_sched_barrier(0);
;       GLOAD(1, (kt + 3 < last ? kt + 3 : last));
;       __builtin_amdgcn_sched_barrier(0);
;       COMPUTE(0);
;       __syncthreads();
;       LWRITE(0, 0);
;       __builtin_amdgcn_sched_barrier(0);
;       GLOAD(0, (kt + 4 < last ? kt + 4 : last));
;       __builtin_amdgcn_sched_barrier(0);
;       COMPUTE(1);
;       __syncthreads();
	s_add_u32 s2, s2, 64
	s_addc_u32 s3, s3, 0
	s_add_u32 s100, s100, 1
	s_add_u32 s19, s19, 24576
	s_cmp_eq_u32 s19, 73728
	s_cselect_b32 s19, 0, s19
	v_mov_b32_e32 v0, 0
	v_mov_b32_e32 v1, 0
	v_mov_b32_e32 v2, 0
	v_mov_b32_e32 v3, 0
	v_mov_b32_e32 v4, 0
	v_mov_b32_e32 v5, 0
	v_mov_b32_e32 v6, 0
	v_mov_b32_e32 v7, 0
	v_mov_b32_e32 v8, 0
	v_mov_b32_e32 v9, 0
	v_mov_b32_e32 v10, 0
	v_mov_b32_e32 v11, 0
	v_mov_b32_e32 v12, 0
	v_mov_b32_e32 v13, 0
	v_mov_b32_e32 v14, 0
	v_mov_b32_e32 v15, 0
	v_mov_b32_e32 v16, 0
	v_mov_b32_e32 v17, 0
	v_mov_b32_e32 v18, 0
	v_mov_b32_e32 v19, 0
	v_mov_b32_e32 v20, 0
	v_mov_b32_e32 v21, 0
	v_mov_b32_e32 v22, 0
	v_mov_b32_e32 v23, 0
	v_mov_b32_e32 v24, 0
	v_mov_b32_e32 v25, 0
	v_mov_b32_e32 v26, 0
	v_mov_b32_e32 v27, 0
	v_mov_b32_e32 v28, 0
	v_mov_b32_e32 v29, 0
	v_mov_b32_e32 v30, 0
	v_mov_b32_e32 v31, 0
	v_mov_b32_e32 v32, 0
	v_mov_b32_e32 v33, 0
	v_mov_b32_e32 v34, 0
	v_mov_b32_e32 v35, 0
	v_mov_b32_e32 v36, 0
	v_mov_b32_e32 v37, 0
	v_mov_b32_e32 v38, 0
	v_mov_b32_e32 v39, 0
	v_mov_b32_e32 v40, 0
	v_mov_b32_e32 v41, 0
	v_mov_b32_e32 v42, 0
	v_mov_b32_e32 v43, 0
	v_mov_b32_e32 v44, 0
	v_mov_b32_e32 v45, 0
	v_mov_b32_e32 v46, 0
	v_mov_b32_e32 v47, 0
	v_mov_b32_e32 v48, 0
	v_mov_b32_e32 v49, 0
	v_mov_b32_e32 v50, 0
	v_mov_b32_e32 v51, 0
	v_mov_b32_e32 v52, 0
	v_mov_b32_e32 v53, 0
	v_mov_b32_e32 v54, 0
	v_mov_b32_e32 v55, 0
	v_mov_b32_e32 v56, 0
	v_mov_b32_e32 v57, 0
	v_mov_b32_e32 v58, 0
	v_mov_b32_e32 v59, 0
	v_mov_b32_e32 v60, 0
	v_mov_b32_e32 v61, 0
	v_mov_b32_e32 v62, 0
	v_mov_b32_e32 v63, 0
	v_mov_b32_e32 v64, 0
	v_mov_b32_e32 v65, 0
	v_mov_b32_e32 v66, 0
	v_mov_b32_e32 v67, 0
	v_mov_b32_e32 v68, 0
	v_mov_b32_e32 v69, 0
	v_mov_b32_e32 v70, 0
	v_mov_b32_e32 v71, 0
	v_mov_b32_e32 v72, 0
	v_mov_b32_e32 v73, 0
	v_mov_b32_e32 v74, 0
	v_mov_b32_e32 v75, 0
	v_mov_b32_e32 v76, 0
	v_mov_b32_e32 v77, 0
	v_mov_b32_e32 v78, 0
	v_mov_b32_e32 v79, 0
	v_mov_b32_e32 v80, 0
	v_mov_b32_e32 v81, 0
	v_mov_b32_e32 v82, 0
	v_mov_b32_e32 v83, 0
	v_mov_b32_e32 v84, 0
	v_mov_b32_e32 v85, 0
	v_mov_b32_e32 v86, 0
	v_mov_b32_e32 v87, 0
	v_mov_b32_e32 v88, 0
	v_mov_b32_e32 v89, 0
	v_mov_b32_e32 v90, 0
	v_mov_b32_e32 v91, 0
	v_mov_b32_e32 v92, 0
	v_mov_b32_e32 v93, 0
	v_mov_b32_e32 v94, 0
	v_mov_b32_e32 v95, 0
	v_mov_b32_e32 v96, 0
	v_mov_b32_e32 v97, 0
	v_mov_b32_e32 v98, 0
	v_mov_b32_e32 v99, 0
	v_mov_b32_e32 v100, 0
	v_mov_b32_e32 v101, 0
	v_mov_b32_e32 v102, 0
	v_mov_b32_e32 v103, 0
	v_mov_b32_e32 v104, 0
	v_mov_b32_e32 v105, 0
	v_mov_b32_e32 v106, 0
	v_mov_b32_e32 v107, 0
	v_mov_b32_e32 v108, 0
	v_mov_b32_e32 v109, 0
	v_mov_b32_e32 v110, 0
	v_mov_b32_e32 v111, 0
	v_mov_b32_e32 v112, 0
	v_mov_b32_e32 v113, 0
	v_mov_b32_e32 v114, 0
	v_mov_b32_e32 v115, 0
	v_mov_b32_e32 v116, 0
	v_mov_b32_e32 v117, 0
	v_mov_b32_e32 v118, 0
	v_mov_b32_e32 v119, 0
	v_mov_b32_e32 v120, 0
	v_mov_b32_e32 v121, 0
	v_mov_b32_e32 v122, 0
	v_mov_b32_e32 v123, 0
	v_mov_b32_e32 v124, 0
	v_mov_b32_e32 v125, 0
	v_mov_b32_e32 v126, 0
	v_mov_b32_e32 v127, 0
	s_mov_b32 s99, 0
	s_mov_b32 s98, 24576
	s_waitcnt vmcnt(12)
	s_barrier
	ds_read_b128 v[128:131], v231 offset:0
	ds_read_b128 v[132:135], v231 offset:1024
	ds_read_b128 v[136:139], v231 offset:2048
	ds_read_b128 v[140:143], v231 offset:3072
	ds_read_b128 v[144:147], v230 offset:0
	ds_read_b128 v[148:151], v230 offset:1024
	ds_read_b128 v[152:155], v230 offset:2048
	ds_read_b128 v[156:159], v230 offset:3072
	ds_read_b128 v[160:163], v230 offset:4096
	ds_read_b128 v[164:167], v230 offset:5120
	ds_read_b128 v[168:171], v230 offset:6144
	ds_read_b128 v[172:175], v230 offset:7168
.Lg14_kloop:
	s_waitcnt vmcnt(6)
	s_waitcnt lgkmcnt(0)
	s_barrier
	v_add_u32_e32 v232, s98, v230
	v_add_u32_e32 v233, s98, v231
	s_add_u32 s11, s19, s101
	v_mfma_f32_16x16x32_bf16 v[0:3], v[128:131], v[144:147], v[0:3]
	v_mfma_f32_16x16x32_bf16 v[4:7], v[132:135], v[144:147], v[4:7]
	v_mfma_f32_16x16x32_bf16 v[8:11], v[136:139], v[144:147], v[8:11]
	v_mfma_f32_16x16x32_bf16 v[12:15], v[140:143], v[144:147], v[12:15]
	ds_read_b128 v[176:179], v233 offset:0
	ds_read_b128 v[180:183], v233 offset:1024
	s_add_u32 m0, s11, 0
	s_nop 0
	global_load_lds_dwordx4 v224, s[0:1]
	v_mfma_f32_16x16x32_bf16 v[16:19], v[128:131], v[148:151], v[16:19]
	v_mfma_f32_16x16x32_bf16 v[20:23], v[132:135], v[148:151], v[20:23]
	v_mfma_f32_16x16x32_bf16 v[24:27], v[136:139], v[148:151], v[24:27]
	v_mfma_f32_16x16x32_bf16 v[28:31], v[140:143], v[148:151], v[28:31]
	ds_read_b128 v[184:187], v233 offset:2048
	ds_read_b128 v[188:191], v233 offset:3072
	s_add_u32 m0, s11, 4096
	s_nop 0
	global_load_lds_dwordx4 v225, s[0:1]
	v_mfma_f32_16x16x32_bf16 v[32:35], v[128:131], v[152:155], v[32:35]
	v_mfma_f32_16x16x32_bf16 v[36:39], v[132:135], v[152:155], v[36:39]
	v_mfma_f32_16x16x32_bf16 v[40:43], v[136:139], v[152:155], v[40:43]
	v_mfma_f32_16x16x32_bf16 v[44:47], v[140:143], v[152:155], v[44:47]
	ds_read_b128 v[192:195], v232 offset:0
	ds_read_b128 v[196:199], v232 offset:1024
	s_add_u32 m0, s11, 8192
	s_nop 0
	global_load_lds_dwordx4 v226, s[0:1]
	v_mfma_f32_16x16x32_bf16 v[48:51], v[128:131], v[156:159], v[48:51]
	v_mfma_f32_16x16x32_bf16 v[52:55], v[132:135], v[156:159], v[52:55]
	v_mfma_f32_16x16x32_bf16 v[56:59], v[136:139], v[156:159], v[56:59]
	v_mfma_f32_16x16x32_bf16 v[60:63], v[140:143], v[156:159], v[60:63]
	ds_read_b128 v[200:203], v232 offset:2048
	ds_read_b128 v[204:207], v232 offset:3072
	s_add_u32 m0, s11, 12288
	s_nop 0
	global_load_lds_dwordx4 v227, s[0:1]
	v_mfma_f32_16x16x32_bf16 v[64:67], v[128:131], v[160:163], v[64:67]
	v_mfma_f32_16x16x32_bf16 v[68:71], v[132:135], v[160:163], v[68:71]
	v_mfma_f32_16x16x32_bf16 v[72:75], v[136:139], v[160:163], v[72:75]
; #define LWRITE(S, buf) do { bf16_t* sA_ = sbase + (buf) * BUF; bf16_t* sB_ = sA_ + 256 * PITCH; \
;     _Pragma("unroll") for (int i_ = 0; i_ < 4; ++i_) *(u32x4*)(sA_ + (sr + i_ * 64) * PITCH + scv * 8) = ra[S][i_]; \
;     _Pragma("unroll") for (int i_ = 0; i_ < 2; ++i_) *(u32x4*)(sB_ + (sr + i_ * 64) * PITCH + scv * 8) = rb[S][i_]; } while (0)
; template <class Epi>
; DI void gemm_tile(char* smem, const bf16_t* __restrict__ A0, int lda0, int ksplit, const bf16_t* __restrict__ A1, int lda1,
;                   const bf16_t* __restrict__ Bt, int K, int row0, int col0, const Epi& epi, int tid) {
;     ...
;   __syncthreads();
;   {
;     const int last = nk - 1;
;     GLOAD(0, 0);
;     __builtin_amdgcn_sched_barrier(0);
;     GLOAD(1, 1);
;     __builtin_amdgcn_sched_barrier(0);
;     LWRITE(0, 0);
;     __builtin_amdgcn_sched_barrier(0);
;     GLOAD(0, (2 < last ? 2 : last));
;     __builtin_amdgcn_sched_barrier(0);
;     __syncthreads();
;     for (int kt = 0; kt < nk; kt += 2) {
;       LWRITE(1, 1);
;       __builtin_amdgcn_sched_barrier(0);
;       GLOAD(1, (kt + 3 < last ? kt + 3 : last));
;       __builtin_amdgcn_sched_barrier(0);
;       COMPUTE(0);
;       __syncthreads();
;       LWRITE(0, 0);
;       __builtin_amdgcn_sched_barrier(0);
;       GLOAD(0, (kt + 4 < last ? kt + 4 : last));
;       __builtin_amdgcn_sched_barrier(0);
;       COMPUTE(1);
;       __syncthreads();
	v_mfma_f32_16x16x32_bf16 v[76:79], v[140:143], v[160:163], v[76:79]
	ds_read_b128 v[208:211], v232 offset:4096
	s_add_u32 m0, s11, 16384
	s_nop 0
	global_load_lds_dwordx4 v228, s[2:3]
	v_mfma_f32_16x16x32_bf16 v[80:83], v[128:131], v[164:167], v[80:83]
	v_mfma_f32_16x16x32_bf16 v[84:87], v[132:135], v[164:167], v[84:87]
	v_mfma_f32_16x16x32_bf16 v[88:91], v[136:139], v[164:167], v[88:91]
	v_mfma_f32_16x16x32_bf16 v[92:95], v[140:143], v[164:167], v[92:95]
	ds_read_b128 v[212:215], v232 offset:5120
	s_add_u32 m0, s11, 20480
	s_nop 0
	global_load_lds_dwordx4 v229, s[2:3]
	v_mfma_f32_16x16x32_bf16 v[96:99], v[128:131], v[168:171], v[96:99]
	v_mfma_f32_16x16x32_bf16 v[100:103], v[132:135], v[168:171], v[100:103]
	v_mfma_f32_16x16x32_bf16 v[104:107], v[136:139], v[168:171], v[104:107]
	v_mfma_f32_16x16x32_bf16 v[108:111], v[140:143], v[168:171], v[108:111]
	ds_read_b128 v[216:219], v232 offset:6144
	s_add_u32 s0, s0, 64
	s_addc_u32 s1, s1, 0
	s_add_u32 s2, s2, 64
	s_addc_u32 s3, s3, 0
	s_add_u32 s100, s100, 1
	s_add_u32 s19, s19, 24576
	s_cmp_eq_u32 s19, 73728
	s_cselect_b32 s19, 0, s19
	s_add_u32 s98, s98, 24576
	s_cmp_eq_u32 s98, 73728
	s_cselect_b32 s98, 0, s98
	v_mfma_f32_16x16x32_bf16 v[112:115], v[128:131], v[172:175], v[112:115]
	v_mfma_f32_16x16x32_bf16 v[116:119], v[132:135], v[172:175], v[116:119]
	v_mfma_f32_16x16x32_bf16 v[120:123], v[136:139], v[172:175], v[120:123]
	v_mfma_f32_16x16x32_bf16 v[124:127], v[140:143], v[172:175], v[124:127]
	ds_read_b128 v[220:223], v232 offset:7168
	s_waitcnt vmcnt(6)
	s_waitcnt lgkmcnt(0)
	s_barrier
	v_add_u32_e32 v232, s98, v230
	v_add_u32_e32 v233, s98, v231
	s_add_u32 s11, s19, s101
	v_mfma_f32_16x16x32_bf16 v[0:3], v[176:179], v[192:195], v[0:3]
	v_mfma_f32_16x16x32_bf16 v[4:7], v[180:183], v[192:195], v[4:7]
	v_mfma_f32_16x16x32_bf16 v[8:11], v[184:187], v[192:195], v[8:11]
	v_mfma_f32_16x16x32_bf16 v[12:15], v[188:191], v[192:195], v[12:15]
	ds_read_b128 v[128:131], v233 offset:0
	ds_read_b128 v[132:135], v233 offset:1024
	s_add_u32 m0, s11, 0
	s_nop 0
	global_load_lds_dwordx4 v224, s[0:1]
	v_mfma_f32_16x16x32_bf16 v[16:19], v[176:179], v[196:199], v[16:19]
	v_mfma_f32_16x16x32_bf16 v[20:23], v[180:183], v[196:199], v[20:23]
	v_mfma_f32_16x16x32_bf16 v[24:27], v[184:187], v[196:199], v[24:27]
	v_mfma_f32_16x16x32_bf16 v[28:31], v[188:191], v[196:199], v[28:31]
	ds_read_b128 v[136:139], v233 offset:2048
	ds_read_b128 v[140:143], v233 offset:3072
	s_add_u32 m0, s11, 4096
	s_nop 0
	global_load_lds_dwordx4 v225, s[0:1]
	v_mfma_f32_16x16x32_bf16 v[32:35], v[176:179], v[200:203], v[32:35]
	v_mfma_f32_16x16x32_bf16 v[36:39], v[180:183], v[200:203], v[36:39]
	v_mfma_f32_16x16x32_bf16 v[40:43], v[184:187], v[200:203], v[40:43]
	v_mfma_f32_16x16x32_bf16 v[44:47], v[188:191], v[200:203], v[44:47]
	ds_read_b128 v[144:147], v232 offset:0
	ds_read_b128 v[148:151], v232 offset:1024
	s_add_u32 m0, s11, 8192
	s_nop 0
	global_load_lds_dwordx4 v226, s[0:1]
	v_mfma_f32_16x16x32_bf16 v[48:51], v[176:179], v[204:207], v[48:51]
	v_mfma_f32_16x16x32_bf16 v[52:55], v[180:183], v[204:207], v[52:55]
	v_mfma_f32_16x16x32_bf16 v[56:59], v[184:187], v[204:207], v[56:59]
	v_mfma_f32_16x16x32_bf16 v[60:63], v[188:191], v[204:207], v[60:63]
	ds_read_b128 v[152:155], v232 offset:2048
	ds_read_b128 v[156:159], v232 offset:3072
	s_add_u32 m0, s11, 12288
	s_nop 0
	global_load_lds_dwordx4 v227, s[0:1]
	v_mfma_f32_16x16x32_bf16 v[64:67], v[176:179], v[208:211], v[64:67]
	v_mfma_f32_16x16x32_bf16 v[68:71], v[180:183], v[208:211], v[68:71]
	v_mfma_f32_16x16x32_bf16 v[72:75], v[184:187], v[208:211], v[72:75]
	v_mfma_f32_16x16x32_bf16 v[76:79], v[188:191], v[208:211], v[76:79]
	ds_read_b128 v[160:163], v232 offset:4096
	s_add_u32 m0, s11, 16384
	s_nop 0
	global_load_lds_dwordx4 v228, s[2:3]
	v_mfma_f32_16x16x32_bf16 v[80:83], v[176:179], v[212:215], v[80:83]
	v_mfma_f32_16x16x32_bf16 v[84:87], v[180:183], v[212:215], v[84:87]
	v_mfma_f32_16x16x32_bf16 v[88:91], v[184:187], v[212:215], v[88:91]
	v_mfma_f32_16x16x32_bf16 v[92:95], v[188:191], v[212:215], v[92:95]
	ds_read_b128 v[164:167], v232 offset:5120
	s_add_u32 m0, s11, 20480
	s_nop 0
	global_load_lds_dwordx4 v229, s[2:3]
	v_mfma_f32_16x16x32_bf16 v[96:99], v[176:179], v[216:219], v[96:99]
	v_mfma_f32_16x16x32_bf16 v[100:103], v[180:183], v[216:219], v[100:103]
	v_mfma_f32_16x16x32_bf16 v[104:107], v[184:187], v[216:219], v[104:107]
	v_mfma_f32_16x16x32_bf16 v[108:111], v[188:191], v[216:219], v[108:111]
	ds_read_b128 v[168:171], v232 offset:6144
	s_add_u32 s0, s0, 64
	s_addc_u32 s1, s1, 0
	s_add_u32 s2, s2, 64
	s_addc_u32 s3, s3, 0
	s_add_u32 s100, s100, 1
	s_add_u32 s19, s19, 24576
	s_cmp_eq_u32 s19, 73728
	s_cselect_b32 s19, 0, s19
	s_add_u32 s98, s98, 24576
	s_cmp_eq_u32 s98, 73728
	s_cselect_b32 s98, 0, s98
	v_mfma_f32_16x16x32_bf16 v[112:115], v[176:179], v[220:223], v[112:115]
	v_mfma_f32_16x16x32_bf16 v[116:119], v[180:183], v[220:223], v[116:119]
	v_mfma_f32_16x16x32_bf16 v[120:123], v[184:187], v[220:223], v[120:123]
	v_mfma_f32_16x16x32_bf16 v[124:127], v[188:191], v[220:223], v[124:127]
	ds_read_b128 v[172:175], v232 offset:7168
	s_add_u32 s99, s99, 2
	s_cmp_lt_u32 s99, 12
	s_cbranch_scc1 .Lg14_kloop
	s_waitcnt vmcnt(6)
	s_waitcnt lgkmcnt(0)
	s_barrier
; #define LWRITE(S, buf) do { bf16_t* sA_ = sbase + (buf) * BUF; bf16_t* sB_ = sA_ + 256 * PITCH; \
;     _Pragma("unroll") for (int i_ = 0; i_ < 4; ++i_) *(u32x4*)(sA_ + (sr + i_ * 64) * PITCH + scv * 8) = ra[S][i_]; \
;     _Pragma("unroll") for (int i_ = 0; i_ < 2; ++i_) *(u32x4*)(sB_ + (sr + i_ * 64) * PITCH + scv * 8) = rb[S][i_]; } while (0)
; template <class Epi>
; DI void gemm_tile(char* smem, const bf16_t* __restrict__ A0, int lda0, int ksplit, const bf16_t* __restrict__ A1, int lda1,
;                   const bf16_t* __restrict__ Bt, int K, int row0, int col0, const Epi& epi, int tid) {
;     ...
;   __syncthreads();
;   {
;     const int last = nk - 1;
;     GLOAD(0, 0);
;     __builtin_amdgcn_sched_barrier(0);
;     GLOAD(1, 1);
;     __builtin_amdgcn_sched_barrier(0);
;     LWRITE(0, 0);
;     __builtin_amdgcn_sched_barrier(0);
;     GLOAD(0, (2 < last ? 2 : last));
;     __builtin_amdgcn_sched_barrier(0);
;     __syncthreads();
;     for (int kt = 0; kt < nk; kt += 2) {
;       LWRITE(1, 1);
;       __builtin_amdgcn_sched_barrier(0);
;       GLOAD(1, (kt + 3 < last ? kt + 3 : last));
;       __builtin_amdgcn_sched_barrier(0);
;       COMPUTE(0);
;       __syncthreads();
;       LWRITE(0, 0);
;       __builtin_amdgcn_sched_barrier(0);
;       GLOAD(0, (kt + 4 < last ? kt + 4 : last));
;       __builtin_amdgcn_sched_barrier(0);
;       COMPUTE(1);
;       __syncthreads();
	v_add_u32_e32 v232, s98, v230
	v_add_u32_e32 v233, s98, v231
	s_add_u32 s11, s19, s101
	v_mfma_f32_16x16x32_bf16 v[0:3], v[128:131], v[144:147], v[0:3]
	v_mfma_f32_16x16x32_bf16 v[4:7], v[132:135], v[144:147], v[4:7]
	v_mfma_f32_16x16x32_bf16 v[8:11], v[136:139], v[144:147], v[8:11]
	v_mfma_f32_16x16x32_bf16 v[12:15], v[140:143], v[144:147], v[12:15]
	ds_read_b128 v[176:179], v233 offset:0
	ds_read_b128 v[180:183], v233 offset:1024
	s_add_u32 m0, s11, 0
	s_nop 0
	global_load_lds_dwordx4 v224, s[0:1]
	v_mfma_f32_16x16x32_bf16 v[16:19], v[128:131], v[148:151], v[16:19]
	v_mfma_f32_16x16x32_bf16 v[20:23], v[132:135], v[148:151], v[20:23]
	v_mfma_f32_16x16x32_bf16 v[24:27], v[136:139], v[148:151], v[24:27]
	v_mfma_f32_16x16x32_bf16 v[28:31], v[140:143], v[148:151], v[28:31]
	ds_read_b128 v[184:187], v233 offset:2048
	ds_read_b128 v[188:191], v233 offset:3072
	s_add_u32 m0, s11, 4096
	s_nop 0
	global_load_lds_dwordx4 v225, s[0:1]
	v_mfma_f32_16x16x32_bf16 v[32:35], v[128:131], v[152:155], v[32:35]
	v_mfma_f32_16x16x32_bf16 v[36:39], v[132:135], v[152:155], v[36:39]
	v_mfma_f32_16x16x32_bf16 v[40:43], v[136:139], v[152:155], v[40:43]
	v_mfma_f32_16x16x32_bf16 v[44:47], v[140:143], v[152:155], v[44:47]
	ds_read_b128 v[192:195], v232 offset:0
	ds_read_b128 v[196:199], v232 offset:1024
	s_add_u32 m0, s11, 8192
	s_nop 0
	global_load_lds_dwordx4 v226, s[0:1]
	v_mfma_f32_16x16x32_bf16 v[48:51], v[128:131], v[156:159], v[48:51]
	v_mfma_f32_16x16x32_bf16 v[52:55], v[132:135], v[156:159], v[52:55]
	v_mfma_f32_16x16x32_bf16 v[56:59], v[136:139], v[156:159], v[56:59]
	v_mfma_f32_16x16x32_bf16 v[60:63], v[140:143], v[156:159], v[60:63]
	ds_read_b128 v[200:203], v232 offset:2048
	ds_read_b128 v[204:207], v232 offset:3072
	s_add_u32 m0, s11, 12288
	s_nop 0
	global_load_lds_dwordx4 v227, s[0:1]
	v_mfma_f32_16x16x32_bf16 v[64:67], v[128:131], v[160:163], v[64:67]
	v_mfma_f32_16x16x32_bf16 v[68:71], v[132:135], v[160:163], v[68:71]
	v_mfma_f32_16x16x32_bf16 v[72:75], v[136:139], v[160:163], v[72:75]
	v_mfma_f32_16x16x32_bf16 v[76:79], v[140:143], v[160:163], v[76:79]
	ds_read_b128 v[208:211], v232 offset:4096
	s_add_u32 m0, s11, 16384
	s_nop 0
	global_load_lds_dwordx4 v228, s[2:3]
	v_mfma_f32_16x16x32_bf16 v[80:83], v[128:131], v[164:167], v[80:83]
	v_mfma_f32_16x16x32_bf16 v[84:87], v[132:135], v[164:167], v[84:87]
	v_mfma_f32_16x16x32_bf16 v[88:91], v[136:139], v[164:167], v[88:91]
	v_mfma_f32_16x16x32_bf16 v[92:95], v[140:143], v[164:167], v[92:95]
	ds_read_b128 v[212:215], v232 offset:5120
	s_add_u32 m0, s11, 20480
	s_nop 0
	global_load_lds_dwordx4 v229, s[2:3]
	v_mfma_f32_16x16x32_bf16 v[96:99], v[128:131], v[168:171], v[96:99]
	v_mfma_f32_16x16x32_bf16 v[100:103], v[132:135], v[168:171], v[100:103]
	v_mfma_f32_16x16x32_bf16 v[104:107], v[136:139], v[168:171], v[104:107]
	v_mfma_f32_16x16x32_bf16 v[108:111], v[140:143], v[168:171], v[108:111]
	ds_read_b128 v[216:219], v232 offset:6144
	s_add_u32 s0, s0, 64
	s_addc_u32 s1, s1, 0
	s_add_u32 s2, s2, 64
	s_addc_u32 s3, s3, 0
	s_add_u32 s100, s100, 1
	s_add_u32 s19, s19, 24576
	s_cmp_eq_u32 s19, 73728
	s_cselect_b32 s19, 0, s19
	s_add_u32 s98, s98, 24576
	s_cmp_eq_u32 s98, 73728
	s_cselect_b32 s98, 0, s98
	v_mfma_f32_16x16x32_bf16 v[112:115], v[128:131], v[172:175], v[112:115]
	v_mfma_f32_16x16x32_bf16 v[116:119], v[132:135], v[172:175], v[116:119]
	v_mfma_f32_16x16x32_bf16 v[120:123], v[136:139], v[172:175], v[120:123]
	v_mfma_f32_16x16x32_bf16 v[124:127], v[140:143], v[172:175], v[124:127]
	ds_read_b128 v[220:223], v232 offset:7168
	s_waitcnt vmcnt(6)
	s_waitcnt lgkmcnt(0)
	s_barrier
	v_add_u32_e32 v232, s98, v230
	v_add_u32_e32 v233, s98, v231
	v_mfma_f32_16x16x32_bf16 v[0:3], v[176:179], v[192:195], v[0:3]
	v_mfma_f32_16x16x32_bf16 v[4:7], v[180:183], v[192:195], v[4:7]
	v_mfma_f32_16x16x32_bf16 v[8:11], v[184:187], v[192:195], v[8:11]
	v_mfma_f32_16x16x32_bf16 v[12:15], v[188:191], v[192:195], v[12:15]
	ds_read_b128 v[128:131], v233 offset:0
	ds_read_b128 v[132:135], v233 offset:1024
	v_mfma_f32_16x16x32_bf16 v[16:19], v[176:179], v[196:199], v[16:19]
	v_mfma_f32_16x16x32_bf16 v[20:23], v[180:183], v[196:199], v[20:23]
	v_mfma_f32_16x16x32_bf16 v[24:27], v[184:187], v[196:199], v[24:27]
	v_mfma_f32_16x16x32_bf16 v[28:31], v[188:191], v[196:199], v[28:31]
	ds_read_b128 v[136:139], v233 offset:2048
	ds_read_b128 v[140:143], v233 offset:3072
	v_mfma_f32_16x16x32_bf16 v[32:35], v[176:179], v[200:203], v[32:35]
	v_mfma_f32_16x16x32_bf16 v[36:39], v[180:183], v[200:203], v[36:39]
	v_mfma_f32_16x16x32_bf16 v[40:43], v[184:187], v[200:203], v[40:43]
	v_mfma_f32_16x16x32_bf16 v[44:47], v[188:191], v[200:203], v[44:47]
	ds_read_b128 v[144:147], v232 offset:0
	ds_read_b128 v[148:151], v232 offset:1024
	v_mfma_f32_16x16x32_bf16 v[48:51], v[176:179], v[204:207], v[48:51]
	v_mfma_f32_16x16x32_bf16 v[52:55], v[180:183], v[204:207], v[52:55]
	v_mfma_f32_16x16x32_bf16 v[56:59], v[184:187], v[204:207], v[56:59]
	v_mfma_f32_16x16x32_bf16 v[60:63], v[188:191], v[204:207], v[60:63]
	ds_read_b128 v[152:155], v232 offset:2048
	ds_read_b128 v[156:159], v232 offset:3072
	v_mfma_f32_16x16x32_bf16 v[64:67], v[176:179], v[208:211], v[64:67]
	v_mfma_f32_16x16x32_bf16 v[68:71], v[180:183], v[208:211], v[68:71]
	v_mfma_f32_16x16x32_bf16 v[72:75], v[184:187], v[208:211], v[72:75]
	v_mfma_f32_16x16x32_bf16 v[76:79], v[188:191], v[208:211], v[76:79]
	ds_read_b128 v[160:163], v232 offset:4096
	v_mfma_f32_16x16x32_bf16 v[80:83], v[176:179], v[212:215], v[80:83]
	v_mfma_f32_16x16x32_bf16 v[84:87], v[180:183], v[212:215], v[84:87]
	v_mfma_f32_16x16x32_bf16 v[88:91], v[184:187], v[212:215], v[88:91]
	v_mfma_f32_16x16x32_bf16 v[92:95], v[188:191], v[212:215], v[92:95]
	ds_read_b128 v[164:167], v232 offset:5120
	v_mfma_f32_16x16x32_bf16 v[96:99], v[176:179], v[216:219], v[96:99]
	v_mfma_f32_16x16x32_bf16 v[100:103], v[180:183], v[216:219], v[100:103]
	v_mfma_f32_16x16x32_bf16 v[104:107], v[184:187], v[216:219], v[104:107]
	v_mfma_f32_16x16x32_bf16 v[108:111], v[188:191], v[216:219], v[108:111]
	ds_read_b128 v[168:171], v232 offset:6144
	s_add_u32 s98, s98, 24576
	s_cmp_eq_u32 s98, 73728
	s_cselect_b32 s98, 0, s98
	v_mfma_f32_16x16x32_bf16 v[112:115], v[176:179], v[220:223], v[112:115]
	v_mfma_f32_16x16x32_bf16 v[116:119], v[180:183], v[220:223], v[116:119]
	v_mfma_f32_16x16x32_bf16 v[120:123], v[184:187], v[220:223], v[120:123]
	v_mfma_f32_16x16x32_bf16 v[124:127], v[188:191], v[220:223], v[124:127]
	ds_read_b128 v[172:175], v232 offset:7168
	s_waitcnt vmcnt(0)
	s_waitcnt lgkmcnt(0)
	s_barrier
; #define LWRITE(S, buf) do { bf16_t* sA_ = sbase + (buf) * BUF; bf16_t* sB_ = sA_ + 256 * PITCH; \
;     _Pragma("unroll") for (int i_ = 0; i_ < 4; ++i_) *(u32x4*)(sA_ + (sr + i_ * 64) * PITCH + scv * 8) = ra[S][i_]; \
;     _Pragma("unroll") for (int i_ = 0; i_ < 2; ++i_) *(u32x4*)(sB_ + (sr + i_ * 64) * PITCH + scv * 8) = rb[S][i_]; } while (0)
; template <class Epi>
; DI void gemm_tile(char* smem, const bf16_t* __restrict__ A0, int lda0, int ksplit, const bf16_t* __restrict__ A1, int lda1,
;                   const bf16_t* __restrict__ Bt, int K, int row0, int col0, const Epi& epi, int tid) {
;     ...
;   __syncthreads();
;   {
;     const int last = nk - 1;
;     GLOAD(0, 0);
;     __builtin_amdgcn_sched_barrier(0);
;     GLOAD(1, 1);
;     __builtin_amdgcn_sched_barrier(0);
;     LWRITE(0, 0);
;     __builtin_amdgcn_sched_barrier(0);
;     GLOAD(0, (2 < last ? 2 : last));
;     __builtin_amdgcn_sched_barrier(0);
;     __syncthreads();
;     for (int kt = 0; kt < nk; kt += 2) {
;       LWRITE(1, 1);
;       __builtin_amdgcn_sched_barrier(0);
;       GLOAD(1, (kt + 3 < last ? kt + 3 : last));
;       __builtin_amdgcn_sched_barrier(0);
;       COMPUTE(0);
;       __syncthreads();
;       LWRITE(0, 0);
;       __builtin_amdgcn_sched_barrier(0);
;       GLOAD(0, (kt + 4 < last ? kt + 4 : last));
;       __builtin_amdgcn_sched_barrier(0);
;       COMPUTE(1);
;       __syncthreads();
	v_add_u32_e32 v232, s98, v230
	v_add_u32_e32 v233, s98, v231
	v_mfma_f32_16x16x32_bf16 v[0:3], v[128:131], v[144:147], v[0:3]
	v_mfma_f32_16x16x32_bf16 v[4:7], v[132:135], v[144:147], v[4:7]
	v_mfma_f32_16x16x32_bf16 v[8:11], v[136:139], v[144:147], v[8:11]
	v_mfma_f32_16x16x32_bf16 v[12:15], v[140:143], v[144:147], v[12:15]
	ds_read_b128 v[176:179], v233 offset:0
	ds_read_b128 v[180:183], v233 offset:1024
	v_mfma_f32_16x16x32_bf16 v[16:19], v[128:131], v[148:151], v[16:19]
	v_mfma_f32_16x16x32_bf16 v[20:23], v[132:135], v[148:151], v[20:23]
	v_mfma_f32_16x16x32_bf16 v[24:27], v[136:139], v[148:151], v[24:27]
	v_mfma_f32_16x16x32_bf16 v[28:31], v[140:143], v[148:151], v[28:31]
	ds_read_b128 v[184:187], v233 offset:2048
	ds_read_b128 v[188:191], v233 offset:3072
	v_mfma_f32_16x16x32_bf16 v[32:35], v[128:131], v[152:155], v[32:35]
	v_mfma_f32_16x16x32_bf16 v[36:39], v[132:135], v[152:155], v[36:39]
	v_mfma_f32_16x16x32_bf16 v[40:43], v[136:139], v[152:155], v[40:43]
	v_mfma_f32_16x16x32_bf16 v[44:47], v[140:143], v[152:155], v[44:47]
	ds_read_b128 v[192:195], v232 offset:0
	ds_read_b128 v[196:199], v232 offset:1024
	v_mfma_f32_16x16x32_bf16 v[48:51], v[128:131], v[156:159], v[48:51]
	v_mfma_f32_16x16x32_bf16 v[52:55], v[132:135], v[156:159], v[52:55]
	v_mfma_f32_16x16x32_bf16 v[56:59], v[136:139], v[156:159], v[56:59]
	v_mfma_f32_16x16x32_bf16 v[60:63], v[140:143], v[156:159], v[60:63]
	ds_read_b128 v[200:203], v232 offset:2048
	ds_read_b128 v[204:207], v232 offset:3072
	v_mfma_f32_16x16x32_bf16 v[64:67], v[128:131], v[160:163], v[64:67]
	v_mfma_f32_16x16x32_bf16 v[68:71], v[132:135], v[160:163], v[68:71]
	v_mfma_f32_16x16x32_bf16 v[72:75], v[136:139], v[160:163], v[72:75]
	v_mfma_f32_16x16x32_bf16 v[76:79], v[140:143], v[160:163], v[76:79]
	ds_read_b128 v[208:211], v232 offset:4096
	v_mfma_f32_16x16x32_bf16 v[80:83], v[128:131], v[164:167], v[80:83]
	v_mfma_f32_16x16x32_bf16 v[84:87], v[132:135], v[164:167], v[84:87]
	v_mfma_f32_16x16x32_bf16 v[88:91], v[136:139], v[164:167], v[88:91]
	v_mfma_f32_16x16x32_bf16 v[92:95], v[140:143], v[164:167], v[92:95]
	ds_read_b128 v[212:215], v232 offset:5120
	v_mfma_f32_16x16x32_bf16 v[96:99], v[128:131], v[168:171], v[96:99]
	v_mfma_f32_16x16x32_bf16 v[100:103], v[132:135], v[168:171], v[100:103]
	v_mfma_f32_16x16x32_bf16 v[104:107], v[136:139], v[168:171], v[104:107]
	v_mfma_f32_16x16x32_bf16 v[108:111], v[140:143], v[168:171], v[108:111]
	ds_read_b128 v[216:219], v232 offset:6144
	s_add_u32 s98, s98, 24576
	s_cmp_eq_u32 s98, 73728
	s_cselect_b32 s98, 0, s98
	v_mfma_f32_16x16x32_bf16 v[112:115], v[128:131], v[172:175], v[112:115]
	v_mfma_f32_16x16x32_bf16 v[116:119], v[132:135], v[172:175], v[116:119]
	v_mfma_f32_16x16x32_bf16 v[120:123], v[136:139], v[172:175], v[120:123]
	v_mfma_f32_16x16x32_bf16 v[124:127], v[140:143], v[172:175], v[124:127]
	ds_read_b128 v[220:223], v232 offset:7168
	s_waitcnt lgkmcnt(0)
	s_barrier
	v_mfma_f32_16x16x32_bf16 v[0:3], v[176:179], v[192:195], v[0:3]
	v_mfma_f32_16x16x32_bf16 v[4:7], v[180:183], v[192:195], v[4:7]
	v_mfma_f32_16x16x32_bf16 v[8:11], v[184:187], v[192:195], v[8:11]
	v_mfma_f32_16x16x32_bf16 v[12:15], v[188:191], v[192:195], v[12:15]
	v_mfma_f32_16x16x32_bf16 v[16:19], v[176:179], v[196:199], v[16:19]
	v_mfma_f32_16x16x32_bf16 v[20:23], v[180:183], v[196:199], v[20:23]
	v_mfma_f32_16x16x32_bf16 v[24:27], v[184:187], v[196:199], v[24:27]
	v_mfma_f32_16x16x32_bf16 v[28:31], v[188:191], v[196:199], v[28:31]
	v_mfma_f32_16x16x32_bf16 v[32:35], v[176:179], v[200:203], v[32:35]
	v_mfma_f32_16x16x32_bf16 v[36:39], v[180:183], v[200:203], v[36:39]
	v_mfma_f32_16x16x32_bf16 v[40:43], v[184:187], v[200:203], v[40:43]
	v_mfma_f32_16x16x32_bf16 v[44:47], v[188:191], v[200:203], v[44:47]
	v_mfma_f32_16x16x32_bf16 v[48:51], v[176:179], v[204:207], v[48:51]
	v_mfma_f32_16x16x32_bf16 v[52:55], v[180:183], v[204:207], v[52:55]
	v_mfma_f32_16x16x32_bf16 v[56:59], v[184:187], v[204:207], v[56:59]
	v_mfma_f32_16x16x32_bf16 v[60:63], v[188:191], v[204:207], v[60:63]
	v_mfma_f32_16x16x32_bf16 v[64:67], v[176:179], v[208:211], v[64:67]
	v_mfma_f32_16x16x32_bf16 v[68:71], v[180:183], v[208:211], v[68:71]
	v_mfma_f32_16x16x32_bf16 v[72:75], v[184:187], v[208:211], v[72:75]
	v_mfma_f32_16x16x32_bf16 v[76:79], v[188:191], v[208:211], v[76:79]
	v_mfma_f32_16x16x32_bf16 v[80:83], v[176:179], v[212:215], v[80:83]
	v_mfma_f32_16x16x32_bf16 v[84:87], v[180:183], v[212:215], v[84:87]
	v_mfma_f32_16x16x32_bf16 v[88:91], v[184:187], v[212:215], v[88:91]
	v_mfma_f32_16x16x32_bf16 v[92:95], v[188:191], v[212:215], v[92:95]
	v_mfma_f32_16x16x32_bf16 v[96:99], v[176:179], v[216:219], v[96:99]
	v_mfma_f32_16x16x32_bf16 v[100:103], v[180:183], v[216:219], v[100:103]
	v_mfma_f32_16x16x32_bf16 v[104:107], v[184:187], v[216:219], v[104:107]
	v_mfma_f32_16x16x32_bf16 v[108:111], v[188:191], v[216:219], v[108:111]
	v_mfma_f32_16x16x32_bf16 v[112:115], v[176:179], v[220:223], v[112:115]
	v_mfma_f32_16x16x32_bf16 v[116:119], v[180:183], v[220:223], v[116:119]
	v_mfma_f32_16x16x32_bf16 v[120:123], v[184:187], v[220:223], v[120:123]
	v_mfma_f32_16x16x32_bf16 v[124:127], v[188:191], v[220:223], v[124:127]
	s_branch .Lg14_epi
; template <class Epi>
; DI void gemm_tile(char* smem, const bf16_t* __restrict__ A0, int lda0, int ksplit, const bf16_t* __restrict__ A1, int lda1,
;                   const bf16_t* __restrict__ Bt, int K, int row0, int col0, const Epi& epi, int tid) {
;     ...
; #pragma unroll
;   for (int m = 0; m < 8; ++m)
; #pragma unroll
;     for (int n = 0; n < 4; ++n) epi(row0 + wr * 128 + m * 16 + fr, col0 + wc * 64 + n * 16 + fq * 4, acc[m][n]);
.Lg14_epi:
	s_nop 7
	s_nop 7
	s_lshl_b32 s12, s18, 10
	s_lshl_b32 s11, s13, 1
	s_add_u32 s12, s12, s11
	s_add_u32 s12, s12, 0x11a00000
	s_add_u32 s4, s92, s12
	s_addc_u32 s5, s93, 0
	s_lshl_b32 s12, s18, 10
	s_lshl_b32 s11, s13, 1
	s_add_u32 s12, s12, s11
	s_add_u32 s12, s12, 0x1da00000
	s_add_u32 s0, s92, s12
	s_addc_u32 s1, s93, 0
	s_lshl_b32 s12, s13, 2
	s_add_u32 s2, s6, s12
	s_addc_u32 s3, s7, 0
	global_load_dwordx4 v[192:195], v234, s[2:3]
	ds_write_b128 v245, v[0:3]
	ds_write_b128 v245, v[4:7] offset:64
	ds_write_b128 v245, v[8:11] offset:128
	ds_write_b128 v245, v[12:15] offset:192
	ds_write_b128 v245, v[16:19] offset:4352
	ds_write_b128 v245, v[20:23] offset:4416
	ds_write_b128 v245, v[24:27] offset:4480
	ds_write_b128 v245, v[28:31] offset:4544
	ds_write_b128 v245, v[32:35] offset:8704
	ds_write_b128 v245, v[36:39] offset:8768
	ds_write_b128 v245, v[40:43] offset:8832
	ds_write_b128 v245, v[44:47] offset:8896
	ds_write_b128 v245, v[48:51] offset:13056
	ds_write_b128 v245, v[52:55] offset:13120
	ds_write_b128 v245, v[56:59] offset:13184
	ds_write_b128 v245, v[60:63] offset:13248
	global_load_dwordx2 v[128:129], v235, s[0:1]
	s_add_u32 s0, s0, 0x1000
	s_addc_u32 s1, s1, 0
	global_load_dwordx2 v[130:131], v235, s[0:1]
	s_add_u32 s0, s0, 0x1000
	s_addc_u32 s1, s1, 0
	global_load_dwordx2 v[132:133], v235, s[0:1]
	s_add_u32 s0, s0, 0x1000
	s_addc_u32 s1, s1, 0
	global_load_dwordx2 v[134:135], v235, s[0:1]
	s_add_u32 s0, s0, 0x1000
	s_addc_u32 s1, s1, 0
	global_load_dwordx2 v[136:137], v235, s[0:1]
	s_add_u32 s0, s0, 0x1000
	s_addc_u32 s1, s1, 0
	global_load_dwordx2 v[138:139], v235, s[0:1]
	s_add_u32 s0, s0, 0x1000
	s_addc_u32 s1, s1, 0
	global_load_dwordx2 v[140:141], v235, s[0:1]
	s_add_u32 s0, s0, 0x1000
	s_addc_u32 s1, s1, 0
	global_load_dwordx2 v[142:143], v235, s[0:1]
	s_add_u32 s0, s0, 0x1000
	s_addc_u32 s1, s1, 0
	s_waitcnt lgkmcnt(0)
	ds_read_b128 v[160:163], v246
	ds_read_b128 v[164:167], v246 offset:1088
	ds_read_b128 v[168:171], v246 offset:2176
	ds_read_b128 v[172:175], v246 offset:3264
	ds_read_b128 v[176:179], v246 offset:4352
	ds_read_b128 v[180:183], v246 offset:5440
	ds_read_b128 v[184:187], v246 offset:6528
	ds_read_b128 v[188:191], v246 offset:7616
	s_waitcnt vmcnt(7) lgkmcnt(7)
	v_add_f32_e32 v160, v160, v192
	v_add_f32_e32 v161, v161, v193
	v_add_f32_e32 v162, v162, v194
	v_add_f32_e32 v163, v163, v195
	v_mul_f32_e32 v160, 0xbfb8aa3b, v160
	v_mul_f32_e32 v161, 0xbfb8aa3b, v161
	v_mul_f32_e32 v162, 0xbfb8aa3b, v162
	v_mul_f32_e32 v163, 0xbfb8aa3b, v163
	v_exp_f32_e32 v160, v160
	v_exp_f32_e32 v161, v161
	v_exp_f32_e32 v162, v162
	v_exp_f32_e32 v163, v163
	v_lshlrev_b32_e32 v144, 16, v128
	v_and_b32_e32 v145, 0xffff0000, v128
	v_lshlrev_b32_e32 v146, 16, v129
	v_and_b32_e32 v147, 0xffff0000, v129
	v_add_f32_e32 v160, 1.0, v160
	v_add_f32_e32 v161, 1.0, v161
	v_add_f32_e32 v162, 1.0, v162
	v_add_f32_e32 v163, 1.0, v163
	v_rcp_f32_e32 v160, v160
	v_rcp_f32_e32 v161, v161
	v_rcp_f32_e32 v162, v162
	v_rcp_f32_e32 v163, v163
	s_nop 0
	v_mul_f32_e32 v160, v144, v160
	v_mul_f32_e32 v161, v145, v161
	v_mul_f32_e32 v162, v146, v162
	v_mul_f32_e32 v163, v147, v163
	v_cvt_pk_bf16_f32 v128, v160, v161
	v_cvt_pk_bf16_f32 v129, v162, v163
	global_store_dwordx2 v235, v[128:129], s[4:5]
	s_add_u32 s4, s4, 0x1000
	s_addc_u32 s5, s5, 0
	s_waitcnt vmcnt(7) lgkmcnt(6)
	v_add_f32_e32 v164, v164, v192
	v_add_f32_e32 v165, v165, v193
	v_add_f32_e32 v166, v166, v194
	v_add_f32_e32 v167, v167, v195
	v_mul_f32_e32 v164, 0xbfb8aa3b, v164
	v_mul_f32_e32 v165, 0xbfb8aa3b, v165
	v_mul_f32_e32 v166, 0xbfb8aa3b, v166
	v_mul_f32_e32 v167, 0xbfb8aa3b, v167
	v_exp_f32_e32 v164, v164
	v_exp_f32_e32 v165, v165
	v_exp_f32_e32 v166, v166
	v_exp_f32_e32 v167, v167
	v_lshlrev_b32_e32 v148, 16, v130
	v_and_b32_e32 v149, 0xffff0000, v130
	v_lshlrev_b32_e32 v150, 16, v131
	v_and_b32_e32 v151, 0xffff0000, v131
	v_add_f32_e32 v164, 1.0, v164
	v_add_f32_e32 v165, 1.0, v165
	v_add_f32_e32 v166, 1.0, v166
	v_add_f32_e32 v167, 1.0, v167
	v_rcp_f32_e32 v164, v164
	v_rcp_f32_e32 v165, v165
	v_rcp_f32_e32 v166, v166
	v_rcp_f32_e32 v167, v167
	s_nop 0
	v_mul_f32_e32 v164, v148, v164
	v_mul_f32_e32 v165, v149, v165
	v_mul_f32_e32 v166, v150, v166
	v_mul_f32_e32 v167, v151, v167
	v_cvt_pk_bf16_f32 v130, v164, v165
	v_cvt_pk_bf16_f32 v131, v166, v167
	global_store_dwordx2 v235, v[130:131], s[4:5]
	s_add_u32 s4, s4, 0x1000
	s_addc_u32 s5, s5, 0
	s_waitcnt vmcnt(7) lgkmcnt(5)
	v_add_f32_e32 v168, v168, v192
	v_add_f32_e32 v169, v169, v193
	v_add_f32_e32 v170, v170, v194
	v_add_f32_e32 v171, v171, v195
	v_mul_f32_e32 v168, 0xbfb8aa3b, v168
	v_mul_f32_e32 v169, 0xbfb8aa3b, v169
	v_mul_f32_e32 v170, 0xbfb8aa3b, v170
	v_mul_f32_e32 v171, 0xbfb8aa3b, v171
	v_exp_f32_e32 v168, v168
	v_exp_f32_e32 v169, v169
	v_exp_f32_e32 v170, v170
	v_exp_f32_e32 v171, v171
	v_lshlrev_b32_e32 v144, 16, v132
	v_and_b32_e32 v145, 0xffff0000, v132
	v_lshlrev_b32_e32 v146, 16, v133
	v_and_b32_e32 v147, 0xffff0000, v133
	v_add_f32_e32 v168, 1.0, v168
	v_add_f32_e32 v169, 1.0, v169
	v_add_f32_e32 v170, 1.0, v170
	v_add_f32_e32 v171, 1.0, v171
	v_rcp_f32_e32 v168, v168
	v_rcp_f32_e32 v169, v169
	v_rcp_f32_e32 v170, v170
	v_rcp_f32_e32 v171, v171
	s_nop 0
	v_mul_f32_e32 v168, v144, v168
	v_mul_f32_e32 v169, v145, v169
	v_mul_f32_e32 v170, v146, v170
	v_mul_f32_e32 v171, v147, v171
	v_cvt_pk_bf16_f32 v132, v168, v169
	v_cvt_pk_bf16_f32 v133, v170, v171
	global_store_dwordx2 v235, v[132:133], s[4:5]
	s_add_u32 s4, s4, 0x1000
	s_addc_u32 s5, s5, 0
	s_waitcnt vmcnt(7) lgkmcnt(4)
; template <class Epi>
; DI void gemm_tile(char* smem, const bf16_t* __restrict__ A0, int lda0, int ksplit, const bf16_t* __restrict__ A1, int lda1,
;                   const bf16_t* __restrict__ Bt, int K, int row0, int col0, const Epi& epi, int tid) {
;     ...
; #pragma unroll
;   for (int m = 0; m < 8; ++m)
; #pragma unroll
;     for (int n = 0; n < 4; ++n) epi(row0 + wr * 128 + m * 16 + fr, col0 + wc * 64 + n * 16 + fq * 4, acc[m][n]);
	v_add_f32_e32 v172, v172, v192
	v_add_f32_e32 v173, v173, v193
	v_add_f32_e32 v174, v174, v194
	v_add_f32_e32 v175, v175, v195
	v_mul_f32_e32 v172, 0xbfb8aa3b, v172
	v_mul_f32_e32 v173, 0xbfb8aa3b, v173
	v_mul_f32_e32 v174, 0xbfb8aa3b, v174
	v_mul_f32_e32 v175, 0xbfb8aa3b, v175
	v_exp_f32_e32 v172, v172
	v_exp_f32_e32 v173, v173
	v_exp_f32_e32 v174, v174
	v_exp_f32_e32 v175, v175
	v_lshlrev_b32_e32 v148, 16, v134
	v_and_b32_e32 v149, 0xffff0000, v134
	v_lshlrev_b32_e32 v150, 16, v135
	v_and_b32_e32 v151, 0xffff0000, v135
	v_add_f32_e32 v172, 1.0, v172
	v_add_f32_e32 v173, 1.0, v173
	v_add_f32_e32 v174, 1.0, v174
	v_add_f32_e32 v175, 1.0, v175
	v_rcp_f32_e32 v172, v172
	v_rcp_f32_e32 v173, v173
	v_rcp_f32_e32 v174, v174
	v_rcp_f32_e32 v175, v175
	s_nop 0
	v_mul_f32_e32 v172, v148, v172
	v_mul_f32_e32 v173, v149, v173
	v_mul_f32_e32 v174, v150, v174
	v_mul_f32_e32 v175, v151, v175
	v_cvt_pk_bf16_f32 v134, v172, v173
	v_cvt_pk_bf16_f32 v135, v174, v175
	global_store_dwordx2 v235, v[134:135], s[4:5]
	s_add_u32 s4, s4, 0x1000
	s_addc_u32 s5, s5, 0
	s_waitcnt vmcnt(7) lgkmcnt(3)
	v_add_f32_e32 v176, v176, v192
	v_add_f32_e32 v177, v177, v193
	v_add_f32_e32 v178, v178, v194
	v_add_f32_e32 v179, v179, v195
	v_mul_f32_e32 v176, 0xbfb8aa3b, v176
	v_mul_f32_e32 v177, 0xbfb8aa3b, v177
	v_mul_f32_e32 v178, 0xbfb8aa3b, v178
	v_mul_f32_e32 v179, 0xbfb8aa3b, v179
	v_exp_f32_e32 v176, v176
	v_exp_f32_e32 v177, v177
	v_exp_f32_e32 v178, v178
	v_exp_f32_e32 v179, v179
	v_lshlrev_b32_e32 v144, 16, v136
	v_and_b32_e32 v145, 0xffff0000, v136
	v_lshlrev_b32_e32 v146, 16, v137
	v_and_b32_e32 v147, 0xffff0000, v137
	v_add_f32_e32 v176, 1.0, v176
	v_add_f32_e32 v177, 1.0, v177
	v_add_f32_e32 v178, 1.0, v178
	v_add_f32_e32 v179, 1.0, v179
	v_rcp_f32_e32 v176, v176
	v_rcp_f32_e32 v177, v177
	v_rcp_f32_e32 v178, v178
	v_rcp_f32_e32 v179, v179
	s_nop 0
	v_mul_f32_e32 v176, v144, v176
	v_mul_f32_e32 v177, v145, v177
	v_mul_f32_e32 v178, v146, v178
	v_mul_f32_e32 v179, v147, v179
	v_cvt_pk_bf16_f32 v136, v176, v177
	v_cvt_pk_bf16_f32 v137, v178, v179
	global_store_dwordx2 v235, v[136:137], s[4:5]
	s_add_u32 s4, s4, 0x1000
	s_addc_u32 s5, s5, 0
	s_waitcnt vmcnt(7) lgkmcnt(2)
	v_add_f32_e32 v180, v180, v192
	v_add_f32_e32 v181, v181, v193
	v_add_f32_e32 v182, v182, v194
	v_add_f32_e32 v183, v183, v195
	v_mul_f32_e32 v180, 0xbfb8aa3b, v180
	v_mul_f32_e32 v181, 0xbfb8aa3b, v181
	v_mul_f32_e32 v182, 0xbfb8aa3b, v182
	v_mul_f32_e32 v183, 0xbfb8aa3b, v183
	v_exp_f32_e32 v180, v180
	v_exp_f32_e32 v181, v181
	v_exp_f32_e32 v182, v182
	v_exp_f32_e32 v183, v183
	v_lshlrev_b32_e32 v148, 16, v138
	v_and_b32_e32 v149, 0xffff0000, v138
	v_lshlrev_b32_e32 v150, 16, v139
	v_and_b32_e32 v151, 0xffff0000, v139
	v_add_f32_e32 v180, 1.0, v180
	v_add_f32_e32 v181, 1.0, v181
	v_add_f32_e32 v182, 1.0, v182
	v_add_f32_e32 v183, 1.0, v183
	v_rcp_f32_e32 v180, v180
	v_rcp_f32_e32 v181, v181
	v_rcp_f32_e32 v182, v182
	v_rcp_f32_e32 v183, v183
	s_nop 0
	v_mul_f32_e32 v180, v148, v180
	v_mul_f32_e32 v181, v149, v181
	v_mul_f32_e32 v182, v150, v182
	v_mul_f32_e32 v183, v151, v183
	v_cvt_pk_bf16_f32 v138, v180, v181
	v_cvt_pk_bf16_f32 v139, v182, v183
	global_store_dwordx2 v235, v[138:139], s[4:5]
	s_add_u32 s4, s4, 0x1000
	s_addc_u32 s5, s5, 0
	s_waitcnt vmcnt(7) lgkmcnt(1)
	v_add_f32_e32 v184, v184, v192
	v_add_f32_e32 v185, v185, v193
	v_add_f32_e32 v186, v186, v194
	v_add_f32_e32 v187, v187, v195
	v_mul_f32_e32 v184, 0xbfb8aa3b, v184
	v_mul_f32_e32 v185, 0xbfb8aa3b, v185
	v_mul_f32_e32 v186, 0xbfb8aa3b, v186
	v_mul_f32_e32 v187, 0xbfb8aa3b, v187
	v_exp_f32_e32 v184, v184
	v_exp_f32_e32 v185, v185
	v_exp_f32_e32 v186, v186
	v_exp_f32_e32 v187, v187
	v_lshlrev_b32_e32 v144, 16, v140
	v_and_b32_e32 v145, 0xffff0000, v140
	v_lshlrev_b32_e32 v146, 16, v141
	v_and_b32_e32 v147, 0xffff0000, v141
	v_add_f32_e32 v184, 1.0, v184
	v_add_f32_e32 v185, 1.0, v185
	v_add_f32_e32 v186, 1.0, v186
	v_add_f32_e32 v187, 1.0, v187
	v_rcp_f32_e32 v184, v184
	v_rcp_f32_e32 v185, v185
	v_rcp_f32_e32 v186, v186
	v_rcp_f32_e32 v187, v187
	s_nop 0
	v_mul_f32_e32 v184, v144, v184
	v_mul_f32_e32 v185, v145, v185
	v_mul_f32_e32 v186, v146, v186
	v_mul_f32_e32 v187, v147, v187
	v_cvt_pk_bf16_f32 v140, v184, v185
	v_cvt_pk_bf16_f32 v141, v186, v187
	global_store_dwordx2 v235, v[140:141], s[4:5]
	s_add_u32 s4, s4, 0x1000
	s_addc_u32 s5, s5, 0
	s_waitcnt vmcnt(7) lgkmcnt(0)
	v_add_f32_e32 v188, v188, v192
	v_add_f32_e32 v189, v189, v193
	v_add_f32_e32 v190, v190, v194
	v_add_f32_e32 v191, v191, v195
	v_mul_f32_e32 v188, 0xbfb8aa3b, v188
	v_mul_f32_e32 v189, 0xbfb8aa3b, v189
	v_mul_f32_e32 v190, 0xbfb8aa3b, v190
	v_mul_f32_e32 v191, 0xbfb8aa3b, v191
	v_exp_f32_e32 v188, v188
	v_exp_f32_e32 v189, v189
	v_exp_f32_e32 v190, v190
	v_exp_f32_e32 v191, v191
	v_lshlrev_b32_e32 v148, 16, v142
	v_and_b32_e32 v149, 0xffff0000, v142
	v_lshlrev_b32_e32 v150, 16, v143
	v_and_b32_e32 v151, 0xffff0000, v143
	v_add_f32_e32 v188, 1.0, v188
	v_add_f32_e32 v189, 1.0, v189
	v_add_f32_e32 v190, 1.0, v190
	v_add_f32_e32 v191, 1.0, v191
	v_rcp_f32_e32 v188, v188
	v_rcp_f32_e32 v189, v189
	v_rcp_f32_e32 v190, v190
	v_rcp_f32_e32 v191, v191
	s_nop 0
	v_mul_f32_e32 v188, v148, v188
	v_mul_f32_e32 v189, v149, v189
	v_mul_f32_e32 v190, v150, v190
	v_mul_f32_e32 v191, v151, v191
	v_cvt_pk_bf16_f32 v142, v188, v189
	v_cvt_pk_bf16_f32 v143, v190, v191
	global_store_dwordx2 v235, v[142:143], s[4:5]
	s_add_u32 s4, s4, 0x1000
	s_addc_u32 s5, s5, 0
	s_nop 1
	global_load_dwordx2 v[128:129], v235, s[0:1]
	s_add_u32 s0, s0, 0x1000
	s_addc_u32 s1, s1, 0
	global_load_dwordx2 v[130:131], v235, s[0:1]
	s_add_u32 s0, s0, 0x1000
	s_addc_u32 s1, s1, 0
	global_load_dwordx2 v[132:133], v235, s[0:1]
	s_add_u32 s0, s0, 0x1000
	s_addc_u32 s1, s1, 0
	global_load_dwordx2 v[134:135], v235, s[0:1]
	s_add_u32 s0, s0, 0x1000
	s_addc_u32 s1, s1, 0
	global_load_dwordx2 v[136:137], v235, s[0:1]
	s_add_u32 s0, s0, 0x1000
	s_addc_u32 s1, s1, 0
	global_load_dwordx2 v[138:139], v235, s[0:1]
	s_add_u32 s0, s0, 0x1000
	s_addc_u32 s1, s1, 0
	global_load_dwordx2 v[140:141], v235, s[0:1]
	s_add_u32 s0, s0, 0x1000
	s_addc_u32 s1, s1, 0
	global_load_dwordx2 v[142:143], v235, s[0:1]
	s_add_u32 s0, s0, 0x1000
	s_addc_u32 s1, s1, 0
	ds_read_b128 v[160:163], v246 offset:8704
	ds_read_b128 v[164:167], v246 offset:9792
	ds_read_b128 v[168:171], v246 offset:10880
	ds_read_b128 v[172:175], v246 offset:11968
	ds_read_b128 v[176:179], v246 offset:13056
	ds_read_b128 v[180:183], v246 offset:14144
	ds_read_b128 v[184:187], v246 offset:15232
	ds_read_b128 v[188:191], v246 offset:16320
	s_waitcnt vmcnt(7) lgkmcnt(7)
; template <class Epi>
; DI void gemm_tile(char* smem, const bf16_t* __restrict__ A0, int lda0, int ksplit, const bf16_t* __restrict__ A1, int lda1,
;                   const bf16_t* __restrict__ Bt, int K, int row0, int col0, const Epi& epi, int tid) {
;     ...
; #pragma unroll
;   for (int m = 0; m < 8; ++m)
; #pragma unroll
;     for (int n = 0; n < 4; ++n) epi(row0 + wr * 128 + m * 16 + fr, col0 + wc * 64 + n * 16 + fq * 4, acc[m][n]);
	v_add_f32_e32 v160, v160, v192
	v_add_f32_e32 v161, v161, v193
	v_add_f32_e32 v162, v162, v194
	v_add_f32_e32 v163, v163, v195
	v_mul_f32_e32 v160, 0xbfb8aa3b, v160
	v_mul_f32_e32 v161, 0xbfb8aa3b, v161
	v_mul_f32_e32 v162, 0xbfb8aa3b, v162
	v_mul_f32_e32 v163, 0xbfb8aa3b, v163
	v_exp_f32_e32 v160, v160
	v_exp_f32_e32 v161, v161
	v_exp_f32_e32 v162, v162
	v_exp_f32_e32 v163, v163
	v_lshlrev_b32_e32 v144, 16, v128
	v_and_b32_e32 v145, 0xffff0000, v128
	v_lshlrev_b32_e32 v146, 16, v129
	v_and_b32_e32 v147, 0xffff0000, v129
	v_add_f32_e32 v160, 1.0, v160
	v_add_f32_e32 v161, 1.0, v161
	v_add_f32_e32 v162, 1.0, v162
	v_add_f32_e32 v163, 1.0, v163
	v_rcp_f32_e32 v160, v160
	v_rcp_f32_e32 v161, v161
	v_rcp_f32_e32 v162, v162
	v_rcp_f32_e32 v163, v163
	s_nop 0
	v_mul_f32_e32 v160, v144, v160
	v_mul_f32_e32 v161, v145, v161
	v_mul_f32_e32 v162, v146, v162
	v_mul_f32_e32 v163, v147, v163
	v_cvt_pk_bf16_f32 v128, v160, v161
	v_cvt_pk_bf16_f32 v129, v162, v163
	global_store_dwordx2 v235, v[128:129], s[4:5]
	s_add_u32 s4, s4, 0x1000
	s_addc_u32 s5, s5, 0
	s_waitcnt vmcnt(7) lgkmcnt(6)
	v_add_f32_e32 v164, v164, v192
	v_add_f32_e32 v165, v165, v193
	v_add_f32_e32 v166, v166, v194
	v_add_f32_e32 v167, v167, v195
	v_mul_f32_e32 v164, 0xbfb8aa3b, v164
	v_mul_f32_e32 v165, 0xbfb8aa3b, v165
	v_mul_f32_e32 v166, 0xbfb8aa3b, v166
	v_mul_f32_e32 v167, 0xbfb8aa3b, v167
	v_exp_f32_e32 v164, v164
	v_exp_f32_e32 v165, v165
	v_exp_f32_e32 v166, v166
	v_exp_f32_e32 v167, v167
	v_lshlrev_b32_e32 v148, 16, v130
	v_and_b32_e32 v149, 0xffff0000, v130
	v_lshlrev_b32_e32 v150, 16, v131
	v_and_b32_e32 v151, 0xffff0000, v131
	v_add_f32_e32 v164, 1.0, v164
	v_add_f32_e32 v165, 1.0, v165
	v_add_f32_e32 v166, 1.0, v166
	v_add_f32_e32 v167, 1.0, v167
	v_rcp_f32_e32 v164, v164
	v_rcp_f32_e32 v165, v165
	v_rcp_f32_e32 v166, v166
	v_rcp_f32_e32 v167, v167
	s_nop 0
	v_mul_f32_e32 v164, v148, v164
	v_mul_f32_e32 v165, v149, v165
	v_mul_f32_e32 v166, v150, v166
	v_mul_f32_e32 v167, v151, v167
	v_cvt_pk_bf16_f32 v130, v164, v165
	v_cvt_pk_bf16_f32 v131, v166, v167
	global_store_dwordx2 v235, v[130:131], s[4:5]
	s_add_u32 s4, s4, 0x1000
	s_addc_u32 s5, s5, 0
	s_waitcnt vmcnt(7) lgkmcnt(5)
	v_add_f32_e32 v168, v168, v192
	v_add_f32_e32 v169, v169, v193
	v_add_f32_e32 v170, v170, v194
	v_add_f32_e32 v171, v171, v195
	v_mul_f32_e32 v168, 0xbfb8aa3b, v168
	v_mul_f32_e32 v169, 0xbfb8aa3b, v169
	v_mul_f32_e32 v170, 0xbfb8aa3b, v170
	v_mul_f32_e32 v171, 0xbfb8aa3b, v171
	v_exp_f32_e32 v168, v168
	v_exp_f32_e32 v169, v169
	v_exp_f32_e32 v170, v170
	v_exp_f32_e32 v171, v171
	v_lshlrev_b32_e32 v144, 16, v132
	v_and_b32_e32 v145, 0xffff0000, v132
	v_lshlrev_b32_e32 v146, 16, v133
	v_and_b32_e32 v147, 0xffff0000, v133
	v_add_f32_e32 v168, 1.0, v168
	v_add_f32_e32 v169, 1.0, v169
	v_add_f32_e32 v170, 1.0, v170
	v_add_f32_e32 v171, 1.0, v171
	v_rcp_f32_e32 v168, v168
	v_rcp_f32_e32 v169, v169
	v_rcp_f32_e32 v170, v170
	v_rcp_f32_e32 v171, v171
	s_nop 0
	v_mul_f32_e32 v168, v144, v168
	v_mul_f32_e32 v169, v145, v169
	v_mul_f32_e32 v170, v146, v170
	v_mul_f32_e32 v171, v147, v171
	v_cvt_pk_bf16_f32 v132, v168, v169
	v_cvt_pk_bf16_f32 v133, v170, v171
	global_store_dwordx2 v235, v[132:133], s[4:5]
	s_add_u32 s4, s4, 0x1000
	s_addc_u32 s5, s5, 0
	s_waitcnt vmcnt(7) lgkmcnt(4)
	v_add_f32_e32 v172, v172, v192
	v_add_f32_e32 v173, v173, v193
	v_add_f32_e32 v174, v174, v194
	v_add_f32_e32 v175, v175, v195
	v_mul_f32_e32 v172, 0xbfb8aa3b, v172
	v_mul_f32_e32 v173, 0xbfb8aa3b, v173
	v_mul_f32_e32 v174, 0xbfb8aa3b, v174
	v_mul_f32_e32 v175, 0xbfb8aa3b, v175
	v_exp_f32_e32 v172, v172
	v_exp_f32_e32 v173, v173
	v_exp_f32_e32 v174, v174
	v_exp_f32_e32 v175, v175
	v_lshlrev_b32_e32 v148, 16, v134
	v_and_b32_e32 v149, 0xffff0000, v134
	v_lshlrev_b32_e32 v150, 16, v135
	v_and_b32_e32 v151, 0xffff0000, v135
	v_add_f32_e32 v172, 1.0, v172
	v_add_f32_e32 v173, 1.0, v173
	v_add_f32_e32 v174, 1.0, v174
	v_add_f32_e32 v175, 1.0, v175
	v_rcp_f32_e32 v172, v172
	v_rcp_f32_e32 v173, v173
	v_rcp_f32_e32 v174, v174
	v_rcp_f32_e32 v175, v175
	s_nop 0
	v_mul_f32_e32 v172, v148, v172
	v_mul_f32_e32 v173, v149, v173
	v_mul_f32_e32 v174, v150, v174
	v_mul_f32_e32 v175, v151, v175
	v_cvt_pk_bf16_f32 v134, v172, v173
	v_cvt_pk_bf16_f32 v135, v174, v175
	global_store_dwordx2 v235, v[134:135], s[4:5]
	s_add_u32 s4, s4, 0x1000
	s_addc_u32 s5, s5, 0
	s_waitcnt vmcnt(7) lgkmcnt(3)
	v_add_f32_e32 v176, v176, v192
	v_add_f32_e32 v177, v177, v193
	v_add_f32_e32 v178, v178, v194
	v_add_f32_e32 v179, v179, v195
	v_mul_f32_e32 v176, 0xbfb8aa3b, v176
	v_mul_f32_e32 v177, 0xbfb8aa3b, v177
	v_mul_f32_e32 v178, 0xbfb8aa3b, v178
	v_mul_f32_e32 v179, 0xbfb8aa3b, v179
	v_exp_f32_e32 v176, v176
	v_exp_f32_e32 v177, v177
	v_exp_f32_e32 v178, v178
	v_exp_f32_e32 v179, v179
	v_lshlrev_b32_e32 v144, 16, v136
	v_and_b32_e32 v145, 0xffff0000, v136
	v_lshlrev_b32_e32 v146, 16, v137
	v_and_b32_e32 v147, 0xffff0000, v137
	v_add_f32_e32 v176, 1.0, v176
	v_add_f32_e32 v177, 1.0, v177
	v_add_f32_e32 v178, 1.0, v178
	v_add_f32_e32 v179, 1.0, v179
	v_rcp_f32_e32 v176, v176
	v_rcp_f32_e32 v177, v177
	v_rcp_f32_e32 v178, v178
	v_rcp_f32_e32 v179, v179
	s_nop 0
	v_mul_f32_e32 v176, v144, v176
	v_mul_f32_e32 v177, v145, v177
	v_mul_f32_e32 v178, v146, v178
	v_mul_f32_e32 v179, v147, v179
	v_cvt_pk_bf16_f32 v136, v176, v177
	v_cvt_pk_bf16_f32 v137, v178, v179
	global_store_dwordx2 v235, v[136:137], s[4:5]
	s_add_u32 s4, s4, 0x1000
	s_addc_u32 s5, s5, 0
	s_waitcnt vmcnt(7) lgkmcnt(2)
; template <class Epi>
; DI void gemm_tile(char* smem, const bf16_t* __restrict__ A0, int lda0, int ksplit, const bf16_t* __restrict__ A1, int lda1,
;                   const bf16_t* __restrict__ Bt, int K, int row0, int col0, const Epi& epi, int tid) {
;     ...
; #pragma unroll
;   for (int m = 0; m < 8; ++m)
; #pragma unroll
;     for (int n = 0; n < 4; ++n) epi(row0 + wr * 128 + m * 16 + fr, col0 + wc * 64 + n * 16 + fq * 4, acc[m][n]);
	v_add_f32_e32 v180, v180, v192
	v_add_f32_e32 v181, v181, v193
	v_add_f32_e32 v182, v182, v194
	v_add_f32_e32 v183, v183, v195
	v_mul_f32_e32 v180, 0xbfb8aa3b, v180
	v_mul_f32_e32 v181, 0xbfb8aa3b, v181
	v_mul_f32_e32 v182, 0xbfb8aa3b, v182
	v_mul_f32_e32 v183, 0xbfb8aa3b, v183
	v_exp_f32_e32 v180, v180
	v_exp_f32_e32 v181, v181
	v_exp_f32_e32 v182, v182
	v_exp_f32_e32 v183, v183
	v_lshlrev_b32_e32 v148, 16, v138
	v_and_b32_e32 v149, 0xffff0000, v138
	v_lshlrev_b32_e32 v150, 16, v139
	v_and_b32_e32 v151, 0xffff0000, v139
	v_add_f32_e32 v180, 1.0, v180
	v_add_f32_e32 v181, 1.0, v181
	v_add_f32_e32 v182, 1.0, v182
	v_add_f32_e32 v183, 1.0, v183
	v_rcp_f32_e32 v180, v180
	v_rcp_f32_e32 v181, v181
	v_rcp_f32_e32 v182, v182
	v_rcp_f32_e32 v183, v183
	s_nop 0
	v_mul_f32_e32 v180, v148, v180
	v_mul_f32_e32 v181, v149, v181
	v_mul_f32_e32 v182, v150, v182
	v_mul_f32_e32 v183, v151, v183
	v_cvt_pk_bf16_f32 v138, v180, v181
	v_cvt_pk_bf16_f32 v139, v182, v183
	global_store_dwordx2 v235, v[138:139], s[4:5]
	s_add_u32 s4, s4, 0x1000
	s_addc_u32 s5, s5, 0
	s_waitcnt vmcnt(7) lgkmcnt(1)
	v_add_f32_e32 v184, v184, v192
	v_add_f32_e32 v185, v185, v193
	v_add_f32_e32 v186, v186, v194
	v_add_f32_e32 v187, v187, v195
	v_mul_f32_e32 v184, 0xbfb8aa3b, v184
	v_mul_f32_e32 v185, 0xbfb8aa3b, v185
	v_mul_f32_e32 v186, 0xbfb8aa3b, v186
	v_mul_f32_e32 v187, 0xbfb8aa3b, v187
	v_exp_f32_e32 v184, v184
	v_exp_f32_e32 v185, v185
	v_exp_f32_e32 v186, v186
	v_exp_f32_e32 v187, v187
	v_lshlrev_b32_e32 v144, 16, v140
	v_and_b32_e32 v145, 0xffff0000, v140
	v_lshlrev_b32_e32 v146, 16, v141
	v_and_b32_e32 v147, 0xffff0000, v141
	v_add_f32_e32 v184, 1.0, v184
	v_add_f32_e32 v185, 1.0, v185
	v_add_f32_e32 v186, 1.0, v186
	v_add_f32_e32 v187, 1.0, v187
	v_rcp_f32_e32 v184, v184
	v_rcp_f32_e32 v185, v185
	v_rcp_f32_e32 v186, v186
	v_rcp_f32_e32 v187, v187
	s_nop 0
	v_mul_f32_e32 v184, v144, v184
	v_mul_f32_e32 v185, v145, v185
	v_mul_f32_e32 v186, v146, v186
	v_mul_f32_e32 v187, v147, v187
	v_cvt_pk_bf16_f32 v140, v184, v185
	v_cvt_pk_bf16_f32 v141, v186, v187
	global_store_dwordx2 v235, v[140:141], s[4:5]
	s_add_u32 s4, s4, 0x1000
	s_addc_u32 s5, s5, 0
	s_waitcnt vmcnt(7) lgkmcnt(0)
	v_add_f32_e32 v188, v188, v192
	v_add_f32_e32 v189, v189, v193
	v_add_f32_e32 v190, v190, v194
	v_add_f32_e32 v191, v191, v195
	v_mul_f32_e32 v188, 0xbfb8aa3b, v188
	v_mul_f32_e32 v189, 0xbfb8aa3b, v189
	v_mul_f32_e32 v190, 0xbfb8aa3b, v190
	v_mul_f32_e32 v191, 0xbfb8aa3b, v191
	v_exp_f32_e32 v188, v188
	v_exp_f32_e32 v189, v189
	v_exp_f32_e32 v190, v190
	v_exp_f32_e32 v191, v191
	v_lshlrev_b32_e32 v148, 16, v142
	v_and_b32_e32 v149, 0xffff0000, v142
	v_lshlrev_b32_e32 v150, 16, v143
	v_and_b32_e32 v151, 0xffff0000, v143
	v_add_f32_e32 v188, 1.0, v188
	v_add_f32_e32 v189, 1.0, v189
	v_add_f32_e32 v190, 1.0, v190
	v_add_f32_e32 v191, 1.0, v191
	v_rcp_f32_e32 v188, v188
	v_rcp_f32_e32 v189, v189
	v_rcp_f32_e32 v190, v190
	v_rcp_f32_e32 v191, v191
	s_nop 0
	v_mul_f32_e32 v188, v148, v188
	v_mul_f32_e32 v189, v149, v189
	v_mul_f32_e32 v190, v150, v190
	v_mul_f32_e32 v191, v151, v191
	v_cvt_pk_bf16_f32 v142, v188, v189
	v_cvt_pk_bf16_f32 v143, v190, v191
	global_store_dwordx2 v235, v[142:143], s[4:5]
	s_add_u32 s4, s4, 0x1000
	s_addc_u32 s5, s5, 0
	s_nop 1
	s_waitcnt lgkmcnt(0)
	ds_write_b128 v245, v[64:67]
	ds_write_b128 v245, v[68:71] offset:64
	ds_write_b128 v245, v[72:75] offset:128
	ds_write_b128 v245, v[76:79] offset:192
	ds_write_b128 v245, v[80:83] offset:4352
	ds_write_b128 v245, v[84:87] offset:4416
	ds_write_b128 v245, v[88:91] offset:4480
	ds_write_b128 v245, v[92:95] offset:4544
	ds_write_b128 v245, v[96:99] offset:8704
	ds_write_b128 v245, v[100:103] offset:8768
	ds_write_b128 v245, v[104:107] offset:8832
	ds_write_b128 v245, v[108:111] offset:8896
	ds_write_b128 v245, v[112:115] offset:13056
	ds_write_b128 v245, v[116:119] offset:13120
	ds_write_b128 v245, v[120:123] offset:13184
	ds_write_b128 v245, v[124:127] offset:13248
	global_load_dwordx2 v[128:129], v235, s[0:1]
	s_add_u32 s0, s0, 0x1000
	s_addc_u32 s1, s1, 0
	global_load_dwordx2 v[130:131], v235, s[0:1]
	s_add_u32 s0, s0, 0x1000
	s_addc_u32 s1, s1, 0
	global_load_dwordx2 v[132:133], v235, s[0:1]
	s_add_u32 s0, s0, 0x1000
	s_addc_u32 s1, s1, 0
	global_load_dwordx2 v[134:135], v235, s[0:1]
	s_add_u32 s0, s0, 0x1000
	s_addc_u32 s1, s1, 0
	global_load_dwordx2 v[136:137], v235, s[0:1]
	s_add_u32 s0, s0, 0x1000
	s_addc_u32 s1, s1, 0
	global_load_dwordx2 v[138:139], v235, s[0:1]
	s_add_u32 s0, s0, 0x1000
	s_addc_u32 s1, s1, 0
	global_load_dwordx2 v[140:141], v235, s[0:1]
	s_add_u32 s0, s0, 0x1000
	s_addc_u32 s1, s1, 0
	global_load_dwordx2 v[142:143], v235, s[0:1]
	s_add_u32 s0, s0, 0x1000
	s_addc_u32 s1, s1, 0
	s_waitcnt lgkmcnt(0)
	ds_read_b128 v[160:163], v246
	ds_read_b128 v[164:167], v246 offset:1088
	ds_read_b128 v[168:171], v246 offset:2176
	ds_read_b128 v[172:175], v246 offset:3264
	ds_read_b128 v[176:179], v246 offset:4352
	ds_read_b128 v[180:183], v246 offset:5440
	ds_read_b128 v[184:187], v246 offset:6528
	ds_read_b128 v[188:191], v246 offset:7616
	s_waitcnt vmcnt(7) lgkmcnt(7)
	v_add_f32_e32 v160, v160, v192
	v_add_f32_e32 v161, v161, v193
	v_add_f32_e32 v162, v162, v194
	v_add_f32_e32 v163, v163, v195
	v_mul_f32_e32 v160, 0xbfb8aa3b, v160
	v_mul_f32_e32 v161, 0xbfb8aa3b, v161
	v_mul_f32_e32 v162, 0xbfb8aa3b, v162
	v_mul_f32_e32 v163, 0xbfb8aa3b, v163
	v_exp_f32_e32 v160, v160
	v_exp_f32_e32 v161, v161
	v_exp_f32_e32 v162, v162
	v_exp_f32_e32 v163, v163
	v_lshlrev_b32_e32 v144, 16, v128
	v_and_b32_e32 v145, 0xffff0000, v128
	v_lshlrev_b32_e32 v146, 16, v129
	v_and_b32_e32 v147, 0xffff0000, v129
	v_add_f32_e32 v160, 1.0, v160
	v_add_f32_e32 v161, 1.0, v161
	v_add_f32_e32 v162, 1.0, v162
	v_add_f32_e32 v163, 1.0, v163
	v_rcp_f32_e32 v160, v160
	v_rcp_f32_e32 v161, v161
	v_rcp_f32_e32 v162, v162
	v_rcp_f32_e32 v163, v163
	s_nop 0
	v_mul_f32_e32 v160, v144, v160
	v_mul_f32_e32 v161, v145, v161
	v_mul_f32_e32 v162, v146, v162
	v_mul_f32_e32 v163, v147, v163
	v_cvt_pk_bf16_f32 v128, v160, v161
	v_cvt_pk_bf16_f32 v129, v162, v163
	global_store_dwordx2 v235, v[128:129], s[4:5]
	s_add_u32 s4, s4, 0x1000
	s_addc_u32 s5, s5, 0
	s_waitcnt vmcnt(7) lgkmcnt(6)
; template <class Epi>
; DI void gemm_tile(char* smem, const bf16_t* __restrict__ A0, int lda0, int ksplit, const bf16_t* __restrict__ A1, int lda1,
;                   const bf16_t* __restrict__ Bt, int K, int row0, int col0, const Epi& epi, int tid) {
;     ...
; #pragma unroll
;   for (int m = 0; m < 8; ++m)
; #pragma unroll
;     for (int n = 0; n < 4; ++n) epi(row0 + wr * 128 + m * 16 + fr, col0 + wc * 64 + n * 16 + fq * 4, acc[m][n]);
	v_add_f32_e32 v164, v164, v192
	v_add_f32_e32 v165, v165, v193
	v_add_f32_e32 v166, v166, v194
	v_add_f32_e32 v167, v167, v195
	v_mul_f32_e32 v164, 0xbfb8aa3b, v164
	v_mul_f32_e32 v165, 0xbfb8aa3b, v165
	v_mul_f32_e32 v166, 0xbfb8aa3b, v166
	v_mul_f32_e32 v167, 0xbfb8aa3b, v167
	v_exp_f32_e32 v164, v164
	v_exp_f32_e32 v165, v165
	v_exp_f32_e32 v166, v166
	v_exp_f32_e32 v167, v167
	v_lshlrev_b32_e32 v148, 16, v130
	v_and_b32_e32 v149, 0xffff0000, v130
	v_lshlrev_b32_e32 v150, 16, v131
	v_and_b32_e32 v151, 0xffff0000, v131
	v_add_f32_e32 v164, 1.0, v164
	v_add_f32_e32 v165, 1.0, v165
	v_add_f32_e32 v166, 1.0, v166
	v_add_f32_e32 v167, 1.0, v167
	v_rcp_f32_e32 v164, v164
	v_rcp_f32_e32 v165, v165
	v_rcp_f32_e32 v166, v166
	v_rcp_f32_e32 v167, v167
	s_nop 0
	v_mul_f32_e32 v164, v148, v164
	v_mul_f32_e32 v165, v149, v165
	v_mul_f32_e32 v166, v150, v166
	v_mul_f32_e32 v167, v151, v167
	v_cvt_pk_bf16_f32 v130, v164, v165
	v_cvt_pk_bf16_f32 v131, v166, v167
	global_store_dwordx2 v235, v[130:131], s[4:5]
	s_add_u32 s4, s4, 0x1000
	s_addc_u32 s5, s5, 0
	s_waitcnt vmcnt(7) lgkmcnt(5)
	v_add_f32_e32 v168, v168, v192
	v_add_f32_e32 v169, v169, v193
	v_add_f32_e32 v170, v170, v194
	v_add_f32_e32 v171, v171, v195
	v_mul_f32_e32 v168, 0xbfb8aa3b, v168
	v_mul_f32_e32 v169, 0xbfb8aa3b, v169
	v_mul_f32_e32 v170, 0xbfb8aa3b, v170
	v_mul_f32_e32 v171, 0xbfb8aa3b, v171
	v_exp_f32_e32 v168, v168
	v_exp_f32_e32 v169, v169
	v_exp_f32_e32 v170, v170
	v_exp_f32_e32 v171, v171
	v_lshlrev_b32_e32 v144, 16, v132
	v_and_b32_e32 v145, 0xffff0000, v132
	v_lshlrev_b32_e32 v146, 16, v133
	v_and_b32_e32 v147, 0xffff0000, v133
	v_add_f32_e32 v168, 1.0, v168
	v_add_f32_e32 v169, 1.0, v169
	v_add_f32_e32 v170, 1.0, v170
	v_add_f32_e32 v171, 1.0, v171
	v_rcp_f32_e32 v168, v168
	v_rcp_f32_e32 v169, v169
	v_rcp_f32_e32 v170, v170
	v_rcp_f32_e32 v171, v171
	s_nop 0
	v_mul_f32_e32 v168, v144, v168
	v_mul_f32_e32 v169, v145, v169
	v_mul_f32_e32 v170, v146, v170
	v_mul_f32_e32 v171, v147, v171
	v_cvt_pk_bf16_f32 v132, v168, v169
	v_cvt_pk_bf16_f32 v133, v170, v171
	global_store_dwordx2 v235, v[132:133], s[4:5]
	s_add_u32 s4, s4, 0x1000
	s_addc_u32 s5, s5, 0
	s_waitcnt vmcnt(7) lgkmcnt(4)
	v_add_f32_e32 v172, v172, v192
	v_add_f32_e32 v173, v173, v193
	v_add_f32_e32 v174, v174, v194
	v_add_f32_e32 v175, v175, v195
	v_mul_f32_e32 v172, 0xbfb8aa3b, v172
	v_mul_f32_e32 v173, 0xbfb8aa3b, v173
	v_mul_f32_e32 v174, 0xbfb8aa3b, v174
	v_mul_f32_e32 v175, 0xbfb8aa3b, v175
	v_exp_f32_e32 v172, v172
	v_exp_f32_e32 v173, v173
	v_exp_f32_e32 v174, v174
	v_exp_f32_e32 v175, v175
	v_lshlrev_b32_e32 v148, 16, v134
	v_and_b32_e32 v149, 0xffff0000, v134
	v_lshlrev_b32_e32 v150, 16, v135
	v_and_b32_e32 v151, 0xffff0000, v135
	v_add_f32_e32 v172, 1.0, v172
	v_add_f32_e32 v173, 1.0, v173
	v_add_f32_e32 v174, 1.0, v174
	v_add_f32_e32 v175, 1.0, v175
	v_rcp_f32_e32 v172, v172
	v_rcp_f32_e32 v173, v173
	v_rcp_f32_e32 v174, v174
	v_rcp_f32_e32 v175, v175
	s_nop 0
	v_mul_f32_e32 v172, v148, v172
	v_mul_f32_e32 v173, v149, v173
	v_mul_f32_e32 v174, v150, v174
	v_mul_f32_e32 v175, v151, v175
	v_cvt_pk_bf16_f32 v134, v172, v173
	v_cvt_pk_bf16_f32 v135, v174, v175
	global_store_dwordx2 v235, v[134:135], s[4:5]
	s_add_u32 s4, s4, 0x1000
	s_addc_u32 s5, s5, 0
	s_waitcnt vmcnt(7) lgkmcnt(3)
	v_add_f32_e32 v176, v176, v192
	v_add_f32_e32 v177, v177, v193
	v_add_f32_e32 v178, v178, v194
	v_add_f32_e32 v179, v179, v195
	v_mul_f32_e32 v176, 0xbfb8aa3b, v176
	v_mul_f32_e32 v177, 0xbfb8aa3b, v177
	v_mul_f32_e32 v178, 0xbfb8aa3b, v178
	v_mul_f32_e32 v179, 0xbfb8aa3b, v179
	v_exp_f32_e32 v176, v176
	v_exp_f32_e32 v177, v177
	v_exp_f32_e32 v178, v178
	v_exp_f32_e32 v179, v179
	v_lshlrev_b32_e32 v144, 16, v136
	v_and_b32_e32 v145, 0xffff0000, v136
	v_lshlrev_b32_e32 v146, 16, v137
	v_and_b32_e32 v147, 0xffff0000, v137
	v_add_f32_e32 v176, 1.0, v176
	v_add_f32_e32 v177, 1.0, v177
	v_add_f32_e32 v178, 1.0, v178
	v_add_f32_e32 v179, 1.0, v179
	v_rcp_f32_e32 v176, v176
	v_rcp_f32_e32 v177, v177
	v_rcp_f32_e32 v178, v178
	v_rcp_f32_e32 v179, v179
	s_nop 0
	v_mul_f32_e32 v176, v144, v176
	v_mul_f32_e32 v177, v145, v177
	v_mul_f32_e32 v178, v146, v178
	v_mul_f32_e32 v179, v147, v179
	v_cvt_pk_bf16_f32 v136, v176, v177
	v_cvt_pk_bf16_f32 v137, v178, v179
	global_store_dwordx2 v235, v[136:137], s[4:5]
	s_add_u32 s4, s4, 0x1000
	s_addc_u32 s5, s5, 0
	s_waitcnt vmcnt(7) lgkmcnt(2)
	v_add_f32_e32 v180, v180, v192
	v_add_f32_e32 v181, v181, v193
	v_add_f32_e32 v182, v182, v194
	v_add_f32_e32 v183, v183, v195
	v_mul_f32_e32 v180, 0xbfb8aa3b, v180
	v_mul_f32_e32 v181, 0xbfb8aa3b, v181
	v_mul_f32_e32 v182, 0xbfb8aa3b, v182
	v_mul_f32_e32 v183, 0xbfb8aa3b, v183
	v_exp_f32_e32 v180, v180
	v_exp_f32_e32 v181, v181
	v_exp_f32_e32 v182, v182
	v_exp_f32_e32 v183, v183
	v_lshlrev_b32_e32 v148, 16, v138
	v_and_b32_e32 v149, 0xffff0000, v138
	v_lshlrev_b32_e32 v150, 16, v139
	v_and_b32_e32 v151, 0xffff0000, v139
	v_add_f32_e32 v180, 1.0, v180
	v_add_f32_e32 v181, 1.0, v181
	v_add_f32_e32 v182, 1.0, v182
	v_add_f32_e32 v183, 1.0, v183
	v_rcp_f32_e32 v180, v180
	v_rcp_f32_e32 v181, v181
	v_rcp_f32_e32 v182, v182
	v_rcp_f32_e32 v183, v183
	s_nop 0
	v_mul_f32_e32 v180, v148, v180
	v_mul_f32_e32 v181, v149, v181
	v_mul_f32_e32 v182, v150, v182
	v_mul_f32_e32 v183, v151, v183
	v_cvt_pk_bf16_f32 v138, v180, v181
	v_cvt_pk_bf16_f32 v139, v182, v183
	global_store_dwordx2 v235, v[138:139], s[4:5]
	s_add_u32 s4, s4, 0x1000
	s_addc_u32 s5, s5, 0
	s_waitcnt vmcnt(7) lgkmcnt(1)
; template <class Epi>
; DI void gemm_tile(char* smem, const bf16_t* __restrict__ A0, int lda0, int ksplit, const bf16_t* __restrict__ A1, int lda1,
;                   const bf16_t* __restrict__ Bt, int K, int row0, int col0, const Epi& epi, int tid) {
;     ...
; #pragma unroll
;   for (int m = 0; m < 8; ++m)
; #pragma unroll
;     for (int n = 0; n < 4; ++n) epi(row0 + wr * 128 + m * 16 + fr, col0 + wc * 64 + n * 16 + fq * 4, acc[m][n]);
	v_add_f32_e32 v184, v184, v192
	v_add_f32_e32 v185, v185, v193
	v_add_f32_e32 v186, v186, v194
	v_add_f32_e32 v187, v187, v195
	v_mul_f32_e32 v184, 0xbfb8aa3b, v184
	v_mul_f32_e32 v185, 0xbfb8aa3b, v185
	v_mul_f32_e32 v186, 0xbfb8aa3b, v186
	v_mul_f32_e32 v187, 0xbfb8aa3b, v187
	v_exp_f32_e32 v184, v184
	v_exp_f32_e32 v185, v185
	v_exp_f32_e32 v186, v186
	v_exp_f32_e32 v187, v187
	v_lshlrev_b32_e32 v144, 16, v140
	v_and_b32_e32 v145, 0xffff0000, v140
	v_lshlrev_b32_e32 v146, 16, v141
	v_and_b32_e32 v147, 0xffff0000, v141
	v_add_f32_e32 v184, 1.0, v184
	v_add_f32_e32 v185, 1.0, v185
	v_add_f32_e32 v186, 1.0, v186
	v_add_f32_e32 v187, 1.0, v187
	v_rcp_f32_e32 v184, v184
	v_rcp_f32_e32 v185, v185
	v_rcp_f32_e32 v186, v186
	v_rcp_f32_e32 v187, v187
	s_nop 0
	v_mul_f32_e32 v184, v144, v184
	v_mul_f32_e32 v185, v145, v185
	v_mul_f32_e32 v186, v146, v186
	v_mul_f32_e32 v187, v147, v187
	v_cvt_pk_bf16_f32 v140, v184, v185
	v_cvt_pk_bf16_f32 v141, v186, v187
	global_store_dwordx2 v235, v[140:141], s[4:5]
	s_add_u32 s4, s4, 0x1000
	s_addc_u32 s5, s5, 0
	s_waitcnt vmcnt(7) lgkmcnt(0)
	v_add_f32_e32 v188, v188, v192
	v_add_f32_e32 v189, v189, v193
	v_add_f32_e32 v190, v190, v194
	v_add_f32_e32 v191, v191, v195
	v_mul_f32_e32 v188, 0xbfb8aa3b, v188
	v_mul_f32_e32 v189, 0xbfb8aa3b, v189
	v_mul_f32_e32 v190, 0xbfb8aa3b, v190
	v_mul_f32_e32 v191, 0xbfb8aa3b, v191
	v_exp_f32_e32 v188, v188
	v_exp_f32_e32 v189, v189
	v_exp_f32_e32 v190, v190
	v_exp_f32_e32 v191, v191
	v_lshlrev_b32_e32 v148, 16, v142
	v_and_b32_e32 v149, 0xffff0000, v142
	v_lshlrev_b32_e32 v150, 16, v143
	v_and_b32_e32 v151, 0xffff0000, v143
	v_add_f32_e32 v188, 1.0, v188
	v_add_f32_e32 v189, 1.0, v189
	v_add_f32_e32 v190, 1.0, v190
	v_add_f32_e32 v191, 1.0, v191
	v_rcp_f32_e32 v188, v188
	v_rcp_f32_e32 v189, v189
	v_rcp_f32_e32 v190, v190
	v_rcp_f32_e32 v191, v191
	s_nop 0
	v_mul_f32_e32 v188, v148, v188
	v_mul_f32_e32 v189, v149, v189
	v_mul_f32_e32 v190, v150, v190
	v_mul_f32_e32 v191, v151, v191
	v_cvt_pk_bf16_f32 v142, v188, v189
	v_cvt_pk_bf16_f32 v143, v190, v191
	global_store_dwordx2 v235, v[142:143], s[4:5]
	s_add_u32 s4, s4, 0x1000
	s_addc_u32 s5, s5, 0
	s_nop 1
	global_load_dwordx2 v[128:129], v235, s[0:1]
	s_add_u32 s0, s0, 0x1000
	s_addc_u32 s1, s1, 0
	global_load_dwordx2 v[130:131], v235, s[0:1]
	s_add_u32 s0, s0, 0x1000
	s_addc_u32 s1, s1, 0
	global_load_dwordx2 v[132:133], v235, s[0:1]
	s_add_u32 s0, s0, 0x1000
	s_addc_u32 s1, s1, 0
	global_load_dwordx2 v[134:135], v235, s[0:1]
	s_add_u32 s0, s0, 0x1000
	s_addc_u32 s1, s1, 0
	global_load_dwordx2 v[136:137], v235, s[0:1]
	s_add_u32 s0, s0, 0x1000
	s_addc_u32 s1, s1, 0
	global_load_dwordx2 v[138:139], v235, s[0:1]
	s_add_u32 s0, s0, 0x1000
	s_addc_u32 s1, s1, 0
	global_load_dwordx2 v[140:141], v235, s[0:1]
	s_add_u32 s0, s0, 0x1000
	s_addc_u32 s1, s1, 0
	global_load_dwordx2 v[142:143], v235, s[0:1]
	s_add_u32 s0, s0, 0x1000
	s_addc_u32 s1, s1, 0
	ds_read_b128 v[160:163], v246 offset:8704
	ds_read_b128 v[164:167], v246 offset:9792
	ds_read_b128 v[168:171], v246 offset:10880
	ds_read_b128 v[172:175], v246 offset:11968
	ds_read_b128 v[176:179], v246 offset:13056
	ds_read_b128 v[180:183], v246 offset:14144
	ds_read_b128 v[184:187], v246 offset:15232
	ds_read_b128 v[188:191], v246 offset:16320
	s_waitcnt vmcnt(7) lgkmcnt(7)
	v_add_f32_e32 v160, v160, v192
	v_add_f32_e32 v161, v161, v193
	v_add_f32_e32 v162, v162, v194
	v_add_f32_e32 v163, v163, v195
	v_mul_f32_e32 v160, 0xbfb8aa3b, v160
	v_mul_f32_e32 v161, 0xbfb8aa3b, v161
	v_mul_f32_e32 v162, 0xbfb8aa3b, v162
	v_mul_f32_e32 v163, 0xbfb8aa3b, v163
	v_exp_f32_e32 v160, v160
	v_exp_f32_e32 v161, v161
	v_exp_f32_e32 v162, v162
	v_exp_f32_e32 v163, v163
	v_lshlrev_b32_e32 v144, 16, v128
	v_and_b32_e32 v145, 0xffff0000, v128
	v_lshlrev_b32_e32 v146, 16, v129
	v_and_b32_e32 v147, 0xffff0000, v129
	v_add_f32_e32 v160, 1.0, v160
	v_add_f32_e32 v161, 1.0, v161
	v_add_f32_e32 v162, 1.0, v162
	v_add_f32_e32 v163, 1.0, v163
	v_rcp_f32_e32 v160, v160
	v_rcp_f32_e32 v161, v161
	v_rcp_f32_e32 v162, v162
	v_rcp_f32_e32 v163, v163
	s_nop 0
	v_mul_f32_e32 v160, v144, v160
	v_mul_f32_e32 v161, v145, v161
	v_mul_f32_e32 v162, v146, v162
	v_mul_f32_e32 v163, v147, v163
	v_cvt_pk_bf16_f32 v128, v160, v161
	v_cvt_pk_bf16_f32 v129, v162, v163
	global_store_dwordx2 v235, v[128:129], s[4:5]
	s_add_u32 s4, s4, 0x1000
	s_addc_u32 s5, s5, 0
	s_waitcnt vmcnt(7) lgkmcnt(6)
	v_add_f32_e32 v164, v164, v192
	v_add_f32_e32 v165, v165, v193
	v_add_f32_e32 v166, v166, v194
	v_add_f32_e32 v167, v167, v195
	v_mul_f32_e32 v164, 0xbfb8aa3b, v164
	v_mul_f32_e32 v165, 0xbfb8aa3b, v165
	v_mul_f32_e32 v166, 0xbfb8aa3b, v166
	v_mul_f32_e32 v167, 0xbfb8aa3b, v167
	v_exp_f32_e32 v164, v164
	v_exp_f32_e32 v165, v165
	v_exp_f32_e32 v166, v166
	v_exp_f32_e32 v167, v167
	v_lshlrev_b32_e32 v148, 16, v130
	v_and_b32_e32 v149, 0xffff0000, v130
	v_lshlrev_b32_e32 v150, 16, v131
	v_and_b32_e32 v151, 0xffff0000, v131
	v_add_f32_e32 v164, 1.0, v164
	v_add_f32_e32 v165, 1.0, v165
	v_add_f32_e32 v166, 1.0, v166
	v_add_f32_e32 v167, 1.0, v167
	v_rcp_f32_e32 v164, v164
	v_rcp_f32_e32 v165, v165
	v_rcp_f32_e32 v166, v166
	v_rcp_f32_e32 v167, v167
	s_nop 0
	v_mul_f32_e32 v164, v148, v164
	v_mul_f32_e32 v165, v149, v165
	v_mul_f32_e32 v166, v150, v166
	v_mul_f32_e32 v167, v151, v167
	v_cvt_pk_bf16_f32 v130, v164, v165
	v_cvt_pk_bf16_f32 v131, v166, v167
	global_store_dwordx2 v235, v[130:131], s[4:5]
	s_add_u32 s4, s4, 0x1000
	s_addc_u32 s5, s5, 0
	s_waitcnt vmcnt(7) lgkmcnt(5)
	v_add_f32_e32 v168, v168, v192
	v_add_f32_e32 v169, v169, v193
	v_add_f32_e32 v170, v170, v194
	v_add_f32_e32 v171, v171, v195
	v_mul_f32_e32 v168, 0xbfb8aa3b, v168
	v_mul_f32_e32 v169, 0xbfb8aa3b, v169
	v_mul_f32_e32 v170, 0xbfb8aa3b, v170
	v_mul_f32_e32 v171, 0xbfb8aa3b, v171
	v_exp_f32_e32 v168, v168
	v_exp_f32_e32 v169, v169
	v_exp_f32_e32 v170, v170
	v_exp_f32_e32 v171, v171
	v_lshlrev_b32_e32 v144, 16, v132
	v_and_b32_e32 v145, 0xffff0000, v132
	v_lshlrev_b32_e32 v146, 16, v133
	v_and_b32_e32 v147, 0xffff0000, v133
	v_add_f32_e32 v168, 1.0, v168
	v_add_f32_e32 v169, 1.0, v169
	v_add_f32_e32 v170, 1.0, v170
	v_add_f32_e32 v171, 1.0, v171
	v_rcp_f32_e32 v168, v168
	v_rcp_f32_e32 v169, v169
	v_rcp_f32_e32 v170, v170
	v_rcp_f32_e32 v171, v171
	s_nop 0
	v_mul_f32_e32 v168, v144, v168
	v_mul_f32_e32 v169, v145, v169
	v_mul_f32_e32 v170, v146, v170
	v_mul_f32_e32 v171, v147, v171
	v_cvt_pk_bf16_f32 v132, v168, v169
	v_cvt_pk_bf16_f32 v133, v170, v171
	global_store_dwordx2 v235, v[132:133], s[4:5]
	s_add_u32 s4, s4, 0x1000
	s_addc_u32 s5, s5, 0
	s_waitcnt vmcnt(7) lgkmcnt(4)
	v_add_f32_e32 v172, v172, v192
	v_add_f32_e32 v173, v173, v193
	v_add_f32_e32 v174, v174, v194
	v_add_f32_e32 v175, v175, v195
	v_mul_f32_e32 v172, 0xbfb8aa3b, v172
	v_mul_f32_e32 v173, 0xbfb8aa3b, v173
	v_mul_f32_e32 v174, 0xbfb8aa3b, v174
	v_mul_f32_e32 v175, 0xbfb8aa3b, v175
	v_exp_f32_e32 v172, v172
	v_exp_f32_e32 v173, v173
	v_exp_f32_e32 v174, v174
	v_exp_f32_e32 v175, v175
	v_lshlrev_b32_e32 v148, 16, v134
	v_and_b32_e32 v149, 0xffff0000, v134
	v_lshlrev_b32_e32 v150, 16, v135
	v_and_b32_e32 v151, 0xffff0000, v135
	v_add_f32_e32 v172, 1.0, v172
	v_add_f32_e32 v173, 1.0, v173
	v_add_f32_e32 v174, 1.0, v174
	v_add_f32_e32 v175, 1.0, v175
	v_rcp_f32_e32 v172, v172
	v_rcp_f32_e32 v173, v173
	v_rcp_f32_e32 v174, v174
	v_rcp_f32_e32 v175, v175
	s_nop 0
	v_mul_f32_e32 v172, v148, v172
	v_mul_f32_e32 v173, v149, v173
	v_mul_f32_e32 v174, v150, v174
	v_mul_f32_e32 v175, v151, v175
	v_cvt_pk_bf16_f32 v134, v172, v173
	v_cvt_pk_bf16_f32 v135, v174, v175
	global_store_dwordx2 v235, v[134:135], s[4:5]
	s_add_u32 s4, s4, 0x1000
	s_addc_u32 s5, s5, 0
	s_waitcnt vmcnt(7) lgkmcnt(3)
	v_add_f32_e32 v176, v176, v192
	v_add_f32_e32 v177, v177, v193
	v_add_f32_e32 v178, v178, v194
	v_add_f32_e32 v179, v179, v195
	v_mul_f32_e32 v176, 0xbfb8aa3b, v176
	v_mul_f32_e32 v177, 0xbfb8aa3b, v177
	v_mul_f32_e32 v178, 0xbfb8aa3b, v178
	v_mul_f32_e32 v179, 0xbfb8aa3b, v179
	v_exp_f32_e32 v176, v176
	v_exp_f32_e32 v177, v177
	v_exp_f32_e32 v178, v178
	v_exp_f32_e32 v179, v179
	v_lshlrev_b32_e32 v144, 16, v136
	v_and_b32_e32 v145, 0xffff0000, v136
	v_lshlrev_b32_e32 v146, 16, v137
	v_and_b32_e32 v147, 0xffff0000, v137
	v_add_f32_e32 v176, 1.0, v176
	v_add_f32_e32 v177, 1.0, v177
	v_add_f32_e32 v178, 1.0, v178
	v_add_f32_e32 v179, 1.0, v179
	v_rcp_f32_e32 v176, v176
	v_rcp_f32_e32 v177, v177
	v_rcp_f32_e32 v178, v178
	v_rcp_f32_e32 v179, v179
	s_nop 0
	v_mul_f32_e32 v176, v144, v176
	v_mul_f32_e32 v177, v145, v177
	v_mul_f32_e32 v178, v146, v178
	v_mul_f32_e32 v179, v147, v179
	v_cvt_pk_bf16_f32 v136, v176, v177
	v_cvt_pk_bf16_f32 v137, v178, v179
	global_store_dwordx2 v235, v[136:137], s[4:5]
	s_add_u32 s4, s4, 0x1000
	s_addc_u32 s5, s5, 0
	s_waitcnt vmcnt(7) lgkmcnt(2)
	v_add_f32_e32 v180, v180, v192
	v_add_f32_e32 v181, v181, v193
	v_add_f32_e32 v182, v182, v194
	v_add_f32_e32 v183, v183, v195
	v_mul_f32_e32 v180, 0xbfb8aa3b, v180
	v_mul_f32_e32 v181, 0xbfb8aa3b, v181
	v_mul_f32_e32 v182, 0xbfb8aa3b, v182
	v_mul_f32_e32 v183, 0xbfb8aa3b, v183
	v_exp_f32_e32 v180, v180
	v_exp_f32_e32 v181, v181
	v_exp_f32_e32 v182, v182
	v_exp_f32_e32 v183, v183
	v_lshlrev_b32_e32 v148, 16, v138
	v_and_b32_e32 v149, 0xffff0000, v138
	v_lshlrev_b32_e32 v150, 16, v139
	v_and_b32_e32 v151, 0xffff0000, v139
	v_add_f32_e32 v180, 1.0, v180
	v_add_f32_e32 v181, 1.0, v181
	v_add_f32_e32 v182, 1.0, v182
	v_add_f32_e32 v183, 1.0, v183
	v_rcp_f32_e32 v180, v180
	v_rcp_f32_e32 v181, v181
	v_rcp_f32_e32 v182, v182
	v_rcp_f32_e32 v183, v183
	s_nop 0
	v_mul_f32_e32 v180, v148, v180
	v_mul_f32_e32 v181, v149, v181
	v_mul_f32_e32 v182, v150, v182
	v_mul_f32_e32 v183, v151, v183
	v_cvt_pk_bf16_f32 v138, v180, v181
	v_cvt_pk_bf16_f32 v139, v182, v183
	global_store_dwordx2 v235, v[138:139], s[4:5]
	s_add_u32 s4, s4, 0x1000
	s_addc_u32 s5, s5, 0
	s_waitcnt vmcnt(7) lgkmcnt(1)
	v_add_f32_e32 v184, v184, v192
	v_add_f32_e32 v185, v185, v193
	v_add_f32_e32 v186, v186, v194
	v_add_f32_e32 v187, v187, v195
	v_mul_f32_e32 v184, 0xbfb8aa3b, v184
	v_mul_f32_e32 v185, 0xbfb8aa3b, v185
	v_mul_f32_e32 v186, 0xbfb8aa3b, v186
	v_mul_f32_e32 v187, 0xbfb8aa3b, v187
	v_exp_f32_e32 v184, v184
	v_exp_f32_e32 v185, v185
	v_exp_f32_e32 v186, v186
	v_exp_f32_e32 v187, v187
	v_lshlrev_b32_e32 v144, 16, v140
	v_and_b32_e32 v145, 0xffff0000, v140
	v_lshlrev_b32_e32 v146, 16, v141
	v_and_b32_e32 v147, 0xffff0000, v141
	v_add_f32_e32 v184, 1.0, v184
	v_add_f32_e32 v185, 1.0, v185
	v_add_f32_e32 v186, 1.0, v186
	v_add_f32_e32 v187, 1.0, v187
	v_rcp_f32_e32 v184, v184
	v_rcp_f32_e32 v185, v185
	v_rcp_f32_e32 v186, v186
	v_rcp_f32_e32 v187, v187
	s_nop 0
	v_mul_f32_e32 v184, v144, v184
	v_mul_f32_e32 v185, v145, v185
	v_mul_f32_e32 v186, v146, v186
	v_mul_f32_e32 v187, v147, v187
	v_cvt_pk_bf16_f32 v140, v184, v185
	v_cvt_pk_bf16_f32 v141, v186, v187
	global_store_dwordx2 v235, v[140:141], s[4:5]
	s_add_u32 s4, s4, 0x1000
	s_addc_u32 s5, s5, 0
	s_waitcnt vmcnt(7) lgkmcnt(0)
	v_add_f32_e32 v188, v188, v192
	v_add_f32_e32 v189, v189, v193
	v_add_f32_e32 v190, v190, v194
	v_add_f32_e32 v191, v191, v195
	v_mul_f32_e32 v188, 0xbfb8aa3b, v188
	v_mul_f32_e32 v189, 0xbfb8aa3b, v189
	v_mul_f32_e32 v190, 0xbfb8aa3b, v190
	v_mul_f32_e32 v191, 0xbfb8aa3b, v191
	v_exp_f32_e32 v188, v188
	v_exp_f32_e32 v189, v189
	v_exp_f32_e32 v190, v190
	v_exp_f32_e32 v191, v191
	v_lshlrev_b32_e32 v148, 16, v142
	v_and_b32_e32 v149, 0xffff0000, v142
	v_lshlrev_b32_e32 v150, 16, v143
	v_and_b32_e32 v151, 0xffff0000, v143
	v_add_f32_e32 v188, 1.0, v188
	v_add_f32_e32 v189, 1.0, v189
	v_add_f32_e32 v190, 1.0, v190
	v_add_f32_e32 v191, 1.0, v191
	v_rcp_f32_e32 v188, v188
	v_rcp_f32_e32 v189, v189
	v_rcp_f32_e32 v190, v190
	v_rcp_f32_e32 v191, v191
	s_nop 0
	v_mul_f32_e32 v188, v148, v188
	v_mul_f32_e32 v189, v149, v189
	v_mul_f32_e32 v190, v150, v190
	v_mul_f32_e32 v191, v151, v191
	v_cvt_pk_bf16_f32 v142, v188, v189
	v_cvt_pk_bf16_f32 v143, v190, v191
	global_store_dwordx2 v235, v[142:143], s[4:5]
	s_add_u32 s4, s4, 0x1000
	s_addc_u32 s5, s5, 0
	s_nop 1
	s_add_u32 s17, s17, 64
	s_branch .Lg14_tile
; DI void grid_barrier(const Ctx& c, unsigned idx) {
;   const Params& p = c.p; (void)p;
;   asm volatile("s_waitcnt vmcnt(0)" ::: "memory");
;   __syncthreads();
;   if (TIDX == 0) {
;     unsigned* bar = (unsigned*)(p.ws + OFF_BAR);
;     const unsigned G = gridDim.x, grp = blockIdx.x & 7u;
;     const unsigned gsz = (G >> 3) + ((grp < (G & 7u)) ? 1u : 0u);
;     const unsigned ngrp = G < 8u ? G : 8u;
;     __builtin_amdgcn_fence(__ATOMIC_RELEASE, "agent");
;     asm volatile("s_waitcnt vmcnt(0)" ::: "memory");
;     const unsigned old = __hip_atomic_fetch_add(bar + 64 * (1 + grp), 1u, __ATOMIC_RELAXED, __HIP_MEMORY_SCOPE_AGENT);
.Lg14_done:
	v_mbcnt_lo_u32_b32 v194, -1, 0
	v_mbcnt_hi_u32_b32 v195, -1, v194
.LBB0_1830:
	s_cmp_lt_i32 s95, 16
	s_cbranch_scc1 .LBB0_1844
	s_waitcnt vmcnt(0)
	v_sub_u32_e32 v0, 0, v195
	v_cmp_eq_u32_e32 vcc, s16, v0
	s_barrier
	s_and_saveexec_b64 s[0:1], vcc
	s_cbranch_execz .LBB0_1843
	s_add_u32 s6, s92, 0x1fe00000
	s_mov_b64 s[4:5], exec
	s_addc_u32 s7, s93, 0
	s_and_b32 s10, s96, 7
	buffer_wbl2 sc1
	s_waitcnt vmcnt(0)
	s_waitcnt vmcnt(0)
	s_lshl_b32 s2, s10, 8
	v_mbcnt_lo_u32_b32 v0, s4, 0
	s_add_u32 s2, s6, s2
	v_mbcnt_hi_u32_b32 v0, s5, v0
	s_addc_u32 s3, s7, 0
	v_cmp_eq_u32_e32 vcc, 0, v0
	s_and_saveexec_b64 s[8:9], vcc
	s_cbranch_execz .LBB0_1834
	s_bcnt1_i32_b64 s4, s[4:5]
	v_mov_b32_e32 v1, 0
	v_mov_b32_e32 v2, s4
	global_atomic_add v1, v1, v2, s[2:3] offset:256 sc0

; #define PH(k) case k: if (ONLY_PHASE >= 0 && ONLY_PHASE != k) break;
; template <class Epi>
; DI void gemm_phase(char* smem, const bf16_t* A0, int lda0, int ksplit, const bf16_t* A1, int lda1, const bf16_t* Bt, int K, int nN, const Epi& epi, int tid) {
;   const int G = gridDim.x;
;   if ((G & 7) == 0) {
;     const int x = blockIdx.x & 7, l = blockIdx.x >> 3, L = G >> 3, per = 8 * nN, tot = 2 * per;
;     for (int q = l; q < tot; q += L) { const int rgl = q / per, rem = q % per, ct = rem >> 3, rt = (x * 2 + rgl) * 8 + (rem & 7);
;       gemm_tile(smem, A0, lda0, ksplit, A1, lda1, Bt, K, rt * 256, ct * 128, epi, tid); }
; template <int ph> DI void run_phase(const Ctx& c, char* smem) {
;     ...
;     PH(15) gemm_phase(smem, (const bf16_t*)(ws + OFF_S5Y), 512, 512, (const bf16_t*)(ws + OFF_MLRAW) + 1024, 2080, (const bf16_t*)(ws + OFF_WCDOUT), 1536, 8, EpiResid{p.out, p.out}, TIDX); break;
.LBB0_1844:
	s_cmp_gt_i32 s94, 15
	s_cselect_b64 s[0:1], -1, 0
	s_cmp_lt_i32 s95, 16
	s_cselect_b64 s[2:3], -1, 0
	s_or_b64 s[0:1], s[0:1], s[2:3]
	s_and_b64 vcc, exec, s[0:1]
	s_cbranch_vccnz .LBB0_1872
	s_add_u32 s0, s92, 0x11a00000
	s_load_dword s12, s[74:75], 0x180
	s_addc_u32 s1, s93, 0
	s_add_u32 s6, s92, 0x9800800
	s_addc_u32 s7, s93, 0
	s_add_u32 s2, s92, 0x3100000
	s_addc_u32 s3, s93, 0
	s_and_b32 s8, s72, 0xffffffc0
	v_mbcnt_hi_u32_b32 v195, -1, v194
	s_waitcnt lgkmcnt(0)
	s_and_b32 s10, s12, 7
	s_cmp_lg_u32 s10, 0
	s_waitcnt vmcnt(16)
	v_add_u32_e32 v196, s8, v195
	v_mbcnt_lo_u32_b32 v240, -1, 0
	v_mbcnt_hi_u32_b32 v240, -1, v240
	s_lshr_b32 s20, s72, 6
	s_lshl_b32 s13, s20, 10
	v_and_b32_e32 v241, 15, v240
	v_lshrrev_b32_e32 v242, 4, v240
	v_bfe_u32 v243, v240, 3, 1
	v_mul_u32_u24_e32 v243, 3, v243
	v_xor_b32_e32 v243, v242, v243
	v_lshlrev_b32_e32 v243, 4, v243
	v_lshl_add_u32 v243, v241, 6, v243
	s_lshr_b32 s19, s20, 1
	s_lshl_b32 s19, s19, 13
	v_add_u32_e32 v230, s19, v243
	s_and_b32 s19, s20, 1
	s_lshl_b32 s19, s19, 12
	s_add_u32 s19, s19, 16384
	v_add_u32_e32 v231, s19, v243
	s_lshr_b32 s19, s20, 1
	s_lshl_b32 s19, s19, 7
	v_add_u32_e32 v244, s19, v241
	s_and_b32 s19, s20, 1
	s_lshl_b32 s19, s19, 6
	v_lshl_add_u32 v245, v242, 2, s19
	s_movk_i32 s19, 0x1000
	v_mul_lo_u32 v246, v244, s19
	v_lshl_add_u32 v234, v245, 2, v246
	v_lshrrev_b32_e32 v241, 2, v240
	s_lshl_b32 s19, s20, 4
	v_add_u32_e32 v241, s19, v241
	v_bfe_u32 v242, v240, 5, 1
	v_mul_u32_u24_e32 v242, 3, v242
	v_and_b32_e32 v243, 3, v240
	v_xor_b32_e32 v243, v243, v242
	v_lshlrev_b32_e32 v243, 4, v243
	s_mov_b32 s19, 1024
	v_mad_u32_u24 v224, v241, s19, v243
	v_add_u32_e32 v225, 0x10000, v224
	v_add_u32_e32 v226, 0x20000, v224
	v_add_u32_e32 v227, 0x30000, v224
	s_mov_b32 s19, 4160
	v_mad_u32_u24 v236, v241, s19, v243
	v_add_u32_e32 v237, 0x41000, v236
	v_add_u32_e32 v238, 0x82000, v236
	v_add_u32_e32 v239, 0xc3000, v236
	v_mov_b32_e32 v248, v224
	v_mov_b32_e32 v249, v225
	v_mov_b32_e32 v250, v226
	v_mov_b32_e32 v251, v227
	s_mov_b32 s19, 3072
	v_mad_u32_u24 v228, v241, s19, v243
	v_add_u32_e32 v229, 0x30000, v228
	s_load_dwordx2 s[6:7], s[74:75], 0x168
	v_mbcnt_lo_u32_b32 v240, -1, 0
	v_mbcnt_hi_u32_b32 v240, -1, v240
	s_lshr_b32 s20, s72, 6
	s_mul_i32 s19, s20, 17408
	v_and_b32_e32 v241, 15, v240
	v_lshrrev_b32_e32 v242, 4, v240
	v_mul_u32_u24_e32 v243, 0x110, v241
	v_lshl_add_u32 v243, v242, 4, v243
	v_add_u32_e32 v245, s19, v243
	v_mul_u32_u24_e32 v243, 0x110, v242
	v_lshl_add_u32 v243, v241, 4, v243
	v_add_u32_e32 v246, s19, v243
	s_lshr_b32 s19, s20, 1
	s_lshl_b32 s19, s19, 7
	v_add_u32_e32 v243, s19, v242
	v_lshlrev_b32_e32 v243, 12, v243
	s_and_b32 s19, s20, 1
	s_lshl_b32 s19, s19, 8
	v_lshl_add_u32 v244, v241, 4, s19
	v_add_u32_e32 v247, v243, v244
	s_lshr_b32 s9, s96, 3
	s_and_b32 s11, s96, 7
	s_lshl_b32 s11, s11, 1
	s_waitcnt lgkmcnt(0)
; #define LWRITE(S, buf) do { bf16_t* sA_ = sbase + (buf) * BUF; bf16_t* sB_ = sA_ + 256 * PITCH; \
;     _Pragma("unroll") for (int i_ = 0; i_ < 4; ++i_) *(u32x4*)(sA_ + (sr + i_ * 64) * PITCH + scv * 8) = ra[S][i_]; \
;     _Pragma("unroll") for (int i_ = 0; i_ < 2; ++i_) *(u32x4*)(sB_ + (sr + i_ * 64) * PITCH + scv * 8) = rb[S][i_]; } while (0)
; template <class Epi>
; DI void gemm_tile(char* smem, const bf16_t* __restrict__ A0, int lda0, int ksplit, const bf16_t* __restrict__ A1, int lda1,
;                   const bf16_t* __restrict__ Bt, int K, int row0, int col0, const Epi& epi, int tid) {
;     ...
;   __syncthreads();
;   {
;     const int last = nk - 1;
;     GLOAD(0, 0);
;     __builtin_amdgcn_sched_barrier(0);
;     GLOAD(1, 1);
;     __builtin_amdgcn_sched_barrier(0);
;     LWRITE(0, 0);
;     __builtin_amdgcn_sched_barrier(0);
;     GLOAD(0, (2 < last ? 2 : last));
;     __builtin_amdgcn_sched_barrier(0);
;     __syncthreads();
; template <class Epi>
; DI void gemm_phase(char* smem, const bf16_t* A0, int lda0, int ksplit, const bf16_t* A1, int lda1, const bf16_t* Bt, int K, int nN, const Epi& epi, int tid) {
;     ...
;     for (int q = l; q < tot; q += L) { const int rgl = q / per, rem = q % per, ct = rem >> 3, rt = (x * 2 + rgl) * 8 + (rem & 7);
;       gemm_tile(smem, A0, lda0, ksplit, A1, lda1, Bt, K, rt * 256, ct * 128, epi, tid); }
.Lg15_tile:
	s_cmpk_ge_u32 s9, 128
	s_cbranch_scc1 .Lg15_done
	s_cmpk_ge_u32 s9, 64
	s_cselect_b32 s20, 1, 0
	s_cselect_b32 s19, 64, 0
	s_sub_u32 s19, s9, s19
	s_and_b32 s98, s19, 7
	s_lshl_b32 s98, s98, 3
	s_bfe_u32 s21, s19, 0x30003
	s_or_b32 s98, s98, s21
	s_andn2_b32 s19, s19, 63
	s_or_b32 s19, s19, s98
	s_add_u32 s20, s20, s11
	s_lshl_b32 s20, s20, 3
	s_and_b32 s98, s19, 7
	s_add_u32 s98, s98, s20
	s_lshl_b32 s98, s98, 8
	s_lshr_b32 s21, s19, 3
	s_lshl_b32 s21, s21, 7
	s_mul_i32 s20, s98, 1024
	s_add_u32 s20, s20, 0x11a00000
	s_add_u32 s0, s92, s20
	s_addc_u32 s1, s93, 0
	s_mul_i32 s20, s21, 3072
	s_add_u32 s20, s20, 0x3100000
	s_add_u32 s2, s92, s20
	s_addc_u32 s3, s93, 0
	v_mov_b32_e32 v224, v248
	v_mov_b32_e32 v225, v249
	v_mov_b32_e32 v226, v250
	v_mov_b32_e32 v227, v251
	s_waitcnt lgkmcnt(0)
	s_barrier
	s_mov_b32 s22, 0
	s_mov_b32 s99, 0
	s_add_u32 s19, s99, s13
	s_add_u32 m0, s19, 0
	s_nop 0
	global_load_lds_dwordx4 v224, s[0:1]
	s_add_u32 m0, s19, 4096
	s_nop 0
	global_load_lds_dwordx4 v225, s[0:1]
	s_add_u32 m0, s19, 8192
	s_nop 0
	global_load_lds_dwordx4 v226, s[0:1]
	s_add_u32 m0, s19, 12288
	s_nop 0
	global_load_lds_dwordx4 v227, s[0:1]
	s_add_u32 m0, s19, 16384
	s_nop 0
	global_load_lds_dwordx4 v228, s[2:3]
	s_add_u32 m0, s19, 20480
	s_nop 0
	global_load_lds_dwordx4 v229, s[2:3]
	s_add_u32 s0, s0, 64
	s_addc_u32 s1, s1, 0
	s_add_u32 s2, s2, 64
	s_addc_u32 s3, s3, 0
	s_add_u32 s22, s22, 1
	s_add_u32 s99, s99, 24576
	s_cmp_eq_u32 s99, 73728
	s_cselect_b32 s99, 0, s99
	s_add_u32 s19, s99, s13
	s_add_u32 m0, s19, 0
	s_nop 0
	global_load_lds_dwordx4 v224, s[0:1]
	s_add_u32 m0, s19, 4096
	s_nop 0
	global_load_lds_dwordx4 v225, s[0:1]
	s_add_u32 m0, s19, 8192
	s_nop 0
	global_load_lds_dwordx4 v226, s[0:1]
	s_add_u32 m0, s19, 12288
	s_nop 0
	global_load_lds_dwordx4 v227, s[0:1]
	s_add_u32 m0, s19, 16384
	s_nop 0
	global_load_lds_dwordx4 v228, s[2:3]
	s_add_u32 m0, s19, 20480
	s_nop 0
	global_load_lds_dwordx4 v229, s[2:3]
	s_add_u32 s0, s0, 64
	s_addc_u32 s1, s1, 0
	s_add_u32 s2, s2, 64
	s_addc_u32 s3, s3, 0
	s_add_u32 s22, s22, 1
	s_add_u32 s99, s99, 24576
	s_cmp_eq_u32 s99, 73728
	s_cselect_b32 s99, 0, s99
	s_add_u32 s19, s99, s13
	s_add_u32 m0, s19, 0
	s_nop 0
	global_load_lds_dwordx4 v224, s[0:1]
	s_add_u32 m0, s19, 4096
	s_nop 0
	global_load_lds_dwordx4 v225, s[0:1]
	s_add_u32 m0, s19, 8192
	s_nop 0
	global_load_lds_dwordx4 v226, s[0:1]
	s_add_u32 m0, s19, 12288
	s_nop 0
	global_load_lds_dwordx4 v227, s[0:1]
	s_add_u32 m0, s19, 16384
	s_nop 0
	global_load_lds_dwordx4 v228, s[2:3]
	s_add_u32 m0, s19, 20480
	s_nop 0
	global_load_lds_dwordx4 v229, s[2:3]
	s_add_u32 s0, s0, 64
	s_addc_u32 s1, s1, 0
	s_add_u32 s2, s2, 64
	s_addc_u32 s3, s3, 0
	s_add_u32 s22, s22, 1
	s_add_u32 s99, s99, 24576
	s_cmp_eq_u32 s99, 73728
	s_cselect_b32 s99, 0, s99
	v_mov_b32_e32 v0, 0
	v_mov_b32_e32 v1, 0
	v_mov_b32_e32 v2, 0
	v_mov_b32_e32 v3, 0
	v_mov_b32_e32 v4, 0
	v_mov_b32_e32 v5, 0
	v_mov_b32_e32 v6, 0
	v_mov_b32_e32 v7, 0
	v_mov_b32_e32 v8, 0
	v_mov_b32_e32 v9, 0
	v_mov_b32_e32 v10, 0
	v_mov_b32_e32 v11, 0
	v_mov_b32_e32 v12, 0
	v_mov_b32_e32 v13, 0
	v_mov_b32_e32 v14, 0
	v_mov_b32_e32 v15, 0
	v_mov_b32_e32 v16, 0
	v_mov_b32_e32 v17, 0
	v_mov_b32_e32 v18, 0
	v_mov_b32_e32 v19, 0
	v_mov_b32_e32 v20, 0
	v_mov_b32_e32 v21, 0
	v_mov_b32_e32 v22, 0
	v_mov_b32_e32 v23, 0
	v_mov_b32_e32 v24, 0
	v_mov_b32_e32 v25, 0
	v_mov_b32_e32 v26, 0
	v_mov_b32_e32 v27, 0
	v_mov_b32_e32 v28, 0
	v_mov_b32_e32 v29, 0
	v_mov_b32_e32 v30, 0
	v_mov_b32_e32 v31, 0
	v_mov_b32_e32 v32, 0
	v_mov_b32_e32 v33, 0
	v_mov_b32_e32 v34, 0
	v_mov_b32_e32 v35, 0
	v_mov_b32_e32 v36, 0
	v_mov_b32_e32 v37, 0
	v_mov_b32_e32 v38, 0
	v_mov_b32_e32 v39, 0
	v_mov_b32_e32 v40, 0
	v_mov_b32_e32 v41, 0
	v_mov_b32_e32 v42, 0
	v_mov_b32_e32 v43, 0
	v_mov_b32_e32 v44, 0
	v_mov_b32_e32 v45, 0
	v_mov_b32_e32 v46, 0
	v_mov_b32_e32 v47, 0
	v_mov_b32_e32 v48, 0
	v_mov_b32_e32 v49, 0
	v_mov_b32_e32 v50, 0
	v_mov_b32_e32 v51, 0
	v_mov_b32_e32 v52, 0
	v_mov_b32_e32 v53, 0
	v_mov_b32_e32 v54, 0
	v_mov_b32_e32 v55, 0
	v_mov_b32_e32 v56, 0
	v_mov_b32_e32 v57, 0
	v_mov_b32_e32 v58, 0
	v_mov_b32_e32 v59, 0
	v_mov_b32_e32 v60, 0
	v_mov_b32_e32 v61, 0
	v_mov_b32_e32 v62, 0
	v_mov_b32_e32 v63, 0
	v_mov_b32_e32 v64, 0
	v_mov_b32_e32 v65, 0
	v_mov_b32_e32 v66, 0
	v_mov_b32_e32 v67, 0
	v_mov_b32_e32 v68, 0
	v_mov_b32_e32 v69, 0
	v_mov_b32_e32 v70, 0
	v_mov_b32_e32 v71, 0
	v_mov_b32_e32 v72, 0
	v_mov_b32_e32 v73, 0
	v_mov_b32_e32 v74, 0
	v_mov_b32_e32 v75, 0
	v_mov_b32_e32 v76, 0
	v_mov_b32_e32 v77, 0
	v_mov_b32_e32 v78, 0
	v_mov_b32_e32 v79, 0
	v_mov_b32_e32 v80, 0
	v_mov_b32_e32 v81, 0
	v_mov_b32_e32 v82, 0
	v_mov_b32_e32 v83, 0
	v_mov_b32_e32 v84, 0
	v_mov_b32_e32 v85, 0
	v_mov_b32_e32 v86, 0
	v_mov_b32_e32 v87, 0
	v_mov_b32_e32 v88, 0
	v_mov_b32_e32 v89, 0
	v_mov_b32_e32 v90, 0
	v_mov_b32_e32 v91, 0
	v_mov_b32_e32 v92, 0
	v_mov_b32_e32 v93, 0
	v_mov_b32_e32 v94, 0
	v_mov_b32_e32 v95, 0
	v_mov_b32_e32 v96, 0
	v_mov_b32_e32 v97, 0
	v_mov_b32_e32 v98, 0
	v_mov_b32_e32 v99, 0
	v_mov_b32_e32 v100, 0
	v_mov_b32_e32 v101, 0
	v_mov_b32_e32 v102, 0
	v_mov_b32_e32 v103, 0
	v_mov_b32_e32 v104, 0
	v_mov_b32_e32 v105, 0
	v_mov_b32_e32 v106, 0
	v_mov_b32_e32 v107, 0
	v_mov_b32_e32 v108, 0
	v_mov_b32_e32 v109, 0
	v_mov_b32_e32 v110, 0
	v_mov_b32_e32 v111, 0
	v_mov_b32_e32 v112, 0
	v_mov_b32_e32 v113, 0
	v_mov_b32_e32 v114, 0
	v_mov_b32_e32 v115, 0
	v_mov_b32_e32 v116, 0
	v_mov_b32_e32 v117, 0
	v_mov_b32_e32 v118, 0
	v_mov_b32_e32 v119, 0
	v_mov_b32_e32 v120, 0
	v_mov_b32_e32 v121, 0
	v_mov_b32_e32 v122, 0
	v_mov_b32_e32 v123, 0
	v_mov_b32_e32 v124, 0
	v_mov_b32_e32 v125, 0
	v_mov_b32_e32 v126, 0
	v_mov_b32_e32 v127, 0
	s_mov_b32 s101, 0
	s_mov_b32 s100, 24576
	s_waitcnt vmcnt(12)
	s_barrier
	ds_read_b128 v[128:131], v231 offset:0
	ds_read_b128 v[132:135], v231 offset:1024
	ds_read_b128 v[136:139], v231 offset:2048
	ds_read_b128 v[140:143], v231 offset:3072
	ds_read_b128 v[144:147], v230 offset:0
	ds_read_b128 v[148:151], v230 offset:1024
	ds_read_b128 v[152:155], v230 offset:2048
	ds_read_b128 v[156:159], v230 offset:3072
	ds_read_b128 v[160:163], v230 offset:4096
	ds_read_b128 v[164:167], v230 offset:5120
	ds_read_b128 v[168:171], v230 offset:6144
	ds_read_b128 v[172:175], v230 offset:7168

; template <class Epi>
; DI void gemm_tile(char* smem, const bf16_t* __restrict__ A0, int lda0, int ksplit, const bf16_t* __restrict__ A1, int lda1,
;                   const bf16_t* __restrict__ Bt, int K, int row0, int col0, const Epi& epi, int tid) {
;     ...
; #pragma unroll
;   for (int m = 0; m < 8; ++m)
; #pragma unroll
;     for (int n = 0; n < 4; ++n) epi(row0 + wr * 128 + m * 16 + fr, col0 + wc * 64 + n * 16 + fq * 4, acc[m][n]);
.Lg15_epi:
	s_nop 7
	s_nop 7
	s_lshl_b32 s20, s98, 12
	s_lshl_b32 s19, s21, 2
	s_add_u32 s20, s20, s19
	s_add_u32 s4, s6, s20
	s_addc_u32 s5, s7, 0
	s_lshl_b32 s20, s98, 12
	s_lshl_b32 s19, s21, 2
	s_add_u32 s20, s20, s19
	s_add_u32 s0, s6, s20
	s_addc_u32 s1, s7, 0
	ds_write_b128 v245, v[0:3]
	ds_write_b128 v245, v[4:7] offset:64
	ds_write_b128 v245, v[8:11] offset:128
	ds_write_b128 v245, v[12:15] offset:192
	ds_write_b128 v245, v[16:19] offset:4352
	ds_write_b128 v245, v[20:23] offset:4416
	ds_write_b128 v245, v[24:27] offset:4480
	ds_write_b128 v245, v[28:31] offset:4544
	ds_write_b128 v245, v[32:35] offset:8704
	ds_write_b128 v245, v[36:39] offset:8768
	ds_write_b128 v245, v[40:43] offset:8832
	ds_write_b128 v245, v[44:47] offset:8896
	ds_write_b128 v245, v[48:51] offset:13056
	ds_write_b128 v245, v[52:55] offset:13120
	ds_write_b128 v245, v[56:59] offset:13184
	ds_write_b128 v245, v[60:63] offset:13248
	global_load_dwordx4 v[128:131], v247, s[0:1]
	s_add_u32 s0, s0, 0x4000
	s_addc_u32 s1, s1, 0
	global_load_dwordx4 v[132:135], v247, s[0:1]
	s_add_u32 s0, s0, 0x4000
	s_addc_u32 s1, s1, 0
	global_load_dwordx4 v[136:139], v247, s[0:1]
	s_add_u32 s0, s0, 0x4000
	s_addc_u32 s1, s1, 0
	global_load_dwordx4 v[140:143], v247, s[0:1]
	s_add_u32 s0, s0, 0x4000
	s_addc_u32 s1, s1, 0
	global_load_dwordx4 v[144:147], v247, s[0:1]
	s_add_u32 s0, s0, 0x4000
	s_addc_u32 s1, s1, 0
	global_load_dwordx4 v[148:151], v247, s[0:1]
	s_add_u32 s0, s0, 0x4000
	s_addc_u32 s1, s1, 0
	global_load_dwordx4 v[152:155], v247, s[0:1]
	s_add_u32 s0, s0, 0x4000
	s_addc_u32 s1, s1, 0
	global_load_dwordx4 v[156:159], v247, s[0:1]
	s_add_u32 s0, s0, 0x4000
	s_addc_u32 s1, s1, 0
	s_waitcnt lgkmcnt(0)
	ds_read_b128 v[160:163], v246
	ds_read_b128 v[164:167], v246 offset:1088
	ds_read_b128 v[168:171], v246 offset:2176
	ds_read_b128 v[172:175], v246 offset:3264
	ds_read_b128 v[176:179], v246 offset:4352
	ds_read_b128 v[180:183], v246 offset:5440
	ds_read_b128 v[184:187], v246 offset:6528
	ds_read_b128 v[188:191], v246 offset:7616
	s_waitcnt vmcnt(7) lgkmcnt(7)
	v_pk_add_f32 v[128:129], v[128:129], v[160:161]
	v_pk_add_f32 v[130:131], v[130:131], v[162:163]
	global_store_dwordx4 v247, v[128:131], s[4:5]
	s_add_u32 s4, s4, 0x4000
	s_addc_u32 s5, s5, 0
	s_waitcnt vmcnt(7) lgkmcnt(6)
	v_pk_add_f32 v[132:133], v[132:133], v[164:165]
	v_pk_add_f32 v[134:135], v[134:135], v[166:167]
	global_store_dwordx4 v247, v[132:135], s[4:5]
	s_add_u32 s4, s4, 0x4000
	s_addc_u32 s5, s5, 0
	s_waitcnt vmcnt(7) lgkmcnt(5)
	v_pk_add_f32 v[136:137], v[136:137], v[168:169]
	v_pk_add_f32 v[138:139], v[138:139], v[170:171]
	global_store_dwordx4 v247, v[136:139], s[4:5]
	s_add_u32 s4, s4, 0x4000
	s_addc_u32 s5, s5, 0
	s_waitcnt vmcnt(7) lgkmcnt(4)
	v_pk_add_f32 v[140:141], v[140:141], v[172:173]
	v_pk_add_f32 v[142:143], v[142:143], v[174:175]
	global_store_dwordx4 v247, v[140:143], s[4:5]
	s_add_u32 s4, s4, 0x4000
	s_addc_u32 s5, s5, 0
	s_waitcnt vmcnt(7) lgkmcnt(3)
	v_pk_add_f32 v[144:145], v[144:145], v[176:177]
	v_pk_add_f32 v[146:147], v[146:147], v[178:179]
	global_store_dwordx4 v247, v[144:147], s[4:5]
	s_add_u32 s4, s4, 0x4000
	s_addc_u32 s5, s5, 0
	s_waitcnt vmcnt(7) lgkmcnt(2)
	v_pk_add_f32 v[148:149], v[148:149], v[180:181]
	v_pk_add_f32 v[150:151], v[150:151], v[182:183]
	global_store_dwordx4 v247, v[148:151], s[4:5]
	s_add_u32 s4, s4, 0x4000
	s_addc_u32 s5, s5, 0
	s_waitcnt vmcnt(7) lgkmcnt(1)
	v_pk_add_f32 v[152:153], v[152:153], v[184:185]
	v_pk_add_f32 v[154:155], v[154:155], v[186:187]
	global_store_dwordx4 v247, v[152:155], s[4:5]
	s_add_u32 s4, s4, 0x4000
	s_addc_u32 s5, s5, 0
	s_waitcnt vmcnt(7) lgkmcnt(0)
	v_pk_add_f32 v[156:157], v[156:157], v[188:189]
	v_pk_add_f32 v[158:159], v[158:159], v[190:191]
	global_store_dwordx4 v247, v[156:159], s[4:5]
	s_add_u32 s4, s4, 0x4000
	s_addc_u32 s5, s5, 0
	s_nop 1
	global_load_dwordx4 v[128:131], v247, s[0:1]
	s_add_u32 s0, s0, 0x4000
	s_addc_u32 s1, s1, 0
	global_load_dwordx4 v[132:135], v247, s[0:1]
	s_add_u32 s0, s0, 0x4000
	s_addc_u32 s1, s1, 0
	global_load_dwordx4 v[136:139], v247, s[0:1]
	s_add_u32 s0, s0, 0x4000
	s_addc_u32 s1, s1, 0
	global_load_dwordx4 v[140:143], v247, s[0:1]
	s_add_u32 s0, s0, 0x4000
	s_addc_u32 s1, s1, 0
	global_load_dwordx4 v[144:147], v247, s[0:1]
	s_add_u32 s0, s0, 0x4000
	s_addc_u32 s1, s1, 0
	global_load_dwordx4 v[148:151], v247, s[0:1]
	s_add_u32 s0, s0, 0x4000
	s_addc_u32 s1, s1, 0
	global_load_dwordx4 v[152:155], v247, s[0:1]
	s_add_u32 s0, s0, 0x4000
	s_addc_u32 s1, s1, 0
	global_load_dwordx4 v[156:159], v247, s[0:1]
	s_add_u32 s0, s0, 0x4000
	s_addc_u32 s1, s1, 0
	ds_read_b128 v[160:163], v246 offset:8704
	ds_read_b128 v[164:167], v246 offset:9792
	ds_read_b128 v[168:171], v246 offset:10880
	ds_read_b128 v[172:175], v246 offset:11968
	ds_read_b128 v[176:179], v246 offset:13056
	ds_read_b128 v[180:183], v246 offset:14144
	ds_read_b128 v[184:187], v246 offset:15232
	ds_read_b128 v[188:191], v246 offset:16320
	s_waitcnt vmcnt(7) lgkmcnt(7)
	v_pk_add_f32 v[128:129], v[128:129], v[160:161]
	v_pk_add_f32 v[130:131], v[130:131], v[162:163]
	global_store_dwordx4 v247, v[128:131], s[4:5]
	s_add_u32 s4, s4, 0x4000
	s_addc_u32 s5, s5, 0
	s_waitcnt vmcnt(7) lgkmcnt(6)
	v_pk_add_f32 v[132:133], v[132:133], v[164:165]
	v_pk_add_f32 v[134:135], v[134:135], v[166:167]
	global_store_dwordx4 v247, v[132:135], s[4:5]
	s_add_u32 s4, s4, 0x4000
	s_addc_u32 s5, s5, 0
	s_waitcnt vmcnt(7) lgkmcnt(5)
	v_pk_add_f32 v[136:137], v[136:137], v[168:169]
	v_pk_add_f32 v[138:139], v[138:139], v[170:171]
	global_store_dwordx4 v247, v[136:139], s[4:5]
	s_add_u32 s4, s4, 0x4000
	s_addc_u32 s5, s5, 0
	s_waitcnt vmcnt(7) lgkmcnt(4)
; template <class Epi>
; DI void gemm_tile(char* smem, const bf16_t* __restrict__ A0, int lda0, int ksplit, const bf16_t* __restrict__ A1, int lda1,
;                   const bf16_t* __restrict__ Bt, int K, int row0, int col0, const Epi& epi, int tid) {
;     ...
; #pragma unroll
;   for (int m = 0; m < 8; ++m)
; #pragma unroll
;     for (int n = 0; n < 4; ++n) epi(row0 + wr * 128 + m * 16 + fr, col0 + wc * 64 + n * 16 + fq * 4, acc[m][n]);
	v_pk_add_f32 v[140:141], v[140:141], v[172:173]
	v_pk_add_f32 v[142:143], v[142:143], v[174:175]
	global_store_dwordx4 v247, v[140:143], s[4:5]
	s_add_u32 s4, s4, 0x4000
	s_addc_u32 s5, s5, 0
	s_waitcnt vmcnt(7) lgkmcnt(3)
	v_pk_add_f32 v[144:145], v[144:145], v[176:177]
	v_pk_add_f32 v[146:147], v[146:147], v[178:179]
	global_store_dwordx4 v247, v[144:147], s[4:5]
	s_add_u32 s4, s4, 0x4000
	s_addc_u32 s5, s5, 0
	s_waitcnt vmcnt(7) lgkmcnt(2)
	v_pk_add_f32 v[148:149], v[148:149], v[180:181]
	v_pk_add_f32 v[150:151], v[150:151], v[182:183]
	global_store_dwordx4 v247, v[148:151], s[4:5]
	s_add_u32 s4, s4, 0x4000
	s_addc_u32 s5, s5, 0
	s_waitcnt vmcnt(7) lgkmcnt(1)
	v_pk_add_f32 v[152:153], v[152:153], v[184:185]
	v_pk_add_f32 v[154:155], v[154:155], v[186:187]
	global_store_dwordx4 v247, v[152:155], s[4:5]
	s_add_u32 s4, s4, 0x4000
	s_addc_u32 s5, s5, 0
	s_waitcnt vmcnt(7) lgkmcnt(0)
	v_pk_add_f32 v[156:157], v[156:157], v[188:189]
	v_pk_add_f32 v[158:159], v[158:159], v[190:191]
	global_store_dwordx4 v247, v[156:159], s[4:5]
	s_add_u32 s4, s4, 0x4000
	s_addc_u32 s5, s5, 0
	s_nop 1
	s_waitcnt lgkmcnt(0)
	ds_write_b128 v245, v[64:67]
	ds_write_b128 v245, v[68:71] offset:64
	ds_write_b128 v245, v[72:75] offset:128
	ds_write_b128 v245, v[76:79] offset:192
	ds_write_b128 v245, v[80:83] offset:4352
	ds_write_b128 v245, v[84:87] offset:4416
	ds_write_b128 v245, v[88:91] offset:4480
	ds_write_b128 v245, v[92:95] offset:4544
	ds_write_b128 v245, v[96:99] offset:8704
	ds_write_b128 v245, v[100:103] offset:8768
	ds_write_b128 v245, v[104:107] offset:8832
	ds_write_b128 v245, v[108:111] offset:8896
	ds_write_b128 v245, v[112:115] offset:13056
	ds_write_b128 v245, v[116:119] offset:13120
	ds_write_b128 v245, v[120:123] offset:13184
	ds_write_b128 v245, v[124:127] offset:13248
	global_load_dwordx4 v[128:131], v247, s[0:1]
	s_add_u32 s0, s0, 0x4000
	s_addc_u32 s1, s1, 0
	global_load_dwordx4 v[132:135], v247, s[0:1]
	s_add_u32 s0, s0, 0x4000
	s_addc_u32 s1, s1, 0
	global_load_dwordx4 v[136:139], v247, s[0:1]
	s_add_u32 s0, s0, 0x4000
	s_addc_u32 s1, s1, 0
	global_load_dwordx4 v[140:143], v247, s[0:1]
	s_add_u32 s0, s0, 0x4000
	s_addc_u32 s1, s1, 0
	global_load_dwordx4 v[144:147], v247, s[0:1]
	s_add_u32 s0, s0, 0x4000
	s_addc_u32 s1, s1, 0
	global_load_dwordx4 v[148:151], v247, s[0:1]
	s_add_u32 s0, s0, 0x4000
	s_addc_u32 s1, s1, 0
	global_load_dwordx4 v[152:155], v247, s[0:1]
	s_add_u32 s0, s0, 0x4000
	s_addc_u32 s1, s1, 0
	global_load_dwordx4 v[156:159], v247, s[0:1]
	s_add_u32 s0, s0, 0x4000
	s_addc_u32 s1, s1, 0
	s_waitcnt lgkmcnt(0)
	ds_read_b128 v[160:163], v246
	ds_read_b128 v[164:167], v246 offset:1088
	ds_read_b128 v[168:171], v246 offset:2176
	ds_read_b128 v[172:175], v246 offset:3264
	ds_read_b128 v[176:179], v246 offset:4352
	ds_read_b128 v[180:183], v246 offset:5440
	ds_read_b128 v[184:187], v246 offset:6528
	ds_read_b128 v[188:191], v246 offset:7616
	s_waitcnt vmcnt(7) lgkmcnt(7)
	v_pk_add_f32 v[128:129], v[128:129], v[160:161]
	v_pk_add_f32 v[130:131], v[130:131], v[162:163]
	global_store_dwordx4 v247, v[128:131], s[4:5]
	s_add_u32 s4, s4, 0x4000
	s_addc_u32 s5, s5, 0
	s_waitcnt vmcnt(7) lgkmcnt(6)
	v_pk_add_f32 v[132:133], v[132:133], v[164:165]
	v_pk_add_f32 v[134:135], v[134:135], v[166:167]
	global_store_dwordx4 v247, v[132:135], s[4:5]
	s_add_u32 s4, s4, 0x4000
	s_addc_u32 s5, s5, 0
	s_waitcnt vmcnt(7) lgkmcnt(5)
	v_pk_add_f32 v[136:137], v[136:137], v[168:169]
	v_pk_add_f32 v[138:139], v[138:139], v[170:171]
	global_store_dwordx4 v247, v[136:139], s[4:5]
	s_add_u32 s4, s4, 0x4000
	s_addc_u32 s5, s5, 0
	s_waitcnt vmcnt(7) lgkmcnt(4)
	v_pk_add_f32 v[140:141], v[140:141], v[172:173]
	v_pk_add_f32 v[142:143], v[142:143], v[174:175]
	global_store_dwordx4 v247, v[140:143], s[4:5]
	s_add_u32 s4, s4, 0x4000
	s_addc_u32 s5, s5, 0
	s_waitcnt vmcnt(7) lgkmcnt(3)
; template <class Epi>
; DI void gemm_tile(char* smem, const bf16_t* __restrict__ A0, int lda0, int ksplit, const bf16_t* __restrict__ A1, int lda1,
;                   const bf16_t* __restrict__ Bt, int K, int row0, int col0, const Epi& epi, int tid) {
;     ...
; #pragma unroll
;   for (int m = 0; m < 8; ++m)
; #pragma unroll
;     for (int n = 0; n < 4; ++n) epi(row0 + wr * 128 + m * 16 + fr, col0 + wc * 64 + n * 16 + fq * 4, acc[m][n]);
; template <class Epi>
; DI void gemm_phase(char* smem, const bf16_t* A0, int lda0, int ksplit, const bf16_t* A1, int lda1, const bf16_t* Bt, int K, int nN, const Epi& epi, int tid) {
;     ...
;     for (int q = l; q < tot; q += L) { const int rgl = q / per, rem = q % per, ct = rem >> 3, rt = (x * 2 + rgl) * 8 + (rem & 7);
	v_pk_add_f32 v[144:145], v[144:145], v[176:177]
	v_pk_add_f32 v[146:147], v[146:147], v[178:179]
	global_store_dwordx4 v247, v[144:147], s[4:5]
	s_add_u32 s4, s4, 0x4000
	s_addc_u32 s5, s5, 0
	s_waitcnt vmcnt(7) lgkmcnt(2)
	v_pk_add_f32 v[148:149], v[148:149], v[180:181]
	v_pk_add_f32 v[150:151], v[150:151], v[182:183]
	global_store_dwordx4 v247, v[148:151], s[4:5]
	s_add_u32 s4, s4, 0x4000
	s_addc_u32 s5, s5, 0
	s_waitcnt vmcnt(7) lgkmcnt(1)
	v_pk_add_f32 v[152:153], v[152:153], v[184:185]
	v_pk_add_f32 v[154:155], v[154:155], v[186:187]
	global_store_dwordx4 v247, v[152:155], s[4:5]
	s_add_u32 s4, s4, 0x4000
	s_addc_u32 s5, s5, 0
	s_waitcnt vmcnt(7) lgkmcnt(0)
	v_pk_add_f32 v[156:157], v[156:157], v[188:189]
	v_pk_add_f32 v[158:159], v[158:159], v[190:191]
	global_store_dwordx4 v247, v[156:159], s[4:5]
	s_add_u32 s4, s4, 0x4000
	s_addc_u32 s5, s5, 0
	s_nop 1
	global_load_dwordx4 v[128:131], v247, s[0:1]
	s_add_u32 s0, s0, 0x4000
	s_addc_u32 s1, s1, 0
	global_load_dwordx4 v[132:135], v247, s[0:1]
	s_add_u32 s0, s0, 0x4000
	s_addc_u32 s1, s1, 0
	global_load_dwordx4 v[136:139], v247, s[0:1]
	s_add_u32 s0, s0, 0x4000
	s_addc_u32 s1, s1, 0
	global_load_dwordx4 v[140:143], v247, s[0:1]
	s_add_u32 s0, s0, 0x4000
	s_addc_u32 s1, s1, 0
	global_load_dwordx4 v[144:147], v247, s[0:1]
	s_add_u32 s0, s0, 0x4000
	s_addc_u32 s1, s1, 0
	global_load_dwordx4 v[148:151], v247, s[0:1]
	s_add_u32 s0, s0, 0x4000
	s_addc_u32 s1, s1, 0
	global_load_dwordx4 v[152:155], v247, s[0:1]
	s_add_u32 s0, s0, 0x4000
	s_addc_u32 s1, s1, 0
	global_load_dwordx4 v[156:159], v247, s[0:1]
	s_add_u32 s0, s0, 0x4000
	s_addc_u32 s1, s1, 0
	ds_read_b128 v[160:163], v246 offset:8704
	ds_read_b128 v[164:167], v246 offset:9792
	ds_read_b128 v[168:171], v246 offset:10880
	ds_read_b128 v[172:175], v246 offset:11968
	ds_read_b128 v[176:179], v246 offset:13056
	ds_read_b128 v[180:183], v246 offset:14144
	ds_read_b128 v[184:187], v246 offset:15232
	ds_read_b128 v[188:191], v246 offset:16320
	s_waitcnt vmcnt(7) lgkmcnt(7)
	v_pk_add_f32 v[128:129], v[128:129], v[160:161]
	v_pk_add_f32 v[130:131], v[130:131], v[162:163]
	global_store_dwordx4 v247, v[128:131], s[4:5]
	s_add_u32 s4, s4, 0x4000
	s_addc_u32 s5, s5, 0
	s_waitcnt vmcnt(7) lgkmcnt(6)
	v_pk_add_f32 v[132:133], v[132:133], v[164:165]
	v_pk_add_f32 v[134:135], v[134:135], v[166:167]
	global_store_dwordx4 v247, v[132:135], s[4:5]
	s_add_u32 s4, s4, 0x4000
	s_addc_u32 s5, s5, 0
	s_waitcnt vmcnt(7) lgkmcnt(5)
	v_pk_add_f32 v[136:137], v[136:137], v[168:169]
	v_pk_add_f32 v[138:139], v[138:139], v[170:171]
	global_store_dwordx4 v247, v[136:139], s[4:5]
	s_add_u32 s4, s4, 0x4000
	s_addc_u32 s5, s5, 0
	s_waitcnt vmcnt(7) lgkmcnt(4)
	v_pk_add_f32 v[140:141], v[140:141], v[172:173]
	v_pk_add_f32 v[142:143], v[142:143], v[174:175]
	global_store_dwordx4 v247, v[140:143], s[4:5]
	s_add_u32 s4, s4, 0x4000
	s_addc_u32 s5, s5, 0
	s_waitcnt vmcnt(7) lgkmcnt(3)
	v_pk_add_f32 v[144:145], v[144:145], v[176:177]
	v_pk_add_f32 v[146:147], v[146:147], v[178:179]
	global_store_dwordx4 v247, v[144:147], s[4:5]
	s_add_u32 s4, s4, 0x4000
	s_addc_u32 s5, s5, 0
	s_waitcnt vmcnt(7) lgkmcnt(2)
	v_pk_add_f32 v[148:149], v[148:149], v[180:181]
	v_pk_add_f32 v[150:151], v[150:151], v[182:183]
	global_store_dwordx4 v247, v[148:151], s[4:5]
	s_add_u32 s4, s4, 0x4000
	s_addc_u32 s5, s5, 0
	s_waitcnt vmcnt(7) lgkmcnt(1)
	v_pk_add_f32 v[152:153], v[152:153], v[184:185]
	v_pk_add_f32 v[154:155], v[154:155], v[186:187]
	global_store_dwordx4 v247, v[152:155], s[4:5]
	s_add_u32 s4, s4, 0x4000
	s_addc_u32 s5, s5, 0
	s_waitcnt vmcnt(7) lgkmcnt(0)
	v_pk_add_f32 v[156:157], v[156:157], v[188:189]
	v_pk_add_f32 v[158:159], v[158:159], v[190:191]
	global_store_dwordx4 v247, v[156:159], s[4:5]
	s_add_u32 s4, s4, 0x4000
	s_addc_u32 s5, s5, 0
	s_nop 1
	s_add_u32 s9, s9, 64
	s_branch .Lg15_tile

; #define PH(k) case k: if (ONLY_PHASE >= 0 && ONLY_PHASE != k) break;
; template <class Epi>
; DI void gemm_phase(char* smem, const bf16_t* A0, int lda0, int ksplit, const bf16_t* A1, int lda1, const bf16_t* Bt, int K, int nN, const Epi& epi, int tid) {
;   const int G = gridDim.x;
;   if ((G & 7) == 0) {
;     const int x = blockIdx.x & 7, l = blockIdx.x >> 3, L = G >> 3, per = 8 * nN, tot = 2 * per;
;     for (int q = l; q < tot; q += L) { const int rgl = q / per, rem = q % per, ct = rem >> 3, rt = (x * 2 + rgl) * 8 + (rem & 7);
;       gemm_tile(smem, A0, lda0, ksplit, A1, lda1, Bt, K, rt * 256, ct * 128, epi, tid); }
; template <int ph> DI void run_phase(const Ctx& c, char* smem) {
;     ...
;     PH(18) gemm_phase(smem, (const bf16_t*)(ws + OFF_R1), 4096, 1 << 30, XN, 1024, (const bf16_t*)(ws + OFF_W2) + 4096ull * 1024, 4096, 8, EpiResid{p.out, p.out}, TIDX); break;
.LBB0_1918:
	s_cmp_gt_i32 s94, 18
	s_cselect_b64 s[0:1], -1, 0
	s_cmp_lt_i32 s95, 19
	s_cselect_b64 s[2:3], -1, 0
	s_or_b64 s[0:1], s[0:1], s[2:3]
	s_and_b64 vcc, exec, s[0:1]
	s_cbranch_vccnz .LBB0_1946
	s_load_dword s12, s[74:75], 0x180
	s_add_u32 s0, s92, 0x7800000
	s_addc_u32 s1, s93, 0
	s_add_u32 s2, s92, 0x23c0000
	s_addc_u32 s3, s93, 0
	s_waitcnt lgkmcnt(0)
	s_and_b32 s14, s72, 0xffffffc0
	v_mbcnt_hi_u32_b32 v195, -1, v194
	s_and_b32 s13, s12, 7
	s_cmp_lg_u32 s13, 0
	s_waitcnt vmcnt(16)
	v_add_u32_e32 v196, s14, v195
	v_mbcnt_lo_u32_b32 v240, -1, 0
	v_mbcnt_hi_u32_b32 v240, -1, v240
	s_lshr_b32 s10, s72, 6
	s_lshl_b32 s101, s10, 10
	v_and_b32_e32 v241, 15, v240
	v_lshrrev_b32_e32 v242, 4, v240
	v_bfe_u32 v243, v240, 3, 1
	v_mul_u32_u24_e32 v243, 3, v243
	v_xor_b32_e32 v243, v242, v243
	v_lshlrev_b32_e32 v243, 4, v243
	v_lshl_add_u32 v243, v241, 6, v243
	s_lshr_b32 s9, s10, 1
	s_lshl_b32 s9, s9, 13
	v_add_u32_e32 v230, s9, v243
	s_and_b32 s9, s10, 1
	s_lshl_b32 s9, s9, 12
	s_add_u32 s9, s9, 16384
	v_add_u32_e32 v231, s9, v243
	s_lshr_b32 s9, s10, 1
	s_lshl_b32 s9, s9, 7
	v_add_u32_e32 v244, s9, v241
	s_and_b32 s9, s10, 1
	s_lshl_b32 s9, s9, 6
	v_lshl_add_u32 v245, v242, 2, s9
	s_movk_i32 s9, 0x1000
	v_mul_lo_u32 v246, v244, s9
	v_lshl_add_u32 v234, v245, 2, v246
	v_lshrrev_b32_e32 v241, 2, v240
	s_lshl_b32 s9, s10, 4
	v_add_u32_e32 v241, s9, v241
	v_bfe_u32 v242, v240, 5, 1
	v_mul_u32_u24_e32 v242, 3, v242
	v_and_b32_e32 v243, 3, v240
	v_xor_b32_e32 v243, v243, v242
	v_lshlrev_b32_e32 v243, 4, v243
	s_mov_b32 s9, 8192
	v_mad_u32_u24 v224, v241, s9, v243
	v_add_u32_e32 v225, 0x80000, v224
	v_add_u32_e32 v226, 0x100000, v224
	v_add_u32_e32 v227, 0x180000, v224
	s_mov_b32 s9, 8192
	v_mad_u32_u24 v228, v241, s9, v243
	v_add_u32_e32 v229, 0x80000, v228
	s_load_dwordx2 s[6:7], s[74:75], 0x168
	v_mbcnt_lo_u32_b32 v240, -1, 0
	v_mbcnt_hi_u32_b32 v240, -1, v240
	s_lshr_b32 s10, s72, 6
	s_mul_i32 s9, s10, 17408
	v_and_b32_e32 v241, 15, v240
	v_lshrrev_b32_e32 v242, 4, v240
	v_mul_u32_u24_e32 v243, 0x110, v241
	v_lshl_add_u32 v243, v242, 4, v243
	v_add_u32_e32 v245, s9, v243
	v_mul_u32_u24_e32 v243, 0x110, v242
	v_lshl_add_u32 v243, v241, 4, v243
	v_add_u32_e32 v246, s9, v243
	s_lshr_b32 s9, s10, 1
	s_lshl_b32 s9, s9, 7
	v_add_u32_e32 v243, s9, v242
	v_lshlrev_b32_e32 v243, 12, v243
	s_and_b32 s9, s10, 1
	s_lshl_b32 s9, s9, 8
	v_lshl_add_u32 v244, v241, 4, s9
	v_add_u32_e32 v247, v243, v244
	s_lshr_b32 s15, s96, 3
	s_and_b32 s18, s96, 7
	s_lshl_b32 s18, s18, 1
	s_waitcnt lgkmcnt(0)
; #define LWRITE(S, buf) do { bf16_t* sA_ = sbase + (buf) * BUF; bf16_t* sB_ = sA_ + 256 * PITCH; \
;     _Pragma("unroll") for (int i_ = 0; i_ < 4; ++i_) *(u32x4*)(sA_ + (sr + i_ * 64) * PITCH + scv * 8) = ra[S][i_]; \
;     _Pragma("unroll") for (int i_ = 0; i_ < 2; ++i_) *(u32x4*)(sB_ + (sr + i_ * 64) * PITCH + scv * 8) = rb[S][i_]; } while (0)
; template <class Epi>
; DI void gemm_tile(char* smem, const bf16_t* __restrict__ A0, int lda0, int ksplit, const bf16_t* __restrict__ A1, int lda1,
;                   const bf16_t* __restrict__ Bt, int K, int row0, int col0, const Epi& epi, int tid) {
;     ...
;   __syncthreads();
;   {
;     const int last = nk - 1;
;     GLOAD(0, 0);
;     __builtin_amdgcn_sched_barrier(0);
;     GLOAD(1, 1);
;     __builtin_amdgcn_sched_barrier(0);
;     LWRITE(0, 0);
;     __builtin_amdgcn_sched_barrier(0);
;     GLOAD(0, (2 < last ? 2 : last));
;     __builtin_amdgcn_sched_barrier(0);
;     __syncthreads();
; template <class Epi>
; DI void gemm_phase(char* smem, const bf16_t* A0, int lda0, int ksplit, const bf16_t* A1, int lda1, const bf16_t* Bt, int K, int nN, const Epi& epi, int tid) {
;     ...
;     for (int q = l; q < tot; q += L) { const int rgl = q / per, rem = q % per, ct = rem >> 3, rt = (x * 2 + rgl) * 8 + (rem & 7);
;       gemm_tile(smem, A0, lda0, ksplit, A1, lda1, Bt, K, rt * 256, ct * 128, epi, tid); }
.Lg18_tile:
	s_cmpk_ge_u32 s15, 128
	s_cbranch_scc1 .Lg18_done
	s_cmpk_ge_u32 s15, 64
	s_cselect_b32 s10, 1, 0
	s_cselect_b32 s9, 64, 0
	s_sub_u32 s9, s15, s9
	s_and_b32 s16, s9, 7
	s_lshl_b32 s16, s16, 3
	s_bfe_u32 s11, s9, 0x30003
	s_or_b32 s16, s16, s11
	s_andn2_b32 s9, s9, 63
	s_or_b32 s9, s9, s16
	s_add_u32 s10, s10, s18
	s_lshl_b32 s10, s10, 3
	s_and_b32 s16, s9, 7
	s_add_u32 s16, s16, s10
	s_lshl_b32 s16, s16, 8
	s_lshr_b32 s11, s9, 3
	s_lshl_b32 s11, s11, 7
	s_mul_i32 s10, s16, 8192
	s_add_u32 s10, s10, 0x7800000
	s_add_u32 s0, s92, s10
	s_addc_u32 s1, s93, 0
	s_mul_i32 s10, s11, 8192
	s_add_u32 s10, s10, 0x23c0000
	s_add_u32 s2, s92, s10
	s_addc_u32 s3, s93, 0
	s_waitcnt lgkmcnt(0)
	s_barrier
	s_mov_b32 s100, 0
	s_mov_b32 s17, 0
	s_add_u32 s9, s17, s101
	s_add_u32 m0, s9, 0
	s_nop 0
	global_load_lds_dwordx4 v224, s[0:1]
	s_add_u32 m0, s9, 4096
	s_nop 0
	global_load_lds_dwordx4 v225, s[0:1]
	s_add_u32 m0, s9, 8192
	s_nop 0
	global_load_lds_dwordx4 v226, s[0:1]
	s_add_u32 m0, s9, 12288
	s_nop 0
	global_load_lds_dwordx4 v227, s[0:1]
	s_add_u32 m0, s9, 16384
	s_nop 0
	global_load_lds_dwordx4 v228, s[2:3]
	s_add_u32 m0, s9, 20480
	s_nop 0
	global_load_lds_dwordx4 v229, s[2:3]
	s_add_u32 s0, s0, 64
	s_addc_u32 s1, s1, 0
	s_add_u32 s2, s2, 64
	s_addc_u32 s3, s3, 0
	s_add_u32 s100, s100, 1
	s_add_u32 s17, s17, 24576
	s_cmp_eq_u32 s17, 73728
	s_cselect_b32 s17, 0, s17
	s_add_u32 s9, s17, s101
	s_add_u32 m0, s9, 0
	s_nop 0
	global_load_lds_dwordx4 v224, s[0:1]
	s_add_u32 m0, s9, 4096
	s_nop 0
	global_load_lds_dwordx4 v225, s[0:1]
	s_add_u32 m0, s9, 8192
	s_nop 0
	global_load_lds_dwordx4 v226, s[0:1]
	s_add_u32 m0, s9, 12288
	s_nop 0
	global_load_lds_dwordx4 v227, s[0:1]
	s_add_u32 m0, s9, 16384
	s_nop 0
	global_load_lds_dwordx4 v228, s[2:3]
	s_add_u32 m0, s9, 20480
	s_nop 0
	global_load_lds_dwordx4 v229, s[2:3]
	s_add_u32 s0, s0, 64
	s_addc_u32 s1, s1, 0
	s_add_u32 s2, s2, 64
	s_addc_u32 s3, s3, 0
	s_add_u32 s100, s100, 1
	s_add_u32 s17, s17, 24576
	s_cmp_eq_u32 s17, 73728
	s_cselect_b32 s17, 0, s17
	s_add_u32 s9, s17, s101
	s_add_u32 m0, s9, 0
	s_nop 0
	global_load_lds_dwordx4 v224, s[0:1]
	s_add_u32 m0, s9, 4096
	s_nop 0
	global_load_lds_dwordx4 v225, s[0:1]
	s_add_u32 m0, s9, 8192
	s_nop 0
	global_load_lds_dwordx4 v226, s[0:1]
	s_add_u32 m0, s9, 12288
	s_nop 0
	global_load_lds_dwordx4 v227, s[0:1]
	s_add_u32 m0, s9, 16384
	s_nop 0
	global_load_lds_dwordx4 v228, s[2:3]
	s_add_u32 m0, s9, 20480
	s_nop 0
	global_load_lds_dwordx4 v229, s[2:3]
	s_add_u32 s0, s0, 64
	s_addc_u32 s1, s1, 0
	s_add_u32 s2, s2, 64
	s_addc_u32 s3, s3, 0
	s_add_u32 s100, s100, 1
	s_add_u32 s17, s17, 24576
	s_cmp_eq_u32 s17, 73728
	s_cselect_b32 s17, 0, s17
	v_mov_b32_e32 v0, 0
	v_mov_b32_e32 v1, 0
	v_mov_b32_e32 v2, 0
	v_mov_b32_e32 v3, 0
	v_mov_b32_e32 v4, 0
	v_mov_b32_e32 v5, 0
	v_mov_b32_e32 v6, 0
	v_mov_b32_e32 v7, 0
	v_mov_b32_e32 v8, 0
	v_mov_b32_e32 v9, 0
	v_mov_b32_e32 v10, 0
	v_mov_b32_e32 v11, 0
	v_mov_b32_e32 v12, 0
	v_mov_b32_e32 v13, 0
	v_mov_b32_e32 v14, 0
	v_mov_b32_e32 v15, 0
	v_mov_b32_e32 v16, 0
	v_mov_b32_e32 v17, 0
	v_mov_b32_e32 v18, 0
	v_mov_b32_e32 v19, 0
	v_mov_b32_e32 v20, 0
	v_mov_b32_e32 v21, 0
	v_mov_b32_e32 v22, 0
	v_mov_b32_e32 v23, 0
	v_mov_b32_e32 v24, 0
	v_mov_b32_e32 v25, 0
	v_mov_b32_e32 v26, 0
	v_mov_b32_e32 v27, 0
	v_mov_b32_e32 v28, 0
	v_mov_b32_e32 v29, 0
	v_mov_b32_e32 v30, 0
	v_mov_b32_e32 v31, 0
	v_mov_b32_e32 v32, 0
	v_mov_b32_e32 v33, 0
	v_mov_b32_e32 v34, 0
	v_mov_b32_e32 v35, 0
	v_mov_b32_e32 v36, 0
	v_mov_b32_e32 v37, 0
	v_mov_b32_e32 v38, 0
	v_mov_b32_e32 v39, 0
	v_mov_b32_e32 v40, 0
	v_mov_b32_e32 v41, 0
	v_mov_b32_e32 v42, 0
	v_mov_b32_e32 v43, 0
	v_mov_b32_e32 v44, 0
	v_mov_b32_e32 v45, 0
	v_mov_b32_e32 v46, 0
	v_mov_b32_e32 v47, 0
	v_mov_b32_e32 v48, 0
	v_mov_b32_e32 v49, 0
	v_mov_b32_e32 v50, 0
	v_mov_b32_e32 v51, 0
	v_mov_b32_e32 v52, 0
	v_mov_b32_e32 v53, 0
	v_mov_b32_e32 v54, 0
	v_mov_b32_e32 v55, 0
	v_mov_b32_e32 v56, 0
	v_mov_b32_e32 v57, 0
	v_mov_b32_e32 v58, 0
	v_mov_b32_e32 v59, 0
	v_mov_b32_e32 v60, 0
	v_mov_b32_e32 v61, 0
	v_mov_b32_e32 v62, 0
	v_mov_b32_e32 v63, 0
	v_mov_b32_e32 v64, 0
	v_mov_b32_e32 v65, 0
	v_mov_b32_e32 v66, 0
	v_mov_b32_e32 v67, 0
	v_mov_b32_e32 v68, 0
	v_mov_b32_e32 v69, 0
	v_mov_b32_e32 v70, 0
	v_mov_b32_e32 v71, 0
	v_mov_b32_e32 v72, 0
	v_mov_b32_e32 v73, 0
	v_mov_b32_e32 v74, 0
	v_mov_b32_e32 v75, 0
	v_mov_b32_e32 v76, 0
	v_mov_b32_e32 v77, 0
	v_mov_b32_e32 v78, 0
	v_mov_b32_e32 v79, 0
	v_mov_b32_e32 v80, 0
	v_mov_b32_e32 v81, 0
	v_mov_b32_e32 v82, 0
	v_mov_b32_e32 v83, 0
	v_mov_b32_e32 v84, 0
	v_mov_b32_e32 v85, 0
	v_mov_b32_e32 v86, 0
	v_mov_b32_e32 v87, 0
	v_mov_b32_e32 v88, 0
	v_mov_b32_e32 v89, 0
	v_mov_b32_e32 v90, 0
	v_mov_b32_e32 v91, 0
	v_mov_b32_e32 v92, 0
	v_mov_b32_e32 v93, 0
	v_mov_b32_e32 v94, 0
	v_mov_b32_e32 v95, 0
	v_mov_b32_e32 v96, 0
	v_mov_b32_e32 v97, 0
	v_mov_b32_e32 v98, 0
	v_mov_b32_e32 v99, 0
	v_mov_b32_e32 v100, 0
	v_mov_b32_e32 v101, 0
	v_mov_b32_e32 v102, 0
	v_mov_b32_e32 v103, 0
	v_mov_b32_e32 v104, 0
	v_mov_b32_e32 v105, 0
	v_mov_b32_e32 v106, 0
	v_mov_b32_e32 v107, 0
	v_mov_b32_e32 v108, 0
	v_mov_b32_e32 v109, 0
	v_mov_b32_e32 v110, 0
	v_mov_b32_e32 v111, 0
	v_mov_b32_e32 v112, 0
	v_mov_b32_e32 v113, 0
	v_mov_b32_e32 v114, 0
	v_mov_b32_e32 v115, 0
	v_mov_b32_e32 v116, 0
	v_mov_b32_e32 v117, 0
	v_mov_b32_e32 v118, 0
	v_mov_b32_e32 v119, 0
	v_mov_b32_e32 v120, 0
	v_mov_b32_e32 v121, 0
	v_mov_b32_e32 v122, 0
	v_mov_b32_e32 v123, 0
	v_mov_b32_e32 v124, 0
	v_mov_b32_e32 v125, 0
	v_mov_b32_e32 v126, 0
	v_mov_b32_e32 v127, 0
	s_mov_b32 s99, 0
	s_mov_b32 s98, 24576
	s_waitcnt vmcnt(12)
	s_barrier
	ds_read_b128 v[128:131], v231 offset:0
	ds_read_b128 v[132:135], v231 offset:1024
	ds_read_b128 v[136:139], v231 offset:2048
	ds_read_b128 v[140:143], v231 offset:3072
	ds_read_b128 v[144:147], v230 offset:0
	ds_read_b128 v[148:151], v230 offset:1024
	ds_read_b128 v[152:155], v230 offset:2048
	ds_read_b128 v[156:159], v230 offset:3072
	ds_read_b128 v[160:163], v230 offset:4096
	ds_read_b128 v[164:167], v230 offset:5120
	ds_read_b128 v[168:171], v230 offset:6144
	ds_read_b128 v[172:175], v230 offset:7168
